# e15 stack plus K-loop segment-edge trim in all 14 GEMM loops: loop-control SALU moved in front of the loop-back barrier, s_setprio 1 in front of each pre-MFMA barrier, duplicate lgkmcnt(0) behind it d
# baseline (speedup 1.0000x reference)
; #define PG8_STAGE(bufoff, gbase, voff) do { _Pragma("unroll") for (int _i = 0; _i < 2; ++_i) \
;         __builtin_amdgcn_global_load_lds((const unsigned*)((const char*)(gbase) + (voff)[_i]), (PG8_LAS unsigned*)(lds + (bufoff) + ldsw + _i * 8192), 16, 0, 0); } while (0)
; #define PG8_LDA(dst, b, h) do { _Pragma("unroll") for (int m = 0; m < 4; ++m) _Pragma("unroll") for (int k = 0; k < 2; ++k) dst[m][k] = *(const PG8_LAS bf16x8*)(lds + PG8_SA(b, h) + aoff + m * 2048 + k * 1024); } while (0)
; #define PG8_WAIT_V(n) asm volatile("s_waitcnt vmcnt(" #n ")" ::: "memory")
; #define PG8_BAR __builtin_amdgcn_s_barrier()
; template <class Epi, class Sched, bool ALIGN_EPI = false, bool SP2 = false>
; __device__ __forceinline__ void gemm_phase(PG8_LAS unsigned char* lds, const Gemm g, const Sched& S, const Epi& E) {
;     ...
;         for (int t = 0; t < nt; t += 2) {
;             if constexpr (Epi::MIDHOOK) { if (t == (nt >> 1)) E.mid(acc, cur, wr, wc, fr, fq); }
;             const bool last = (t == nt - 2);
;             const char* a1 = cA + (size_t)(t + 1) * kstep;
;             const char* a2 = last ? nA : cA + (size_t)(t + 2) * kstep; const char* b2 = last ? nB : cB + (size_t)(t + 2) * kstep;
;             const char* a3 = a2 + kstep; const char* b3 = b2 + kstep;
;             if (last && has_next) S.a_ready(nxt);
;             if constexpr (SP2) {
;             PG8_LDB(B0, 0, 0); PG8_LDB(B1, 0, 1); PG8_SCHED; PG8_LDA(At, 0, 0); PG8_STAGE(PG8_SA(1, 1), a1 + hstep, voffA);
;             PG8_WAIT_V(8); PG8_WAIT_L(0); PG8_BAR; PG8_MMA(0, 0, At, B0); PG8_MMA(0, 1, At, B1); PG8_BAR; PG8_SCHED;
;             PG8_LDA(At, 0, 1); PG8_STAGE(PG8_SB(0, 0), b2, voffB); PG8_STAGE(PG8_SB(0, 1), b2 + hstep, voffB); PG8_STAGE(PG8_SA(0, 0), a2, voffA);
;             PG8_WAIT_V(8); PG8_WAIT_L(0); PG8_BAR; PG8_MMA(1, 0, At, B0); PG8_MMA(1, 1, At, B1); PG8_BAR; PG8_SCHED;
;             PG8_LDB(B0, 1, 0); PG8_LDB(B1, 1, 1); PG8_SCHED; PG8_LDA(At, 1, 0); PG8_STAGE(PG8_SA(0, 1), a2 + hstep, voffA);
;             PG8_WAIT_V(8); PG8_WAIT_L(0); PG8_BAR; PG8_MMA(0, 0, At, B0); PG8_MMA(0, 1, At, B1); PG8_BAR; PG8_SCHED;
;             PG8_LDA(At, 1, 1); PG8_STAGE(PG8_SB(1, 0), b3, voffB); PG8_STAGE(PG8_SB(1, 1), b3 + hstep, voffB); PG8_STAGE(PG8_SA(1, 0), a3, voffA);
;             PG8_WAIT_V(8); PG8_WAIT_L(0); PG8_BAR; PG8_MMA(1, 0, At, B0); PG8_MMA(1, 1, At, B1); PG8_BAR; PG8_SCHED;
.LBB0_88:
	ds_read_b128 v[146:149], v153
	ds_read_b128 v[156:159], v153 offset:1024
	ds_read_b128 v[160:163], v153 offset:2048
	ds_read_b128 v[164:167], v153 offset:3072
	ds_read_b128 v[168:171], v154
	ds_read_b128 v[172:175], v154 offset:1024
	ds_read_b128 v[176:179], v154 offset:2048
	ds_read_b128 v[180:183], v154 offset:3072
	s_add_u32 s42, s40, 0xfff80080
	s_addc_u32 s43, s41, -1
	s_cmp_eq_u32 s52, 28
	s_cselect_b32 s45, s21, s43
	s_cselect_b32 s44, s48, s42
	s_cselect_b32 s43, s15, s51
	s_cselect_b32 s42, s49, s50
	v_lshl_add_u64 v[216:217], s[40:41], 0, v[138:139]
	s_add_i32 m0, s19, 0xc000
	ds_read_b128 v[184:187], v155
	ds_read_b128 v[188:191], v155 offset:1024
	ds_read_b128 v[192:195], v155 offset:2048
	ds_read_b128 v[196:199], v155 offset:3072
	ds_read_b128 v[200:203], v155 offset:4096
	ds_read_b128 v[204:207], v155 offset:5120
	ds_read_b128 v[208:211], v155 offset:6144
	ds_read_b128 v[212:215], v155 offset:7168
	global_load_lds_dwordx4 v[216:217], off
	v_lshl_add_u64 v[216:217], s[40:41], 0, v[140:141]
	s_add_i32 m0, s19, 0xe000
	s_nop 0
	global_load_lds_dwordx4 v[216:217], off
	s_waitcnt vmcnt(8)
	s_waitcnt lgkmcnt(0)
	s_setprio 1
	s_barrier
	v_mfma_f32_16x16x32_bf16 v[126:129], v[146:149], v[184:187], v[126:129]
	v_mfma_f32_16x16x32_bf16 v[122:125], v[160:163], v[184:187], v[122:125]
	v_mfma_f32_16x16x32_bf16 v[110:113], v[146:149], v[192:195], v[110:113]
	v_mfma_f32_16x16x32_bf16 v[106:109], v[160:163], v[192:195], v[106:109]
	v_mfma_f32_16x16x32_bf16 v[94:97], v[146:149], v[200:203], v[94:97]
	v_mfma_f32_16x16x32_bf16 v[90:93], v[160:163], v[200:203], v[90:93]
	v_mfma_f32_16x16x32_bf16 v[78:81], v[146:149], v[208:211], v[78:81]
	v_mfma_f32_16x16x32_bf16 v[74:77], v[160:163], v[208:211], v[74:77]
	v_mfma_f32_16x16x32_bf16 v[126:129], v[156:159], v[188:191], v[126:129]
	v_mfma_f32_16x16x32_bf16 v[122:125], v[164:167], v[188:191], v[122:125]
	v_mfma_f32_16x16x32_bf16 v[110:113], v[156:159], v[196:199], v[110:113]
	v_mfma_f32_16x16x32_bf16 v[106:109], v[164:167], v[196:199], v[106:109]
	v_mfma_f32_16x16x32_bf16 v[94:97], v[156:159], v[204:207], v[94:97]
	v_mfma_f32_16x16x32_bf16 v[90:93], v[164:167], v[204:207], v[90:93]
	v_mfma_f32_16x16x32_bf16 v[78:81], v[156:159], v[212:215], v[78:81]
	v_mfma_f32_16x16x32_bf16 v[74:77], v[164:167], v[212:215], v[74:77]
	s_setprio 0
	s_setprio 1
	v_mfma_f32_16x16x32_bf16 v[118:121], v[168:171], v[184:187], v[118:121]
	v_mfma_f32_16x16x32_bf16 v[114:117], v[176:179], v[184:187], v[114:117]
	v_mfma_f32_16x16x32_bf16 v[102:105], v[168:171], v[192:195], v[102:105]
	v_mfma_f32_16x16x32_bf16 v[98:101], v[176:179], v[192:195], v[98:101]
	v_mfma_f32_16x16x32_bf16 v[86:89], v[168:171], v[200:203], v[86:89]
	v_mfma_f32_16x16x32_bf16 v[82:85], v[176:179], v[200:203], v[82:85]
	v_mfma_f32_16x16x32_bf16 v[70:73], v[168:171], v[208:211], v[70:73]
	v_mfma_f32_16x16x32_bf16 v[66:69], v[176:179], v[208:211], v[66:69]
	v_mfma_f32_16x16x32_bf16 v[118:121], v[172:175], v[188:191], v[118:121]
	v_mfma_f32_16x16x32_bf16 v[114:117], v[180:183], v[188:191], v[114:117]
	v_mfma_f32_16x16x32_bf16 v[102:105], v[172:175], v[196:199], v[102:105]
	v_mfma_f32_16x16x32_bf16 v[98:101], v[180:183], v[196:199], v[98:101]
	v_mfma_f32_16x16x32_bf16 v[86:89], v[172:175], v[204:207], v[86:89]
	v_mfma_f32_16x16x32_bf16 v[82:85], v[180:183], v[204:207], v[82:85]
	v_mfma_f32_16x16x32_bf16 v[70:73], v[172:175], v[212:215], v[70:73]
	v_mfma_f32_16x16x32_bf16 v[66:69], v[180:183], v[212:215], v[66:69]
	s_setprio 0
	s_barrier
	s_add_i32 s53, s31, s16
	v_lshl_add_u64 v[216:217], s[42:43], 0, v[134:135]
	s_mov_b32 m0, s53
	ds_read_b128 v[184:187], v155 offset:16384
	ds_read_b128 v[188:191], v155 offset:17408
	ds_read_b128 v[192:195], v155 offset:18432
	ds_read_b128 v[196:199], v155 offset:19456
	ds_read_b128 v[200:203], v155 offset:20480
	ds_read_b128 v[204:207], v155 offset:21504
	ds_read_b128 v[208:211], v155 offset:22528
	ds_read_b128 v[212:215], v155 offset:23552
	global_load_lds_dwordx4 v[216:217], off
	s_add_i32 m0, s53, 0x2000
	s_add_u32 s54, s42, 0x80000
	v_lshl_add_u64 v[218:219], s[42:43], 0, v[130:131]
	s_addc_u32 s55, s43, 0
	s_add_i32 s53, s39, s16
	global_load_lds_dwordx4 v[218:219], off
	v_lshl_add_u64 v[220:221], s[54:55], 0, v[134:135]
	s_mov_b32 m0, s53
	v_lshl_add_u64 v[222:223], s[44:45], 0, v[132:133]
	global_load_lds_dwordx4 v[220:221], off
	v_lshl_add_u64 v[220:221], s[54:55], 0, v[130:131]
	s_add_i32 m0, s53, 0x2000
	s_nop 0
	global_load_lds_dwordx4 v[220:221], off
	v_lshl_add_u64 v[220:221], s[44:45], 0, v[136:137]
	s_mov_b32 m0, s19
	s_nop 0
	global_load_lds_dwordx4 v[220:221], off
	s_mov_b32 m0, s24
	s_nop 0
	global_load_lds_dwordx4 v[222:223], off
	s_waitcnt vmcnt(8)
	s_waitcnt lgkmcnt(0)
	s_setprio 1
	s_barrier
; #define PG8_STAGE(bufoff, gbase, voff) do { _Pragma("unroll") for (int _i = 0; _i < 2; ++_i) \
;         __builtin_amdgcn_global_load_lds((const unsigned*)((const char*)(gbase) + (voff)[_i]), (PG8_LAS unsigned*)(lds + (bufoff) + ldsw + _i * 8192), 16, 0, 0); } while (0)
; #define PG8_LDA(dst, b, h) do { _Pragma("unroll") for (int m = 0; m < 4; ++m) _Pragma("unroll") for (int k = 0; k < 2; ++k) dst[m][k] = *(const PG8_LAS bf16x8*)(lds + PG8_SA(b, h) + aoff + m * 2048 + k * 1024); } while (0)
; #define PG8_LDB(dst, b, h) do { _Pragma("unroll") for (int n = 0; n < 2; ++n) _Pragma("unroll") for (int k = 0; k < 2; ++k) dst[n][k] = *(const PG8_LAS bf16x8*)(lds + PG8_SB(b, h) + boff + n * 2048 + k * 1024); } while (0)
; #define PG8_MMA(ai, bj, At, Bt) do { __builtin_amdgcn_s_setprio(1); _Pragma("unroll") for (int m = 0; m < 4; ++m) _Pragma("unroll") for (int n = 0; n < 2; ++n) _Pragma("unroll") for (int k = 0; k < 2; ++k) \
;         acc[ai][bj][m][n] = __builtin_amdgcn_mfma_f32_16x16x32_bf16(Bt[n][k], At[m][k], acc[ai][bj][m][n], 0, 0, 0); __builtin_amdgcn_s_setprio(0); } while (0)
; #define PG8_WAIT_V(n) asm volatile("s_waitcnt vmcnt(" #n ")" ::: "memory")
; template <class Epi, class Sched, bool ALIGN_EPI = false, bool SP2 = false>
; __device__ __forceinline__ void gemm_phase(PG8_LAS unsigned char* lds, const Gemm g, const Sched& S, const Epi& E) {
;     ...
;             PG8_LDB(B0, 0, 0); PG8_LDB(B1, 0, 1); PG8_SCHED; PG8_LDA(At, 0, 0); PG8_STAGE(PG8_SA(1, 1), a1 + hstep, voffA);
;             PG8_WAIT_V(8); PG8_WAIT_L(0); PG8_BAR; PG8_MMA(0, 0, At, B0); PG8_MMA(0, 1, At, B1); PG8_BAR; PG8_SCHED;
;             PG8_LDA(At, 0, 1); PG8_STAGE(PG8_SB(0, 0), b2, voffB); PG8_STAGE(PG8_SB(0, 1), b2 + hstep, voffB); PG8_STAGE(PG8_SA(0, 0), a2, voffA);
;             PG8_WAIT_V(8); PG8_WAIT_L(0); PG8_BAR; PG8_MMA(1, 0, At, B0); PG8_MMA(1, 1, At, B1); PG8_BAR; PG8_SCHED;
;             PG8_LDB(B0, 1, 0); PG8_LDB(B1, 1, 1); PG8_SCHED; PG8_LDA(At, 1, 0); PG8_STAGE(PG8_SA(0, 1), a2 + hstep, voffA);
;             PG8_WAIT_V(8); PG8_WAIT_L(0); PG8_BAR; PG8_MMA(0, 0, At, B0); PG8_MMA(0, 1, At, B1); PG8_BAR; PG8_SCHED;
;             PG8_LDA(At, 1, 1); PG8_STAGE(PG8_SB(1, 0), b3, voffB); PG8_STAGE(PG8_SB(1, 1), b3 + hstep, voffB); PG8_STAGE(PG8_SA(1, 0), a3, voffA);
;             PG8_WAIT_V(8); PG8_WAIT_L(0); PG8_BAR; PG8_MMA(1, 0, At, B0); PG8_MMA(1, 1, At, B1); PG8_BAR; PG8_SCHED;
	v_mfma_f32_16x16x32_bf16 v[62:65], v[146:149], v[184:187], v[62:65]
	v_mfma_f32_16x16x32_bf16 v[58:61], v[160:163], v[184:187], v[58:61]
	v_mfma_f32_16x16x32_bf16 v[46:49], v[146:149], v[192:195], v[46:49]
	v_mfma_f32_16x16x32_bf16 v[42:45], v[160:163], v[192:195], v[42:45]
	v_mfma_f32_16x16x32_bf16 v[30:33], v[146:149], v[200:203], v[30:33]
	v_mfma_f32_16x16x32_bf16 v[26:29], v[160:163], v[200:203], v[26:29]
	v_mfma_f32_16x16x32_bf16 v[14:17], v[146:149], v[208:211], v[14:17]
	v_mfma_f32_16x16x32_bf16 v[10:13], v[160:163], v[208:211], v[10:13]
	v_mfma_f32_16x16x32_bf16 v[62:65], v[156:159], v[188:191], v[62:65]
	v_mfma_f32_16x16x32_bf16 v[58:61], v[164:167], v[188:191], v[58:61]
	v_mfma_f32_16x16x32_bf16 v[46:49], v[156:159], v[196:199], v[46:49]
	v_mfma_f32_16x16x32_bf16 v[42:45], v[164:167], v[196:199], v[42:45]
	v_mfma_f32_16x16x32_bf16 v[30:33], v[156:159], v[204:207], v[30:33]
	v_mfma_f32_16x16x32_bf16 v[26:29], v[164:167], v[204:207], v[26:29]
	v_mfma_f32_16x16x32_bf16 v[14:17], v[156:159], v[212:215], v[14:17]
	v_mfma_f32_16x16x32_bf16 v[10:13], v[164:167], v[212:215], v[10:13]
	s_setprio 0
	s_setprio 1
	v_mfma_f32_16x16x32_bf16 v[54:57], v[168:171], v[184:187], v[54:57]
	v_mfma_f32_16x16x32_bf16 v[50:53], v[176:179], v[184:187], v[50:53]
	v_mfma_f32_16x16x32_bf16 v[38:41], v[168:171], v[192:195], v[38:41]
	v_mfma_f32_16x16x32_bf16 v[34:37], v[176:179], v[192:195], v[34:37]
	v_mfma_f32_16x16x32_bf16 v[22:25], v[168:171], v[200:203], v[22:25]
	v_mfma_f32_16x16x32_bf16 v[18:21], v[176:179], v[200:203], v[18:21]
	v_mfma_f32_16x16x32_bf16 v[6:9], v[168:171], v[208:211], v[6:9]
	v_mfma_f32_16x16x32_bf16 v[2:5], v[176:179], v[208:211], v[2:5]
	v_mfma_f32_16x16x32_bf16 v[54:57], v[172:175], v[188:191], v[54:57]
	v_mfma_f32_16x16x32_bf16 v[50:53], v[180:183], v[188:191], v[50:53]
	v_mfma_f32_16x16x32_bf16 v[38:41], v[172:175], v[196:199], v[38:41]
	v_mfma_f32_16x16x32_bf16 v[34:37], v[180:183], v[196:199], v[34:37]
	v_mfma_f32_16x16x32_bf16 v[22:25], v[172:175], v[204:207], v[22:25]
	v_mfma_f32_16x16x32_bf16 v[18:21], v[180:183], v[204:207], v[18:21]
	v_mfma_f32_16x16x32_bf16 v[6:9], v[172:175], v[212:215], v[6:9]
	v_mfma_f32_16x16x32_bf16 v[2:5], v[180:183], v[212:215], v[2:5]
	s_setprio 0
	s_barrier
	s_add_i32 s53, 0, 0x18000
	s_add_i32 s54, 0, 0x1c000
	v_add_u32_e32 v164, s53, v151
	v_add_u32_e32 v180, s54, v151
	ds_read_b128 v[146:149], v164
	ds_read_b128 v[156:159], v164 offset:1024
	ds_read_b128 v[160:163], v164 offset:2048
	ds_read_b128 v[164:167], v164 offset:3072
	ds_read_b128 v[168:171], v180
	ds_read_b128 v[172:175], v180 offset:1024
	ds_read_b128 v[176:179], v180 offset:2048
	ds_read_b128 v[180:183], v180 offset:3072
	s_add_u32 s44, s44, 0x80000
	s_addc_u32 s45, s45, 0
	s_mov_b32 m0, s25
	v_lshl_add_u64 v[224:225], s[44:45], 0, v[136:137]
	ds_read_b128 v[184:187], v155 offset:32768
	ds_read_b128 v[188:191], v155 offset:33792
	ds_read_b128 v[192:195], v155 offset:34816
	ds_read_b128 v[196:199], v155 offset:35840
	ds_read_b128 v[200:203], v155 offset:36864
	ds_read_b128 v[204:207], v155 offset:37888
	ds_read_b128 v[208:211], v155 offset:38912
	ds_read_b128 v[212:215], v155 offset:39936
	global_load_lds_dwordx4 v[224:225], off
	v_lshl_add_u64 v[224:225], s[44:45], 0, v[132:133]
	s_mov_b32 m0, s26
	s_nop 0
	global_load_lds_dwordx4 v[224:225], off
	s_waitcnt vmcnt(8)
	s_waitcnt lgkmcnt(0)
	s_setprio 1
	s_barrier
	v_mfma_f32_16x16x32_bf16 v[126:129], v[146:149], v[184:187], v[126:129]
	v_mfma_f32_16x16x32_bf16 v[122:125], v[160:163], v[184:187], v[122:125]
	v_mfma_f32_16x16x32_bf16 v[110:113], v[146:149], v[192:195], v[110:113]
	v_mfma_f32_16x16x32_bf16 v[106:109], v[160:163], v[192:195], v[106:109]
	v_mfma_f32_16x16x32_bf16 v[94:97], v[146:149], v[200:203], v[94:97]
	v_mfma_f32_16x16x32_bf16 v[90:93], v[160:163], v[200:203], v[90:93]
	v_mfma_f32_16x16x32_bf16 v[78:81], v[146:149], v[208:211], v[78:81]
	v_mfma_f32_16x16x32_bf16 v[74:77], v[160:163], v[208:211], v[74:77]
	v_mfma_f32_16x16x32_bf16 v[126:129], v[156:159], v[188:191], v[126:129]
	v_mfma_f32_16x16x32_bf16 v[122:125], v[164:167], v[188:191], v[122:125]
	v_mfma_f32_16x16x32_bf16 v[110:113], v[156:159], v[196:199], v[110:113]
	v_mfma_f32_16x16x32_bf16 v[106:109], v[164:167], v[196:199], v[106:109]
	v_mfma_f32_16x16x32_bf16 v[94:97], v[156:159], v[204:207], v[94:97]
	v_mfma_f32_16x16x32_bf16 v[90:93], v[164:167], v[204:207], v[90:93]
	v_mfma_f32_16x16x32_bf16 v[78:81], v[156:159], v[212:215], v[78:81]
	v_mfma_f32_16x16x32_bf16 v[74:77], v[164:167], v[212:215], v[74:77]
	s_setprio 0
	s_setprio 1
	v_mfma_f32_16x16x32_bf16 v[118:121], v[168:171], v[184:187], v[118:121]
	v_mfma_f32_16x16x32_bf16 v[114:117], v[176:179], v[184:187], v[114:117]
	v_mfma_f32_16x16x32_bf16 v[102:105], v[168:171], v[192:195], v[102:105]
	v_mfma_f32_16x16x32_bf16 v[98:101], v[176:179], v[192:195], v[98:101]
	v_mfma_f32_16x16x32_bf16 v[86:89], v[168:171], v[200:203], v[86:89]
	v_mfma_f32_16x16x32_bf16 v[82:85], v[176:179], v[200:203], v[82:85]
	v_mfma_f32_16x16x32_bf16 v[70:73], v[168:171], v[208:211], v[70:73]
	v_mfma_f32_16x16x32_bf16 v[66:69], v[176:179], v[208:211], v[66:69]
	v_mfma_f32_16x16x32_bf16 v[118:121], v[172:175], v[188:191], v[118:121]
	v_mfma_f32_16x16x32_bf16 v[114:117], v[180:183], v[188:191], v[114:117]
	v_mfma_f32_16x16x32_bf16 v[102:105], v[172:175], v[196:199], v[102:105]
	v_mfma_f32_16x16x32_bf16 v[98:101], v[180:183], v[196:199], v[98:101]
	v_mfma_f32_16x16x32_bf16 v[86:89], v[172:175], v[204:207], v[86:89]
	v_mfma_f32_16x16x32_bf16 v[82:85], v[180:183], v[204:207], v[82:85]
	v_mfma_f32_16x16x32_bf16 v[70:73], v[172:175], v[212:215], v[70:73]
	v_mfma_f32_16x16x32_bf16 v[66:69], v[180:183], v[212:215], v[66:69]
	s_setprio 0
	s_barrier
; #define PG8_STAGE(bufoff, gbase, voff) do { _Pragma("unroll") for (int _i = 0; _i < 2; ++_i) \
;         __builtin_amdgcn_global_load_lds((const unsigned*)((const char*)(gbase) + (voff)[_i]), (PG8_LAS unsigned*)(lds + (bufoff) + ldsw + _i * 8192), 16, 0, 0); } while (0)
; #define PG8_LDA(dst, b, h) do { _Pragma("unroll") for (int m = 0; m < 4; ++m) _Pragma("unroll") for (int k = 0; k < 2; ++k) dst[m][k] = *(const PG8_LAS bf16x8*)(lds + PG8_SA(b, h) + aoff + m * 2048 + k * 1024); } while (0)
; #define PG8_LDB(dst, b, h) do { _Pragma("unroll") for (int n = 0; n < 2; ++n) _Pragma("unroll") for (int k = 0; k < 2; ++k) dst[n][k] = *(const PG8_LAS bf16x8*)(lds + PG8_SB(b, h) + boff + n * 2048 + k * 1024); } while (0)
; #define PG8_MMA(ai, bj, At, Bt) do { __builtin_amdgcn_s_setprio(1); _Pragma("unroll") for (int m = 0; m < 4; ++m) _Pragma("unroll") for (int n = 0; n < 2; ++n) _Pragma("unroll") for (int k = 0; k < 2; ++k) \
;         acc[ai][bj][m][n] = __builtin_amdgcn_mfma_f32_16x16x32_bf16(Bt[n][k], At[m][k], acc[ai][bj][m][n], 0, 0, 0); __builtin_amdgcn_s_setprio(0); } while (0)
; #define PG8_WAIT_V(n) asm volatile("s_waitcnt vmcnt(" #n ")" ::: "memory")
; #define PG8_WAIT_L(n) asm volatile("s_waitcnt lgkmcnt(" #n ")" ::: "memory")
; #define PG8_BAR __builtin_amdgcn_s_barrier()
; #define PG8_SCHED __builtin_amdgcn_sched_barrier(0)
; template <class Epi, class Sched, bool ALIGN_EPI = false, bool SP2 = false>
; __device__ __forceinline__ void gemm_phase(PG8_LAS unsigned char* lds, const Gemm g, const Sched& S, const Epi& E) {
;     ...
;             PG8_LDB(B0, 1, 0); PG8_LDB(B1, 1, 1); PG8_SCHED; PG8_LDA(At, 1, 0); PG8_STAGE(PG8_SA(0, 1), a2 + hstep, voffA);
;             PG8_WAIT_V(8); PG8_WAIT_L(0); PG8_BAR; PG8_MMA(0, 0, At, B0); PG8_MMA(0, 1, At, B1); PG8_BAR; PG8_SCHED;
;             PG8_LDA(At, 1, 1); PG8_STAGE(PG8_SB(1, 0), b3, voffB); PG8_STAGE(PG8_SB(1, 1), b3 + hstep, voffB); PG8_STAGE(PG8_SA(1, 0), a3, voffA);
;             PG8_WAIT_V(8); PG8_WAIT_L(0); PG8_BAR; PG8_MMA(1, 0, At, B0); PG8_MMA(1, 1, At, B1); PG8_BAR; PG8_SCHED;
;     ...
;         if constexpr (ALIGN_EPI) { if (wr == 0) PG8_BAR; }
	s_add_i32 s44, s53, s16
	v_lshl_add_u64 v[216:217], v[216:217], 0, s[10:11]
	s_mov_b32 m0, s44
	ds_read_b128 v[184:187], v155 offset:49152
	ds_read_b128 v[188:191], v155 offset:50176
	ds_read_b128 v[192:195], v155 offset:51200
	ds_read_b128 v[196:199], v155 offset:52224
	ds_read_b128 v[200:203], v155 offset:53248
	ds_read_b128 v[204:207], v155 offset:54272
	ds_read_b128 v[208:211], v155 offset:55296
	ds_read_b128 v[212:215], v155 offset:56320
	global_load_lds_dwordx4 v[216:217], off
	s_add_i32 m0, s44, 0x2000
	s_add_u32 s42, s42, 0x80080
	v_lshl_add_u64 v[216:217], v[218:219], 0, s[10:11]
	s_addc_u32 s43, s43, 0
	s_add_i32 s44, s54, s16
	global_load_lds_dwordx4 v[216:217], off
	v_lshl_add_u64 v[216:217], s[42:43], 0, v[134:135]
	s_mov_b32 m0, s44
	s_nop 0
	global_load_lds_dwordx4 v[216:217], off
	v_lshl_add_u64 v[216:217], s[42:43], 0, v[130:131]
	s_add_i32 m0, s44, 0x2000
	s_nop 0
	global_load_lds_dwordx4 v[216:217], off
	v_lshl_add_u64 v[216:217], v[220:221], 0, s[10:11]
	s_mov_b32 m0, s29
	s_nop 0
	global_load_lds_dwordx4 v[216:217], off
	v_lshl_add_u64 v[216:217], v[222:223], 0, s[10:11]
	s_mov_b32 m0, s30
	s_nop 0
	global_load_lds_dwordx4 v[216:217], off
	s_waitcnt vmcnt(8)
	s_waitcnt lgkmcnt(0)
	s_setprio 1
	s_barrier
	v_mfma_f32_16x16x32_bf16 v[62:65], v[146:149], v[184:187], v[62:65]
	v_mfma_f32_16x16x32_bf16 v[58:61], v[160:163], v[184:187], v[58:61]
	v_mfma_f32_16x16x32_bf16 v[46:49], v[146:149], v[192:195], v[46:49]
	v_mfma_f32_16x16x32_bf16 v[42:45], v[160:163], v[192:195], v[42:45]
	v_mfma_f32_16x16x32_bf16 v[30:33], v[146:149], v[200:203], v[30:33]
	v_mfma_f32_16x16x32_bf16 v[26:29], v[160:163], v[200:203], v[26:29]
	v_mfma_f32_16x16x32_bf16 v[14:17], v[146:149], v[208:211], v[14:17]
	v_mfma_f32_16x16x32_bf16 v[10:13], v[160:163], v[208:211], v[10:13]
	v_mfma_f32_16x16x32_bf16 v[62:65], v[156:159], v[188:191], v[62:65]
	v_mfma_f32_16x16x32_bf16 v[58:61], v[164:167], v[188:191], v[58:61]
	v_mfma_f32_16x16x32_bf16 v[46:49], v[156:159], v[196:199], v[46:49]
	v_mfma_f32_16x16x32_bf16 v[42:45], v[164:167], v[196:199], v[42:45]
	v_mfma_f32_16x16x32_bf16 v[30:33], v[156:159], v[204:207], v[30:33]
	v_mfma_f32_16x16x32_bf16 v[26:29], v[164:167], v[204:207], v[26:29]
	v_mfma_f32_16x16x32_bf16 v[14:17], v[156:159], v[212:215], v[14:17]
	v_mfma_f32_16x16x32_bf16 v[10:13], v[164:167], v[212:215], v[10:13]
	s_setprio 0
	s_setprio 1
	v_mfma_f32_16x16x32_bf16 v[54:57], v[168:171], v[184:187], v[54:57]
	v_mfma_f32_16x16x32_bf16 v[50:53], v[176:179], v[184:187], v[50:53]
	v_mfma_f32_16x16x32_bf16 v[38:41], v[168:171], v[192:195], v[38:41]
	v_mfma_f32_16x16x32_bf16 v[34:37], v[176:179], v[192:195], v[34:37]
	v_mfma_f32_16x16x32_bf16 v[22:25], v[168:171], v[200:203], v[22:25]
	v_mfma_f32_16x16x32_bf16 v[18:21], v[176:179], v[200:203], v[18:21]
	v_mfma_f32_16x16x32_bf16 v[6:9], v[168:171], v[208:211], v[6:9]
	v_mfma_f32_16x16x32_bf16 v[2:5], v[176:179], v[208:211], v[2:5]
	v_mfma_f32_16x16x32_bf16 v[54:57], v[172:175], v[188:191], v[54:57]
	v_mfma_f32_16x16x32_bf16 v[50:53], v[180:183], v[188:191], v[50:53]
	v_mfma_f32_16x16x32_bf16 v[38:41], v[172:175], v[196:199], v[38:41]
	v_mfma_f32_16x16x32_bf16 v[34:37], v[180:183], v[196:199], v[34:37]
	v_mfma_f32_16x16x32_bf16 v[22:25], v[172:175], v[204:207], v[22:25]
	v_mfma_f32_16x16x32_bf16 v[18:21], v[180:183], v[204:207], v[18:21]
	v_mfma_f32_16x16x32_bf16 v[6:9], v[172:175], v[212:215], v[6:9]
	v_mfma_f32_16x16x32_bf16 v[2:5], v[180:183], v[212:215], v[2:5]
	s_setprio 0
	s_add_i32 s52, s52, 2
	s_add_u32 s40, s40, 0x100
	s_addc_u32 s41, s41, 0
	s_add_u32 s50, s50, 0x100
	s_addc_u32 s51, s51, 0
	s_cmp_gt_u32 s52, 29
	s_barrier
	s_cbranch_scc0 .LBB0_88
	s_and_b64 vcc, exec, s[12:13]
	s_cbranch_vccz .LBB0_91
	s_barrier

; #define PG8_STAGE(bufoff, gbase, voff) do { _Pragma("unroll") for (int _i = 0; _i < 2; ++_i) \
;         __builtin_amdgcn_global_load_lds((const unsigned*)((const char*)(gbase) + (voff)[_i]), (PG8_LAS unsigned*)(lds + (bufoff) + ldsw + _i * 8192), 16, 0, 0); } while (0)
; #define PG8_LDA(dst, b, h) do { _Pragma("unroll") for (int m = 0; m < 4; ++m) _Pragma("unroll") for (int k = 0; k < 2; ++k) dst[m][k] = *(const PG8_LAS bf16x8*)(lds + PG8_SA(b, h) + aoff + m * 2048 + k * 1024); } while (0)
; #define PG8_WAIT_V(n) asm volatile("s_waitcnt vmcnt(" #n ")" ::: "memory")
; #define PG8_BAR __builtin_amdgcn_s_barrier()
; template <class Epi, class Sched, bool ALIGN_EPI = false, bool SP2 = false>
; __device__ __forceinline__ void gemm_phase(PG8_LAS unsigned char* lds, const Gemm g, const Sched& S, const Epi& E) {
;     ...
;         for (int t = 0; t < nt; t += 2) {
;             if constexpr (Epi::MIDHOOK) { if (t == (nt >> 1)) E.mid(acc, cur, wr, wc, fr, fq); }
;             const bool last = (t == nt - 2);
;             const char* a1 = cA + (size_t)(t + 1) * kstep;
;             const char* a2 = last ? nA : cA + (size_t)(t + 2) * kstep; const char* b2 = last ? nB : cB + (size_t)(t + 2) * kstep;
;             const char* a3 = a2 + kstep; const char* b3 = b2 + kstep;
;             if (last && has_next) S.a_ready(nxt);
;             if constexpr (SP2) {
;             PG8_LDB(B0, 0, 0); PG8_LDB(B1, 0, 1); PG8_SCHED; PG8_LDA(At, 0, 0); PG8_STAGE(PG8_SA(1, 1), a1 + hstep, voffA);
;             PG8_WAIT_V(8); PG8_WAIT_L(0); PG8_BAR; PG8_MMA(0, 0, At, B0); PG8_MMA(0, 1, At, B1); PG8_BAR; PG8_SCHED;
;             PG8_LDA(At, 0, 1); PG8_STAGE(PG8_SB(0, 0), b2, voffB); PG8_STAGE(PG8_SB(0, 1), b2 + hstep, voffB); PG8_STAGE(PG8_SA(0, 0), a2, voffA);
;             PG8_WAIT_V(8); PG8_WAIT_L(0); PG8_BAR; PG8_MMA(1, 0, At, B0); PG8_MMA(1, 1, At, B1); PG8_BAR; PG8_SCHED;
;             PG8_LDB(B0, 1, 0); PG8_LDB(B1, 1, 1); PG8_SCHED; PG8_LDA(At, 1, 0); PG8_STAGE(PG8_SA(0, 1), a2 + hstep, voffA);
;             PG8_WAIT_V(8); PG8_WAIT_L(0); PG8_BAR; PG8_MMA(0, 0, At, B0); PG8_MMA(0, 1, At, B1); PG8_BAR; PG8_SCHED;
;             PG8_LDA(At, 1, 1); PG8_STAGE(PG8_SB(1, 0), b3, voffB); PG8_STAGE(PG8_SB(1, 1), b3 + hstep, voffB); PG8_STAGE(PG8_SA(1, 0), a3, voffA);
;             PG8_WAIT_V(8); PG8_WAIT_L(0); PG8_BAR; PG8_MMA(1, 0, At, B0); PG8_MMA(1, 1, At, B1); PG8_BAR; PG8_SCHED;
.LBB0_173:
	ds_read_b128 v[154:157], v151
	ds_read_b128 v[158:161], v151 offset:1024
	ds_read_b128 v[162:165], v151 offset:2048
	ds_read_b128 v[166:169], v151 offset:3072
	ds_read_b128 v[170:173], v152
	ds_read_b128 v[174:177], v152 offset:1024
	ds_read_b128 v[178:181], v152 offset:2048
	ds_read_b128 v[182:185], v152 offset:3072
	s_add_u32 s36, s22, 0x100
	s_addc_u32 s37, s23, 0
	s_cmpk_eq_i32 s48, 0x54
	s_cselect_b32 s41, s7, s37
	s_cselect_b32 s40, s6, s36
	s_cselect_b32 s39, s21, s47
	s_cselect_b32 s38, s20, s46
	v_lshl_add_u64 v[146:147], s[22:23], 0, v[138:139]
	s_add_i32 m0, s18, 0xc000
	ds_read_b128 v[186:189], v153
	ds_read_b128 v[190:193], v153 offset:1024
	ds_read_b128 v[194:197], v153 offset:2048
	ds_read_b128 v[198:201], v153 offset:3072
	ds_read_b128 v[202:205], v153 offset:4096
	ds_read_b128 v[206:209], v153 offset:5120
	ds_read_b128 v[210:213], v153 offset:6144
	ds_read_b128 v[214:217], v153 offset:7168
	global_load_lds_dwordx4 v[146:147], off
	v_lshl_add_u64 v[146:147], s[22:23], 0, v[140:141]
	s_add_i32 m0, s18, 0xe000
	s_nop 0
	global_load_lds_dwordx4 v[146:147], off
	s_waitcnt vmcnt(8)
	s_waitcnt lgkmcnt(0)
	s_setprio 1
	s_barrier
	v_mfma_f32_16x16x32_bf16 v[126:129], v[154:157], v[186:189], v[126:129]
	v_mfma_f32_16x16x32_bf16 v[122:125], v[162:165], v[186:189], v[122:125]
	v_mfma_f32_16x16x32_bf16 v[118:121], v[154:157], v[194:197], v[118:121]
	v_mfma_f32_16x16x32_bf16 v[110:113], v[162:165], v[194:197], v[110:113]
	v_mfma_f32_16x16x32_bf16 v[102:105], v[154:157], v[202:205], v[102:105]
	v_mfma_f32_16x16x32_bf16 v[94:97], v[162:165], v[202:205], v[94:97]
	v_mfma_f32_16x16x32_bf16 v[86:89], v[154:157], v[210:213], v[86:89]
	v_mfma_f32_16x16x32_bf16 v[78:81], v[162:165], v[210:213], v[78:81]
	v_mfma_f32_16x16x32_bf16 v[126:129], v[158:161], v[190:193], v[126:129]
	v_mfma_f32_16x16x32_bf16 v[122:125], v[166:169], v[190:193], v[122:125]
	v_mfma_f32_16x16x32_bf16 v[118:121], v[158:161], v[198:201], v[118:121]
	v_mfma_f32_16x16x32_bf16 v[110:113], v[166:169], v[198:201], v[110:113]
	v_mfma_f32_16x16x32_bf16 v[102:105], v[158:161], v[206:209], v[102:105]
	v_mfma_f32_16x16x32_bf16 v[94:97], v[166:169], v[206:209], v[94:97]
	v_mfma_f32_16x16x32_bf16 v[86:89], v[158:161], v[214:217], v[86:89]
	v_mfma_f32_16x16x32_bf16 v[78:81], v[166:169], v[214:217], v[78:81]
	s_setprio 0
	s_setprio 1
	v_mfma_f32_16x16x32_bf16 v[114:117], v[170:173], v[186:189], v[114:117]
	v_mfma_f32_16x16x32_bf16 v[106:109], v[178:181], v[186:189], v[106:109]
	v_mfma_f32_16x16x32_bf16 v[98:101], v[170:173], v[194:197], v[98:101]
	v_mfma_f32_16x16x32_bf16 v[90:93], v[178:181], v[194:197], v[90:93]
	v_mfma_f32_16x16x32_bf16 v[82:85], v[170:173], v[202:205], v[82:85]
	v_mfma_f32_16x16x32_bf16 v[74:77], v[178:181], v[202:205], v[74:77]
	v_mfma_f32_16x16x32_bf16 v[70:73], v[170:173], v[210:213], v[70:73]
	v_mfma_f32_16x16x32_bf16 v[66:69], v[178:181], v[210:213], v[66:69]
	v_mfma_f32_16x16x32_bf16 v[114:117], v[174:177], v[190:193], v[114:117]
	v_mfma_f32_16x16x32_bf16 v[106:109], v[182:185], v[190:193], v[106:109]
	v_mfma_f32_16x16x32_bf16 v[98:101], v[174:177], v[198:201], v[98:101]
	v_mfma_f32_16x16x32_bf16 v[90:93], v[182:185], v[198:201], v[90:93]
	v_mfma_f32_16x16x32_bf16 v[82:85], v[174:177], v[206:209], v[82:85]
	v_mfma_f32_16x16x32_bf16 v[74:77], v[182:185], v[206:209], v[74:77]
	v_mfma_f32_16x16x32_bf16 v[70:73], v[174:177], v[214:217], v[70:73]
	v_mfma_f32_16x16x32_bf16 v[66:69], v[182:185], v[214:217], v[66:69]
	s_setprio 0
	s_barrier
	s_add_i32 s22, s30, s16
	v_lshl_add_u64 v[146:147], s[38:39], 0, v[134:135]
	s_mov_b32 m0, s22
	ds_read_b128 v[186:189], v153 offset:16384
	ds_read_b128 v[190:193], v153 offset:17408
	ds_read_b128 v[194:197], v153 offset:18432
	ds_read_b128 v[198:201], v153 offset:19456
	ds_read_b128 v[202:205], v153 offset:20480
	ds_read_b128 v[206:209], v153 offset:21504
	ds_read_b128 v[210:213], v153 offset:22528
	ds_read_b128 v[214:217], v153 offset:23552
	global_load_lds_dwordx4 v[146:147], off
	s_add_i32 m0, s22, 0x2000
	s_add_u32 s22, s38, 0x160000
	v_lshl_add_u64 v[218:219], s[38:39], 0, v[130:131]
	s_addc_u32 s23, s39, 0
	s_add_i32 s49, s31, s16
	global_load_lds_dwordx4 v[218:219], off
	v_lshl_add_u64 v[220:221], s[22:23], 0, v[134:135]
	s_mov_b32 m0, s49
	v_lshl_add_u64 v[222:223], s[40:41], 0, v[132:133]
	global_load_lds_dwordx4 v[220:221], off
	v_lshl_add_u64 v[220:221], s[22:23], 0, v[130:131]
	s_add_i32 m0, s49, 0x2000
	s_nop 0
	global_load_lds_dwordx4 v[220:221], off
	v_lshl_add_u64 v[220:221], s[40:41], 0, v[136:137]
	s_mov_b32 m0, s18
	s_nop 0
	global_load_lds_dwordx4 v[220:221], off
	s_mov_b32 m0, s19
	s_nop 0
	global_load_lds_dwordx4 v[222:223], off
	s_waitcnt vmcnt(8)
	s_waitcnt lgkmcnt(0)
	s_setprio 1
	s_barrier
; #define PG8_STAGE(bufoff, gbase, voff) do { _Pragma("unroll") for (int _i = 0; _i < 2; ++_i) \
;         __builtin_amdgcn_global_load_lds((const unsigned*)((const char*)(gbase) + (voff)[_i]), (PG8_LAS unsigned*)(lds + (bufoff) + ldsw + _i * 8192), 16, 0, 0); } while (0)
; #define PG8_LDA(dst, b, h) do { _Pragma("unroll") for (int m = 0; m < 4; ++m) _Pragma("unroll") for (int k = 0; k < 2; ++k) dst[m][k] = *(const PG8_LAS bf16x8*)(lds + PG8_SA(b, h) + aoff + m * 2048 + k * 1024); } while (0)
; #define PG8_LDB(dst, b, h) do { _Pragma("unroll") for (int n = 0; n < 2; ++n) _Pragma("unroll") for (int k = 0; k < 2; ++k) dst[n][k] = *(const PG8_LAS bf16x8*)(lds + PG8_SB(b, h) + boff + n * 2048 + k * 1024); } while (0)
; #define PG8_MMA(ai, bj, At, Bt) do { __builtin_amdgcn_s_setprio(1); _Pragma("unroll") for (int m = 0; m < 4; ++m) _Pragma("unroll") for (int n = 0; n < 2; ++n) _Pragma("unroll") for (int k = 0; k < 2; ++k) \
;         acc[ai][bj][m][n] = __builtin_amdgcn_mfma_f32_16x16x32_bf16(Bt[n][k], At[m][k], acc[ai][bj][m][n], 0, 0, 0); __builtin_amdgcn_s_setprio(0); } while (0)
; #define PG8_WAIT_V(n) asm volatile("s_waitcnt vmcnt(" #n ")" ::: "memory")
; template <class Epi, class Sched, bool ALIGN_EPI = false, bool SP2 = false>
; __device__ __forceinline__ void gemm_phase(PG8_LAS unsigned char* lds, const Gemm g, const Sched& S, const Epi& E) {
;     ...
;             PG8_LDB(B0, 0, 0); PG8_LDB(B1, 0, 1); PG8_SCHED; PG8_LDA(At, 0, 0); PG8_STAGE(PG8_SA(1, 1), a1 + hstep, voffA);
;             PG8_WAIT_V(8); PG8_WAIT_L(0); PG8_BAR; PG8_MMA(0, 0, At, B0); PG8_MMA(0, 1, At, B1); PG8_BAR; PG8_SCHED;
;             PG8_LDA(At, 0, 1); PG8_STAGE(PG8_SB(0, 0), b2, voffB); PG8_STAGE(PG8_SB(0, 1), b2 + hstep, voffB); PG8_STAGE(PG8_SA(0, 0), a2, voffA);
;             PG8_WAIT_V(8); PG8_WAIT_L(0); PG8_BAR; PG8_MMA(1, 0, At, B0); PG8_MMA(1, 1, At, B1); PG8_BAR; PG8_SCHED;
;             PG8_LDB(B0, 1, 0); PG8_LDB(B1, 1, 1); PG8_SCHED; PG8_LDA(At, 1, 0); PG8_STAGE(PG8_SA(0, 1), a2 + hstep, voffA);
;             PG8_WAIT_V(8); PG8_WAIT_L(0); PG8_BAR; PG8_MMA(0, 0, At, B0); PG8_MMA(0, 1, At, B1); PG8_BAR; PG8_SCHED;
;             PG8_LDA(At, 1, 1); PG8_STAGE(PG8_SB(1, 0), b3, voffB); PG8_STAGE(PG8_SB(1, 1), b3 + hstep, voffB); PG8_STAGE(PG8_SA(1, 0), a3, voffA);
;             PG8_WAIT_V(8); PG8_WAIT_L(0); PG8_BAR; PG8_MMA(1, 0, At, B0); PG8_MMA(1, 1, At, B1); PG8_BAR; PG8_SCHED;
	v_mfma_f32_16x16x32_bf16 v[62:65], v[154:157], v[186:189], v[62:65]
	v_mfma_f32_16x16x32_bf16 v[58:61], v[162:165], v[186:189], v[58:61]
	v_mfma_f32_16x16x32_bf16 v[54:57], v[154:157], v[194:197], v[54:57]
	v_mfma_f32_16x16x32_bf16 v[46:49], v[162:165], v[194:197], v[46:49]
	v_mfma_f32_16x16x32_bf16 v[38:41], v[154:157], v[202:205], v[38:41]
	v_mfma_f32_16x16x32_bf16 v[30:33], v[162:165], v[202:205], v[30:33]
	v_mfma_f32_16x16x32_bf16 v[22:25], v[154:157], v[210:213], v[22:25]
	v_mfma_f32_16x16x32_bf16 v[14:17], v[162:165], v[210:213], v[14:17]
	v_mfma_f32_16x16x32_bf16 v[62:65], v[158:161], v[190:193], v[62:65]
	v_mfma_f32_16x16x32_bf16 v[58:61], v[166:169], v[190:193], v[58:61]
	v_mfma_f32_16x16x32_bf16 v[54:57], v[158:161], v[198:201], v[54:57]
	v_mfma_f32_16x16x32_bf16 v[46:49], v[166:169], v[198:201], v[46:49]
	v_mfma_f32_16x16x32_bf16 v[38:41], v[158:161], v[206:209], v[38:41]
	v_mfma_f32_16x16x32_bf16 v[30:33], v[166:169], v[206:209], v[30:33]
	v_mfma_f32_16x16x32_bf16 v[22:25], v[158:161], v[214:217], v[22:25]
	v_mfma_f32_16x16x32_bf16 v[14:17], v[166:169], v[214:217], v[14:17]
	s_setprio 0
	s_setprio 1
	v_mfma_f32_16x16x32_bf16 v[50:53], v[170:173], v[186:189], v[50:53]
	v_mfma_f32_16x16x32_bf16 v[42:45], v[178:181], v[186:189], v[42:45]
	v_mfma_f32_16x16x32_bf16 v[34:37], v[170:173], v[194:197], v[34:37]
	v_mfma_f32_16x16x32_bf16 v[26:29], v[178:181], v[194:197], v[26:29]
	v_mfma_f32_16x16x32_bf16 v[18:21], v[170:173], v[202:205], v[18:21]
	v_mfma_f32_16x16x32_bf16 v[10:13], v[178:181], v[202:205], v[10:13]
	v_mfma_f32_16x16x32_bf16 v[6:9], v[170:173], v[210:213], v[6:9]
	v_mfma_f32_16x16x32_bf16 v[2:5], v[178:181], v[210:213], v[2:5]
	v_mfma_f32_16x16x32_bf16 v[50:53], v[174:177], v[190:193], v[50:53]
	v_mfma_f32_16x16x32_bf16 v[42:45], v[182:185], v[190:193], v[42:45]
	v_mfma_f32_16x16x32_bf16 v[34:37], v[174:177], v[198:201], v[34:37]
	v_mfma_f32_16x16x32_bf16 v[26:29], v[182:185], v[198:201], v[26:29]
	v_mfma_f32_16x16x32_bf16 v[18:21], v[174:177], v[206:209], v[18:21]
	v_mfma_f32_16x16x32_bf16 v[10:13], v[182:185], v[206:209], v[10:13]
	v_mfma_f32_16x16x32_bf16 v[6:9], v[174:177], v[214:217], v[6:9]
	v_mfma_f32_16x16x32_bf16 v[2:5], v[182:185], v[214:217], v[2:5]
	s_setprio 0
	s_barrier
	s_add_i32 s49, 0, 0x18000
	s_add_i32 s50, 0, 0x1c000
	v_add_u32_e32 v166, s49, v149
	v_add_u32_e32 v182, s50, v149
	ds_read_b128 v[154:157], v166
	ds_read_b128 v[158:161], v166 offset:1024
	ds_read_b128 v[162:165], v166 offset:2048
	ds_read_b128 v[166:169], v166 offset:3072
	ds_read_b128 v[170:173], v182
	ds_read_b128 v[174:177], v182 offset:1024
	ds_read_b128 v[178:181], v182 offset:2048
	ds_read_b128 v[182:185], v182 offset:3072
	s_add_u32 s22, s40, 0x160000
	s_addc_u32 s23, s41, 0
	s_mov_b32 m0, s24
	v_lshl_add_u64 v[224:225], s[22:23], 0, v[136:137]
	ds_read_b128 v[186:189], v153 offset:32768
	ds_read_b128 v[190:193], v153 offset:33792
	ds_read_b128 v[194:197], v153 offset:34816
	ds_read_b128 v[198:201], v153 offset:35840
	ds_read_b128 v[202:205], v153 offset:36864
	ds_read_b128 v[206:209], v153 offset:37888
	ds_read_b128 v[210:213], v153 offset:38912
	ds_read_b128 v[214:217], v153 offset:39936
	global_load_lds_dwordx4 v[224:225], off
	v_lshl_add_u64 v[224:225], s[22:23], 0, v[132:133]
	s_mov_b32 m0, s25
	s_nop 0
	global_load_lds_dwordx4 v[224:225], off
	s_waitcnt vmcnt(8)
	s_waitcnt lgkmcnt(0)
	s_setprio 1
	s_barrier
	v_mfma_f32_16x16x32_bf16 v[126:129], v[154:157], v[186:189], v[126:129]
	v_mfma_f32_16x16x32_bf16 v[122:125], v[162:165], v[186:189], v[122:125]
	v_mfma_f32_16x16x32_bf16 v[118:121], v[154:157], v[194:197], v[118:121]
	v_mfma_f32_16x16x32_bf16 v[110:113], v[162:165], v[194:197], v[110:113]
	v_mfma_f32_16x16x32_bf16 v[102:105], v[154:157], v[202:205], v[102:105]
	v_mfma_f32_16x16x32_bf16 v[94:97], v[162:165], v[202:205], v[94:97]
	v_mfma_f32_16x16x32_bf16 v[86:89], v[154:157], v[210:213], v[86:89]
	v_mfma_f32_16x16x32_bf16 v[78:81], v[162:165], v[210:213], v[78:81]
	v_mfma_f32_16x16x32_bf16 v[126:129], v[158:161], v[190:193], v[126:129]
	v_mfma_f32_16x16x32_bf16 v[122:125], v[166:169], v[190:193], v[122:125]
	v_mfma_f32_16x16x32_bf16 v[118:121], v[158:161], v[198:201], v[118:121]
	v_mfma_f32_16x16x32_bf16 v[110:113], v[166:169], v[198:201], v[110:113]
	v_mfma_f32_16x16x32_bf16 v[102:105], v[158:161], v[206:209], v[102:105]
	v_mfma_f32_16x16x32_bf16 v[94:97], v[166:169], v[206:209], v[94:97]
	v_mfma_f32_16x16x32_bf16 v[86:89], v[158:161], v[214:217], v[86:89]
	v_mfma_f32_16x16x32_bf16 v[78:81], v[166:169], v[214:217], v[78:81]
	s_setprio 0
	s_setprio 1
	v_mfma_f32_16x16x32_bf16 v[114:117], v[170:173], v[186:189], v[114:117]
	v_mfma_f32_16x16x32_bf16 v[106:109], v[178:181], v[186:189], v[106:109]
	v_mfma_f32_16x16x32_bf16 v[98:101], v[170:173], v[194:197], v[98:101]
	v_mfma_f32_16x16x32_bf16 v[90:93], v[178:181], v[194:197], v[90:93]
	v_mfma_f32_16x16x32_bf16 v[82:85], v[170:173], v[202:205], v[82:85]
	v_mfma_f32_16x16x32_bf16 v[74:77], v[178:181], v[202:205], v[74:77]
	v_mfma_f32_16x16x32_bf16 v[70:73], v[170:173], v[210:213], v[70:73]
	v_mfma_f32_16x16x32_bf16 v[66:69], v[178:181], v[210:213], v[66:69]
	v_mfma_f32_16x16x32_bf16 v[114:117], v[174:177], v[190:193], v[114:117]
	v_mfma_f32_16x16x32_bf16 v[106:109], v[182:185], v[190:193], v[106:109]
	v_mfma_f32_16x16x32_bf16 v[98:101], v[174:177], v[198:201], v[98:101]
	v_mfma_f32_16x16x32_bf16 v[90:93], v[182:185], v[198:201], v[90:93]
	v_mfma_f32_16x16x32_bf16 v[82:85], v[174:177], v[206:209], v[82:85]
	v_mfma_f32_16x16x32_bf16 v[74:77], v[182:185], v[206:209], v[74:77]
	v_mfma_f32_16x16x32_bf16 v[70:73], v[174:177], v[214:217], v[70:73]
	v_mfma_f32_16x16x32_bf16 v[66:69], v[182:185], v[214:217], v[66:69]
	s_setprio 0
	s_barrier
; #define PG8_STAGE(bufoff, gbase, voff) do { _Pragma("unroll") for (int _i = 0; _i < 2; ++_i) \
;         __builtin_amdgcn_global_load_lds((const unsigned*)((const char*)(gbase) + (voff)[_i]), (PG8_LAS unsigned*)(lds + (bufoff) + ldsw + _i * 8192), 16, 0, 0); } while (0)
; #define PG8_LDA(dst, b, h) do { _Pragma("unroll") for (int m = 0; m < 4; ++m) _Pragma("unroll") for (int k = 0; k < 2; ++k) dst[m][k] = *(const PG8_LAS bf16x8*)(lds + PG8_SA(b, h) + aoff + m * 2048 + k * 1024); } while (0)
; #define PG8_LDB(dst, b, h) do { _Pragma("unroll") for (int n = 0; n < 2; ++n) _Pragma("unroll") for (int k = 0; k < 2; ++k) dst[n][k] = *(const PG8_LAS bf16x8*)(lds + PG8_SB(b, h) + boff + n * 2048 + k * 1024); } while (0)
; #define PG8_MMA(ai, bj, At, Bt) do { __builtin_amdgcn_s_setprio(1); _Pragma("unroll") for (int m = 0; m < 4; ++m) _Pragma("unroll") for (int n = 0; n < 2; ++n) _Pragma("unroll") for (int k = 0; k < 2; ++k) \
;         acc[ai][bj][m][n] = __builtin_amdgcn_mfma_f32_16x16x32_bf16(Bt[n][k], At[m][k], acc[ai][bj][m][n], 0, 0, 0); __builtin_amdgcn_s_setprio(0); } while (0)
; #define PG8_WAIT_V(n) asm volatile("s_waitcnt vmcnt(" #n ")" ::: "memory")
; #define PG8_WAIT_L(n) asm volatile("s_waitcnt lgkmcnt(" #n ")" ::: "memory")
; #define PG8_BAR __builtin_amdgcn_s_barrier()
; #define PG8_SCHED __builtin_amdgcn_sched_barrier(0)
; template <class Epi, class Sched, bool ALIGN_EPI = false, bool SP2 = false>
; __device__ __forceinline__ void gemm_phase(PG8_LAS unsigned char* lds, const Gemm g, const Sched& S, const Epi& E) {
;     ...
;             PG8_LDB(B0, 1, 0); PG8_LDB(B1, 1, 1); PG8_SCHED; PG8_LDA(At, 1, 0); PG8_STAGE(PG8_SA(0, 1), a2 + hstep, voffA);
;             PG8_WAIT_V(8); PG8_WAIT_L(0); PG8_BAR; PG8_MMA(0, 0, At, B0); PG8_MMA(0, 1, At, B1); PG8_BAR; PG8_SCHED;
;             PG8_LDA(At, 1, 1); PG8_STAGE(PG8_SB(1, 0), b3, voffB); PG8_STAGE(PG8_SB(1, 1), b3 + hstep, voffB); PG8_STAGE(PG8_SA(1, 0), a3, voffA);
;             PG8_WAIT_V(8); PG8_WAIT_L(0); PG8_BAR; PG8_MMA(1, 0, At, B0); PG8_MMA(1, 1, At, B1); PG8_BAR; PG8_SCHED;
;     ...
;         if constexpr (ALIGN_EPI) { if (wr == 0) PG8_BAR; }
	s_add_i32 s22, s49, s16
	v_lshl_add_u64 v[146:147], v[146:147], 0, s[12:13]
	s_mov_b32 m0, s22
	ds_read_b128 v[186:189], v153 offset:49152
	ds_read_b128 v[190:193], v153 offset:50176
	ds_read_b128 v[194:197], v153 offset:51200
	ds_read_b128 v[198:201], v153 offset:52224
	ds_read_b128 v[202:205], v153 offset:53248
	ds_read_b128 v[206:209], v153 offset:54272
	ds_read_b128 v[210:213], v153 offset:55296
	ds_read_b128 v[214:217], v153 offset:56320
	global_load_lds_dwordx4 v[146:147], off
	s_add_i32 m0, s22, 0x2000
	s_add_u32 s22, s38, 0x160080
	v_lshl_add_u64 v[146:147], v[218:219], 0, s[12:13]
	s_addc_u32 s23, s39, 0
	s_add_i32 s38, s50, s16
	global_load_lds_dwordx4 v[146:147], off
	v_lshl_add_u64 v[146:147], s[22:23], 0, v[134:135]
	s_mov_b32 m0, s38
	s_nop 0
	global_load_lds_dwordx4 v[146:147], off
	v_lshl_add_u64 v[146:147], s[22:23], 0, v[130:131]
	s_add_i32 m0, s38, 0x2000
	s_nop 0
	global_load_lds_dwordx4 v[146:147], off
	v_lshl_add_u64 v[146:147], v[220:221], 0, s[12:13]
	s_mov_b32 m0, s28
	s_nop 0
	global_load_lds_dwordx4 v[146:147], off
	v_lshl_add_u64 v[146:147], v[222:223], 0, s[12:13]
	s_mov_b32 m0, s29
	s_nop 0
	global_load_lds_dwordx4 v[146:147], off
	s_waitcnt vmcnt(8)
	s_waitcnt lgkmcnt(0)
	s_setprio 1
	s_barrier
	v_mfma_f32_16x16x32_bf16 v[62:65], v[154:157], v[186:189], v[62:65]
	v_mfma_f32_16x16x32_bf16 v[58:61], v[162:165], v[186:189], v[58:61]
	v_mfma_f32_16x16x32_bf16 v[54:57], v[154:157], v[194:197], v[54:57]
	v_mfma_f32_16x16x32_bf16 v[46:49], v[162:165], v[194:197], v[46:49]
	v_mfma_f32_16x16x32_bf16 v[38:41], v[154:157], v[202:205], v[38:41]
	v_mfma_f32_16x16x32_bf16 v[30:33], v[162:165], v[202:205], v[30:33]
	v_mfma_f32_16x16x32_bf16 v[22:25], v[154:157], v[210:213], v[22:25]
	v_mfma_f32_16x16x32_bf16 v[14:17], v[162:165], v[210:213], v[14:17]
	v_mfma_f32_16x16x32_bf16 v[62:65], v[158:161], v[190:193], v[62:65]
	v_mfma_f32_16x16x32_bf16 v[58:61], v[166:169], v[190:193], v[58:61]
	v_mfma_f32_16x16x32_bf16 v[54:57], v[158:161], v[198:201], v[54:57]
	v_mfma_f32_16x16x32_bf16 v[46:49], v[166:169], v[198:201], v[46:49]
	v_mfma_f32_16x16x32_bf16 v[38:41], v[158:161], v[206:209], v[38:41]
	v_mfma_f32_16x16x32_bf16 v[30:33], v[166:169], v[206:209], v[30:33]
	v_mfma_f32_16x16x32_bf16 v[22:25], v[158:161], v[214:217], v[22:25]
	v_mfma_f32_16x16x32_bf16 v[14:17], v[166:169], v[214:217], v[14:17]
	s_setprio 0
	s_setprio 1
	v_mfma_f32_16x16x32_bf16 v[50:53], v[170:173], v[186:189], v[50:53]
	v_mfma_f32_16x16x32_bf16 v[42:45], v[178:181], v[186:189], v[42:45]
	v_mfma_f32_16x16x32_bf16 v[34:37], v[170:173], v[194:197], v[34:37]
	v_mfma_f32_16x16x32_bf16 v[26:29], v[178:181], v[194:197], v[26:29]
	v_mfma_f32_16x16x32_bf16 v[18:21], v[170:173], v[202:205], v[18:21]
	v_mfma_f32_16x16x32_bf16 v[10:13], v[178:181], v[202:205], v[10:13]
	v_mfma_f32_16x16x32_bf16 v[6:9], v[170:173], v[210:213], v[6:9]
	v_mfma_f32_16x16x32_bf16 v[2:5], v[178:181], v[210:213], v[2:5]
	v_mfma_f32_16x16x32_bf16 v[50:53], v[174:177], v[190:193], v[50:53]
	v_mfma_f32_16x16x32_bf16 v[42:45], v[182:185], v[190:193], v[42:45]
	v_mfma_f32_16x16x32_bf16 v[34:37], v[174:177], v[198:201], v[34:37]
	v_mfma_f32_16x16x32_bf16 v[26:29], v[182:185], v[198:201], v[26:29]
	v_mfma_f32_16x16x32_bf16 v[18:21], v[174:177], v[206:209], v[18:21]
	v_mfma_f32_16x16x32_bf16 v[10:13], v[182:185], v[206:209], v[10:13]
	v_mfma_f32_16x16x32_bf16 v[6:9], v[174:177], v[214:217], v[6:9]
	v_mfma_f32_16x16x32_bf16 v[2:5], v[182:185], v[214:217], v[2:5]
	s_setprio 0
	s_add_i32 s48, s48, 2
	s_add_u32 s46, s46, 0x100
	s_addc_u32 s47, s47, 0
	s_cmpk_gt_u32 s48, 0x55
	s_mov_b64 s[22:23], s[36:37]
	s_barrier
	s_cbranch_scc0 .LBB0_173
	s_and_b64 vcc, exec, s[14:15]
	s_cbranch_vccz .LBB0_176
	s_barrier

; #define PG8_STAGE(bufoff, gbase, voff) do { _Pragma("unroll") for (int _i = 0; _i < 2; ++_i) \
;         __builtin_amdgcn_global_load_lds((const unsigned*)((const char*)(gbase) + (voff)[_i]), (PG8_LAS unsigned*)(lds + (bufoff) + ldsw + _i * 8192), 16, 0, 0); } while (0)
; #define PG8_LDA(dst, b, h) do { _Pragma("unroll") for (int m = 0; m < 4; ++m) _Pragma("unroll") for (int k = 0; k < 2; ++k) dst[m][k] = *(const PG8_LAS bf16x8*)(lds + PG8_SA(b, h) + aoff + m * 2048 + k * 1024); } while (0)
; #define PG8_WAIT_V(n) asm volatile("s_waitcnt vmcnt(" #n ")" ::: "memory")
; #define PG8_BAR __builtin_amdgcn_s_barrier()
; template <class Epi, class Sched, bool ALIGN_EPI = false, bool SP2 = false>
; __device__ __forceinline__ void gemm_phase(PG8_LAS unsigned char* lds, const Gemm g, const Sched& S, const Epi& E) {
;     ...
;         for (int t = 0; t < nt; t += 2) {
;             if constexpr (Epi::MIDHOOK) { if (t == (nt >> 1)) E.mid(acc, cur, wr, wc, fr, fq); }
;             const bool last = (t == nt - 2);
;             const char* a1 = cA + (size_t)(t + 1) * kstep;
;             const char* a2 = last ? nA : cA + (size_t)(t + 2) * kstep; const char* b2 = last ? nB : cB + (size_t)(t + 2) * kstep;
;             const char* a3 = a2 + kstep; const char* b3 = b2 + kstep;
;             if (last && has_next) S.a_ready(nxt);
;             if constexpr (SP2) {
;             PG8_LDB(B0, 0, 0); PG8_LDB(B1, 0, 1); PG8_SCHED; PG8_LDA(At, 0, 0); PG8_STAGE(PG8_SA(1, 1), a1 + hstep, voffA);
;             PG8_WAIT_V(8); PG8_WAIT_L(0); PG8_BAR; PG8_MMA(0, 0, At, B0); PG8_MMA(0, 1, At, B1); PG8_BAR; PG8_SCHED;
;             PG8_LDA(At, 0, 1); PG8_STAGE(PG8_SB(0, 0), b2, voffB); PG8_STAGE(PG8_SB(0, 1), b2 + hstep, voffB); PG8_STAGE(PG8_SA(0, 0), a2, voffA);
;             PG8_WAIT_V(8); PG8_WAIT_L(0); PG8_BAR; PG8_MMA(1, 0, At, B0); PG8_MMA(1, 1, At, B1); PG8_BAR; PG8_SCHED;
;             PG8_LDB(B0, 1, 0); PG8_LDB(B1, 1, 1); PG8_SCHED; PG8_LDA(At, 1, 0); PG8_STAGE(PG8_SA(0, 1), a2 + hstep, voffA);
;             PG8_WAIT_V(8); PG8_WAIT_L(0); PG8_BAR; PG8_MMA(0, 0, At, B0); PG8_MMA(0, 1, At, B1); PG8_BAR; PG8_SCHED;
;             PG8_LDA(At, 1, 1); PG8_STAGE(PG8_SB(1, 0), b3, voffB); PG8_STAGE(PG8_SB(1, 1), b3 + hstep, voffB); PG8_STAGE(PG8_SA(1, 0), a3, voffA);
;             PG8_WAIT_V(8); PG8_WAIT_L(0); PG8_BAR; PG8_MMA(1, 0, At, B0); PG8_MMA(1, 1, At, B1); PG8_BAR; PG8_SCHED;
.LBB0_193:
	ds_read_b128 v[144:147], v141
	ds_read_b128 v[148:151], v141 offset:1024
	ds_read_b128 v[152:155], v141 offset:2048
	ds_read_b128 v[156:159], v141 offset:3072
	ds_read_b128 v[160:163], v142
	ds_read_b128 v[164:167], v142 offset:1024
	ds_read_b128 v[168:171], v142 offset:2048
	ds_read_b128 v[172:175], v142 offset:3072
	s_add_u32 s40, s38, 0x100
	s_addc_u32 s41, s39, 0
	s_cmp_eq_u32 s53, 18
	s_cselect_b32 s45, s23, s41
	s_cselect_b32 s44, s22, s40
	s_cselect_b32 s43, s37, s52
	s_cselect_b32 s42, s36, s11
	v_lshl_add_u64 v[208:209], s[38:39], 0, v[134:135]
	s_add_i32 m0, s19, 0xc000
	ds_read_b128 v[176:179], v143
	ds_read_b128 v[180:183], v143 offset:1024
	ds_read_b128 v[184:187], v143 offset:2048
	ds_read_b128 v[188:191], v143 offset:3072
	ds_read_b128 v[192:195], v143 offset:4096
	ds_read_b128 v[196:199], v143 offset:5120
	ds_read_b128 v[200:203], v143 offset:6144
	ds_read_b128 v[204:207], v143 offset:7168
	global_load_lds_dwordx4 v[208:209], off
	v_lshl_add_u64 v[208:209], s[38:39], 0, v[136:137]
	s_add_i32 m0, s19, 0xe000
	s_nop 0
	global_load_lds_dwordx4 v[208:209], off
	s_waitcnt vmcnt(8)
	s_waitcnt lgkmcnt(0)
	s_setprio 1
	s_barrier
	v_mfma_f32_16x16x32_bf16 v[126:129], v[144:147], v[176:179], v[126:129]
	v_mfma_f32_16x16x32_bf16 v[122:125], v[152:155], v[176:179], v[122:125]
	v_mfma_f32_16x16x32_bf16 v[118:121], v[144:147], v[184:187], v[118:121]
	v_mfma_f32_16x16x32_bf16 v[114:117], v[152:155], v[184:187], v[114:117]
	v_mfma_f32_16x16x32_bf16 v[106:109], v[144:147], v[192:195], v[106:109]
	v_mfma_f32_16x16x32_bf16 v[98:101], v[152:155], v[192:195], v[98:101]
	v_mfma_f32_16x16x32_bf16 v[90:93], v[144:147], v[200:203], v[90:93]
	v_mfma_f32_16x16x32_bf16 v[82:85], v[152:155], v[200:203], v[82:85]
	v_mfma_f32_16x16x32_bf16 v[126:129], v[148:151], v[180:183], v[126:129]
	v_mfma_f32_16x16x32_bf16 v[122:125], v[156:159], v[180:183], v[122:125]
	v_mfma_f32_16x16x32_bf16 v[118:121], v[148:151], v[188:191], v[118:121]
	v_mfma_f32_16x16x32_bf16 v[114:117], v[156:159], v[188:191], v[114:117]
	v_mfma_f32_16x16x32_bf16 v[106:109], v[148:151], v[196:199], v[106:109]
	v_mfma_f32_16x16x32_bf16 v[98:101], v[156:159], v[196:199], v[98:101]
	v_mfma_f32_16x16x32_bf16 v[90:93], v[148:151], v[204:207], v[90:93]
	v_mfma_f32_16x16x32_bf16 v[82:85], v[156:159], v[204:207], v[82:85]
	s_setprio 0
	s_setprio 1
	v_mfma_f32_16x16x32_bf16 v[110:113], v[160:163], v[176:179], v[110:113]
	v_mfma_f32_16x16x32_bf16 v[102:105], v[168:171], v[176:179], v[102:105]
	v_mfma_f32_16x16x32_bf16 v[94:97], v[160:163], v[184:187], v[94:97]
	v_mfma_f32_16x16x32_bf16 v[86:89], v[168:171], v[184:187], v[86:89]
	v_mfma_f32_16x16x32_bf16 v[78:81], v[160:163], v[192:195], v[78:81]
	v_mfma_f32_16x16x32_bf16 v[74:77], v[168:171], v[192:195], v[74:77]
	v_mfma_f32_16x16x32_bf16 v[70:73], v[160:163], v[200:203], v[70:73]
	v_mfma_f32_16x16x32_bf16 v[66:69], v[168:171], v[200:203], v[66:69]
	v_mfma_f32_16x16x32_bf16 v[110:113], v[164:167], v[180:183], v[110:113]
	v_mfma_f32_16x16x32_bf16 v[102:105], v[172:175], v[180:183], v[102:105]
	v_mfma_f32_16x16x32_bf16 v[94:97], v[164:167], v[188:191], v[94:97]
	v_mfma_f32_16x16x32_bf16 v[86:89], v[172:175], v[188:191], v[86:89]
	v_mfma_f32_16x16x32_bf16 v[78:81], v[164:167], v[196:199], v[78:81]
	v_mfma_f32_16x16x32_bf16 v[74:77], v[172:175], v[196:199], v[74:77]
	v_mfma_f32_16x16x32_bf16 v[70:73], v[164:167], v[204:207], v[70:73]
	v_mfma_f32_16x16x32_bf16 v[66:69], v[172:175], v[204:207], v[66:69]
	s_setprio 0
	s_barrier
	s_add_i32 s38, s46, s16
	v_lshl_add_u64 v[208:209], s[42:43], 0, v[132:133]
	s_mov_b32 m0, s38
	ds_read_b128 v[176:179], v143 offset:16384
	ds_read_b128 v[180:183], v143 offset:17408
	ds_read_b128 v[184:187], v143 offset:18432
	ds_read_b128 v[188:191], v143 offset:19456
	ds_read_b128 v[192:195], v143 offset:20480
	ds_read_b128 v[196:199], v143 offset:21504
	ds_read_b128 v[200:203], v143 offset:22528
	ds_read_b128 v[204:207], v143 offset:23552
	global_load_lds_dwordx4 v[208:209], off
	s_add_i32 m0, s38, 0x2000
	s_add_u32 s38, s42, 0x160000
	v_lshl_add_u64 v[210:211], s[42:43], 0, v[130:131]
	s_addc_u32 s39, s43, 0
	s_add_i32 s54, s47, s16
	global_load_lds_dwordx4 v[210:211], off
	v_lshl_add_u64 v[212:213], s[38:39], 0, v[132:133]
	s_mov_b32 m0, s54
	v_lshl_add_u64 v[214:215], s[44:45], 0, v[130:131]
	global_load_lds_dwordx4 v[212:213], off
	v_lshl_add_u64 v[212:213], s[38:39], 0, v[130:131]
	s_add_i32 m0, s54, 0x2000
	s_nop 0
	global_load_lds_dwordx4 v[212:213], off
	v_lshl_add_u64 v[212:213], s[44:45], 0, v[132:133]
	s_mov_b32 m0, s19
	s_nop 0
	global_load_lds_dwordx4 v[212:213], off
	s_mov_b32 m0, s24
	s_nop 0
	global_load_lds_dwordx4 v[214:215], off
	s_waitcnt vmcnt(8)
	s_waitcnt lgkmcnt(0)
	s_setprio 1
	s_barrier
; #define PG8_STAGE(bufoff, gbase, voff) do { _Pragma("unroll") for (int _i = 0; _i < 2; ++_i) \
;         __builtin_amdgcn_global_load_lds((const unsigned*)((const char*)(gbase) + (voff)[_i]), (PG8_LAS unsigned*)(lds + (bufoff) + ldsw + _i * 8192), 16, 0, 0); } while (0)
; #define PG8_LDA(dst, b, h) do { _Pragma("unroll") for (int m = 0; m < 4; ++m) _Pragma("unroll") for (int k = 0; k < 2; ++k) dst[m][k] = *(const PG8_LAS bf16x8*)(lds + PG8_SA(b, h) + aoff + m * 2048 + k * 1024); } while (0)
; #define PG8_LDB(dst, b, h) do { _Pragma("unroll") for (int n = 0; n < 2; ++n) _Pragma("unroll") for (int k = 0; k < 2; ++k) dst[n][k] = *(const PG8_LAS bf16x8*)(lds + PG8_SB(b, h) + boff + n * 2048 + k * 1024); } while (0)
; #define PG8_MMA(ai, bj, At, Bt) do { __builtin_amdgcn_s_setprio(1); _Pragma("unroll") for (int m = 0; m < 4; ++m) _Pragma("unroll") for (int n = 0; n < 2; ++n) _Pragma("unroll") for (int k = 0; k < 2; ++k) \
;         acc[ai][bj][m][n] = __builtin_amdgcn_mfma_f32_16x16x32_bf16(Bt[n][k], At[m][k], acc[ai][bj][m][n], 0, 0, 0); __builtin_amdgcn_s_setprio(0); } while (0)
; #define PG8_WAIT_V(n) asm volatile("s_waitcnt vmcnt(" #n ")" ::: "memory")
; template <class Epi, class Sched, bool ALIGN_EPI = false, bool SP2 = false>
; __device__ __forceinline__ void gemm_phase(PG8_LAS unsigned char* lds, const Gemm g, const Sched& S, const Epi& E) {
;     ...
;             PG8_LDB(B0, 0, 0); PG8_LDB(B1, 0, 1); PG8_SCHED; PG8_LDA(At, 0, 0); PG8_STAGE(PG8_SA(1, 1), a1 + hstep, voffA);
;             PG8_WAIT_V(8); PG8_WAIT_L(0); PG8_BAR; PG8_MMA(0, 0, At, B0); PG8_MMA(0, 1, At, B1); PG8_BAR; PG8_SCHED;
;             PG8_LDA(At, 0, 1); PG8_STAGE(PG8_SB(0, 0), b2, voffB); PG8_STAGE(PG8_SB(0, 1), b2 + hstep, voffB); PG8_STAGE(PG8_SA(0, 0), a2, voffA);
;             PG8_WAIT_V(8); PG8_WAIT_L(0); PG8_BAR; PG8_MMA(1, 0, At, B0); PG8_MMA(1, 1, At, B1); PG8_BAR; PG8_SCHED;
;             PG8_LDB(B0, 1, 0); PG8_LDB(B1, 1, 1); PG8_SCHED; PG8_LDA(At, 1, 0); PG8_STAGE(PG8_SA(0, 1), a2 + hstep, voffA);
;             PG8_WAIT_V(8); PG8_WAIT_L(0); PG8_BAR; PG8_MMA(0, 0, At, B0); PG8_MMA(0, 1, At, B1); PG8_BAR; PG8_SCHED;
;             PG8_LDA(At, 1, 1); PG8_STAGE(PG8_SB(1, 0), b3, voffB); PG8_STAGE(PG8_SB(1, 1), b3 + hstep, voffB); PG8_STAGE(PG8_SA(1, 0), a3, voffA);
;             PG8_WAIT_V(8); PG8_WAIT_L(0); PG8_BAR; PG8_MMA(1, 0, At, B0); PG8_MMA(1, 1, At, B1); PG8_BAR; PG8_SCHED;
	v_mfma_f32_16x16x32_bf16 v[62:65], v[144:147], v[176:179], v[62:65]
	v_mfma_f32_16x16x32_bf16 v[58:61], v[152:155], v[176:179], v[58:61]
	v_mfma_f32_16x16x32_bf16 v[54:57], v[144:147], v[184:187], v[54:57]
	v_mfma_f32_16x16x32_bf16 v[50:53], v[152:155], v[184:187], v[50:53]
	v_mfma_f32_16x16x32_bf16 v[38:41], v[144:147], v[192:195], v[38:41]
	v_mfma_f32_16x16x32_bf16 v[34:37], v[152:155], v[192:195], v[34:37]
	v_mfma_f32_16x16x32_bf16 v[22:25], v[144:147], v[200:203], v[22:25]
	v_mfma_f32_16x16x32_bf16 v[18:21], v[152:155], v[200:203], v[18:21]
	v_mfma_f32_16x16x32_bf16 v[62:65], v[148:151], v[180:183], v[62:65]
	v_mfma_f32_16x16x32_bf16 v[58:61], v[156:159], v[180:183], v[58:61]
	v_mfma_f32_16x16x32_bf16 v[54:57], v[148:151], v[188:191], v[54:57]
	v_mfma_f32_16x16x32_bf16 v[50:53], v[156:159], v[188:191], v[50:53]
	v_mfma_f32_16x16x32_bf16 v[38:41], v[148:151], v[196:199], v[38:41]
	v_mfma_f32_16x16x32_bf16 v[34:37], v[156:159], v[196:199], v[34:37]
	v_mfma_f32_16x16x32_bf16 v[22:25], v[148:151], v[204:207], v[22:25]
	v_mfma_f32_16x16x32_bf16 v[18:21], v[156:159], v[204:207], v[18:21]
	s_setprio 0
	s_setprio 1
	v_mfma_f32_16x16x32_bf16 v[46:49], v[160:163], v[176:179], v[46:49]
	v_mfma_f32_16x16x32_bf16 v[42:45], v[168:171], v[176:179], v[42:45]
	v_mfma_f32_16x16x32_bf16 v[30:33], v[160:163], v[184:187], v[30:33]
	v_mfma_f32_16x16x32_bf16 v[26:29], v[168:171], v[184:187], v[26:29]
	v_mfma_f32_16x16x32_bf16 v[14:17], v[160:163], v[192:195], v[14:17]
	v_mfma_f32_16x16x32_bf16 v[10:13], v[168:171], v[192:195], v[10:13]
	v_mfma_f32_16x16x32_bf16 v[6:9], v[160:163], v[200:203], v[6:9]
	v_mfma_f32_16x16x32_bf16 v[2:5], v[168:171], v[200:203], v[2:5]
	v_mfma_f32_16x16x32_bf16 v[46:49], v[164:167], v[180:183], v[46:49]
	v_mfma_f32_16x16x32_bf16 v[42:45], v[172:175], v[180:183], v[42:45]
	v_mfma_f32_16x16x32_bf16 v[30:33], v[164:167], v[188:191], v[30:33]
	v_mfma_f32_16x16x32_bf16 v[26:29], v[172:175], v[188:191], v[26:29]
	v_mfma_f32_16x16x32_bf16 v[14:17], v[164:167], v[196:199], v[14:17]
	v_mfma_f32_16x16x32_bf16 v[10:13], v[172:175], v[196:199], v[10:13]
	v_mfma_f32_16x16x32_bf16 v[6:9], v[164:167], v[204:207], v[6:9]
	v_mfma_f32_16x16x32_bf16 v[2:5], v[172:175], v[204:207], v[2:5]
	s_setprio 0
	s_barrier
	s_add_i32 s54, 0, 0x18000
	s_add_i32 s55, 0, 0x1c000
	v_add_u32_e32 v156, s54, v138
	v_add_u32_e32 v172, s55, v138
	ds_read_b128 v[144:147], v156
	ds_read_b128 v[148:151], v156 offset:1024
	ds_read_b128 v[152:155], v156 offset:2048
	ds_read_b128 v[156:159], v156 offset:3072
	ds_read_b128 v[160:163], v172
	ds_read_b128 v[164:167], v172 offset:1024
	ds_read_b128 v[168:171], v172 offset:2048
	ds_read_b128 v[172:175], v172 offset:3072
	s_add_u32 s38, s44, 0x160000
	s_addc_u32 s39, s45, 0
	s_mov_b32 m0, s25
	v_lshl_add_u64 v[216:217], s[38:39], 0, v[132:133]
	ds_read_b128 v[176:179], v143 offset:32768
	ds_read_b128 v[180:183], v143 offset:33792
	ds_read_b128 v[184:187], v143 offset:34816
	ds_read_b128 v[188:191], v143 offset:35840
	ds_read_b128 v[192:195], v143 offset:36864
	ds_read_b128 v[196:199], v143 offset:37888
	ds_read_b128 v[200:203], v143 offset:38912
	ds_read_b128 v[204:207], v143 offset:39936
	global_load_lds_dwordx4 v[216:217], off
	v_lshl_add_u64 v[216:217], s[38:39], 0, v[130:131]
	s_mov_b32 m0, s26
	s_nop 0
	global_load_lds_dwordx4 v[216:217], off
	s_waitcnt vmcnt(8)
	s_waitcnt lgkmcnt(0)
	s_setprio 1
	s_barrier
	v_mfma_f32_16x16x32_bf16 v[126:129], v[144:147], v[176:179], v[126:129]
	v_mfma_f32_16x16x32_bf16 v[122:125], v[152:155], v[176:179], v[122:125]
	v_mfma_f32_16x16x32_bf16 v[118:121], v[144:147], v[184:187], v[118:121]
	v_mfma_f32_16x16x32_bf16 v[114:117], v[152:155], v[184:187], v[114:117]
	v_mfma_f32_16x16x32_bf16 v[106:109], v[144:147], v[192:195], v[106:109]
	v_mfma_f32_16x16x32_bf16 v[98:101], v[152:155], v[192:195], v[98:101]
	v_mfma_f32_16x16x32_bf16 v[90:93], v[144:147], v[200:203], v[90:93]
	v_mfma_f32_16x16x32_bf16 v[82:85], v[152:155], v[200:203], v[82:85]
	v_mfma_f32_16x16x32_bf16 v[126:129], v[148:151], v[180:183], v[126:129]
	v_mfma_f32_16x16x32_bf16 v[122:125], v[156:159], v[180:183], v[122:125]
	v_mfma_f32_16x16x32_bf16 v[118:121], v[148:151], v[188:191], v[118:121]
	v_mfma_f32_16x16x32_bf16 v[114:117], v[156:159], v[188:191], v[114:117]
	v_mfma_f32_16x16x32_bf16 v[106:109], v[148:151], v[196:199], v[106:109]
	v_mfma_f32_16x16x32_bf16 v[98:101], v[156:159], v[196:199], v[98:101]
	v_mfma_f32_16x16x32_bf16 v[90:93], v[148:151], v[204:207], v[90:93]
	v_mfma_f32_16x16x32_bf16 v[82:85], v[156:159], v[204:207], v[82:85]
	s_setprio 0
	s_setprio 1
	v_mfma_f32_16x16x32_bf16 v[110:113], v[160:163], v[176:179], v[110:113]
	v_mfma_f32_16x16x32_bf16 v[102:105], v[168:171], v[176:179], v[102:105]
	v_mfma_f32_16x16x32_bf16 v[94:97], v[160:163], v[184:187], v[94:97]
	v_mfma_f32_16x16x32_bf16 v[86:89], v[168:171], v[184:187], v[86:89]
	v_mfma_f32_16x16x32_bf16 v[78:81], v[160:163], v[192:195], v[78:81]
	v_mfma_f32_16x16x32_bf16 v[74:77], v[168:171], v[192:195], v[74:77]
	v_mfma_f32_16x16x32_bf16 v[70:73], v[160:163], v[200:203], v[70:73]
	v_mfma_f32_16x16x32_bf16 v[66:69], v[168:171], v[200:203], v[66:69]
	v_mfma_f32_16x16x32_bf16 v[110:113], v[164:167], v[180:183], v[110:113]
	v_mfma_f32_16x16x32_bf16 v[102:105], v[172:175], v[180:183], v[102:105]
	v_mfma_f32_16x16x32_bf16 v[94:97], v[164:167], v[188:191], v[94:97]
	v_mfma_f32_16x16x32_bf16 v[86:89], v[172:175], v[188:191], v[86:89]
	v_mfma_f32_16x16x32_bf16 v[78:81], v[164:167], v[196:199], v[78:81]
	v_mfma_f32_16x16x32_bf16 v[74:77], v[172:175], v[196:199], v[74:77]
	v_mfma_f32_16x16x32_bf16 v[70:73], v[164:167], v[204:207], v[70:73]
	v_mfma_f32_16x16x32_bf16 v[66:69], v[172:175], v[204:207], v[66:69]
	s_setprio 0
	s_barrier
; #define PG8_STAGE(bufoff, gbase, voff) do { _Pragma("unroll") for (int _i = 0; _i < 2; ++_i) \
;         __builtin_amdgcn_global_load_lds((const unsigned*)((const char*)(gbase) + (voff)[_i]), (PG8_LAS unsigned*)(lds + (bufoff) + ldsw + _i * 8192), 16, 0, 0); } while (0)
; #define PG8_LDA(dst, b, h) do { _Pragma("unroll") for (int m = 0; m < 4; ++m) _Pragma("unroll") for (int k = 0; k < 2; ++k) dst[m][k] = *(const PG8_LAS bf16x8*)(lds + PG8_SA(b, h) + aoff + m * 2048 + k * 1024); } while (0)
; #define PG8_LDB(dst, b, h) do { _Pragma("unroll") for (int n = 0; n < 2; ++n) _Pragma("unroll") for (int k = 0; k < 2; ++k) dst[n][k] = *(const PG8_LAS bf16x8*)(lds + PG8_SB(b, h) + boff + n * 2048 + k * 1024); } while (0)
; #define PG8_MMA(ai, bj, At, Bt) do { __builtin_amdgcn_s_setprio(1); _Pragma("unroll") for (int m = 0; m < 4; ++m) _Pragma("unroll") for (int n = 0; n < 2; ++n) _Pragma("unroll") for (int k = 0; k < 2; ++k) \
;         acc[ai][bj][m][n] = __builtin_amdgcn_mfma_f32_16x16x32_bf16(Bt[n][k], At[m][k], acc[ai][bj][m][n], 0, 0, 0); __builtin_amdgcn_s_setprio(0); } while (0)
; #define PG8_WAIT_V(n) asm volatile("s_waitcnt vmcnt(" #n ")" ::: "memory")
; #define PG8_WAIT_L(n) asm volatile("s_waitcnt lgkmcnt(" #n ")" ::: "memory")
; #define PG8_BAR __builtin_amdgcn_s_barrier()
; #define PG8_SCHED __builtin_amdgcn_sched_barrier(0)
; template <class Epi, class Sched, bool ALIGN_EPI = false, bool SP2 = false>
; __device__ __forceinline__ void gemm_phase(PG8_LAS unsigned char* lds, const Gemm g, const Sched& S, const Epi& E) {
;     ...
;             PG8_LDB(B0, 1, 0); PG8_LDB(B1, 1, 1); PG8_SCHED; PG8_LDA(At, 1, 0); PG8_STAGE(PG8_SA(0, 1), a2 + hstep, voffA);
;             PG8_WAIT_V(8); PG8_WAIT_L(0); PG8_BAR; PG8_MMA(0, 0, At, B0); PG8_MMA(0, 1, At, B1); PG8_BAR; PG8_SCHED;
;             PG8_LDA(At, 1, 1); PG8_STAGE(PG8_SB(1, 0), b3, voffB); PG8_STAGE(PG8_SB(1, 1), b3 + hstep, voffB); PG8_STAGE(PG8_SA(1, 0), a3, voffA);
;             PG8_WAIT_V(8); PG8_WAIT_L(0); PG8_BAR; PG8_MMA(1, 0, At, B0); PG8_MMA(1, 1, At, B1); PG8_BAR; PG8_SCHED;
;     ...
;         if constexpr (ALIGN_EPI) { if (wr == 0) PG8_BAR; }
	s_add_i32 s38, s54, s16
	v_lshl_add_u64 v[208:209], v[208:209], 0, s[14:15]
	s_mov_b32 m0, s38
	ds_read_b128 v[176:179], v143 offset:49152
	ds_read_b128 v[180:183], v143 offset:50176
	ds_read_b128 v[184:187], v143 offset:51200
	ds_read_b128 v[188:191], v143 offset:52224
	ds_read_b128 v[192:195], v143 offset:53248
	ds_read_b128 v[196:199], v143 offset:54272
	ds_read_b128 v[200:203], v143 offset:55296
	ds_read_b128 v[204:207], v143 offset:56320
	global_load_lds_dwordx4 v[208:209], off
	s_add_i32 m0, s38, 0x2000
	s_add_u32 s38, s42, 0x160080
	v_lshl_add_u64 v[208:209], v[210:211], 0, s[14:15]
	s_addc_u32 s39, s43, 0
	s_add_i32 s42, s55, s16
	global_load_lds_dwordx4 v[208:209], off
	v_lshl_add_u64 v[208:209], s[38:39], 0, v[132:133]
	s_mov_b32 m0, s42
	s_nop 0
	global_load_lds_dwordx4 v[208:209], off
	v_lshl_add_u64 v[208:209], s[38:39], 0, v[130:131]
	s_add_i32 m0, s42, 0x2000
	s_nop 0
	global_load_lds_dwordx4 v[208:209], off
	v_lshl_add_u64 v[208:209], v[212:213], 0, s[14:15]
	s_mov_b32 m0, s29
	s_nop 0
	global_load_lds_dwordx4 v[208:209], off
	v_lshl_add_u64 v[208:209], v[214:215], 0, s[14:15]
	s_mov_b32 m0, s30
	s_nop 0
	global_load_lds_dwordx4 v[208:209], off
	s_waitcnt vmcnt(8)
	s_waitcnt lgkmcnt(0)
	s_setprio 1
	s_barrier
	v_mfma_f32_16x16x32_bf16 v[62:65], v[144:147], v[176:179], v[62:65]
	v_mfma_f32_16x16x32_bf16 v[58:61], v[152:155], v[176:179], v[58:61]
	v_mfma_f32_16x16x32_bf16 v[54:57], v[144:147], v[184:187], v[54:57]
	v_mfma_f32_16x16x32_bf16 v[50:53], v[152:155], v[184:187], v[50:53]
	v_mfma_f32_16x16x32_bf16 v[38:41], v[144:147], v[192:195], v[38:41]
	v_mfma_f32_16x16x32_bf16 v[34:37], v[152:155], v[192:195], v[34:37]
	v_mfma_f32_16x16x32_bf16 v[22:25], v[144:147], v[200:203], v[22:25]
	v_mfma_f32_16x16x32_bf16 v[18:21], v[152:155], v[200:203], v[18:21]
	v_mfma_f32_16x16x32_bf16 v[62:65], v[148:151], v[180:183], v[62:65]
	v_mfma_f32_16x16x32_bf16 v[58:61], v[156:159], v[180:183], v[58:61]
	v_mfma_f32_16x16x32_bf16 v[54:57], v[148:151], v[188:191], v[54:57]
	v_mfma_f32_16x16x32_bf16 v[50:53], v[156:159], v[188:191], v[50:53]
	v_mfma_f32_16x16x32_bf16 v[38:41], v[148:151], v[196:199], v[38:41]
	v_mfma_f32_16x16x32_bf16 v[34:37], v[156:159], v[196:199], v[34:37]
	v_mfma_f32_16x16x32_bf16 v[22:25], v[148:151], v[204:207], v[22:25]
	v_mfma_f32_16x16x32_bf16 v[18:21], v[156:159], v[204:207], v[18:21]
	s_setprio 0
	s_setprio 1
	v_mfma_f32_16x16x32_bf16 v[46:49], v[160:163], v[176:179], v[46:49]
	v_mfma_f32_16x16x32_bf16 v[42:45], v[168:171], v[176:179], v[42:45]
	v_mfma_f32_16x16x32_bf16 v[30:33], v[160:163], v[184:187], v[30:33]
	v_mfma_f32_16x16x32_bf16 v[26:29], v[168:171], v[184:187], v[26:29]
	v_mfma_f32_16x16x32_bf16 v[14:17], v[160:163], v[192:195], v[14:17]
	v_mfma_f32_16x16x32_bf16 v[10:13], v[168:171], v[192:195], v[10:13]
	v_mfma_f32_16x16x32_bf16 v[6:9], v[160:163], v[200:203], v[6:9]
	v_mfma_f32_16x16x32_bf16 v[2:5], v[168:171], v[200:203], v[2:5]
	v_mfma_f32_16x16x32_bf16 v[46:49], v[164:167], v[180:183], v[46:49]
	v_mfma_f32_16x16x32_bf16 v[42:45], v[172:175], v[180:183], v[42:45]
	v_mfma_f32_16x16x32_bf16 v[30:33], v[164:167], v[188:191], v[30:33]
	v_mfma_f32_16x16x32_bf16 v[26:29], v[172:175], v[188:191], v[26:29]
	v_mfma_f32_16x16x32_bf16 v[14:17], v[164:167], v[196:199], v[14:17]
	v_mfma_f32_16x16x32_bf16 v[10:13], v[172:175], v[196:199], v[10:13]
	v_mfma_f32_16x16x32_bf16 v[6:9], v[164:167], v[204:207], v[6:9]
	v_mfma_f32_16x16x32_bf16 v[2:5], v[172:175], v[204:207], v[2:5]
	s_setprio 0
	s_add_i32 s53, s53, 2
	s_add_u32 s11, s11, 0x100
	s_addc_u32 s52, s52, 0
	s_cmp_gt_u32 s53, 19
	s_mov_b64 s[38:39], s[40:41]
	s_barrier
	s_cbranch_scc0 .LBB0_193
	s_and_b64 vcc, exec, s[20:21]
	s_cbranch_vccz .LBB0_196
	s_barrier

; #define PG8_STAGE(bufoff, gbase, voff) do { _Pragma("unroll") for (int _i = 0; _i < 2; ++_i) \
;         __builtin_amdgcn_global_load_lds((const unsigned*)((const char*)(gbase) + (voff)[_i]), (PG8_LAS unsigned*)(lds + (bufoff) + ldsw + _i * 8192), 16, 0, 0); } while (0)
; #define PG8_LDA(dst, b, h) do { _Pragma("unroll") for (int m = 0; m < 4; ++m) _Pragma("unroll") for (int k = 0; k < 2; ++k) dst[m][k] = *(const PG8_LAS bf16x8*)(lds + PG8_SA(b, h) + aoff + m * 2048 + k * 1024); } while (0)
; #define PG8_WAIT_V(n) asm volatile("s_waitcnt vmcnt(" #n ")" ::: "memory")
; #define PG8_BAR __builtin_amdgcn_s_barrier()
; template <class Epi, class Sched, bool ALIGN_EPI = false, bool SP2 = false>
; __device__ __forceinline__ void gemm_phase(PG8_LAS unsigned char* lds, const Gemm g, const Sched& S, const Epi& E) {
;     ...
;         for (int t = 0; t < nt; t += 2) {
;             if constexpr (Epi::MIDHOOK) { if (t == (nt >> 1)) E.mid(acc, cur, wr, wc, fr, fq); }
;             const bool last = (t == nt - 2);
;             const char* a1 = cA + (size_t)(t + 1) * kstep;
;             const char* a2 = last ? nA : cA + (size_t)(t + 2) * kstep; const char* b2 = last ? nB : cB + (size_t)(t + 2) * kstep;
;             const char* a3 = a2 + kstep; const char* b3 = b2 + kstep;
;             if (last && has_next) S.a_ready(nxt);
;             if constexpr (SP2) {
;             PG8_LDB(B0, 0, 0); PG8_LDB(B1, 0, 1); PG8_SCHED; PG8_LDA(At, 0, 0); PG8_STAGE(PG8_SA(1, 1), a1 + hstep, voffA);
;             PG8_WAIT_V(8); PG8_WAIT_L(0); PG8_BAR; PG8_MMA(0, 0, At, B0); PG8_MMA(0, 1, At, B1); PG8_BAR; PG8_SCHED;
;             PG8_LDA(At, 0, 1); PG8_STAGE(PG8_SB(0, 0), b2, voffB); PG8_STAGE(PG8_SB(0, 1), b2 + hstep, voffB); PG8_STAGE(PG8_SA(0, 0), a2, voffA);
;             PG8_WAIT_V(8); PG8_WAIT_L(0); PG8_BAR; PG8_MMA(1, 0, At, B0); PG8_MMA(1, 1, At, B1); PG8_BAR; PG8_SCHED;
;             PG8_LDB(B0, 1, 0); PG8_LDB(B1, 1, 1); PG8_SCHED; PG8_LDA(At, 1, 0); PG8_STAGE(PG8_SA(0, 1), a2 + hstep, voffA);
;             PG8_WAIT_V(8); PG8_WAIT_L(0); PG8_BAR; PG8_MMA(0, 0, At, B0); PG8_MMA(0, 1, At, B1); PG8_BAR; PG8_SCHED;
;             PG8_LDA(At, 1, 1); PG8_STAGE(PG8_SB(1, 0), b3, voffB); PG8_STAGE(PG8_SB(1, 1), b3 + hstep, voffB); PG8_STAGE(PG8_SA(1, 0), a3, voffA);
;             PG8_WAIT_V(8); PG8_WAIT_L(0); PG8_BAR; PG8_MMA(1, 0, At, B0); PG8_MMA(1, 1, At, B1); PG8_BAR; PG8_SCHED;
.LBB0_346:
	ds_read_b128 v[150:153], v177
	ds_read_b128 v[154:157], v177 offset:1024
	ds_read_b128 v[158:161], v177 offset:2048
	ds_read_b128 v[162:165], v177 offset:3072
	ds_read_b128 v[166:169], v178
	ds_read_b128 v[182:185], v178 offset:1024
	ds_read_b128 v[186:189], v178 offset:2048
	ds_read_b128 v[190:193], v178 offset:3072
	s_add_u32 s14, s10, 0xfff80080
	s_addc_u32 s15, s11, -1
	s_cmp_eq_u32 s23, 28
	s_cselect_b32 s17, s6, s15
	s_cselect_b32 s16, s7, s14
	s_cselect_b32 s15, s13, s22
	s_cselect_b32 s14, s18, s19
	v_lshl_add_u64 v[170:171], s[10:11], 0, v[142:143]
	s_add_i32 m0, s59, 0xc000
	ds_read_b128 v[194:197], v179
	ds_read_b128 v[198:201], v179 offset:1024
	ds_read_b128 v[202:205], v179 offset:2048
	ds_read_b128 v[206:209], v179 offset:3072
	ds_read_b128 v[210:213], v179 offset:4096
	ds_read_b128 v[214:217], v179 offset:5120
	ds_read_b128 v[218:221], v179 offset:6144
	ds_read_b128 v[222:225], v179 offset:7168
	global_load_lds_dwordx4 v[170:171], off
	v_lshl_add_u64 v[170:171], s[10:11], 0, v[144:145]
	s_add_i32 m0, s59, 0xe000
	s_nop 0
	global_load_lds_dwordx4 v[170:171], off
	s_waitcnt vmcnt(8)
	s_waitcnt lgkmcnt(0)
	s_setprio 1
	s_barrier
	v_mfma_f32_16x16x32_bf16 v[58:61], v[150:153], v[194:197], v[58:61]
	v_mfma_f32_16x16x32_bf16 v[62:65], v[158:161], v[194:197], v[62:65]
	v_mfma_f32_16x16x32_bf16 v[50:53], v[150:153], v[202:205], v[50:53]
	v_mfma_f32_16x16x32_bf16 v[54:57], v[158:161], v[202:205], v[54:57]
	v_mfma_f32_16x16x32_bf16 v[42:45], v[150:153], v[210:213], v[42:45]
	v_mfma_f32_16x16x32_bf16 v[46:49], v[158:161], v[210:213], v[46:49]
	v_mfma_f32_16x16x32_bf16 v[34:37], v[150:153], v[218:221], v[34:37]
	v_mfma_f32_16x16x32_bf16 v[38:41], v[158:161], v[218:221], v[38:41]
	v_mfma_f32_16x16x32_bf16 v[58:61], v[154:157], v[198:201], v[58:61]
	v_mfma_f32_16x16x32_bf16 v[62:65], v[162:165], v[198:201], v[62:65]
	v_mfma_f32_16x16x32_bf16 v[50:53], v[154:157], v[206:209], v[50:53]
	v_mfma_f32_16x16x32_bf16 v[54:57], v[162:165], v[206:209], v[54:57]
	v_mfma_f32_16x16x32_bf16 v[42:45], v[154:157], v[214:217], v[42:45]
	v_mfma_f32_16x16x32_bf16 v[46:49], v[162:165], v[214:217], v[46:49]
	v_mfma_f32_16x16x32_bf16 v[34:37], v[154:157], v[222:225], v[34:37]
	v_mfma_f32_16x16x32_bf16 v[38:41], v[162:165], v[222:225], v[38:41]
	s_setprio 0
	s_setprio 1
	v_mfma_f32_16x16x32_bf16 v[126:129], v[166:169], v[194:197], v[126:129]
	v_mfma_f32_16x16x32_bf16 v[122:125], v[186:189], v[194:197], v[122:125]
	v_mfma_f32_16x16x32_bf16 v[118:121], v[166:169], v[202:205], v[118:121]
	v_mfma_f32_16x16x32_bf16 v[114:117], v[186:189], v[202:205], v[114:117]
	v_mfma_f32_16x16x32_bf16 v[110:113], v[166:169], v[210:213], v[110:113]
	v_mfma_f32_16x16x32_bf16 v[106:109], v[186:189], v[210:213], v[106:109]
	v_mfma_f32_16x16x32_bf16 v[102:105], v[166:169], v[218:221], v[102:105]
	v_mfma_f32_16x16x32_bf16 v[98:101], v[186:189], v[218:221], v[98:101]
	v_mfma_f32_16x16x32_bf16 v[126:129], v[182:185], v[198:201], v[126:129]
	v_mfma_f32_16x16x32_bf16 v[122:125], v[190:193], v[198:201], v[122:125]
	v_mfma_f32_16x16x32_bf16 v[118:121], v[182:185], v[206:209], v[118:121]
	v_mfma_f32_16x16x32_bf16 v[114:117], v[190:193], v[206:209], v[114:117]
	v_mfma_f32_16x16x32_bf16 v[110:113], v[182:185], v[214:217], v[110:113]
	v_mfma_f32_16x16x32_bf16 v[106:109], v[190:193], v[214:217], v[106:109]
	v_mfma_f32_16x16x32_bf16 v[102:105], v[182:185], v[222:225], v[102:105]
	v_mfma_f32_16x16x32_bf16 v[98:101], v[190:193], v[222:225], v[98:101]
	s_setprio 0
	s_barrier
	s_add_i32 s24, s95, s55
	v_lshl_add_u64 v[170:171], s[14:15], 0, v[132:133]
	s_mov_b32 m0, s24
	ds_read_b128 v[194:197], v179 offset:16384
	ds_read_b128 v[198:201], v179 offset:17408
	ds_read_b128 v[202:205], v179 offset:18432
	ds_read_b128 v[206:209], v179 offset:19456
	ds_read_b128 v[210:213], v179 offset:20480
	ds_read_b128 v[214:217], v179 offset:21504
	ds_read_b128 v[218:221], v179 offset:22528
	ds_read_b128 v[222:225], v179 offset:23552
	global_load_lds_dwordx4 v[170:171], off
	s_add_i32 m0, s24, 0x2000
	s_add_u32 s24, s14, 0x80000
	v_lshl_add_u64 v[226:227], s[14:15], 0, v[136:137]
	s_addc_u32 s25, s15, 0
	s_add_i32 s26, s81, s55
	global_load_lds_dwordx4 v[226:227], off
	v_lshl_add_u64 v[228:229], s[24:25], 0, v[132:133]
	s_mov_b32 m0, s26
	v_lshl_add_u64 v[230:231], s[16:17], 0, v[134:135]
	global_load_lds_dwordx4 v[228:229], off
	v_lshl_add_u64 v[228:229], s[24:25], 0, v[136:137]
	s_add_i32 m0, s26, 0x2000
	s_nop 0
	global_load_lds_dwordx4 v[228:229], off
	v_lshl_add_u64 v[228:229], s[16:17], 0, v[130:131]
	s_mov_b32 m0, s59
	s_nop 0
	global_load_lds_dwordx4 v[228:229], off
	s_mov_b32 m0, s61
	s_nop 0
	global_load_lds_dwordx4 v[230:231], off
	s_waitcnt vmcnt(8)
	s_waitcnt lgkmcnt(0)
	s_setprio 1
	s_barrier
; #define PG8_STAGE(bufoff, gbase, voff) do { _Pragma("unroll") for (int _i = 0; _i < 2; ++_i) \
;         __builtin_amdgcn_global_load_lds((const unsigned*)((const char*)(gbase) + (voff)[_i]), (PG8_LAS unsigned*)(lds + (bufoff) + ldsw + _i * 8192), 16, 0, 0); } while (0)
; #define PG8_LDA(dst, b, h) do { _Pragma("unroll") for (int m = 0; m < 4; ++m) _Pragma("unroll") for (int k = 0; k < 2; ++k) dst[m][k] = *(const PG8_LAS bf16x8*)(lds + PG8_SA(b, h) + aoff + m * 2048 + k * 1024); } while (0)
; #define PG8_LDB(dst, b, h) do { _Pragma("unroll") for (int n = 0; n < 2; ++n) _Pragma("unroll") for (int k = 0; k < 2; ++k) dst[n][k] = *(const PG8_LAS bf16x8*)(lds + PG8_SB(b, h) + boff + n * 2048 + k * 1024); } while (0)
; #define PG8_MMA(ai, bj, At, Bt) do { __builtin_amdgcn_s_setprio(1); _Pragma("unroll") for (int m = 0; m < 4; ++m) _Pragma("unroll") for (int n = 0; n < 2; ++n) _Pragma("unroll") for (int k = 0; k < 2; ++k) \
;         acc[ai][bj][m][n] = __builtin_amdgcn_mfma_f32_16x16x32_bf16(Bt[n][k], At[m][k], acc[ai][bj][m][n], 0, 0, 0); __builtin_amdgcn_s_setprio(0); } while (0)
; #define PG8_WAIT_V(n) asm volatile("s_waitcnt vmcnt(" #n ")" ::: "memory")
; template <class Epi, class Sched, bool ALIGN_EPI = false, bool SP2 = false>
; __device__ __forceinline__ void gemm_phase(PG8_LAS unsigned char* lds, const Gemm g, const Sched& S, const Epi& E) {
;     ...
;             PG8_LDB(B0, 0, 0); PG8_LDB(B1, 0, 1); PG8_SCHED; PG8_LDA(At, 0, 0); PG8_STAGE(PG8_SA(1, 1), a1 + hstep, voffA);
;             PG8_WAIT_V(8); PG8_WAIT_L(0); PG8_BAR; PG8_MMA(0, 0, At, B0); PG8_MMA(0, 1, At, B1); PG8_BAR; PG8_SCHED;
;             PG8_LDA(At, 0, 1); PG8_STAGE(PG8_SB(0, 0), b2, voffB); PG8_STAGE(PG8_SB(0, 1), b2 + hstep, voffB); PG8_STAGE(PG8_SA(0, 0), a2, voffA);
;             PG8_WAIT_V(8); PG8_WAIT_L(0); PG8_BAR; PG8_MMA(1, 0, At, B0); PG8_MMA(1, 1, At, B1); PG8_BAR; PG8_SCHED;
;             PG8_LDB(B0, 1, 0); PG8_LDB(B1, 1, 1); PG8_SCHED; PG8_LDA(At, 1, 0); PG8_STAGE(PG8_SA(0, 1), a2 + hstep, voffA);
;             PG8_WAIT_V(8); PG8_WAIT_L(0); PG8_BAR; PG8_MMA(0, 0, At, B0); PG8_MMA(0, 1, At, B1); PG8_BAR; PG8_SCHED;
;             PG8_LDA(At, 1, 1); PG8_STAGE(PG8_SB(1, 0), b3, voffB); PG8_STAGE(PG8_SB(1, 1), b3 + hstep, voffB); PG8_STAGE(PG8_SA(1, 0), a3, voffA);
;             PG8_WAIT_V(8); PG8_WAIT_L(0); PG8_BAR; PG8_MMA(1, 0, At, B0); PG8_MMA(1, 1, At, B1); PG8_BAR; PG8_SCHED;
	v_mfma_f32_16x16x32_bf16 v[26:29], v[150:153], v[194:197], v[26:29]
	v_mfma_f32_16x16x32_bf16 v[30:33], v[158:161], v[194:197], v[30:33]
	v_mfma_f32_16x16x32_bf16 v[18:21], v[150:153], v[202:205], v[18:21]
	v_mfma_f32_16x16x32_bf16 v[22:25], v[158:161], v[202:205], v[22:25]
	v_mfma_f32_16x16x32_bf16 v[10:13], v[150:153], v[210:213], v[10:13]
	v_mfma_f32_16x16x32_bf16 v[14:17], v[158:161], v[210:213], v[14:17]
	v_mfma_f32_16x16x32_bf16 v[2:5], v[150:153], v[218:221], v[2:5]
	v_mfma_f32_16x16x32_bf16 v[6:9], v[158:161], v[218:221], v[6:9]
	v_mfma_f32_16x16x32_bf16 v[26:29], v[154:157], v[198:201], v[26:29]
	v_mfma_f32_16x16x32_bf16 v[30:33], v[162:165], v[198:201], v[30:33]
	v_mfma_f32_16x16x32_bf16 v[18:21], v[154:157], v[206:209], v[18:21]
	v_mfma_f32_16x16x32_bf16 v[22:25], v[162:165], v[206:209], v[22:25]
	v_mfma_f32_16x16x32_bf16 v[10:13], v[154:157], v[214:217], v[10:13]
	v_mfma_f32_16x16x32_bf16 v[14:17], v[162:165], v[214:217], v[14:17]
	v_mfma_f32_16x16x32_bf16 v[2:5], v[154:157], v[222:225], v[2:5]
	v_mfma_f32_16x16x32_bf16 v[6:9], v[162:165], v[222:225], v[6:9]
	s_setprio 0
	s_setprio 1
	v_mfma_f32_16x16x32_bf16 v[94:97], v[166:169], v[194:197], v[94:97]
	v_mfma_f32_16x16x32_bf16 v[90:93], v[186:189], v[194:197], v[90:93]
	v_mfma_f32_16x16x32_bf16 v[86:89], v[166:169], v[202:205], v[86:89]
	v_mfma_f32_16x16x32_bf16 v[82:85], v[186:189], v[202:205], v[82:85]
	v_mfma_f32_16x16x32_bf16 v[78:81], v[166:169], v[210:213], v[78:81]
	v_mfma_f32_16x16x32_bf16 v[74:77], v[186:189], v[210:213], v[74:77]
	v_mfma_f32_16x16x32_bf16 v[70:73], v[166:169], v[218:221], v[70:73]
	v_mfma_f32_16x16x32_bf16 v[66:69], v[186:189], v[218:221], v[66:69]
	v_mfma_f32_16x16x32_bf16 v[94:97], v[182:185], v[198:201], v[94:97]
	v_mfma_f32_16x16x32_bf16 v[90:93], v[190:193], v[198:201], v[90:93]
	v_mfma_f32_16x16x32_bf16 v[86:89], v[182:185], v[206:209], v[86:89]
	v_mfma_f32_16x16x32_bf16 v[82:85], v[190:193], v[206:209], v[82:85]
	v_mfma_f32_16x16x32_bf16 v[78:81], v[182:185], v[214:217], v[78:81]
	v_mfma_f32_16x16x32_bf16 v[74:77], v[190:193], v[214:217], v[74:77]
	v_mfma_f32_16x16x32_bf16 v[70:73], v[182:185], v[222:225], v[70:73]
	v_mfma_f32_16x16x32_bf16 v[66:69], v[190:193], v[222:225], v[66:69]
	s_setprio 0
	s_barrier
	s_add_i32 s24, 0, 0x18000
	v_add_u32_e32 v138, s24, v172
	s_add_i32 s25, 0, 0x1c000
	ds_read_b128 v[150:153], v138
	ds_read_b128 v[154:157], v138 offset:1024
	ds_read_b128 v[158:161], v138 offset:2048
	ds_read_b128 v[162:165], v138 offset:3072
	v_add_u32_e32 v138, s25, v172
	ds_read_b128 v[166:169], v138
	ds_read_b128 v[182:185], v138 offset:1024
	ds_read_b128 v[186:189], v138 offset:2048
	ds_read_b128 v[190:193], v138 offset:3072
	s_add_u32 s16, s16, 0x80000
	s_addc_u32 s17, s17, 0
	s_mov_b32 m0, s63
	v_lshl_add_u64 v[232:233], s[16:17], 0, v[130:131]
	ds_read_b128 v[194:197], v179 offset:32768
	ds_read_b128 v[198:201], v179 offset:33792
	ds_read_b128 v[202:205], v179 offset:34816
	ds_read_b128 v[206:209], v179 offset:35840
	ds_read_b128 v[210:213], v179 offset:36864
	ds_read_b128 v[214:217], v179 offset:37888
	ds_read_b128 v[218:221], v179 offset:38912
	ds_read_b128 v[222:225], v179 offset:39936
	global_load_lds_dwordx4 v[232:233], off
	v_lshl_add_u64 v[232:233], s[16:17], 0, v[134:135]
	s_mov_b32 m0, s65
	s_nop 0
	global_load_lds_dwordx4 v[232:233], off
	s_waitcnt vmcnt(8)
	s_waitcnt lgkmcnt(0)
	s_setprio 1
	s_barrier
	v_mfma_f32_16x16x32_bf16 v[58:61], v[150:153], v[194:197], v[58:61]
	v_mfma_f32_16x16x32_bf16 v[62:65], v[158:161], v[194:197], v[62:65]
	v_mfma_f32_16x16x32_bf16 v[50:53], v[150:153], v[202:205], v[50:53]
	v_mfma_f32_16x16x32_bf16 v[54:57], v[158:161], v[202:205], v[54:57]
	v_mfma_f32_16x16x32_bf16 v[42:45], v[150:153], v[210:213], v[42:45]
	v_mfma_f32_16x16x32_bf16 v[46:49], v[158:161], v[210:213], v[46:49]
	v_mfma_f32_16x16x32_bf16 v[34:37], v[150:153], v[218:221], v[34:37]
	v_mfma_f32_16x16x32_bf16 v[38:41], v[158:161], v[218:221], v[38:41]
	v_mfma_f32_16x16x32_bf16 v[58:61], v[154:157], v[198:201], v[58:61]
	v_mfma_f32_16x16x32_bf16 v[62:65], v[162:165], v[198:201], v[62:65]
	v_mfma_f32_16x16x32_bf16 v[50:53], v[154:157], v[206:209], v[50:53]
	v_mfma_f32_16x16x32_bf16 v[54:57], v[162:165], v[206:209], v[54:57]
	v_mfma_f32_16x16x32_bf16 v[42:45], v[154:157], v[214:217], v[42:45]
	v_mfma_f32_16x16x32_bf16 v[46:49], v[162:165], v[214:217], v[46:49]
	v_mfma_f32_16x16x32_bf16 v[34:37], v[154:157], v[222:225], v[34:37]
	v_mfma_f32_16x16x32_bf16 v[38:41], v[162:165], v[222:225], v[38:41]
	s_setprio 0
	s_setprio 1
	v_mfma_f32_16x16x32_bf16 v[126:129], v[166:169], v[194:197], v[126:129]
	v_mfma_f32_16x16x32_bf16 v[122:125], v[186:189], v[194:197], v[122:125]
	v_mfma_f32_16x16x32_bf16 v[118:121], v[166:169], v[202:205], v[118:121]
	v_mfma_f32_16x16x32_bf16 v[114:117], v[186:189], v[202:205], v[114:117]
	v_mfma_f32_16x16x32_bf16 v[110:113], v[166:169], v[210:213], v[110:113]
	v_mfma_f32_16x16x32_bf16 v[106:109], v[186:189], v[210:213], v[106:109]
	v_mfma_f32_16x16x32_bf16 v[102:105], v[166:169], v[218:221], v[102:105]
	v_mfma_f32_16x16x32_bf16 v[98:101], v[186:189], v[218:221], v[98:101]
	v_mfma_f32_16x16x32_bf16 v[126:129], v[182:185], v[198:201], v[126:129]
	v_mfma_f32_16x16x32_bf16 v[122:125], v[190:193], v[198:201], v[122:125]
	v_mfma_f32_16x16x32_bf16 v[118:121], v[182:185], v[206:209], v[118:121]
	v_mfma_f32_16x16x32_bf16 v[114:117], v[190:193], v[206:209], v[114:117]
	v_mfma_f32_16x16x32_bf16 v[110:113], v[182:185], v[214:217], v[110:113]
	v_mfma_f32_16x16x32_bf16 v[106:109], v[190:193], v[214:217], v[106:109]
	v_mfma_f32_16x16x32_bf16 v[102:105], v[182:185], v[222:225], v[102:105]
	v_mfma_f32_16x16x32_bf16 v[98:101], v[190:193], v[222:225], v[98:101]
	s_setprio 0
	s_barrier
; #define PG8_STAGE(bufoff, gbase, voff) do { _Pragma("unroll") for (int _i = 0; _i < 2; ++_i) \
;         __builtin_amdgcn_global_load_lds((const unsigned*)((const char*)(gbase) + (voff)[_i]), (PG8_LAS unsigned*)(lds + (bufoff) + ldsw + _i * 8192), 16, 0, 0); } while (0)
; #define PG8_LDA(dst, b, h) do { _Pragma("unroll") for (int m = 0; m < 4; ++m) _Pragma("unroll") for (int k = 0; k < 2; ++k) dst[m][k] = *(const PG8_LAS bf16x8*)(lds + PG8_SA(b, h) + aoff + m * 2048 + k * 1024); } while (0)
; #define PG8_LDB(dst, b, h) do { _Pragma("unroll") for (int n = 0; n < 2; ++n) _Pragma("unroll") for (int k = 0; k < 2; ++k) dst[n][k] = *(const PG8_LAS bf16x8*)(lds + PG8_SB(b, h) + boff + n * 2048 + k * 1024); } while (0)
; #define PG8_MMA(ai, bj, At, Bt) do { __builtin_amdgcn_s_setprio(1); _Pragma("unroll") for (int m = 0; m < 4; ++m) _Pragma("unroll") for (int n = 0; n < 2; ++n) _Pragma("unroll") for (int k = 0; k < 2; ++k) \
;         acc[ai][bj][m][n] = __builtin_amdgcn_mfma_f32_16x16x32_bf16(Bt[n][k], At[m][k], acc[ai][bj][m][n], 0, 0, 0); __builtin_amdgcn_s_setprio(0); } while (0)
; #define PG8_WAIT_V(n) asm volatile("s_waitcnt vmcnt(" #n ")" ::: "memory")
; #define PG8_WAIT_L(n) asm volatile("s_waitcnt lgkmcnt(" #n ")" ::: "memory")
; #define PG8_BAR __builtin_amdgcn_s_barrier()
; #define PG8_SCHED __builtin_amdgcn_sched_barrier(0)
;     __device__ __forceinline__ void operator()(const f32x4 (&acc)[2][2][4][2], const Unit& u, int wr, int wc, int fr, int fq) const {
;         const int sec = u.pn >> 3, pnl = u.pn & 7;
;         if (sec == 7) {
; template <class Epi, class Sched, bool ALIGN_EPI = false, bool SP2 = false>
; __device__ __forceinline__ void gemm_phase(PG8_LAS unsigned char* lds, const Gemm g, const Sched& S, const Epi& E) {
;     ...
;             PG8_LDB(B0, 1, 0); PG8_LDB(B1, 1, 1); PG8_SCHED; PG8_LDA(At, 1, 0); PG8_STAGE(PG8_SA(0, 1), a2 + hstep, voffA);
;             PG8_WAIT_V(8); PG8_WAIT_L(0); PG8_BAR; PG8_MMA(0, 0, At, B0); PG8_MMA(0, 1, At, B1); PG8_BAR; PG8_SCHED;
;             PG8_LDA(At, 1, 1); PG8_STAGE(PG8_SB(1, 0), b3, voffB); PG8_STAGE(PG8_SB(1, 1), b3 + hstep, voffB); PG8_STAGE(PG8_SA(1, 0), a3, voffA);
;             PG8_WAIT_V(8); PG8_WAIT_L(0); PG8_BAR; PG8_MMA(1, 0, At, B0); PG8_MMA(1, 1, At, B1); PG8_BAR; PG8_SCHED;
;     ...
;         if constexpr (ALIGN_EPI) { if (wr == 0) PG8_BAR; }
	s_add_i32 s16, s24, s55
	v_lshl_add_u64 v[170:171], v[170:171], 0, s[90:91]
	s_mov_b32 m0, s16
	ds_read_b128 v[194:197], v179 offset:49152
	ds_read_b128 v[198:201], v179 offset:50176
	ds_read_b128 v[202:205], v179 offset:51200
	ds_read_b128 v[206:209], v179 offset:52224
	ds_read_b128 v[210:213], v179 offset:53248
	ds_read_b128 v[214:217], v179 offset:54272
	ds_read_b128 v[218:221], v179 offset:55296
	ds_read_b128 v[222:225], v179 offset:56320
	global_load_lds_dwordx4 v[170:171], off
	s_add_i32 m0, s16, 0x2000
	s_add_u32 s14, s14, 0x80080
	v_lshl_add_u64 v[170:171], v[226:227], 0, s[90:91]
	s_addc_u32 s15, s15, 0
	s_add_i32 s16, s25, s55
	global_load_lds_dwordx4 v[170:171], off
	v_lshl_add_u64 v[170:171], s[14:15], 0, v[132:133]
	s_mov_b32 m0, s16
	s_nop 0
	global_load_lds_dwordx4 v[170:171], off
	v_lshl_add_u64 v[170:171], s[14:15], 0, v[136:137]
	s_add_i32 m0, s16, 0x2000
	s_nop 0
	global_load_lds_dwordx4 v[170:171], off
	v_lshl_add_u64 v[170:171], v[228:229], 0, s[90:91]
	s_mov_b32 m0, s92
	s_nop 0
	global_load_lds_dwordx4 v[170:171], off
	v_lshl_add_u64 v[170:171], v[230:231], 0, s[90:91]
	s_mov_b32 m0, s93
	s_nop 0
	global_load_lds_dwordx4 v[170:171], off
	s_waitcnt vmcnt(8)
	s_waitcnt lgkmcnt(0)
	s_setprio 1
	s_barrier
	v_mfma_f32_16x16x32_bf16 v[26:29], v[150:153], v[194:197], v[26:29]
	v_mfma_f32_16x16x32_bf16 v[30:33], v[158:161], v[194:197], v[30:33]
	v_mfma_f32_16x16x32_bf16 v[18:21], v[150:153], v[202:205], v[18:21]
	v_mfma_f32_16x16x32_bf16 v[22:25], v[158:161], v[202:205], v[22:25]
	v_mfma_f32_16x16x32_bf16 v[10:13], v[150:153], v[210:213], v[10:13]
	v_mfma_f32_16x16x32_bf16 v[14:17], v[158:161], v[210:213], v[14:17]
	v_mfma_f32_16x16x32_bf16 v[2:5], v[150:153], v[218:221], v[2:5]
	v_mfma_f32_16x16x32_bf16 v[6:9], v[158:161], v[218:221], v[6:9]
	v_mfma_f32_16x16x32_bf16 v[26:29], v[154:157], v[198:201], v[26:29]
	v_mfma_f32_16x16x32_bf16 v[30:33], v[162:165], v[198:201], v[30:33]
	v_mfma_f32_16x16x32_bf16 v[18:21], v[154:157], v[206:209], v[18:21]
	v_mfma_f32_16x16x32_bf16 v[22:25], v[162:165], v[206:209], v[22:25]
	v_mfma_f32_16x16x32_bf16 v[10:13], v[154:157], v[214:217], v[10:13]
	v_mfma_f32_16x16x32_bf16 v[14:17], v[162:165], v[214:217], v[14:17]
	v_mfma_f32_16x16x32_bf16 v[2:5], v[154:157], v[222:225], v[2:5]
	v_mfma_f32_16x16x32_bf16 v[6:9], v[162:165], v[222:225], v[6:9]
	s_setprio 0
	s_setprio 1
	v_mfma_f32_16x16x32_bf16 v[94:97], v[166:169], v[194:197], v[94:97]
	v_mfma_f32_16x16x32_bf16 v[90:93], v[186:189], v[194:197], v[90:93]
	v_mfma_f32_16x16x32_bf16 v[86:89], v[166:169], v[202:205], v[86:89]
	v_mfma_f32_16x16x32_bf16 v[82:85], v[186:189], v[202:205], v[82:85]
	v_mfma_f32_16x16x32_bf16 v[78:81], v[166:169], v[210:213], v[78:81]
	v_mfma_f32_16x16x32_bf16 v[74:77], v[186:189], v[210:213], v[74:77]
	v_mfma_f32_16x16x32_bf16 v[70:73], v[166:169], v[218:221], v[70:73]
	v_mfma_f32_16x16x32_bf16 v[66:69], v[186:189], v[218:221], v[66:69]
	v_mfma_f32_16x16x32_bf16 v[94:97], v[182:185], v[198:201], v[94:97]
	v_mfma_f32_16x16x32_bf16 v[90:93], v[190:193], v[198:201], v[90:93]
	v_mfma_f32_16x16x32_bf16 v[86:89], v[182:185], v[206:209], v[86:89]
	v_mfma_f32_16x16x32_bf16 v[82:85], v[190:193], v[206:209], v[82:85]
	v_mfma_f32_16x16x32_bf16 v[78:81], v[182:185], v[214:217], v[78:81]
	v_mfma_f32_16x16x32_bf16 v[74:77], v[190:193], v[214:217], v[74:77]
	v_mfma_f32_16x16x32_bf16 v[70:73], v[182:185], v[222:225], v[70:73]
	v_mfma_f32_16x16x32_bf16 v[66:69], v[190:193], v[222:225], v[66:69]
	s_setprio 0
	s_add_i32 s23, s23, 2
	s_add_u32 s10, s10, 0x100
	s_addc_u32 s11, s11, 0
	s_add_u32 s19, s19, 0x100
	s_addc_u32 s22, s22, 0
	s_cmp_gt_u32 s23, 29
	s_barrier
	s_cbranch_scc0 .LBB0_346
	v_readlane_b32 s6, v244, 18
	v_readlane_b32 s7, v244, 19
	s_and_b64 vcc, exec, s[6:7]
	s_cbranch_vccnz .LBB0_351
	s_ashr_i32 s13, s12, 3
	s_cmp_lg_u32 s13, 7
	s_mov_b64 s[6:7], -1
	s_cbranch_scc1 .LBB0_352

; #define PG8_STAGE(bufoff, gbase, voff) do { _Pragma("unroll") for (int _i = 0; _i < 2; ++_i) \
;         __builtin_amdgcn_global_load_lds((const unsigned*)((const char*)(gbase) + (voff)[_i]), (PG8_LAS unsigned*)(lds + (bufoff) + ldsw + _i * 8192), 16, 0, 0); } while (0)
; #define PG8_LDA(dst, b, h) do { _Pragma("unroll") for (int m = 0; m < 4; ++m) _Pragma("unroll") for (int k = 0; k < 2; ++k) dst[m][k] = *(const PG8_LAS bf16x8*)(lds + PG8_SA(b, h) + aoff + m * 2048 + k * 1024); } while (0)
; #define PG8_WAIT_V(n) asm volatile("s_waitcnt vmcnt(" #n ")" ::: "memory")
; #define PG8_BAR __builtin_amdgcn_s_barrier()
; template <class Epi, class Sched, bool ALIGN_EPI = false, bool SP2 = false>
; __device__ __forceinline__ void gemm_phase(PG8_LAS unsigned char* lds, const Gemm g, const Sched& S, const Epi& E) {
;     ...
;         for (int t = 0; t < nt; t += 2) {
;             if constexpr (Epi::MIDHOOK) { if (t == (nt >> 1)) E.mid(acc, cur, wr, wc, fr, fq); }
;             const bool last = (t == nt - 2);
;             const char* a1 = cA + (size_t)(t + 1) * kstep;
;             const char* a2 = last ? nA : cA + (size_t)(t + 2) * kstep; const char* b2 = last ? nB : cB + (size_t)(t + 2) * kstep;
;             const char* a3 = a2 + kstep; const char* b3 = b2 + kstep;
;             if (last && has_next) S.a_ready(nxt);
;             if constexpr (SP2) {
;             PG8_LDB(B0, 0, 0); PG8_LDB(B1, 0, 1); PG8_SCHED; PG8_LDA(At, 0, 0); PG8_STAGE(PG8_SA(1, 1), a1 + hstep, voffA);
;             PG8_WAIT_V(8); PG8_WAIT_L(0); PG8_BAR; PG8_MMA(0, 0, At, B0); PG8_MMA(0, 1, At, B1); PG8_BAR; PG8_SCHED;
;             PG8_LDA(At, 0, 1); PG8_STAGE(PG8_SB(0, 0), b2, voffB); PG8_STAGE(PG8_SB(0, 1), b2 + hstep, voffB); PG8_STAGE(PG8_SA(0, 0), a2, voffA);
;             PG8_WAIT_V(8); PG8_WAIT_L(0); PG8_BAR; PG8_MMA(1, 0, At, B0); PG8_MMA(1, 1, At, B1); PG8_BAR; PG8_SCHED;
;             PG8_LDB(B0, 1, 0); PG8_LDB(B1, 1, 1); PG8_SCHED; PG8_LDA(At, 1, 0); PG8_STAGE(PG8_SA(0, 1), a2 + hstep, voffA);
;             PG8_WAIT_V(8); PG8_WAIT_L(0); PG8_BAR; PG8_MMA(0, 0, At, B0); PG8_MMA(0, 1, At, B1); PG8_BAR; PG8_SCHED;
;             PG8_LDA(At, 1, 1); PG8_STAGE(PG8_SB(1, 0), b3, voffB); PG8_STAGE(PG8_SB(1, 1), b3 + hstep, voffB); PG8_STAGE(PG8_SA(1, 0), a3, voffA);
;             PG8_WAIT_V(8); PG8_WAIT_L(0); PG8_BAR; PG8_MMA(1, 0, At, B0); PG8_MMA(1, 1, At, B1); PG8_BAR; PG8_SCHED;
.LBB0_1199:
	s_add_u32 s36, s28, s30
	s_addc_u32 s37, s29, s31
	s_add_u32 s36, s36, 0x100
	s_addc_u32 s37, s37, 0
	s_add_u32 s44, s59, s30
	s_addc_u32 s45, s60, s31
	s_add_i32 s62, 0, 0x10000
	v_add_u32_e32 v146, s62, v161
	ds_read_b128 v[130:133], v146
	ds_read_b128 v[134:137], v146 offset:1024
	ds_read_b128 v[166:169], v146 offset:2048
	ds_read_b128 v[170:173], v146 offset:3072
	v_add_u32_e32 v146, s54, v161
	ds_read_b128 v[174:177], v146
	ds_read_b128 v[178:181], v146 offset:1024
	ds_read_b128 v[182:185], v146 offset:2048
	ds_read_b128 v[186:189], v146 offset:3072
	s_cmpk_eq_i32 s30, 0x1f00
	s_cselect_b32 s39, s21, s37
	s_cselect_b32 s38, s55, s36
	s_cselect_b32 s37, s56, s45
	s_cselect_b32 s36, s57, s44
	v_lshl_add_u64 v[222:223], v[156:157], 0, s[30:31]
	s_add_i32 m0, s27, 0xc000
	ds_read_b128 v[190:193], v164
	ds_read_b128 v[194:197], v164 offset:1024
	ds_read_b128 v[198:201], v164 offset:2048
	ds_read_b128 v[202:205], v164 offset:3072
	ds_read_b128 v[206:209], v164 offset:4096
	ds_read_b128 v[210:213], v164 offset:5120
	ds_read_b128 v[214:217], v164 offset:6144
	ds_read_b128 v[218:221], v164 offset:7168
	global_load_lds_dwordx4 v[222:223], off
	v_lshl_add_u64 v[222:223], v[158:159], 0, s[30:31]
	s_add_i32 m0, s27, 0xe000
	s_nop 0
	global_load_lds_dwordx4 v[222:223], off
	s_waitcnt vmcnt(8)
	s_waitcnt lgkmcnt(0)
	s_setprio 1
	s_barrier
	v_mfma_f32_16x16x32_bf16 v[126:129], v[130:133], v[190:193], v[126:129]
	v_mfma_f32_16x16x32_bf16 v[122:125], v[166:169], v[190:193], v[122:125]
	v_mfma_f32_16x16x32_bf16 v[110:113], v[130:133], v[198:201], v[110:113]
	v_mfma_f32_16x16x32_bf16 v[106:109], v[166:169], v[198:201], v[106:109]
	v_mfma_f32_16x16x32_bf16 v[94:97], v[130:133], v[206:209], v[94:97]
	v_mfma_f32_16x16x32_bf16 v[90:93], v[166:169], v[206:209], v[90:93]
	v_mfma_f32_16x16x32_bf16 v[78:81], v[130:133], v[214:217], v[78:81]
	v_mfma_f32_16x16x32_bf16 v[74:77], v[166:169], v[214:217], v[74:77]
	v_mfma_f32_16x16x32_bf16 v[126:129], v[134:137], v[194:197], v[126:129]
	v_mfma_f32_16x16x32_bf16 v[122:125], v[170:173], v[194:197], v[122:125]
	v_mfma_f32_16x16x32_bf16 v[110:113], v[134:137], v[202:205], v[110:113]
	v_mfma_f32_16x16x32_bf16 v[106:109], v[170:173], v[202:205], v[106:109]
	v_mfma_f32_16x16x32_bf16 v[94:97], v[134:137], v[210:213], v[94:97]
	v_mfma_f32_16x16x32_bf16 v[90:93], v[170:173], v[210:213], v[90:93]
	v_mfma_f32_16x16x32_bf16 v[78:81], v[134:137], v[218:221], v[78:81]
	v_mfma_f32_16x16x32_bf16 v[74:77], v[170:173], v[218:221], v[74:77]
	s_setprio 0
	s_setprio 1
	v_mfma_f32_16x16x32_bf16 v[118:121], v[174:177], v[190:193], v[118:121]
	v_mfma_f32_16x16x32_bf16 v[114:117], v[182:185], v[190:193], v[114:117]
	v_mfma_f32_16x16x32_bf16 v[102:105], v[174:177], v[198:201], v[102:105]
	v_mfma_f32_16x16x32_bf16 v[98:101], v[182:185], v[198:201], v[98:101]
	v_mfma_f32_16x16x32_bf16 v[86:89], v[174:177], v[206:209], v[86:89]
	v_mfma_f32_16x16x32_bf16 v[82:85], v[182:185], v[206:209], v[82:85]
	v_mfma_f32_16x16x32_bf16 v[70:73], v[174:177], v[214:217], v[70:73]
	v_mfma_f32_16x16x32_bf16 v[66:69], v[182:185], v[214:217], v[66:69]
	v_mfma_f32_16x16x32_bf16 v[118:121], v[178:181], v[194:197], v[118:121]
	v_mfma_f32_16x16x32_bf16 v[114:117], v[186:189], v[194:197], v[114:117]
	v_mfma_f32_16x16x32_bf16 v[102:105], v[178:181], v[202:205], v[102:105]
	v_mfma_f32_16x16x32_bf16 v[98:101], v[186:189], v[202:205], v[98:101]
	v_mfma_f32_16x16x32_bf16 v[86:89], v[178:181], v[210:213], v[86:89]
	v_mfma_f32_16x16x32_bf16 v[82:85], v[186:189], v[210:213], v[82:85]
	v_mfma_f32_16x16x32_bf16 v[70:73], v[178:181], v[218:221], v[70:73]
	v_mfma_f32_16x16x32_bf16 v[66:69], v[186:189], v[218:221], v[66:69]
	s_setprio 0
	s_barrier
	s_add_i32 s44, s62, s42
	v_lshl_add_u64 v[222:223], s[36:37], 0, v[142:143]
	s_mov_b32 m0, s44
	ds_read_b128 v[190:193], v164 offset:16384
	ds_read_b128 v[194:197], v164 offset:17408
	ds_read_b128 v[198:201], v164 offset:18432
	ds_read_b128 v[202:205], v164 offset:19456
	ds_read_b128 v[206:209], v164 offset:20480
	ds_read_b128 v[210:213], v164 offset:21504
	ds_read_b128 v[214:217], v164 offset:22528
	ds_read_b128 v[218:221], v164 offset:23552
	global_load_lds_dwordx4 v[222:223], off
	s_add_i32 m0, s44, 0x2000
	s_add_u32 s44, s36, 0x100000
	v_lshl_add_u64 v[224:225], s[36:37], 0, v[138:139]
	s_addc_u32 s45, s37, 0
	s_add_i32 s62, s54, s42
	global_load_lds_dwordx4 v[224:225], off
	v_lshl_add_u64 v[226:227], s[44:45], 0, v[142:143]
	s_mov_b32 m0, s62
	v_lshl_add_u64 v[228:229], s[38:39], 0, v[140:141]
	global_load_lds_dwordx4 v[226:227], off
	v_lshl_add_u64 v[226:227], s[44:45], 0, v[138:139]
	s_add_i32 m0, s62, 0x2000
	s_nop 0
	global_load_lds_dwordx4 v[226:227], off
	v_lshl_add_u64 v[226:227], s[38:39], 0, v[144:145]
	s_mov_b32 m0, s27
	s_nop 0
	global_load_lds_dwordx4 v[226:227], off
	s_mov_b32 m0, s46
	s_nop 0
	global_load_lds_dwordx4 v[228:229], off
	s_waitcnt vmcnt(8)
	s_waitcnt lgkmcnt(0)
	s_setprio 1
	s_barrier
; #define PG8_STAGE(bufoff, gbase, voff) do { _Pragma("unroll") for (int _i = 0; _i < 2; ++_i) \
;         __builtin_amdgcn_global_load_lds((const unsigned*)((const char*)(gbase) + (voff)[_i]), (PG8_LAS unsigned*)(lds + (bufoff) + ldsw + _i * 8192), 16, 0, 0); } while (0)
; #define PG8_LDA(dst, b, h) do { _Pragma("unroll") for (int m = 0; m < 4; ++m) _Pragma("unroll") for (int k = 0; k < 2; ++k) dst[m][k] = *(const PG8_LAS bf16x8*)(lds + PG8_SA(b, h) + aoff + m * 2048 + k * 1024); } while (0)
; #define PG8_LDB(dst, b, h) do { _Pragma("unroll") for (int n = 0; n < 2; ++n) _Pragma("unroll") for (int k = 0; k < 2; ++k) dst[n][k] = *(const PG8_LAS bf16x8*)(lds + PG8_SB(b, h) + boff + n * 2048 + k * 1024); } while (0)
; #define PG8_MMA(ai, bj, At, Bt) do { __builtin_amdgcn_s_setprio(1); _Pragma("unroll") for (int m = 0; m < 4; ++m) _Pragma("unroll") for (int n = 0; n < 2; ++n) _Pragma("unroll") for (int k = 0; k < 2; ++k) \
;         acc[ai][bj][m][n] = __builtin_amdgcn_mfma_f32_16x16x32_bf16(Bt[n][k], At[m][k], acc[ai][bj][m][n], 0, 0, 0); __builtin_amdgcn_s_setprio(0); } while (0)
; #define PG8_WAIT_V(n) asm volatile("s_waitcnt vmcnt(" #n ")" ::: "memory")
; template <class Epi, class Sched, bool ALIGN_EPI = false, bool SP2 = false>
; __device__ __forceinline__ void gemm_phase(PG8_LAS unsigned char* lds, const Gemm g, const Sched& S, const Epi& E) {
;     ...
;             PG8_LDB(B0, 0, 0); PG8_LDB(B1, 0, 1); PG8_SCHED; PG8_LDA(At, 0, 0); PG8_STAGE(PG8_SA(1, 1), a1 + hstep, voffA);
;             PG8_WAIT_V(8); PG8_WAIT_L(0); PG8_BAR; PG8_MMA(0, 0, At, B0); PG8_MMA(0, 1, At, B1); PG8_BAR; PG8_SCHED;
;             PG8_LDA(At, 0, 1); PG8_STAGE(PG8_SB(0, 0), b2, voffB); PG8_STAGE(PG8_SB(0, 1), b2 + hstep, voffB); PG8_STAGE(PG8_SA(0, 0), a2, voffA);
;             PG8_WAIT_V(8); PG8_WAIT_L(0); PG8_BAR; PG8_MMA(1, 0, At, B0); PG8_MMA(1, 1, At, B1); PG8_BAR; PG8_SCHED;
;             PG8_LDB(B0, 1, 0); PG8_LDB(B1, 1, 1); PG8_SCHED; PG8_LDA(At, 1, 0); PG8_STAGE(PG8_SA(0, 1), a2 + hstep, voffA);
;             PG8_WAIT_V(8); PG8_WAIT_L(0); PG8_BAR; PG8_MMA(0, 0, At, B0); PG8_MMA(0, 1, At, B1); PG8_BAR; PG8_SCHED;
;             PG8_LDA(At, 1, 1); PG8_STAGE(PG8_SB(1, 0), b3, voffB); PG8_STAGE(PG8_SB(1, 1), b3 + hstep, voffB); PG8_STAGE(PG8_SA(1, 0), a3, voffA);
;             PG8_WAIT_V(8); PG8_WAIT_L(0); PG8_BAR; PG8_MMA(1, 0, At, B0); PG8_MMA(1, 1, At, B1); PG8_BAR; PG8_SCHED;
	v_mfma_f32_16x16x32_bf16 v[62:65], v[130:133], v[190:193], v[62:65]
	v_mfma_f32_16x16x32_bf16 v[58:61], v[166:169], v[190:193], v[58:61]
	v_mfma_f32_16x16x32_bf16 v[46:49], v[130:133], v[198:201], v[46:49]
	v_mfma_f32_16x16x32_bf16 v[42:45], v[166:169], v[198:201], v[42:45]
	v_mfma_f32_16x16x32_bf16 v[30:33], v[130:133], v[206:209], v[30:33]
	v_mfma_f32_16x16x32_bf16 v[26:29], v[166:169], v[206:209], v[26:29]
	v_mfma_f32_16x16x32_bf16 v[14:17], v[130:133], v[214:217], v[14:17]
	v_mfma_f32_16x16x32_bf16 v[10:13], v[166:169], v[214:217], v[10:13]
	v_mfma_f32_16x16x32_bf16 v[62:65], v[134:137], v[194:197], v[62:65]
	v_mfma_f32_16x16x32_bf16 v[58:61], v[170:173], v[194:197], v[58:61]
	v_mfma_f32_16x16x32_bf16 v[46:49], v[134:137], v[202:205], v[46:49]
	v_mfma_f32_16x16x32_bf16 v[42:45], v[170:173], v[202:205], v[42:45]
	v_mfma_f32_16x16x32_bf16 v[30:33], v[134:137], v[210:213], v[30:33]
	v_mfma_f32_16x16x32_bf16 v[26:29], v[170:173], v[210:213], v[26:29]
	v_mfma_f32_16x16x32_bf16 v[14:17], v[134:137], v[218:221], v[14:17]
	v_mfma_f32_16x16x32_bf16 v[10:13], v[170:173], v[218:221], v[10:13]
	s_setprio 0
	s_setprio 1
	v_mfma_f32_16x16x32_bf16 v[54:57], v[174:177], v[190:193], v[54:57]
	v_mfma_f32_16x16x32_bf16 v[50:53], v[182:185], v[190:193], v[50:53]
	v_mfma_f32_16x16x32_bf16 v[38:41], v[174:177], v[198:201], v[38:41]
	v_mfma_f32_16x16x32_bf16 v[34:37], v[182:185], v[198:201], v[34:37]
	v_mfma_f32_16x16x32_bf16 v[22:25], v[174:177], v[206:209], v[22:25]
	v_mfma_f32_16x16x32_bf16 v[18:21], v[182:185], v[206:209], v[18:21]
	v_mfma_f32_16x16x32_bf16 v[6:9], v[174:177], v[214:217], v[6:9]
	v_mfma_f32_16x16x32_bf16 v[2:5], v[182:185], v[214:217], v[2:5]
	v_mfma_f32_16x16x32_bf16 v[54:57], v[178:181], v[194:197], v[54:57]
	v_mfma_f32_16x16x32_bf16 v[50:53], v[186:189], v[194:197], v[50:53]
	v_mfma_f32_16x16x32_bf16 v[38:41], v[178:181], v[202:205], v[38:41]
	v_mfma_f32_16x16x32_bf16 v[34:37], v[186:189], v[202:205], v[34:37]
	v_mfma_f32_16x16x32_bf16 v[22:25], v[178:181], v[210:213], v[22:25]
	v_mfma_f32_16x16x32_bf16 v[18:21], v[186:189], v[210:213], v[18:21]
	v_mfma_f32_16x16x32_bf16 v[6:9], v[178:181], v[218:221], v[6:9]
	v_mfma_f32_16x16x32_bf16 v[2:5], v[186:189], v[218:221], v[2:5]
	s_setprio 0
	s_barrier
	s_add_i32 s44, 0, 0x18000
	v_add_u32_e32 v146, s44, v161
	s_add_i32 s45, 0, 0x1c000
	ds_read_b128 v[130:133], v146
	ds_read_b128 v[134:137], v146 offset:1024
	ds_read_b128 v[166:169], v146 offset:2048
	ds_read_b128 v[170:173], v146 offset:3072
	v_add_u32_e32 v146, s45, v161
	ds_read_b128 v[174:177], v146
	ds_read_b128 v[178:181], v146 offset:1024
	ds_read_b128 v[182:185], v146 offset:2048
	ds_read_b128 v[186:189], v146 offset:3072
	s_add_u32 s38, s38, 0x100000
	s_addc_u32 s39, s39, 0
	s_mov_b32 m0, s47
	v_lshl_add_u64 v[230:231], s[38:39], 0, v[144:145]
	ds_read_b128 v[190:193], v164 offset:32768
	ds_read_b128 v[194:197], v164 offset:33792
	ds_read_b128 v[198:201], v164 offset:34816
	ds_read_b128 v[202:205], v164 offset:35840
	ds_read_b128 v[206:209], v164 offset:36864
	ds_read_b128 v[210:213], v164 offset:37888
	ds_read_b128 v[214:217], v164 offset:38912
	ds_read_b128 v[218:221], v164 offset:39936
	global_load_lds_dwordx4 v[230:231], off
	v_lshl_add_u64 v[230:231], s[38:39], 0, v[140:141]
	s_mov_b32 m0, s48
	s_nop 0
	global_load_lds_dwordx4 v[230:231], off
	s_waitcnt vmcnt(8)
	s_waitcnt lgkmcnt(0)
	s_setprio 1
	s_barrier
	v_mfma_f32_16x16x32_bf16 v[126:129], v[130:133], v[190:193], v[126:129]
	v_mfma_f32_16x16x32_bf16 v[122:125], v[166:169], v[190:193], v[122:125]
	v_mfma_f32_16x16x32_bf16 v[110:113], v[130:133], v[198:201], v[110:113]
	v_mfma_f32_16x16x32_bf16 v[106:109], v[166:169], v[198:201], v[106:109]
	v_mfma_f32_16x16x32_bf16 v[94:97], v[130:133], v[206:209], v[94:97]
	v_mfma_f32_16x16x32_bf16 v[90:93], v[166:169], v[206:209], v[90:93]
	v_mfma_f32_16x16x32_bf16 v[78:81], v[130:133], v[214:217], v[78:81]
	v_mfma_f32_16x16x32_bf16 v[74:77], v[166:169], v[214:217], v[74:77]
	v_mfma_f32_16x16x32_bf16 v[126:129], v[134:137], v[194:197], v[126:129]
	v_mfma_f32_16x16x32_bf16 v[122:125], v[170:173], v[194:197], v[122:125]
	v_mfma_f32_16x16x32_bf16 v[110:113], v[134:137], v[202:205], v[110:113]
	v_mfma_f32_16x16x32_bf16 v[106:109], v[170:173], v[202:205], v[106:109]
	v_mfma_f32_16x16x32_bf16 v[94:97], v[134:137], v[210:213], v[94:97]
	v_mfma_f32_16x16x32_bf16 v[90:93], v[170:173], v[210:213], v[90:93]
	v_mfma_f32_16x16x32_bf16 v[78:81], v[134:137], v[218:221], v[78:81]
	v_mfma_f32_16x16x32_bf16 v[74:77], v[170:173], v[218:221], v[74:77]
	s_setprio 0
	s_setprio 1
	v_mfma_f32_16x16x32_bf16 v[118:121], v[174:177], v[190:193], v[118:121]
	v_mfma_f32_16x16x32_bf16 v[114:117], v[182:185], v[190:193], v[114:117]
	v_mfma_f32_16x16x32_bf16 v[102:105], v[174:177], v[198:201], v[102:105]
	v_mfma_f32_16x16x32_bf16 v[98:101], v[182:185], v[198:201], v[98:101]
	v_mfma_f32_16x16x32_bf16 v[86:89], v[174:177], v[206:209], v[86:89]
	v_mfma_f32_16x16x32_bf16 v[82:85], v[182:185], v[206:209], v[82:85]
	v_mfma_f32_16x16x32_bf16 v[70:73], v[174:177], v[214:217], v[70:73]
	v_mfma_f32_16x16x32_bf16 v[66:69], v[182:185], v[214:217], v[66:69]
	v_mfma_f32_16x16x32_bf16 v[118:121], v[178:181], v[194:197], v[118:121]
	v_mfma_f32_16x16x32_bf16 v[114:117], v[186:189], v[194:197], v[114:117]
	v_mfma_f32_16x16x32_bf16 v[102:105], v[178:181], v[202:205], v[102:105]
	v_mfma_f32_16x16x32_bf16 v[98:101], v[186:189], v[202:205], v[98:101]
	v_mfma_f32_16x16x32_bf16 v[86:89], v[178:181], v[210:213], v[86:89]
	v_mfma_f32_16x16x32_bf16 v[82:85], v[186:189], v[210:213], v[82:85]
	v_mfma_f32_16x16x32_bf16 v[70:73], v[178:181], v[218:221], v[70:73]
	v_mfma_f32_16x16x32_bf16 v[66:69], v[186:189], v[218:221], v[66:69]
	s_setprio 0
	s_barrier
; #define PG8_STAGE(bufoff, gbase, voff) do { _Pragma("unroll") for (int _i = 0; _i < 2; ++_i) \
;         __builtin_amdgcn_global_load_lds((const unsigned*)((const char*)(gbase) + (voff)[_i]), (PG8_LAS unsigned*)(lds + (bufoff) + ldsw + _i * 8192), 16, 0, 0); } while (0)
; #define PG8_LDA(dst, b, h) do { _Pragma("unroll") for (int m = 0; m < 4; ++m) _Pragma("unroll") for (int k = 0; k < 2; ++k) dst[m][k] = *(const PG8_LAS bf16x8*)(lds + PG8_SA(b, h) + aoff + m * 2048 + k * 1024); } while (0)
; #define PG8_LDB(dst, b, h) do { _Pragma("unroll") for (int n = 0; n < 2; ++n) _Pragma("unroll") for (int k = 0; k < 2; ++k) dst[n][k] = *(const PG8_LAS bf16x8*)(lds + PG8_SB(b, h) + boff + n * 2048 + k * 1024); } while (0)
; #define PG8_MMA(ai, bj, At, Bt) do { __builtin_amdgcn_s_setprio(1); _Pragma("unroll") for (int m = 0; m < 4; ++m) _Pragma("unroll") for (int n = 0; n < 2; ++n) _Pragma("unroll") for (int k = 0; k < 2; ++k) \
;         acc[ai][bj][m][n] = __builtin_amdgcn_mfma_f32_16x16x32_bf16(Bt[n][k], At[m][k], acc[ai][bj][m][n], 0, 0, 0); __builtin_amdgcn_s_setprio(0); } while (0)
; #define PG8_WAIT_V(n) asm volatile("s_waitcnt vmcnt(" #n ")" ::: "memory")
; #define PG8_WAIT_L(n) asm volatile("s_waitcnt lgkmcnt(" #n ")" ::: "memory")
; #define PG8_BAR __builtin_amdgcn_s_barrier()
; #define PG8_SCHED __builtin_amdgcn_sched_barrier(0)
; template <class Epi, class Sched, bool ALIGN_EPI = false, bool SP2 = false>
; __device__ __forceinline__ void gemm_phase(PG8_LAS unsigned char* lds, const Gemm g, const Sched& S, const Epi& E) {
;     ...
;             PG8_LDB(B0, 1, 0); PG8_LDB(B1, 1, 1); PG8_SCHED; PG8_LDA(At, 1, 0); PG8_STAGE(PG8_SA(0, 1), a2 + hstep, voffA);
;             PG8_WAIT_V(8); PG8_WAIT_L(0); PG8_BAR; PG8_MMA(0, 0, At, B0); PG8_MMA(0, 1, At, B1); PG8_BAR; PG8_SCHED;
;             PG8_LDA(At, 1, 1); PG8_STAGE(PG8_SB(1, 0), b3, voffB); PG8_STAGE(PG8_SB(1, 1), b3 + hstep, voffB); PG8_STAGE(PG8_SA(1, 0), a3, voffA);
;             PG8_WAIT_V(8); PG8_WAIT_L(0); PG8_BAR; PG8_MMA(1, 0, At, B0); PG8_MMA(1, 1, At, B1); PG8_BAR; PG8_SCHED;
	s_add_i32 s38, s44, s42
	v_lshl_add_u64 v[222:223], v[222:223], 0, s[14:15]
	s_mov_b32 m0, s38
	ds_read_b128 v[190:193], v164 offset:49152
	ds_read_b128 v[194:197], v164 offset:50176
	ds_read_b128 v[198:201], v164 offset:51200
	ds_read_b128 v[202:205], v164 offset:52224
	ds_read_b128 v[206:209], v164 offset:53248
	ds_read_b128 v[210:213], v164 offset:54272
	ds_read_b128 v[214:217], v164 offset:55296
	ds_read_b128 v[218:221], v164 offset:56320
	global_load_lds_dwordx4 v[222:223], off
	s_add_i32 m0, s38, 0x2000
	s_add_u32 s36, s36, 0x100080
	v_lshl_add_u64 v[222:223], v[224:225], 0, s[14:15]
	s_addc_u32 s37, s37, 0
	s_add_i32 s38, s45, s42
	global_load_lds_dwordx4 v[222:223], off
	v_lshl_add_u64 v[222:223], s[36:37], 0, v[142:143]
	s_mov_b32 m0, s38
	s_nop 0
	global_load_lds_dwordx4 v[222:223], off
	v_lshl_add_u64 v[222:223], s[36:37], 0, v[138:139]
	s_add_i32 m0, s38, 0x2000
	s_nop 0
	global_load_lds_dwordx4 v[222:223], off
	v_lshl_add_u64 v[222:223], v[226:227], 0, s[14:15]
	s_mov_b32 m0, s51
	s_nop 0
	global_load_lds_dwordx4 v[222:223], off
	v_lshl_add_u64 v[222:223], v[228:229], 0, s[14:15]
	s_mov_b32 m0, s52
	s_nop 0
	global_load_lds_dwordx4 v[222:223], off
	s_waitcnt vmcnt(8)
	s_waitcnt lgkmcnt(0)
	s_setprio 1
	s_barrier
	v_mfma_f32_16x16x32_bf16 v[62:65], v[130:133], v[190:193], v[62:65]
	v_mfma_f32_16x16x32_bf16 v[58:61], v[166:169], v[190:193], v[58:61]
	v_mfma_f32_16x16x32_bf16 v[46:49], v[130:133], v[198:201], v[46:49]
	v_mfma_f32_16x16x32_bf16 v[42:45], v[166:169], v[198:201], v[42:45]
	v_mfma_f32_16x16x32_bf16 v[30:33], v[130:133], v[206:209], v[30:33]
	v_mfma_f32_16x16x32_bf16 v[26:29], v[166:169], v[206:209], v[26:29]
	v_mfma_f32_16x16x32_bf16 v[14:17], v[130:133], v[214:217], v[14:17]
	v_mfma_f32_16x16x32_bf16 v[10:13], v[166:169], v[214:217], v[10:13]
	v_mfma_f32_16x16x32_bf16 v[62:65], v[134:137], v[194:197], v[62:65]
	v_mfma_f32_16x16x32_bf16 v[58:61], v[170:173], v[194:197], v[58:61]
	v_mfma_f32_16x16x32_bf16 v[46:49], v[134:137], v[202:205], v[46:49]
	v_mfma_f32_16x16x32_bf16 v[42:45], v[170:173], v[202:205], v[42:45]
	v_mfma_f32_16x16x32_bf16 v[30:33], v[134:137], v[210:213], v[30:33]
	v_mfma_f32_16x16x32_bf16 v[26:29], v[170:173], v[210:213], v[26:29]
	v_mfma_f32_16x16x32_bf16 v[14:17], v[134:137], v[218:221], v[14:17]
	v_mfma_f32_16x16x32_bf16 v[10:13], v[170:173], v[218:221], v[10:13]
	s_setprio 0
	s_setprio 1
	v_mfma_f32_16x16x32_bf16 v[54:57], v[174:177], v[190:193], v[54:57]
	v_mfma_f32_16x16x32_bf16 v[50:53], v[182:185], v[190:193], v[50:53]
	v_mfma_f32_16x16x32_bf16 v[38:41], v[174:177], v[198:201], v[38:41]
	v_mfma_f32_16x16x32_bf16 v[34:37], v[182:185], v[198:201], v[34:37]
	v_mfma_f32_16x16x32_bf16 v[22:25], v[174:177], v[206:209], v[22:25]
	v_mfma_f32_16x16x32_bf16 v[18:21], v[182:185], v[206:209], v[18:21]
	v_mfma_f32_16x16x32_bf16 v[6:9], v[174:177], v[214:217], v[6:9]
	v_mfma_f32_16x16x32_bf16 v[2:5], v[182:185], v[214:217], v[2:5]
	v_mfma_f32_16x16x32_bf16 v[54:57], v[178:181], v[194:197], v[54:57]
	v_mfma_f32_16x16x32_bf16 v[50:53], v[186:189], v[194:197], v[50:53]
	v_mfma_f32_16x16x32_bf16 v[38:41], v[178:181], v[202:205], v[38:41]
	v_mfma_f32_16x16x32_bf16 v[34:37], v[186:189], v[202:205], v[34:37]
	v_mfma_f32_16x16x32_bf16 v[22:25], v[178:181], v[210:213], v[22:25]
	v_mfma_f32_16x16x32_bf16 v[18:21], v[186:189], v[210:213], v[18:21]
	v_mfma_f32_16x16x32_bf16 v[6:9], v[178:181], v[218:221], v[6:9]
	v_mfma_f32_16x16x32_bf16 v[2:5], v[186:189], v[218:221], v[2:5]
	s_setprio 0
	s_add_i32 s61, s61, 2
	s_add_u32 s30, s30, 0x100
	s_addc_u32 s31, s31, 0
	s_cmp_gt_u32 s61, 61
	s_barrier
	s_cbranch_scc1 .LBB0_1202

; #define PG8_STAGE(bufoff, gbase, voff) do { _Pragma("unroll") for (int _i = 0; _i < 2; ++_i) \
;         __builtin_amdgcn_global_load_lds((const unsigned*)((const char*)(gbase) + (voff)[_i]), (PG8_LAS unsigned*)(lds + (bufoff) + ldsw + _i * 8192), 16, 0, 0); } while (0)
; #define PG8_LDA(dst, b, h) do { _Pragma("unroll") for (int m = 0; m < 4; ++m) _Pragma("unroll") for (int k = 0; k < 2; ++k) dst[m][k] = *(const PG8_LAS bf16x8*)(lds + PG8_SA(b, h) + aoff + m * 2048 + k * 1024); } while (0)
; #define PG8_WAIT_V(n) asm volatile("s_waitcnt vmcnt(" #n ")" ::: "memory")
; #define PG8_BAR __builtin_amdgcn_s_barrier()
; template <class Epi, class Sched, bool ALIGN_EPI = false, bool SP2 = false>
; __device__ __forceinline__ void gemm_phase(PG8_LAS unsigned char* lds, const Gemm g, const Sched& S, const Epi& E) {
;     ...
;         for (int t = 0; t < nt; t += 2) {
;             if constexpr (Epi::MIDHOOK) { if (t == (nt >> 1)) E.mid(acc, cur, wr, wc, fr, fq); }
;             const bool last = (t == nt - 2);
;             const char* a1 = cA + (size_t)(t + 1) * kstep;
;             const char* a2 = last ? nA : cA + (size_t)(t + 2) * kstep; const char* b2 = last ? nB : cB + (size_t)(t + 2) * kstep;
;             const char* a3 = a2 + kstep; const char* b3 = b2 + kstep;
;             if (last && has_next) S.a_ready(nxt);
;             if constexpr (SP2) {
;             PG8_LDB(B0, 0, 0); PG8_LDB(B1, 0, 1); PG8_SCHED; PG8_LDA(At, 0, 0); PG8_STAGE(PG8_SA(1, 1), a1 + hstep, voffA);
;             PG8_WAIT_V(8); PG8_WAIT_L(0); PG8_BAR; PG8_MMA(0, 0, At, B0); PG8_MMA(0, 1, At, B1); PG8_BAR; PG8_SCHED;
;             PG8_LDA(At, 0, 1); PG8_STAGE(PG8_SB(0, 0), b2, voffB); PG8_STAGE(PG8_SB(0, 1), b2 + hstep, voffB); PG8_STAGE(PG8_SA(0, 0), a2, voffA);
;             PG8_WAIT_V(8); PG8_WAIT_L(0); PG8_BAR; PG8_MMA(1, 0, At, B0); PG8_MMA(1, 1, At, B1); PG8_BAR; PG8_SCHED;
;             PG8_LDB(B0, 1, 0); PG8_LDB(B1, 1, 1); PG8_SCHED; PG8_LDA(At, 1, 0); PG8_STAGE(PG8_SA(0, 1), a2 + hstep, voffA);
;             PG8_WAIT_V(8); PG8_WAIT_L(0); PG8_BAR; PG8_MMA(0, 0, At, B0); PG8_MMA(0, 1, At, B1); PG8_BAR; PG8_SCHED;
;             PG8_LDA(At, 1, 1); PG8_STAGE(PG8_SB(1, 0), b3, voffB); PG8_STAGE(PG8_SB(1, 1), b3 + hstep, voffB); PG8_STAGE(PG8_SA(1, 0), a3, voffA);
;             PG8_WAIT_V(8); PG8_WAIT_L(0); PG8_BAR; PG8_MMA(1, 0, At, B0); PG8_MMA(1, 1, At, B1); PG8_BAR; PG8_SCHED;
.LBB0_1219:
	ds_read_b128 v[138:141], v147
	ds_read_b128 v[150:153], v147 offset:1024
	ds_read_b128 v[154:157], v147 offset:2048
	ds_read_b128 v[158:161], v147 offset:3072
	ds_read_b128 v[162:165], v148
	ds_read_b128 v[166:169], v148 offset:1024
	ds_read_b128 v[170:173], v148 offset:2048
	ds_read_b128 v[174:177], v148 offset:3072
	s_add_u32 s36, s30, 0xfff00080
	s_addc_u32 s37, s31, -1
	s_cmp_eq_u32 s61, 4
	s_cselect_b32 s39, s11, s37
	s_cselect_b32 s38, s21, s36
	s_cselect_b32 s37, s23, s60
	s_cselect_b32 s36, s58, s59
	v_lshl_add_u64 v[142:143], s[30:31], 0, v[134:135]
	s_add_i32 m0, s45, 0xc000
	ds_read_b128 v[178:181], v149
	ds_read_b128 v[182:185], v149 offset:1024
	ds_read_b128 v[186:189], v149 offset:2048
	ds_read_b128 v[190:193], v149 offset:3072
	ds_read_b128 v[194:197], v149 offset:4096
	ds_read_b128 v[198:201], v149 offset:5120
	ds_read_b128 v[202:205], v149 offset:6144
	ds_read_b128 v[206:209], v149 offset:7168
	global_load_lds_dwordx4 v[142:143], off
	v_lshl_add_u64 v[142:143], s[30:31], 0, v[136:137]
	s_add_i32 m0, s45, 0xe000
	s_nop 0
	global_load_lds_dwordx4 v[142:143], off
	s_waitcnt vmcnt(8)
	s_waitcnt lgkmcnt(0)
	s_setprio 1
	s_barrier
	v_mfma_f32_16x16x32_bf16 v[126:129], v[138:141], v[178:181], v[126:129]
	v_mfma_f32_16x16x32_bf16 v[122:125], v[154:157], v[178:181], v[122:125]
	v_mfma_f32_16x16x32_bf16 v[110:113], v[138:141], v[186:189], v[110:113]
	v_mfma_f32_16x16x32_bf16 v[106:109], v[154:157], v[186:189], v[106:109]
	v_mfma_f32_16x16x32_bf16 v[94:97], v[138:141], v[194:197], v[94:97]
	v_mfma_f32_16x16x32_bf16 v[90:93], v[154:157], v[194:197], v[90:93]
	v_mfma_f32_16x16x32_bf16 v[78:81], v[138:141], v[202:205], v[78:81]
	v_mfma_f32_16x16x32_bf16 v[74:77], v[154:157], v[202:205], v[74:77]
	v_mfma_f32_16x16x32_bf16 v[126:129], v[150:153], v[182:185], v[126:129]
	v_mfma_f32_16x16x32_bf16 v[122:125], v[158:161], v[182:185], v[122:125]
	v_mfma_f32_16x16x32_bf16 v[110:113], v[150:153], v[190:193], v[110:113]
	v_mfma_f32_16x16x32_bf16 v[106:109], v[158:161], v[190:193], v[106:109]
	v_mfma_f32_16x16x32_bf16 v[94:97], v[150:153], v[198:201], v[94:97]
	v_mfma_f32_16x16x32_bf16 v[90:93], v[158:161], v[198:201], v[90:93]
	v_mfma_f32_16x16x32_bf16 v[78:81], v[150:153], v[206:209], v[78:81]
	v_mfma_f32_16x16x32_bf16 v[74:77], v[158:161], v[206:209], v[74:77]
	s_setprio 0
	s_setprio 1
	v_mfma_f32_16x16x32_bf16 v[118:121], v[162:165], v[178:181], v[118:121]
	v_mfma_f32_16x16x32_bf16 v[114:117], v[170:173], v[178:181], v[114:117]
	v_mfma_f32_16x16x32_bf16 v[102:105], v[162:165], v[186:189], v[102:105]
	v_mfma_f32_16x16x32_bf16 v[98:101], v[170:173], v[186:189], v[98:101]
	v_mfma_f32_16x16x32_bf16 v[86:89], v[162:165], v[194:197], v[86:89]
	v_mfma_f32_16x16x32_bf16 v[82:85], v[170:173], v[194:197], v[82:85]
	v_mfma_f32_16x16x32_bf16 v[70:73], v[162:165], v[202:205], v[70:73]
	v_mfma_f32_16x16x32_bf16 v[66:69], v[170:173], v[202:205], v[66:69]
	v_mfma_f32_16x16x32_bf16 v[118:121], v[166:169], v[182:185], v[118:121]
	v_mfma_f32_16x16x32_bf16 v[114:117], v[174:177], v[182:185], v[114:117]
	v_mfma_f32_16x16x32_bf16 v[102:105], v[166:169], v[190:193], v[102:105]
	v_mfma_f32_16x16x32_bf16 v[98:101], v[174:177], v[190:193], v[98:101]
	v_mfma_f32_16x16x32_bf16 v[86:89], v[166:169], v[198:201], v[86:89]
	v_mfma_f32_16x16x32_bf16 v[82:85], v[174:177], v[198:201], v[82:85]
	v_mfma_f32_16x16x32_bf16 v[70:73], v[166:169], v[206:209], v[70:73]
	v_mfma_f32_16x16x32_bf16 v[66:69], v[174:177], v[206:209], v[66:69]
	s_setprio 0
	s_barrier
	s_add_i32 s62, s54, s42
	v_lshl_add_u64 v[142:143], s[36:37], 0, v[132:133]
	s_mov_b32 m0, s62
	ds_read_b128 v[178:181], v149 offset:16384
	ds_read_b128 v[182:185], v149 offset:17408
	ds_read_b128 v[186:189], v149 offset:18432
	ds_read_b128 v[190:193], v149 offset:19456
	ds_read_b128 v[194:197], v149 offset:20480
	ds_read_b128 v[198:201], v149 offset:21504
	ds_read_b128 v[202:205], v149 offset:22528
	ds_read_b128 v[206:209], v149 offset:23552
	global_load_lds_dwordx4 v[142:143], off
	s_add_i32 m0, s62, 0x2000
	s_add_u32 s62, s36, 0x100000
	v_lshl_add_u64 v[210:211], s[36:37], 0, v[130:131]
	s_addc_u32 s63, s37, 0
	s_add_i32 s64, s55, s42
	global_load_lds_dwordx4 v[210:211], off
	v_lshl_add_u64 v[212:213], s[62:63], 0, v[132:133]
	s_mov_b32 m0, s64
	v_lshl_add_u64 v[214:215], s[38:39], 0, v[130:131]
	global_load_lds_dwordx4 v[212:213], off
	v_lshl_add_u64 v[212:213], s[62:63], 0, v[130:131]
	s_add_i32 m0, s64, 0x2000
	s_nop 0
	global_load_lds_dwordx4 v[212:213], off
	v_lshl_add_u64 v[212:213], s[38:39], 0, v[132:133]
	s_mov_b32 m0, s45
	s_nop 0
	global_load_lds_dwordx4 v[212:213], off
	s_mov_b32 m0, s46
	s_nop 0
	global_load_lds_dwordx4 v[214:215], off
	s_waitcnt vmcnt(8)
	s_waitcnt lgkmcnt(0)
	s_setprio 1
	s_barrier
; #define PG8_STAGE(bufoff, gbase, voff) do { _Pragma("unroll") for (int _i = 0; _i < 2; ++_i) \
;         __builtin_amdgcn_global_load_lds((const unsigned*)((const char*)(gbase) + (voff)[_i]), (PG8_LAS unsigned*)(lds + (bufoff) + ldsw + _i * 8192), 16, 0, 0); } while (0)
; #define PG8_LDA(dst, b, h) do { _Pragma("unroll") for (int m = 0; m < 4; ++m) _Pragma("unroll") for (int k = 0; k < 2; ++k) dst[m][k] = *(const PG8_LAS bf16x8*)(lds + PG8_SA(b, h) + aoff + m * 2048 + k * 1024); } while (0)
; #define PG8_LDB(dst, b, h) do { _Pragma("unroll") for (int n = 0; n < 2; ++n) _Pragma("unroll") for (int k = 0; k < 2; ++k) dst[n][k] = *(const PG8_LAS bf16x8*)(lds + PG8_SB(b, h) + boff + n * 2048 + k * 1024); } while (0)
; #define PG8_MMA(ai, bj, At, Bt) do { __builtin_amdgcn_s_setprio(1); _Pragma("unroll") for (int m = 0; m < 4; ++m) _Pragma("unroll") for (int n = 0; n < 2; ++n) _Pragma("unroll") for (int k = 0; k < 2; ++k) \
;         acc[ai][bj][m][n] = __builtin_amdgcn_mfma_f32_16x16x32_bf16(Bt[n][k], At[m][k], acc[ai][bj][m][n], 0, 0, 0); __builtin_amdgcn_s_setprio(0); } while (0)
; #define PG8_WAIT_V(n) asm volatile("s_waitcnt vmcnt(" #n ")" ::: "memory")
; template <class Epi, class Sched, bool ALIGN_EPI = false, bool SP2 = false>
; __device__ __forceinline__ void gemm_phase(PG8_LAS unsigned char* lds, const Gemm g, const Sched& S, const Epi& E) {
;     ...
;             PG8_LDB(B0, 0, 0); PG8_LDB(B1, 0, 1); PG8_SCHED; PG8_LDA(At, 0, 0); PG8_STAGE(PG8_SA(1, 1), a1 + hstep, voffA);
;             PG8_WAIT_V(8); PG8_WAIT_L(0); PG8_BAR; PG8_MMA(0, 0, At, B0); PG8_MMA(0, 1, At, B1); PG8_BAR; PG8_SCHED;
;             PG8_LDA(At, 0, 1); PG8_STAGE(PG8_SB(0, 0), b2, voffB); PG8_STAGE(PG8_SB(0, 1), b2 + hstep, voffB); PG8_STAGE(PG8_SA(0, 0), a2, voffA);
;             PG8_WAIT_V(8); PG8_WAIT_L(0); PG8_BAR; PG8_MMA(1, 0, At, B0); PG8_MMA(1, 1, At, B1); PG8_BAR; PG8_SCHED;
;             PG8_LDB(B0, 1, 0); PG8_LDB(B1, 1, 1); PG8_SCHED; PG8_LDA(At, 1, 0); PG8_STAGE(PG8_SA(0, 1), a2 + hstep, voffA);
;             PG8_WAIT_V(8); PG8_WAIT_L(0); PG8_BAR; PG8_MMA(0, 0, At, B0); PG8_MMA(0, 1, At, B1); PG8_BAR; PG8_SCHED;
;             PG8_LDA(At, 1, 1); PG8_STAGE(PG8_SB(1, 0), b3, voffB); PG8_STAGE(PG8_SB(1, 1), b3 + hstep, voffB); PG8_STAGE(PG8_SA(1, 0), a3, voffA);
;             PG8_WAIT_V(8); PG8_WAIT_L(0); PG8_BAR; PG8_MMA(1, 0, At, B0); PG8_MMA(1, 1, At, B1); PG8_BAR; PG8_SCHED;
	v_mfma_f32_16x16x32_bf16 v[62:65], v[138:141], v[178:181], v[62:65]
	v_mfma_f32_16x16x32_bf16 v[58:61], v[154:157], v[178:181], v[58:61]
	v_mfma_f32_16x16x32_bf16 v[46:49], v[138:141], v[186:189], v[46:49]
	v_mfma_f32_16x16x32_bf16 v[42:45], v[154:157], v[186:189], v[42:45]
	v_mfma_f32_16x16x32_bf16 v[30:33], v[138:141], v[194:197], v[30:33]
	v_mfma_f32_16x16x32_bf16 v[26:29], v[154:157], v[194:197], v[26:29]
	v_mfma_f32_16x16x32_bf16 v[14:17], v[138:141], v[202:205], v[14:17]
	v_mfma_f32_16x16x32_bf16 v[10:13], v[154:157], v[202:205], v[10:13]
	v_mfma_f32_16x16x32_bf16 v[62:65], v[150:153], v[182:185], v[62:65]
	v_mfma_f32_16x16x32_bf16 v[58:61], v[158:161], v[182:185], v[58:61]
	v_mfma_f32_16x16x32_bf16 v[46:49], v[150:153], v[190:193], v[46:49]
	v_mfma_f32_16x16x32_bf16 v[42:45], v[158:161], v[190:193], v[42:45]
	v_mfma_f32_16x16x32_bf16 v[30:33], v[150:153], v[198:201], v[30:33]
	v_mfma_f32_16x16x32_bf16 v[26:29], v[158:161], v[198:201], v[26:29]
	v_mfma_f32_16x16x32_bf16 v[14:17], v[150:153], v[206:209], v[14:17]
	v_mfma_f32_16x16x32_bf16 v[10:13], v[158:161], v[206:209], v[10:13]
	s_setprio 0
	s_setprio 1
	v_mfma_f32_16x16x32_bf16 v[54:57], v[162:165], v[178:181], v[54:57]
	v_mfma_f32_16x16x32_bf16 v[50:53], v[170:173], v[178:181], v[50:53]
	v_mfma_f32_16x16x32_bf16 v[38:41], v[162:165], v[186:189], v[38:41]
	v_mfma_f32_16x16x32_bf16 v[34:37], v[170:173], v[186:189], v[34:37]
	v_mfma_f32_16x16x32_bf16 v[22:25], v[162:165], v[194:197], v[22:25]
	v_mfma_f32_16x16x32_bf16 v[18:21], v[170:173], v[194:197], v[18:21]
	v_mfma_f32_16x16x32_bf16 v[6:9], v[162:165], v[202:205], v[6:9]
	v_mfma_f32_16x16x32_bf16 v[2:5], v[170:173], v[202:205], v[2:5]
	v_mfma_f32_16x16x32_bf16 v[54:57], v[166:169], v[182:185], v[54:57]
	v_mfma_f32_16x16x32_bf16 v[50:53], v[174:177], v[182:185], v[50:53]
	v_mfma_f32_16x16x32_bf16 v[38:41], v[166:169], v[190:193], v[38:41]
	v_mfma_f32_16x16x32_bf16 v[34:37], v[174:177], v[190:193], v[34:37]
	v_mfma_f32_16x16x32_bf16 v[22:25], v[166:169], v[198:201], v[22:25]
	v_mfma_f32_16x16x32_bf16 v[18:21], v[174:177], v[198:201], v[18:21]
	v_mfma_f32_16x16x32_bf16 v[6:9], v[166:169], v[206:209], v[6:9]
	v_mfma_f32_16x16x32_bf16 v[2:5], v[174:177], v[206:209], v[2:5]
	s_setprio 0
	s_barrier
	s_add_i32 s62, 0, 0x18000
	s_add_i32 s63, 0, 0x1c000
	v_add_u32_e32 v158, s62, v144
	v_add_u32_e32 v174, s63, v144
	ds_read_b128 v[138:141], v158
	ds_read_b128 v[150:153], v158 offset:1024
	ds_read_b128 v[154:157], v158 offset:2048
	ds_read_b128 v[158:161], v158 offset:3072
	ds_read_b128 v[162:165], v174
	ds_read_b128 v[166:169], v174 offset:1024
	ds_read_b128 v[170:173], v174 offset:2048
	ds_read_b128 v[174:177], v174 offset:3072
	s_add_u32 s38, s38, 0x100000
	s_addc_u32 s39, s39, 0
	s_mov_b32 m0, s47
	v_lshl_add_u64 v[216:217], s[38:39], 0, v[132:133]
	ds_read_b128 v[178:181], v149 offset:32768
	ds_read_b128 v[182:185], v149 offset:33792
	ds_read_b128 v[186:189], v149 offset:34816
	ds_read_b128 v[190:193], v149 offset:35840
	ds_read_b128 v[194:197], v149 offset:36864
	ds_read_b128 v[198:201], v149 offset:37888
	ds_read_b128 v[202:205], v149 offset:38912
	ds_read_b128 v[206:209], v149 offset:39936
	global_load_lds_dwordx4 v[216:217], off
	v_lshl_add_u64 v[216:217], s[38:39], 0, v[130:131]
	s_mov_b32 m0, s48
	s_nop 0
	global_load_lds_dwordx4 v[216:217], off
	s_waitcnt vmcnt(8)
	s_waitcnt lgkmcnt(0)
	s_setprio 1
	s_barrier
	v_mfma_f32_16x16x32_bf16 v[126:129], v[138:141], v[178:181], v[126:129]
	v_mfma_f32_16x16x32_bf16 v[122:125], v[154:157], v[178:181], v[122:125]
	v_mfma_f32_16x16x32_bf16 v[110:113], v[138:141], v[186:189], v[110:113]
	v_mfma_f32_16x16x32_bf16 v[106:109], v[154:157], v[186:189], v[106:109]
	v_mfma_f32_16x16x32_bf16 v[94:97], v[138:141], v[194:197], v[94:97]
	v_mfma_f32_16x16x32_bf16 v[90:93], v[154:157], v[194:197], v[90:93]
	v_mfma_f32_16x16x32_bf16 v[78:81], v[138:141], v[202:205], v[78:81]
	v_mfma_f32_16x16x32_bf16 v[74:77], v[154:157], v[202:205], v[74:77]
	v_mfma_f32_16x16x32_bf16 v[126:129], v[150:153], v[182:185], v[126:129]
	v_mfma_f32_16x16x32_bf16 v[122:125], v[158:161], v[182:185], v[122:125]
	v_mfma_f32_16x16x32_bf16 v[110:113], v[150:153], v[190:193], v[110:113]
	v_mfma_f32_16x16x32_bf16 v[106:109], v[158:161], v[190:193], v[106:109]
	v_mfma_f32_16x16x32_bf16 v[94:97], v[150:153], v[198:201], v[94:97]
	v_mfma_f32_16x16x32_bf16 v[90:93], v[158:161], v[198:201], v[90:93]
	v_mfma_f32_16x16x32_bf16 v[78:81], v[150:153], v[206:209], v[78:81]
	v_mfma_f32_16x16x32_bf16 v[74:77], v[158:161], v[206:209], v[74:77]
	s_setprio 0
	s_setprio 1
	v_mfma_f32_16x16x32_bf16 v[118:121], v[162:165], v[178:181], v[118:121]
	v_mfma_f32_16x16x32_bf16 v[114:117], v[170:173], v[178:181], v[114:117]
	v_mfma_f32_16x16x32_bf16 v[102:105], v[162:165], v[186:189], v[102:105]
	v_mfma_f32_16x16x32_bf16 v[98:101], v[170:173], v[186:189], v[98:101]
	v_mfma_f32_16x16x32_bf16 v[86:89], v[162:165], v[194:197], v[86:89]
	v_mfma_f32_16x16x32_bf16 v[82:85], v[170:173], v[194:197], v[82:85]
	v_mfma_f32_16x16x32_bf16 v[70:73], v[162:165], v[202:205], v[70:73]
	v_mfma_f32_16x16x32_bf16 v[66:69], v[170:173], v[202:205], v[66:69]
	v_mfma_f32_16x16x32_bf16 v[118:121], v[166:169], v[182:185], v[118:121]
	v_mfma_f32_16x16x32_bf16 v[114:117], v[174:177], v[182:185], v[114:117]
	v_mfma_f32_16x16x32_bf16 v[102:105], v[166:169], v[190:193], v[102:105]
	v_mfma_f32_16x16x32_bf16 v[98:101], v[174:177], v[190:193], v[98:101]
	v_mfma_f32_16x16x32_bf16 v[86:89], v[166:169], v[198:201], v[86:89]
	v_mfma_f32_16x16x32_bf16 v[82:85], v[174:177], v[198:201], v[82:85]
	v_mfma_f32_16x16x32_bf16 v[70:73], v[166:169], v[206:209], v[70:73]
	v_mfma_f32_16x16x32_bf16 v[66:69], v[174:177], v[206:209], v[66:69]
	s_setprio 0
	s_barrier
; #define PG8_STAGE(bufoff, gbase, voff) do { _Pragma("unroll") for (int _i = 0; _i < 2; ++_i) \
;         __builtin_amdgcn_global_load_lds((const unsigned*)((const char*)(gbase) + (voff)[_i]), (PG8_LAS unsigned*)(lds + (bufoff) + ldsw + _i * 8192), 16, 0, 0); } while (0)
; #define PG8_LDA(dst, b, h) do { _Pragma("unroll") for (int m = 0; m < 4; ++m) _Pragma("unroll") for (int k = 0; k < 2; ++k) dst[m][k] = *(const PG8_LAS bf16x8*)(lds + PG8_SA(b, h) + aoff + m * 2048 + k * 1024); } while (0)
; #define PG8_LDB(dst, b, h) do { _Pragma("unroll") for (int n = 0; n < 2; ++n) _Pragma("unroll") for (int k = 0; k < 2; ++k) dst[n][k] = *(const PG8_LAS bf16x8*)(lds + PG8_SB(b, h) + boff + n * 2048 + k * 1024); } while (0)
; #define PG8_MMA(ai, bj, At, Bt) do { __builtin_amdgcn_s_setprio(1); _Pragma("unroll") for (int m = 0; m < 4; ++m) _Pragma("unroll") for (int n = 0; n < 2; ++n) _Pragma("unroll") for (int k = 0; k < 2; ++k) \
;         acc[ai][bj][m][n] = __builtin_amdgcn_mfma_f32_16x16x32_bf16(Bt[n][k], At[m][k], acc[ai][bj][m][n], 0, 0, 0); __builtin_amdgcn_s_setprio(0); } while (0)
; #define PG8_WAIT_V(n) asm volatile("s_waitcnt vmcnt(" #n ")" ::: "memory")
; #define PG8_WAIT_L(n) asm volatile("s_waitcnt lgkmcnt(" #n ")" ::: "memory")
; #define PG8_BAR __builtin_amdgcn_s_barrier()
; #define PG8_SCHED __builtin_amdgcn_sched_barrier(0)
; template <class Epi, class Sched, bool ALIGN_EPI = false, bool SP2 = false>
; __device__ __forceinline__ void gemm_phase(PG8_LAS unsigned char* lds, const Gemm g, const Sched& S, const Epi& E) {
;     ...
;             PG8_LDB(B0, 1, 0); PG8_LDB(B1, 1, 1); PG8_SCHED; PG8_LDA(At, 1, 0); PG8_STAGE(PG8_SA(0, 1), a2 + hstep, voffA);
;             PG8_WAIT_V(8); PG8_WAIT_L(0); PG8_BAR; PG8_MMA(0, 0, At, B0); PG8_MMA(0, 1, At, B1); PG8_BAR; PG8_SCHED;
;             PG8_LDA(At, 1, 1); PG8_STAGE(PG8_SB(1, 0), b3, voffB); PG8_STAGE(PG8_SB(1, 1), b3 + hstep, voffB); PG8_STAGE(PG8_SA(1, 0), a3, voffA);
;             PG8_WAIT_V(8); PG8_WAIT_L(0); PG8_BAR; PG8_MMA(1, 0, At, B0); PG8_MMA(1, 1, At, B1); PG8_BAR; PG8_SCHED;
;     ...
;         if constexpr (ALIGN_EPI) { if (wr == 0) PG8_BAR; }
	s_add_i32 s38, s62, s42
	v_lshl_add_u64 v[142:143], v[142:143], 0, s[16:17]
	s_mov_b32 m0, s38
	ds_read_b128 v[178:181], v149 offset:49152
	ds_read_b128 v[182:185], v149 offset:50176
	ds_read_b128 v[186:189], v149 offset:51200
	ds_read_b128 v[190:193], v149 offset:52224
	ds_read_b128 v[194:197], v149 offset:53248
	ds_read_b128 v[198:201], v149 offset:54272
	ds_read_b128 v[202:205], v149 offset:55296
	ds_read_b128 v[206:209], v149 offset:56320
	global_load_lds_dwordx4 v[142:143], off
	s_add_i32 m0, s38, 0x2000
	s_add_u32 s36, s36, 0x100080
	v_lshl_add_u64 v[142:143], v[210:211], 0, s[16:17]
	s_addc_u32 s37, s37, 0
	s_add_i32 s38, s63, s42
	global_load_lds_dwordx4 v[142:143], off
	v_lshl_add_u64 v[142:143], s[36:37], 0, v[132:133]
	s_mov_b32 m0, s38
	s_nop 0
	global_load_lds_dwordx4 v[142:143], off
	v_lshl_add_u64 v[142:143], s[36:37], 0, v[130:131]
	s_add_i32 m0, s38, 0x2000
	s_nop 0
	global_load_lds_dwordx4 v[142:143], off
	v_lshl_add_u64 v[142:143], v[212:213], 0, s[16:17]
	s_mov_b32 m0, s51
	s_nop 0
	global_load_lds_dwordx4 v[142:143], off
	v_lshl_add_u64 v[142:143], v[214:215], 0, s[16:17]
	s_mov_b32 m0, s52
	s_nop 0
	global_load_lds_dwordx4 v[142:143], off
	s_waitcnt vmcnt(8)
	s_waitcnt lgkmcnt(0)
	s_setprio 1
	s_barrier
	v_mfma_f32_16x16x32_bf16 v[62:65], v[138:141], v[178:181], v[62:65]
	v_mfma_f32_16x16x32_bf16 v[58:61], v[154:157], v[178:181], v[58:61]
	v_mfma_f32_16x16x32_bf16 v[46:49], v[138:141], v[186:189], v[46:49]
	v_mfma_f32_16x16x32_bf16 v[42:45], v[154:157], v[186:189], v[42:45]
	v_mfma_f32_16x16x32_bf16 v[30:33], v[138:141], v[194:197], v[30:33]
	v_mfma_f32_16x16x32_bf16 v[26:29], v[154:157], v[194:197], v[26:29]
	v_mfma_f32_16x16x32_bf16 v[14:17], v[138:141], v[202:205], v[14:17]
	v_mfma_f32_16x16x32_bf16 v[10:13], v[154:157], v[202:205], v[10:13]
	v_mfma_f32_16x16x32_bf16 v[62:65], v[150:153], v[182:185], v[62:65]
	v_mfma_f32_16x16x32_bf16 v[58:61], v[158:161], v[182:185], v[58:61]
	v_mfma_f32_16x16x32_bf16 v[46:49], v[150:153], v[190:193], v[46:49]
	v_mfma_f32_16x16x32_bf16 v[42:45], v[158:161], v[190:193], v[42:45]
	v_mfma_f32_16x16x32_bf16 v[30:33], v[150:153], v[198:201], v[30:33]
	v_mfma_f32_16x16x32_bf16 v[26:29], v[158:161], v[198:201], v[26:29]
	v_mfma_f32_16x16x32_bf16 v[14:17], v[150:153], v[206:209], v[14:17]
	v_mfma_f32_16x16x32_bf16 v[10:13], v[158:161], v[206:209], v[10:13]
	s_setprio 0
	s_setprio 1
	v_mfma_f32_16x16x32_bf16 v[54:57], v[162:165], v[178:181], v[54:57]
	v_mfma_f32_16x16x32_bf16 v[50:53], v[170:173], v[178:181], v[50:53]
	v_mfma_f32_16x16x32_bf16 v[38:41], v[162:165], v[186:189], v[38:41]
	v_mfma_f32_16x16x32_bf16 v[34:37], v[170:173], v[186:189], v[34:37]
	v_mfma_f32_16x16x32_bf16 v[22:25], v[162:165], v[194:197], v[22:25]
	v_mfma_f32_16x16x32_bf16 v[18:21], v[170:173], v[194:197], v[18:21]
	v_mfma_f32_16x16x32_bf16 v[6:9], v[162:165], v[202:205], v[6:9]
	v_mfma_f32_16x16x32_bf16 v[2:5], v[170:173], v[202:205], v[2:5]
	v_mfma_f32_16x16x32_bf16 v[54:57], v[166:169], v[182:185], v[54:57]
	v_mfma_f32_16x16x32_bf16 v[50:53], v[174:177], v[182:185], v[50:53]
	v_mfma_f32_16x16x32_bf16 v[38:41], v[166:169], v[190:193], v[38:41]
	v_mfma_f32_16x16x32_bf16 v[34:37], v[174:177], v[190:193], v[34:37]
	v_mfma_f32_16x16x32_bf16 v[22:25], v[166:169], v[198:201], v[22:25]
	v_mfma_f32_16x16x32_bf16 v[18:21], v[174:177], v[198:201], v[18:21]
	v_mfma_f32_16x16x32_bf16 v[6:9], v[166:169], v[206:209], v[6:9]
	v_mfma_f32_16x16x32_bf16 v[2:5], v[174:177], v[206:209], v[2:5]
	s_setprio 0
	s_add_i32 s61, s61, 2
	s_add_u32 s30, s30, 0x100
	s_addc_u32 s31, s31, 0
	s_add_u32 s59, s59, 0x100
	s_addc_u32 s60, s60, 0
	s_cmp_gt_u32 s61, 5
	s_barrier
	s_cbranch_scc0 .LBB0_1219
	s_and_b64 vcc, exec, s[18:19]
	s_cbranch_vccz .LBB0_1222
	s_barrier

; #define PG8_STAGE(bufoff, gbase, voff) do { _Pragma("unroll") for (int _i = 0; _i < 2; ++_i) \
;         __builtin_amdgcn_global_load_lds((const unsigned*)((const char*)(gbase) + (voff)[_i]), (PG8_LAS unsigned*)(lds + (bufoff) + ldsw + _i * 8192), 16, 0, 0); } while (0)
; #define PG8_LDA(dst, b, h) do { _Pragma("unroll") for (int m = 0; m < 4; ++m) _Pragma("unroll") for (int k = 0; k < 2; ++k) dst[m][k] = *(const PG8_LAS bf16x8*)(lds + PG8_SA(b, h) + aoff + m * 2048 + k * 1024); } while (0)
; #define PG8_WAIT_V(n) asm volatile("s_waitcnt vmcnt(" #n ")" ::: "memory")
; #define PG8_BAR __builtin_amdgcn_s_barrier()
; template <class Epi, class Sched, bool ALIGN_EPI = false, bool SP2 = false>
; __device__ __forceinline__ void gemm_phase(PG8_LAS unsigned char* lds, const Gemm g, const Sched& S, const Epi& E) {
;     ...
;         for (int t = 0; t < nt; t += 2) {
;             if constexpr (Epi::MIDHOOK) { if (t == (nt >> 1)) E.mid(acc, cur, wr, wc, fr, fq); }
;             const bool last = (t == nt - 2);
;             const char* a1 = cA + (size_t)(t + 1) * kstep;
;             const char* a2 = last ? nA : cA + (size_t)(t + 2) * kstep; const char* b2 = last ? nB : cB + (size_t)(t + 2) * kstep;
;             const char* a3 = a2 + kstep; const char* b3 = b2 + kstep;
;             if (last && has_next) S.a_ready(nxt);
;             if constexpr (SP2) {
;             PG8_LDB(B0, 0, 0); PG8_LDB(B1, 0, 1); PG8_SCHED; PG8_LDA(At, 0, 0); PG8_STAGE(PG8_SA(1, 1), a1 + hstep, voffA);
;             PG8_WAIT_V(8); PG8_WAIT_L(0); PG8_BAR; PG8_MMA(0, 0, At, B0); PG8_MMA(0, 1, At, B1); PG8_BAR; PG8_SCHED;
;             PG8_LDA(At, 0, 1); PG8_STAGE(PG8_SB(0, 0), b2, voffB); PG8_STAGE(PG8_SB(0, 1), b2 + hstep, voffB); PG8_STAGE(PG8_SA(0, 0), a2, voffA);
;             PG8_WAIT_V(8); PG8_WAIT_L(0); PG8_BAR; PG8_MMA(1, 0, At, B0); PG8_MMA(1, 1, At, B1); PG8_BAR; PG8_SCHED;
;             PG8_LDB(B0, 1, 0); PG8_LDB(B1, 1, 1); PG8_SCHED; PG8_LDA(At, 1, 0); PG8_STAGE(PG8_SA(0, 1), a2 + hstep, voffA);
;             PG8_WAIT_V(8); PG8_WAIT_L(0); PG8_BAR; PG8_MMA(0, 0, At, B0); PG8_MMA(0, 1, At, B1); PG8_BAR; PG8_SCHED;
;             PG8_LDA(At, 1, 1); PG8_STAGE(PG8_SB(1, 0), b3, voffB); PG8_STAGE(PG8_SB(1, 1), b3 + hstep, voffB); PG8_STAGE(PG8_SA(1, 0), a3, voffA);
;             PG8_WAIT_V(8); PG8_WAIT_L(0); PG8_BAR; PG8_MMA(1, 0, At, B0); PG8_MMA(1, 1, At, B1); PG8_BAR; PG8_SCHED;
.LBB0_1393:
	ds_read_b128 v[156:159], v152
	ds_read_b128 v[160:163], v152 offset:1024
	ds_read_b128 v[164:167], v152 offset:2048
	ds_read_b128 v[168:171], v152 offset:3072
	ds_read_b128 v[172:175], v153
	ds_read_b128 v[176:179], v153 offset:1024
	ds_read_b128 v[180:183], v153 offset:2048
	ds_read_b128 v[184:187], v153 offset:3072
	s_add_u32 s28, s26, 0xfff80080
	s_addc_u32 s29, s27, -1
	s_cmp_eq_u32 s54, 28
	s_cselect_b32 s31, s19, s29
	s_cselect_b32 s30, s50, s28
	s_cselect_b32 s29, s17, s53
	s_cselect_b32 s28, s51, s52
	v_lshl_add_u64 v[146:147], s[26:27], 0, v[138:139]
	s_add_i32 m0, s25, 0xc000
	ds_read_b128 v[188:191], v154
	ds_read_b128 v[192:195], v154 offset:1024
	ds_read_b128 v[196:199], v154 offset:2048
	ds_read_b128 v[200:203], v154 offset:3072
	ds_read_b128 v[204:207], v154 offset:4096
	ds_read_b128 v[208:211], v154 offset:5120
	ds_read_b128 v[212:215], v154 offset:6144
	ds_read_b128 v[216:219], v154 offset:7168
	global_load_lds_dwordx4 v[146:147], off
	v_lshl_add_u64 v[146:147], s[26:27], 0, v[140:141]
	s_add_i32 m0, s25, 0xe000
	s_nop 0
	global_load_lds_dwordx4 v[146:147], off
	s_waitcnt vmcnt(8)
	s_waitcnt lgkmcnt(0)
	s_setprio 1
	s_barrier
	v_mfma_f32_16x16x32_bf16 v[126:129], v[156:159], v[188:191], v[126:129]
	v_mfma_f32_16x16x32_bf16 v[122:125], v[164:167], v[188:191], v[122:125]
	v_mfma_f32_16x16x32_bf16 v[118:121], v[156:159], v[196:199], v[118:121]
	v_mfma_f32_16x16x32_bf16 v[110:113], v[164:167], v[196:199], v[110:113]
	v_mfma_f32_16x16x32_bf16 v[102:105], v[156:159], v[204:207], v[102:105]
	v_mfma_f32_16x16x32_bf16 v[94:97], v[164:167], v[204:207], v[94:97]
	v_mfma_f32_16x16x32_bf16 v[86:89], v[156:159], v[212:215], v[86:89]
	v_mfma_f32_16x16x32_bf16 v[78:81], v[164:167], v[212:215], v[78:81]
	v_mfma_f32_16x16x32_bf16 v[126:129], v[160:163], v[192:195], v[126:129]
	v_mfma_f32_16x16x32_bf16 v[122:125], v[168:171], v[192:195], v[122:125]
	v_mfma_f32_16x16x32_bf16 v[118:121], v[160:163], v[200:203], v[118:121]
	v_mfma_f32_16x16x32_bf16 v[110:113], v[168:171], v[200:203], v[110:113]
	v_mfma_f32_16x16x32_bf16 v[102:105], v[160:163], v[208:211], v[102:105]
	v_mfma_f32_16x16x32_bf16 v[94:97], v[168:171], v[208:211], v[94:97]
	v_mfma_f32_16x16x32_bf16 v[86:89], v[160:163], v[216:219], v[86:89]
	v_mfma_f32_16x16x32_bf16 v[78:81], v[168:171], v[216:219], v[78:81]
	s_setprio 0
	s_setprio 1
	v_mfma_f32_16x16x32_bf16 v[114:117], v[172:175], v[188:191], v[114:117]
	v_mfma_f32_16x16x32_bf16 v[106:109], v[180:183], v[188:191], v[106:109]
	v_mfma_f32_16x16x32_bf16 v[98:101], v[172:175], v[196:199], v[98:101]
	v_mfma_f32_16x16x32_bf16 v[90:93], v[180:183], v[196:199], v[90:93]
	v_mfma_f32_16x16x32_bf16 v[82:85], v[172:175], v[204:207], v[82:85]
	v_mfma_f32_16x16x32_bf16 v[74:77], v[180:183], v[204:207], v[74:77]
	v_mfma_f32_16x16x32_bf16 v[70:73], v[172:175], v[212:215], v[70:73]
	v_mfma_f32_16x16x32_bf16 v[66:69], v[180:183], v[212:215], v[66:69]
	v_mfma_f32_16x16x32_bf16 v[114:117], v[176:179], v[192:195], v[114:117]
	v_mfma_f32_16x16x32_bf16 v[106:109], v[184:187], v[192:195], v[106:109]
	v_mfma_f32_16x16x32_bf16 v[98:101], v[176:179], v[200:203], v[98:101]
	v_mfma_f32_16x16x32_bf16 v[90:93], v[184:187], v[200:203], v[90:93]
	v_mfma_f32_16x16x32_bf16 v[82:85], v[176:179], v[208:211], v[82:85]
	v_mfma_f32_16x16x32_bf16 v[74:77], v[184:187], v[208:211], v[74:77]
	v_mfma_f32_16x16x32_bf16 v[70:73], v[176:179], v[216:219], v[70:73]
	v_mfma_f32_16x16x32_bf16 v[66:69], v[184:187], v[216:219], v[66:69]
	s_setprio 0
	s_barrier
	s_add_i32 s55, s45, s36
	v_lshl_add_u64 v[146:147], s[28:29], 0, v[134:135]
	s_mov_b32 m0, s55
	ds_read_b128 v[188:191], v154 offset:16384
	ds_read_b128 v[192:195], v154 offset:17408
	ds_read_b128 v[196:199], v154 offset:18432
	ds_read_b128 v[200:203], v154 offset:19456
	ds_read_b128 v[204:207], v154 offset:20480
	ds_read_b128 v[208:211], v154 offset:21504
	ds_read_b128 v[212:215], v154 offset:22528
	ds_read_b128 v[216:219], v154 offset:23552
	global_load_lds_dwordx4 v[146:147], off
	s_add_i32 m0, s55, 0x2000
	s_add_u32 s56, s28, 0x80000
	v_lshl_add_u64 v[220:221], s[28:29], 0, v[130:131]
	s_addc_u32 s57, s29, 0
	s_add_i32 s55, s46, s36
	global_load_lds_dwordx4 v[220:221], off
	v_lshl_add_u64 v[222:223], s[56:57], 0, v[134:135]
	s_mov_b32 m0, s55
	v_lshl_add_u64 v[224:225], s[30:31], 0, v[132:133]
	global_load_lds_dwordx4 v[222:223], off
	v_lshl_add_u64 v[222:223], s[56:57], 0, v[130:131]
	s_add_i32 m0, s55, 0x2000
	s_nop 0
	global_load_lds_dwordx4 v[222:223], off
	v_lshl_add_u64 v[222:223], s[30:31], 0, v[136:137]
	s_mov_b32 m0, s25
	s_nop 0
	global_load_lds_dwordx4 v[222:223], off
	s_mov_b32 m0, s38
	s_nop 0
	global_load_lds_dwordx4 v[224:225], off
	s_waitcnt vmcnt(8)
	s_waitcnt lgkmcnt(0)
	s_setprio 1
	s_barrier
; #define PG8_STAGE(bufoff, gbase, voff) do { _Pragma("unroll") for (int _i = 0; _i < 2; ++_i) \
;         __builtin_amdgcn_global_load_lds((const unsigned*)((const char*)(gbase) + (voff)[_i]), (PG8_LAS unsigned*)(lds + (bufoff) + ldsw + _i * 8192), 16, 0, 0); } while (0)
; #define PG8_LDA(dst, b, h) do { _Pragma("unroll") for (int m = 0; m < 4; ++m) _Pragma("unroll") for (int k = 0; k < 2; ++k) dst[m][k] = *(const PG8_LAS bf16x8*)(lds + PG8_SA(b, h) + aoff + m * 2048 + k * 1024); } while (0)
; #define PG8_LDB(dst, b, h) do { _Pragma("unroll") for (int n = 0; n < 2; ++n) _Pragma("unroll") for (int k = 0; k < 2; ++k) dst[n][k] = *(const PG8_LAS bf16x8*)(lds + PG8_SB(b, h) + boff + n * 2048 + k * 1024); } while (0)
; #define PG8_MMA(ai, bj, At, Bt) do { __builtin_amdgcn_s_setprio(1); _Pragma("unroll") for (int m = 0; m < 4; ++m) _Pragma("unroll") for (int n = 0; n < 2; ++n) _Pragma("unroll") for (int k = 0; k < 2; ++k) \
;         acc[ai][bj][m][n] = __builtin_amdgcn_mfma_f32_16x16x32_bf16(Bt[n][k], At[m][k], acc[ai][bj][m][n], 0, 0, 0); __builtin_amdgcn_s_setprio(0); } while (0)
; #define PG8_WAIT_V(n) asm volatile("s_waitcnt vmcnt(" #n ")" ::: "memory")
; template <class Epi, class Sched, bool ALIGN_EPI = false, bool SP2 = false>
; __device__ __forceinline__ void gemm_phase(PG8_LAS unsigned char* lds, const Gemm g, const Sched& S, const Epi& E) {
;     ...
;             PG8_LDB(B0, 0, 0); PG8_LDB(B1, 0, 1); PG8_SCHED; PG8_LDA(At, 0, 0); PG8_STAGE(PG8_SA(1, 1), a1 + hstep, voffA);
;             PG8_WAIT_V(8); PG8_WAIT_L(0); PG8_BAR; PG8_MMA(0, 0, At, B0); PG8_MMA(0, 1, At, B1); PG8_BAR; PG8_SCHED;
;             PG8_LDA(At, 0, 1); PG8_STAGE(PG8_SB(0, 0), b2, voffB); PG8_STAGE(PG8_SB(0, 1), b2 + hstep, voffB); PG8_STAGE(PG8_SA(0, 0), a2, voffA);
;             PG8_WAIT_V(8); PG8_WAIT_L(0); PG8_BAR; PG8_MMA(1, 0, At, B0); PG8_MMA(1, 1, At, B1); PG8_BAR; PG8_SCHED;
;             PG8_LDB(B0, 1, 0); PG8_LDB(B1, 1, 1); PG8_SCHED; PG8_LDA(At, 1, 0); PG8_STAGE(PG8_SA(0, 1), a2 + hstep, voffA);
;             PG8_WAIT_V(8); PG8_WAIT_L(0); PG8_BAR; PG8_MMA(0, 0, At, B0); PG8_MMA(0, 1, At, B1); PG8_BAR; PG8_SCHED;
;             PG8_LDA(At, 1, 1); PG8_STAGE(PG8_SB(1, 0), b3, voffB); PG8_STAGE(PG8_SB(1, 1), b3 + hstep, voffB); PG8_STAGE(PG8_SA(1, 0), a3, voffA);
;             PG8_WAIT_V(8); PG8_WAIT_L(0); PG8_BAR; PG8_MMA(1, 0, At, B0); PG8_MMA(1, 1, At, B1); PG8_BAR; PG8_SCHED;
	v_mfma_f32_16x16x32_bf16 v[62:65], v[156:159], v[188:191], v[62:65]
	v_mfma_f32_16x16x32_bf16 v[58:61], v[164:167], v[188:191], v[58:61]
	v_mfma_f32_16x16x32_bf16 v[54:57], v[156:159], v[196:199], v[54:57]
	v_mfma_f32_16x16x32_bf16 v[46:49], v[164:167], v[196:199], v[46:49]
	v_mfma_f32_16x16x32_bf16 v[38:41], v[156:159], v[204:207], v[38:41]
	v_mfma_f32_16x16x32_bf16 v[30:33], v[164:167], v[204:207], v[30:33]
	v_mfma_f32_16x16x32_bf16 v[22:25], v[156:159], v[212:215], v[22:25]
	v_mfma_f32_16x16x32_bf16 v[14:17], v[164:167], v[212:215], v[14:17]
	v_mfma_f32_16x16x32_bf16 v[62:65], v[160:163], v[192:195], v[62:65]
	v_mfma_f32_16x16x32_bf16 v[58:61], v[168:171], v[192:195], v[58:61]
	v_mfma_f32_16x16x32_bf16 v[54:57], v[160:163], v[200:203], v[54:57]
	v_mfma_f32_16x16x32_bf16 v[46:49], v[168:171], v[200:203], v[46:49]
	v_mfma_f32_16x16x32_bf16 v[38:41], v[160:163], v[208:211], v[38:41]
	v_mfma_f32_16x16x32_bf16 v[30:33], v[168:171], v[208:211], v[30:33]
	v_mfma_f32_16x16x32_bf16 v[22:25], v[160:163], v[216:219], v[22:25]
	v_mfma_f32_16x16x32_bf16 v[14:17], v[168:171], v[216:219], v[14:17]
	s_setprio 0
	s_setprio 1
	v_mfma_f32_16x16x32_bf16 v[50:53], v[172:175], v[188:191], v[50:53]
	v_mfma_f32_16x16x32_bf16 v[42:45], v[180:183], v[188:191], v[42:45]
	v_mfma_f32_16x16x32_bf16 v[34:37], v[172:175], v[196:199], v[34:37]
	v_mfma_f32_16x16x32_bf16 v[26:29], v[180:183], v[196:199], v[26:29]
	v_mfma_f32_16x16x32_bf16 v[18:21], v[172:175], v[204:207], v[18:21]
	v_mfma_f32_16x16x32_bf16 v[10:13], v[180:183], v[204:207], v[10:13]
	v_mfma_f32_16x16x32_bf16 v[6:9], v[172:175], v[212:215], v[6:9]
	v_mfma_f32_16x16x32_bf16 v[2:5], v[180:183], v[212:215], v[2:5]
	v_mfma_f32_16x16x32_bf16 v[50:53], v[176:179], v[192:195], v[50:53]
	v_mfma_f32_16x16x32_bf16 v[42:45], v[184:187], v[192:195], v[42:45]
	v_mfma_f32_16x16x32_bf16 v[34:37], v[176:179], v[200:203], v[34:37]
	v_mfma_f32_16x16x32_bf16 v[26:29], v[184:187], v[200:203], v[26:29]
	v_mfma_f32_16x16x32_bf16 v[18:21], v[176:179], v[208:211], v[18:21]
	v_mfma_f32_16x16x32_bf16 v[10:13], v[184:187], v[208:211], v[10:13]
	v_mfma_f32_16x16x32_bf16 v[6:9], v[176:179], v[216:219], v[6:9]
	v_mfma_f32_16x16x32_bf16 v[2:5], v[184:187], v[216:219], v[2:5]
	s_setprio 0
	s_barrier
	s_add_i32 s55, 0, 0x18000
	v_add_u32_e32 v155, s55, v150
	s_add_i32 s56, 0, 0x1c000
	ds_read_b128 v[156:159], v155
	ds_read_b128 v[160:163], v155 offset:1024
	ds_read_b128 v[164:167], v155 offset:2048
	ds_read_b128 v[168:171], v155 offset:3072
	v_add_u32_e32 v155, s56, v150
	ds_read_b128 v[172:175], v155
	ds_read_b128 v[176:179], v155 offset:1024
	ds_read_b128 v[180:183], v155 offset:2048
	ds_read_b128 v[184:187], v155 offset:3072
	s_add_u32 s30, s30, 0x80000
	s_addc_u32 s31, s31, 0
	s_mov_b32 m0, s39
	v_lshl_add_u64 v[226:227], s[30:31], 0, v[136:137]
	ds_read_b128 v[188:191], v154 offset:32768
	ds_read_b128 v[192:195], v154 offset:33792
	ds_read_b128 v[196:199], v154 offset:34816
	ds_read_b128 v[200:203], v154 offset:35840
	ds_read_b128 v[204:207], v154 offset:36864
	ds_read_b128 v[208:211], v154 offset:37888
	ds_read_b128 v[212:215], v154 offset:38912
	ds_read_b128 v[216:219], v154 offset:39936
	global_load_lds_dwordx4 v[226:227], off
	v_lshl_add_u64 v[226:227], s[30:31], 0, v[132:133]
	s_mov_b32 m0, s40
	s_nop 0
	global_load_lds_dwordx4 v[226:227], off
	s_waitcnt vmcnt(8)
	s_waitcnt lgkmcnt(0)
	s_setprio 1
	s_barrier
	v_mfma_f32_16x16x32_bf16 v[126:129], v[156:159], v[188:191], v[126:129]
	v_mfma_f32_16x16x32_bf16 v[122:125], v[164:167], v[188:191], v[122:125]
	v_mfma_f32_16x16x32_bf16 v[118:121], v[156:159], v[196:199], v[118:121]
	v_mfma_f32_16x16x32_bf16 v[110:113], v[164:167], v[196:199], v[110:113]
	v_mfma_f32_16x16x32_bf16 v[102:105], v[156:159], v[204:207], v[102:105]
	v_mfma_f32_16x16x32_bf16 v[94:97], v[164:167], v[204:207], v[94:97]
	v_mfma_f32_16x16x32_bf16 v[86:89], v[156:159], v[212:215], v[86:89]
	v_mfma_f32_16x16x32_bf16 v[78:81], v[164:167], v[212:215], v[78:81]
	v_mfma_f32_16x16x32_bf16 v[126:129], v[160:163], v[192:195], v[126:129]
	v_mfma_f32_16x16x32_bf16 v[122:125], v[168:171], v[192:195], v[122:125]
	v_mfma_f32_16x16x32_bf16 v[118:121], v[160:163], v[200:203], v[118:121]
	v_mfma_f32_16x16x32_bf16 v[110:113], v[168:171], v[200:203], v[110:113]
	v_mfma_f32_16x16x32_bf16 v[102:105], v[160:163], v[208:211], v[102:105]
	v_mfma_f32_16x16x32_bf16 v[94:97], v[168:171], v[208:211], v[94:97]
	v_mfma_f32_16x16x32_bf16 v[86:89], v[160:163], v[216:219], v[86:89]
	v_mfma_f32_16x16x32_bf16 v[78:81], v[168:171], v[216:219], v[78:81]
	s_setprio 0
	s_setprio 1
	v_mfma_f32_16x16x32_bf16 v[114:117], v[172:175], v[188:191], v[114:117]
	v_mfma_f32_16x16x32_bf16 v[106:109], v[180:183], v[188:191], v[106:109]
	v_mfma_f32_16x16x32_bf16 v[98:101], v[172:175], v[196:199], v[98:101]
	v_mfma_f32_16x16x32_bf16 v[90:93], v[180:183], v[196:199], v[90:93]
	v_mfma_f32_16x16x32_bf16 v[82:85], v[172:175], v[204:207], v[82:85]
	v_mfma_f32_16x16x32_bf16 v[74:77], v[180:183], v[204:207], v[74:77]
	v_mfma_f32_16x16x32_bf16 v[70:73], v[172:175], v[212:215], v[70:73]
	v_mfma_f32_16x16x32_bf16 v[66:69], v[180:183], v[212:215], v[66:69]
	v_mfma_f32_16x16x32_bf16 v[114:117], v[176:179], v[192:195], v[114:117]
	v_mfma_f32_16x16x32_bf16 v[106:109], v[184:187], v[192:195], v[106:109]
	v_mfma_f32_16x16x32_bf16 v[98:101], v[176:179], v[200:203], v[98:101]
	v_mfma_f32_16x16x32_bf16 v[90:93], v[184:187], v[200:203], v[90:93]
	v_mfma_f32_16x16x32_bf16 v[82:85], v[176:179], v[208:211], v[82:85]
	v_mfma_f32_16x16x32_bf16 v[74:77], v[184:187], v[208:211], v[74:77]
	v_mfma_f32_16x16x32_bf16 v[70:73], v[176:179], v[216:219], v[70:73]
	v_mfma_f32_16x16x32_bf16 v[66:69], v[184:187], v[216:219], v[66:69]
	s_setprio 0
	s_barrier
; #define PG8_STAGE(bufoff, gbase, voff) do { _Pragma("unroll") for (int _i = 0; _i < 2; ++_i) \
;         __builtin_amdgcn_global_load_lds((const unsigned*)((const char*)(gbase) + (voff)[_i]), (PG8_LAS unsigned*)(lds + (bufoff) + ldsw + _i * 8192), 16, 0, 0); } while (0)
; #define PG8_LDA(dst, b, h) do { _Pragma("unroll") for (int m = 0; m < 4; ++m) _Pragma("unroll") for (int k = 0; k < 2; ++k) dst[m][k] = *(const PG8_LAS bf16x8*)(lds + PG8_SA(b, h) + aoff + m * 2048 + k * 1024); } while (0)
; #define PG8_LDB(dst, b, h) do { _Pragma("unroll") for (int n = 0; n < 2; ++n) _Pragma("unroll") for (int k = 0; k < 2; ++k) dst[n][k] = *(const PG8_LAS bf16x8*)(lds + PG8_SB(b, h) + boff + n * 2048 + k * 1024); } while (0)
; #define PG8_MMA(ai, bj, At, Bt) do { __builtin_amdgcn_s_setprio(1); _Pragma("unroll") for (int m = 0; m < 4; ++m) _Pragma("unroll") for (int n = 0; n < 2; ++n) _Pragma("unroll") for (int k = 0; k < 2; ++k) \
;         acc[ai][bj][m][n] = __builtin_amdgcn_mfma_f32_16x16x32_bf16(Bt[n][k], At[m][k], acc[ai][bj][m][n], 0, 0, 0); __builtin_amdgcn_s_setprio(0); } while (0)
; #define PG8_WAIT_V(n) asm volatile("s_waitcnt vmcnt(" #n ")" ::: "memory")
; #define PG8_WAIT_L(n) asm volatile("s_waitcnt lgkmcnt(" #n ")" ::: "memory")
; #define PG8_BAR __builtin_amdgcn_s_barrier()
; #define PG8_SCHED __builtin_amdgcn_sched_barrier(0)
; template <class Epi, class Sched, bool ALIGN_EPI = false, bool SP2 = false>
; __device__ __forceinline__ void gemm_phase(PG8_LAS unsigned char* lds, const Gemm g, const Sched& S, const Epi& E) {
;     ...
;             PG8_LDB(B0, 1, 0); PG8_LDB(B1, 1, 1); PG8_SCHED; PG8_LDA(At, 1, 0); PG8_STAGE(PG8_SA(0, 1), a2 + hstep, voffA);
;             PG8_WAIT_V(8); PG8_WAIT_L(0); PG8_BAR; PG8_MMA(0, 0, At, B0); PG8_MMA(0, 1, At, B1); PG8_BAR; PG8_SCHED;
;             PG8_LDA(At, 1, 1); PG8_STAGE(PG8_SB(1, 0), b3, voffB); PG8_STAGE(PG8_SB(1, 1), b3 + hstep, voffB); PG8_STAGE(PG8_SA(1, 0), a3, voffA);
;             PG8_WAIT_V(8); PG8_WAIT_L(0); PG8_BAR; PG8_MMA(1, 0, At, B0); PG8_MMA(1, 1, At, B1); PG8_BAR; PG8_SCHED;
;     ...
;         if constexpr (ALIGN_EPI) { if (wr == 0) PG8_BAR; }
	s_add_i32 s30, s55, s36
	v_lshl_add_u64 v[146:147], v[146:147], 0, s[12:13]
	s_mov_b32 m0, s30
	ds_read_b128 v[188:191], v154 offset:49152
	ds_read_b128 v[192:195], v154 offset:50176
	ds_read_b128 v[196:199], v154 offset:51200
	ds_read_b128 v[200:203], v154 offset:52224
	ds_read_b128 v[204:207], v154 offset:53248
	ds_read_b128 v[208:211], v154 offset:54272
	ds_read_b128 v[212:215], v154 offset:55296
	ds_read_b128 v[216:219], v154 offset:56320
	global_load_lds_dwordx4 v[146:147], off
	s_add_i32 m0, s30, 0x2000
	s_add_u32 s28, s28, 0x80080
	v_lshl_add_u64 v[146:147], v[220:221], 0, s[12:13]
	s_addc_u32 s29, s29, 0
	s_add_i32 s30, s56, s36
	global_load_lds_dwordx4 v[146:147], off
	v_lshl_add_u64 v[146:147], s[28:29], 0, v[134:135]
	s_mov_b32 m0, s30
	s_nop 0
	global_load_lds_dwordx4 v[146:147], off
	v_lshl_add_u64 v[146:147], s[28:29], 0, v[130:131]
	s_add_i32 m0, s30, 0x2000
	s_nop 0
	global_load_lds_dwordx4 v[146:147], off
	v_lshl_add_u64 v[146:147], v[222:223], 0, s[12:13]
	s_mov_b32 m0, s43
	s_nop 0
	global_load_lds_dwordx4 v[146:147], off
	v_lshl_add_u64 v[146:147], v[224:225], 0, s[12:13]
	s_mov_b32 m0, s44
	s_nop 0
	global_load_lds_dwordx4 v[146:147], off
	s_waitcnt vmcnt(8)
	s_waitcnt lgkmcnt(0)
	s_setprio 1
	s_barrier
	v_mfma_f32_16x16x32_bf16 v[62:65], v[156:159], v[188:191], v[62:65]
	v_mfma_f32_16x16x32_bf16 v[58:61], v[164:167], v[188:191], v[58:61]
	v_mfma_f32_16x16x32_bf16 v[54:57], v[156:159], v[196:199], v[54:57]
	v_mfma_f32_16x16x32_bf16 v[46:49], v[164:167], v[196:199], v[46:49]
	v_mfma_f32_16x16x32_bf16 v[38:41], v[156:159], v[204:207], v[38:41]
	v_mfma_f32_16x16x32_bf16 v[30:33], v[164:167], v[204:207], v[30:33]
	v_mfma_f32_16x16x32_bf16 v[22:25], v[156:159], v[212:215], v[22:25]
	v_mfma_f32_16x16x32_bf16 v[14:17], v[164:167], v[212:215], v[14:17]
	v_mfma_f32_16x16x32_bf16 v[62:65], v[160:163], v[192:195], v[62:65]
	v_mfma_f32_16x16x32_bf16 v[58:61], v[168:171], v[192:195], v[58:61]
	v_mfma_f32_16x16x32_bf16 v[54:57], v[160:163], v[200:203], v[54:57]
	v_mfma_f32_16x16x32_bf16 v[46:49], v[168:171], v[200:203], v[46:49]
	v_mfma_f32_16x16x32_bf16 v[38:41], v[160:163], v[208:211], v[38:41]
	v_mfma_f32_16x16x32_bf16 v[30:33], v[168:171], v[208:211], v[30:33]
	v_mfma_f32_16x16x32_bf16 v[22:25], v[160:163], v[216:219], v[22:25]
	v_mfma_f32_16x16x32_bf16 v[14:17], v[168:171], v[216:219], v[14:17]
	s_setprio 0
	s_setprio 1
	v_mfma_f32_16x16x32_bf16 v[50:53], v[172:175], v[188:191], v[50:53]
	v_mfma_f32_16x16x32_bf16 v[42:45], v[180:183], v[188:191], v[42:45]
	v_mfma_f32_16x16x32_bf16 v[34:37], v[172:175], v[196:199], v[34:37]
	v_mfma_f32_16x16x32_bf16 v[26:29], v[180:183], v[196:199], v[26:29]
	v_mfma_f32_16x16x32_bf16 v[18:21], v[172:175], v[204:207], v[18:21]
	v_mfma_f32_16x16x32_bf16 v[10:13], v[180:183], v[204:207], v[10:13]
	v_mfma_f32_16x16x32_bf16 v[6:9], v[172:175], v[212:215], v[6:9]
	v_mfma_f32_16x16x32_bf16 v[2:5], v[180:183], v[212:215], v[2:5]
	v_mfma_f32_16x16x32_bf16 v[50:53], v[176:179], v[192:195], v[50:53]
	v_mfma_f32_16x16x32_bf16 v[42:45], v[184:187], v[192:195], v[42:45]
	v_mfma_f32_16x16x32_bf16 v[34:37], v[176:179], v[200:203], v[34:37]
	v_mfma_f32_16x16x32_bf16 v[26:29], v[184:187], v[200:203], v[26:29]
	v_mfma_f32_16x16x32_bf16 v[18:21], v[176:179], v[208:211], v[18:21]
	v_mfma_f32_16x16x32_bf16 v[10:13], v[184:187], v[208:211], v[10:13]
	v_mfma_f32_16x16x32_bf16 v[6:9], v[176:179], v[216:219], v[6:9]
	v_mfma_f32_16x16x32_bf16 v[2:5], v[184:187], v[216:219], v[2:5]
	s_setprio 0
	s_add_i32 s54, s54, 2
	s_add_u32 s26, s26, 0x100
	s_addc_u32 s27, s27, 0
	s_add_u32 s52, s52, 0x100
	s_addc_u32 s53, s53, 0
	s_cmp_gt_u32 s54, 29
	s_barrier
	s_cbranch_scc0 .LBB0_1393
	s_and_b64 vcc, exec, s[14:15]
	s_cbranch_vccz .LBB0_1396
	s_barrier

; #define PG8_STAGE(bufoff, gbase, voff) do { _Pragma("unroll") for (int _i = 0; _i < 2; ++_i) \
;         __builtin_amdgcn_global_load_lds((const unsigned*)((const char*)(gbase) + (voff)[_i]), (PG8_LAS unsigned*)(lds + (bufoff) + ldsw + _i * 8192), 16, 0, 0); } while (0)
; #define PG8_LDA(dst, b, h) do { _Pragma("unroll") for (int m = 0; m < 4; ++m) _Pragma("unroll") for (int k = 0; k < 2; ++k) dst[m][k] = *(const PG8_LAS bf16x8*)(lds + PG8_SA(b, h) + aoff + m * 2048 + k * 1024); } while (0)
; #define PG8_WAIT_V(n) asm volatile("s_waitcnt vmcnt(" #n ")" ::: "memory")
; #define PG8_BAR __builtin_amdgcn_s_barrier()
; template <class Epi, class Sched, bool ALIGN_EPI = false, bool SP2 = false>
; __device__ __forceinline__ void gemm_phase(PG8_LAS unsigned char* lds, const Gemm g, const Sched& S, const Epi& E) {
;     ...
;         for (int t = 0; t < nt; t += 2) {
;             if constexpr (Epi::MIDHOOK) { if (t == (nt >> 1)) E.mid(acc, cur, wr, wc, fr, fq); }
;             const bool last = (t == nt - 2);
;             const char* a1 = cA + (size_t)(t + 1) * kstep;
;             const char* a2 = last ? nA : cA + (size_t)(t + 2) * kstep; const char* b2 = last ? nB : cB + (size_t)(t + 2) * kstep;
;             const char* a3 = a2 + kstep; const char* b3 = b2 + kstep;
;             if (last && has_next) S.a_ready(nxt);
;             if constexpr (SP2) {
;             PG8_LDB(B0, 0, 0); PG8_LDB(B1, 0, 1); PG8_SCHED; PG8_LDA(At, 0, 0); PG8_STAGE(PG8_SA(1, 1), a1 + hstep, voffA);
;             PG8_WAIT_V(8); PG8_WAIT_L(0); PG8_BAR; PG8_MMA(0, 0, At, B0); PG8_MMA(0, 1, At, B1); PG8_BAR; PG8_SCHED;
;             PG8_LDA(At, 0, 1); PG8_STAGE(PG8_SB(0, 0), b2, voffB); PG8_STAGE(PG8_SB(0, 1), b2 + hstep, voffB); PG8_STAGE(PG8_SA(0, 0), a2, voffA);
;             PG8_WAIT_V(8); PG8_WAIT_L(0); PG8_BAR; PG8_MMA(1, 0, At, B0); PG8_MMA(1, 1, At, B1); PG8_BAR; PG8_SCHED;
;             PG8_LDB(B0, 1, 0); PG8_LDB(B1, 1, 1); PG8_SCHED; PG8_LDA(At, 1, 0); PG8_STAGE(PG8_SA(0, 1), a2 + hstep, voffA);
;             PG8_WAIT_V(8); PG8_WAIT_L(0); PG8_BAR; PG8_MMA(0, 0, At, B0); PG8_MMA(0, 1, At, B1); PG8_BAR; PG8_SCHED;
;             PG8_LDA(At, 1, 1); PG8_STAGE(PG8_SB(1, 0), b3, voffB); PG8_STAGE(PG8_SB(1, 1), b3 + hstep, voffB); PG8_STAGE(PG8_SA(1, 0), a3, voffA);
;             PG8_WAIT_V(8); PG8_WAIT_L(0); PG8_BAR; PG8_MMA(1, 0, At, B0); PG8_MMA(1, 1, At, B1); PG8_BAR; PG8_SCHED;
.LBB0_1428:
	s_add_u32 s21, s16, s7
	s_addc_u32 s23, s17, 0
	s_add_u32 s38, s21, 0x100
	s_addc_u32 s39, s23, 0
	s_and_b64 s[36:37], s[30:31], exec
	s_cselect_b32 s39, s25, s39
	s_cselect_b32 s38, s24, s38
	s_add_u32 s7, s14, s7
	s_addc_u32 s36, s15, 0
	s_add_u32 s7, s7, 0x100
	s_addc_u32 s36, s36, 0
	s_and_b64 s[30:31], s[30:31], exec
	s_cselect_b32 s41, s27, s36
	s_cselect_b32 s40, s26, s7
	s_add_u32 s46, s21, 0x80080
	s_addc_u32 s47, s23, 0
	s_add_i32 s70, s60, s44
	ds_read_b128 v[140:143], v137
	ds_read_b128 v[144:147], v137 offset:1024
	ds_read_b128 v[148:151], v137 offset:2048
	ds_read_b128 v[152:155], v137 offset:3072
	ds_read_b128 v[156:159], v138
	ds_read_b128 v[160:163], v138 offset:1024
	ds_read_b128 v[164:167], v138 offset:2048
	ds_read_b128 v[168:171], v138 offset:3072
	s_add_i32 m0, s51, 0xc000
	s_add_i32 s71, s51, 0xe000
	s_add_i32 s67, s70, 0x2000
	s_add_u32 s42, s40, 0x80000
	s_addc_u32 s43, s41, 0
	s_add_i32 s69, s61, s44
	s_add_i32 s68, s69, 0x2000
	s_add_i32 s66, 0, 0x18000
	s_add_i32 s65, 0, 0x1c000
	s_add_u32 s36, s38, 0x80000
	s_addc_u32 s37, s39, 0
	s_add_i32 s64, s66, s44
	s_add_i32 s21, s64, 0x2000
	s_add_u32 s30, s40, 0x80080
	s_addc_u32 s31, s41, 0
	s_add_i32 s23, s65, s44
	s_add_i32 s7, s23, 0x2000
	v_lshl_add_u64 v[204:205], s[46:47], 0, v[132:133]
	ds_read_b128 v[172:175], v139
	ds_read_b128 v[176:179], v139 offset:1024
	ds_read_b128 v[180:183], v139 offset:2048
	ds_read_b128 v[184:187], v139 offset:3072
	ds_read_b128 v[188:191], v139 offset:4096
	ds_read_b128 v[192:195], v139 offset:5120
	ds_read_b128 v[196:199], v139 offset:6144
	ds_read_b128 v[200:203], v139 offset:7168
	global_load_lds_dwordx4 v[204:205], off
	v_lshl_add_u64 v[204:205], s[46:47], 0, v[130:131]
	s_mov_b32 m0, s71
	s_nop 0
	global_load_lds_dwordx4 v[204:205], off
	s_waitcnt vmcnt(8)
	s_waitcnt lgkmcnt(0)
	s_setprio 1
	s_barrier
	v_mfma_f32_16x16x32_bf16 v[126:129], v[140:143], v[172:175], v[126:129]
	v_mfma_f32_16x16x32_bf16 v[122:125], v[148:151], v[172:175], v[122:125]
	v_mfma_f32_16x16x32_bf16 v[118:121], v[140:143], v[180:183], v[118:121]
	v_mfma_f32_16x16x32_bf16 v[114:117], v[148:151], v[180:183], v[114:117]
	v_mfma_f32_16x16x32_bf16 v[106:109], v[140:143], v[188:191], v[106:109]
	v_mfma_f32_16x16x32_bf16 v[98:101], v[148:151], v[188:191], v[98:101]
	v_mfma_f32_16x16x32_bf16 v[90:93], v[140:143], v[196:199], v[90:93]
	v_mfma_f32_16x16x32_bf16 v[82:85], v[148:151], v[196:199], v[82:85]
	v_mfma_f32_16x16x32_bf16 v[126:129], v[144:147], v[176:179], v[126:129]
	v_mfma_f32_16x16x32_bf16 v[122:125], v[152:155], v[176:179], v[122:125]
	v_mfma_f32_16x16x32_bf16 v[118:121], v[144:147], v[184:187], v[118:121]
	v_mfma_f32_16x16x32_bf16 v[114:117], v[152:155], v[184:187], v[114:117]
	v_mfma_f32_16x16x32_bf16 v[106:109], v[144:147], v[192:195], v[106:109]
	v_mfma_f32_16x16x32_bf16 v[98:101], v[152:155], v[192:195], v[98:101]
	v_mfma_f32_16x16x32_bf16 v[90:93], v[144:147], v[200:203], v[90:93]
	v_mfma_f32_16x16x32_bf16 v[82:85], v[152:155], v[200:203], v[82:85]
	s_setprio 0
	s_setprio 1
	v_mfma_f32_16x16x32_bf16 v[110:113], v[156:159], v[172:175], v[110:113]
	v_mfma_f32_16x16x32_bf16 v[102:105], v[164:167], v[172:175], v[102:105]
	v_mfma_f32_16x16x32_bf16 v[94:97], v[156:159], v[180:183], v[94:97]
	v_mfma_f32_16x16x32_bf16 v[86:89], v[164:167], v[180:183], v[86:89]
	v_mfma_f32_16x16x32_bf16 v[78:81], v[156:159], v[188:191], v[78:81]
	v_mfma_f32_16x16x32_bf16 v[74:77], v[164:167], v[188:191], v[74:77]
	v_mfma_f32_16x16x32_bf16 v[70:73], v[156:159], v[196:199], v[70:73]
	v_mfma_f32_16x16x32_bf16 v[66:69], v[164:167], v[196:199], v[66:69]
	v_mfma_f32_16x16x32_bf16 v[110:113], v[160:163], v[176:179], v[110:113]
	v_mfma_f32_16x16x32_bf16 v[102:105], v[168:171], v[176:179], v[102:105]
	v_mfma_f32_16x16x32_bf16 v[94:97], v[160:163], v[184:187], v[94:97]
	v_mfma_f32_16x16x32_bf16 v[86:89], v[168:171], v[184:187], v[86:89]
	v_mfma_f32_16x16x32_bf16 v[78:81], v[160:163], v[192:195], v[78:81]
	v_mfma_f32_16x16x32_bf16 v[74:77], v[168:171], v[192:195], v[74:77]
	v_mfma_f32_16x16x32_bf16 v[70:73], v[160:163], v[200:203], v[70:73]
	v_mfma_f32_16x16x32_bf16 v[66:69], v[168:171], v[200:203], v[66:69]
	s_setprio 0
	s_barrier
	s_mov_b32 m0, s70
	v_lshl_add_u64 v[204:205], s[40:41], 0, v[132:133]
	ds_read_b128 v[172:175], v139 offset:16384
	ds_read_b128 v[176:179], v139 offset:17408
	ds_read_b128 v[180:183], v139 offset:18432
	ds_read_b128 v[184:187], v139 offset:19456
	ds_read_b128 v[188:191], v139 offset:20480
	ds_read_b128 v[192:195], v139 offset:21504
	ds_read_b128 v[196:199], v139 offset:22528
	ds_read_b128 v[200:203], v139 offset:23552
	global_load_lds_dwordx4 v[204:205], off
	v_lshl_add_u64 v[206:207], s[40:41], 0, v[130:131]
	s_mov_b32 m0, s67
	v_lshl_add_u64 v[208:209], s[42:43], 0, v[132:133]
	global_load_lds_dwordx4 v[206:207], off
	s_mov_b32 m0, s69
	v_lshl_add_u64 v[210:211], s[38:39], 0, v[130:131]
	global_load_lds_dwordx4 v[208:209], off
	v_lshl_add_u64 v[208:209], s[42:43], 0, v[130:131]
	s_mov_b32 m0, s68
	s_nop 0
	global_load_lds_dwordx4 v[208:209], off
	v_lshl_add_u64 v[208:209], s[38:39], 0, v[132:133]
	s_mov_b32 m0, s51
	s_nop 0
	global_load_lds_dwordx4 v[208:209], off
	s_mov_b32 m0, s52
	s_nop 0
	global_load_lds_dwordx4 v[210:211], off
	s_waitcnt vmcnt(8)
	s_waitcnt lgkmcnt(0)
	s_setprio 1
	s_barrier
; #define PG8_STAGE(bufoff, gbase, voff) do { _Pragma("unroll") for (int _i = 0; _i < 2; ++_i) \
;         __builtin_amdgcn_global_load_lds((const unsigned*)((const char*)(gbase) + (voff)[_i]), (PG8_LAS unsigned*)(lds + (bufoff) + ldsw + _i * 8192), 16, 0, 0); } while (0)
; #define PG8_LDA(dst, b, h) do { _Pragma("unroll") for (int m = 0; m < 4; ++m) _Pragma("unroll") for (int k = 0; k < 2; ++k) dst[m][k] = *(const PG8_LAS bf16x8*)(lds + PG8_SA(b, h) + aoff + m * 2048 + k * 1024); } while (0)
; #define PG8_LDB(dst, b, h) do { _Pragma("unroll") for (int n = 0; n < 2; ++n) _Pragma("unroll") for (int k = 0; k < 2; ++k) dst[n][k] = *(const PG8_LAS bf16x8*)(lds + PG8_SB(b, h) + boff + n * 2048 + k * 1024); } while (0)
; #define PG8_MMA(ai, bj, At, Bt) do { __builtin_amdgcn_s_setprio(1); _Pragma("unroll") for (int m = 0; m < 4; ++m) _Pragma("unroll") for (int n = 0; n < 2; ++n) _Pragma("unroll") for (int k = 0; k < 2; ++k) \
;         acc[ai][bj][m][n] = __builtin_amdgcn_mfma_f32_16x16x32_bf16(Bt[n][k], At[m][k], acc[ai][bj][m][n], 0, 0, 0); __builtin_amdgcn_s_setprio(0); } while (0)
; #define PG8_WAIT_V(n) asm volatile("s_waitcnt vmcnt(" #n ")" ::: "memory")
; template <class Epi, class Sched, bool ALIGN_EPI = false, bool SP2 = false>
; __device__ __forceinline__ void gemm_phase(PG8_LAS unsigned char* lds, const Gemm g, const Sched& S, const Epi& E) {
;     ...
;             PG8_LDB(B0, 0, 0); PG8_LDB(B1, 0, 1); PG8_SCHED; PG8_LDA(At, 0, 0); PG8_STAGE(PG8_SA(1, 1), a1 + hstep, voffA);
;             PG8_WAIT_V(8); PG8_WAIT_L(0); PG8_BAR; PG8_MMA(0, 0, At, B0); PG8_MMA(0, 1, At, B1); PG8_BAR; PG8_SCHED;
;             PG8_LDA(At, 0, 1); PG8_STAGE(PG8_SB(0, 0), b2, voffB); PG8_STAGE(PG8_SB(0, 1), b2 + hstep, voffB); PG8_STAGE(PG8_SA(0, 0), a2, voffA);
;             PG8_WAIT_V(8); PG8_WAIT_L(0); PG8_BAR; PG8_MMA(1, 0, At, B0); PG8_MMA(1, 1, At, B1); PG8_BAR; PG8_SCHED;
;             PG8_LDB(B0, 1, 0); PG8_LDB(B1, 1, 1); PG8_SCHED; PG8_LDA(At, 1, 0); PG8_STAGE(PG8_SA(0, 1), a2 + hstep, voffA);
;             PG8_WAIT_V(8); PG8_WAIT_L(0); PG8_BAR; PG8_MMA(0, 0, At, B0); PG8_MMA(0, 1, At, B1); PG8_BAR; PG8_SCHED;
;             PG8_LDA(At, 1, 1); PG8_STAGE(PG8_SB(1, 0), b3, voffB); PG8_STAGE(PG8_SB(1, 1), b3 + hstep, voffB); PG8_STAGE(PG8_SA(1, 0), a3, voffA);
;             PG8_WAIT_V(8); PG8_WAIT_L(0); PG8_BAR; PG8_MMA(1, 0, At, B0); PG8_MMA(1, 1, At, B1); PG8_BAR; PG8_SCHED;
	v_mfma_f32_16x16x32_bf16 v[62:65], v[140:143], v[172:175], v[62:65]
	v_mfma_f32_16x16x32_bf16 v[58:61], v[148:151], v[172:175], v[58:61]
	v_mfma_f32_16x16x32_bf16 v[54:57], v[140:143], v[180:183], v[54:57]
	v_mfma_f32_16x16x32_bf16 v[50:53], v[148:151], v[180:183], v[50:53]
	v_mfma_f32_16x16x32_bf16 v[38:41], v[140:143], v[188:191], v[38:41]
	v_mfma_f32_16x16x32_bf16 v[34:37], v[148:151], v[188:191], v[34:37]
	v_mfma_f32_16x16x32_bf16 v[22:25], v[140:143], v[196:199], v[22:25]
	v_mfma_f32_16x16x32_bf16 v[18:21], v[148:151], v[196:199], v[18:21]
	v_mfma_f32_16x16x32_bf16 v[62:65], v[144:147], v[176:179], v[62:65]
	v_mfma_f32_16x16x32_bf16 v[58:61], v[152:155], v[176:179], v[58:61]
	v_mfma_f32_16x16x32_bf16 v[54:57], v[144:147], v[184:187], v[54:57]
	v_mfma_f32_16x16x32_bf16 v[50:53], v[152:155], v[184:187], v[50:53]
	v_mfma_f32_16x16x32_bf16 v[38:41], v[144:147], v[192:195], v[38:41]
	v_mfma_f32_16x16x32_bf16 v[34:37], v[152:155], v[192:195], v[34:37]
	v_mfma_f32_16x16x32_bf16 v[22:25], v[144:147], v[200:203], v[22:25]
	v_mfma_f32_16x16x32_bf16 v[18:21], v[152:155], v[200:203], v[18:21]
	s_setprio 0
	s_setprio 1
	v_mfma_f32_16x16x32_bf16 v[46:49], v[156:159], v[172:175], v[46:49]
	v_mfma_f32_16x16x32_bf16 v[42:45], v[164:167], v[172:175], v[42:45]
	v_mfma_f32_16x16x32_bf16 v[30:33], v[156:159], v[180:183], v[30:33]
	v_mfma_f32_16x16x32_bf16 v[26:29], v[164:167], v[180:183], v[26:29]
	v_mfma_f32_16x16x32_bf16 v[14:17], v[156:159], v[188:191], v[14:17]
	v_mfma_f32_16x16x32_bf16 v[10:13], v[164:167], v[188:191], v[10:13]
	v_mfma_f32_16x16x32_bf16 v[6:9], v[156:159], v[196:199], v[6:9]
	v_mfma_f32_16x16x32_bf16 v[2:5], v[164:167], v[196:199], v[2:5]
	v_mfma_f32_16x16x32_bf16 v[46:49], v[160:163], v[176:179], v[46:49]
	v_mfma_f32_16x16x32_bf16 v[42:45], v[168:171], v[176:179], v[42:45]
	v_mfma_f32_16x16x32_bf16 v[30:33], v[160:163], v[184:187], v[30:33]
	v_mfma_f32_16x16x32_bf16 v[26:29], v[168:171], v[184:187], v[26:29]
	v_mfma_f32_16x16x32_bf16 v[14:17], v[160:163], v[192:195], v[14:17]
	v_mfma_f32_16x16x32_bf16 v[10:13], v[168:171], v[192:195], v[10:13]
	v_mfma_f32_16x16x32_bf16 v[6:9], v[160:163], v[200:203], v[6:9]
	v_mfma_f32_16x16x32_bf16 v[2:5], v[168:171], v[200:203], v[2:5]
	s_setprio 0
	s_barrier
	v_add_u32_e32 v152, s66, v134
	v_add_u32_e32 v168, s65, v134
	ds_read_b128 v[140:143], v152
	ds_read_b128 v[144:147], v152 offset:1024
	ds_read_b128 v[148:151], v152 offset:2048
	ds_read_b128 v[152:155], v152 offset:3072
	ds_read_b128 v[156:159], v168
	ds_read_b128 v[160:163], v168 offset:1024
	ds_read_b128 v[164:167], v168 offset:2048
	ds_read_b128 v[168:171], v168 offset:3072
	s_mov_b32 m0, s53
	v_lshl_add_u64 v[212:213], s[36:37], 0, v[132:133]
	ds_read_b128 v[172:175], v139 offset:32768
	ds_read_b128 v[176:179], v139 offset:33792
	ds_read_b128 v[180:183], v139 offset:34816
	ds_read_b128 v[184:187], v139 offset:35840
	ds_read_b128 v[188:191], v139 offset:36864
	ds_read_b128 v[192:195], v139 offset:37888
	ds_read_b128 v[196:199], v139 offset:38912
	ds_read_b128 v[200:203], v139 offset:39936
	global_load_lds_dwordx4 v[212:213], off
	v_lshl_add_u64 v[212:213], s[36:37], 0, v[130:131]
	s_mov_b32 m0, s54
	s_nop 0
	global_load_lds_dwordx4 v[212:213], off
	s_waitcnt vmcnt(8)
	s_waitcnt lgkmcnt(0)
	s_setprio 1
	s_barrier
	v_mfma_f32_16x16x32_bf16 v[126:129], v[140:143], v[172:175], v[126:129]
	v_mfma_f32_16x16x32_bf16 v[122:125], v[148:151], v[172:175], v[122:125]
	v_mfma_f32_16x16x32_bf16 v[118:121], v[140:143], v[180:183], v[118:121]
	v_mfma_f32_16x16x32_bf16 v[114:117], v[148:151], v[180:183], v[114:117]
	v_mfma_f32_16x16x32_bf16 v[106:109], v[140:143], v[188:191], v[106:109]
	v_mfma_f32_16x16x32_bf16 v[98:101], v[148:151], v[188:191], v[98:101]
	v_mfma_f32_16x16x32_bf16 v[90:93], v[140:143], v[196:199], v[90:93]
	v_mfma_f32_16x16x32_bf16 v[82:85], v[148:151], v[196:199], v[82:85]
	v_mfma_f32_16x16x32_bf16 v[126:129], v[144:147], v[176:179], v[126:129]
	v_mfma_f32_16x16x32_bf16 v[122:125], v[152:155], v[176:179], v[122:125]
	v_mfma_f32_16x16x32_bf16 v[118:121], v[144:147], v[184:187], v[118:121]
	v_mfma_f32_16x16x32_bf16 v[114:117], v[152:155], v[184:187], v[114:117]
	v_mfma_f32_16x16x32_bf16 v[106:109], v[144:147], v[192:195], v[106:109]
	v_mfma_f32_16x16x32_bf16 v[98:101], v[152:155], v[192:195], v[98:101]
	v_mfma_f32_16x16x32_bf16 v[90:93], v[144:147], v[200:203], v[90:93]
	v_mfma_f32_16x16x32_bf16 v[82:85], v[152:155], v[200:203], v[82:85]
	s_setprio 0
	s_setprio 1
	v_mfma_f32_16x16x32_bf16 v[110:113], v[156:159], v[172:175], v[110:113]
	v_mfma_f32_16x16x32_bf16 v[102:105], v[164:167], v[172:175], v[102:105]
	v_mfma_f32_16x16x32_bf16 v[94:97], v[156:159], v[180:183], v[94:97]
	v_mfma_f32_16x16x32_bf16 v[86:89], v[164:167], v[180:183], v[86:89]
	v_mfma_f32_16x16x32_bf16 v[78:81], v[156:159], v[188:191], v[78:81]
	v_mfma_f32_16x16x32_bf16 v[74:77], v[164:167], v[188:191], v[74:77]
	v_mfma_f32_16x16x32_bf16 v[70:73], v[156:159], v[196:199], v[70:73]
	v_mfma_f32_16x16x32_bf16 v[66:69], v[164:167], v[196:199], v[66:69]
	v_mfma_f32_16x16x32_bf16 v[110:113], v[160:163], v[176:179], v[110:113]
	v_mfma_f32_16x16x32_bf16 v[102:105], v[168:171], v[176:179], v[102:105]
	v_mfma_f32_16x16x32_bf16 v[94:97], v[160:163], v[184:187], v[94:97]
	v_mfma_f32_16x16x32_bf16 v[86:89], v[168:171], v[184:187], v[86:89]
	v_mfma_f32_16x16x32_bf16 v[78:81], v[160:163], v[192:195], v[78:81]
	v_mfma_f32_16x16x32_bf16 v[74:77], v[168:171], v[192:195], v[74:77]
	v_mfma_f32_16x16x32_bf16 v[70:73], v[160:163], v[200:203], v[70:73]
	v_mfma_f32_16x16x32_bf16 v[66:69], v[168:171], v[200:203], v[66:69]
	s_setprio 0
	s_barrier
; #define PG8_STAGE(bufoff, gbase, voff) do { _Pragma("unroll") for (int _i = 0; _i < 2; ++_i) \
;         __builtin_amdgcn_global_load_lds((const unsigned*)((const char*)(gbase) + (voff)[_i]), (PG8_LAS unsigned*)(lds + (bufoff) + ldsw + _i * 8192), 16, 0, 0); } while (0)
; #define PG8_LDA(dst, b, h) do { _Pragma("unroll") for (int m = 0; m < 4; ++m) _Pragma("unroll") for (int k = 0; k < 2; ++k) dst[m][k] = *(const PG8_LAS bf16x8*)(lds + PG8_SA(b, h) + aoff + m * 2048 + k * 1024); } while (0)
; #define PG8_LDB(dst, b, h) do { _Pragma("unroll") for (int n = 0; n < 2; ++n) _Pragma("unroll") for (int k = 0; k < 2; ++k) dst[n][k] = *(const PG8_LAS bf16x8*)(lds + PG8_SB(b, h) + boff + n * 2048 + k * 1024); } while (0)
; #define PG8_MMA(ai, bj, At, Bt) do { __builtin_amdgcn_s_setprio(1); _Pragma("unroll") for (int m = 0; m < 4; ++m) _Pragma("unroll") for (int n = 0; n < 2; ++n) _Pragma("unroll") for (int k = 0; k < 2; ++k) \
;         acc[ai][bj][m][n] = __builtin_amdgcn_mfma_f32_16x16x32_bf16(Bt[n][k], At[m][k], acc[ai][bj][m][n], 0, 0, 0); __builtin_amdgcn_s_setprio(0); } while (0)
; #define PG8_WAIT_V(n) asm volatile("s_waitcnt vmcnt(" #n ")" ::: "memory")
; #define PG8_WAIT_L(n) asm volatile("s_waitcnt lgkmcnt(" #n ")" ::: "memory")
; #define PG8_BAR __builtin_amdgcn_s_barrier()
; #define PG8_SCHED __builtin_amdgcn_sched_barrier(0)
; template <class Epi, class Sched, bool ALIGN_EPI = false, bool SP2 = false>
; __device__ __forceinline__ void gemm_phase(PG8_LAS unsigned char* lds, const Gemm g, const Sched& S, const Epi& E) {
;     ...
;             PG8_LDB(B0, 1, 0); PG8_LDB(B1, 1, 1); PG8_SCHED; PG8_LDA(At, 1, 0); PG8_STAGE(PG8_SA(0, 1), a2 + hstep, voffA);
;             PG8_WAIT_V(8); PG8_WAIT_L(0); PG8_BAR; PG8_MMA(0, 0, At, B0); PG8_MMA(0, 1, At, B1); PG8_BAR; PG8_SCHED;
;             PG8_LDA(At, 1, 1); PG8_STAGE(PG8_SB(1, 0), b3, voffB); PG8_STAGE(PG8_SB(1, 1), b3 + hstep, voffB); PG8_STAGE(PG8_SA(1, 0), a3, voffA);
;             PG8_WAIT_V(8); PG8_WAIT_L(0); PG8_BAR; PG8_MMA(1, 0, At, B0); PG8_MMA(1, 1, At, B1); PG8_BAR; PG8_SCHED;
;     ...
;         if constexpr (ALIGN_EPI) { if (wr == 0) PG8_BAR; }
	s_mov_b32 m0, s64
	v_lshl_add_u64 v[204:205], v[204:205], 0, s[12:13]
	ds_read_b128 v[172:175], v139 offset:49152
	ds_read_b128 v[176:179], v139 offset:50176
	ds_read_b128 v[180:183], v139 offset:51200
	ds_read_b128 v[184:187], v139 offset:52224
	ds_read_b128 v[188:191], v139 offset:53248
	ds_read_b128 v[192:195], v139 offset:54272
	ds_read_b128 v[196:199], v139 offset:55296
	ds_read_b128 v[200:203], v139 offset:56320
	global_load_lds_dwordx4 v[204:205], off
	v_lshl_add_u64 v[204:205], v[206:207], 0, s[12:13]
	s_mov_b32 m0, s21
	s_nop 0
	global_load_lds_dwordx4 v[204:205], off
	v_lshl_add_u64 v[204:205], s[30:31], 0, v[132:133]
	s_mov_b32 m0, s23
	s_nop 0
	global_load_lds_dwordx4 v[204:205], off
	v_lshl_add_u64 v[204:205], s[30:31], 0, v[130:131]
	s_mov_b32 m0, s7
	s_nop 0
	global_load_lds_dwordx4 v[204:205], off
	v_lshl_add_u64 v[204:205], v[208:209], 0, s[12:13]
	s_mov_b32 m0, s57
	s_nop 0
	global_load_lds_dwordx4 v[204:205], off
	v_lshl_add_u64 v[204:205], v[210:211], 0, s[12:13]
	s_mov_b32 m0, s58
	s_nop 0
	global_load_lds_dwordx4 v[204:205], off
	s_waitcnt vmcnt(8)
	s_waitcnt lgkmcnt(0)
	s_setprio 1
	s_barrier
	v_mfma_f32_16x16x32_bf16 v[62:65], v[140:143], v[172:175], v[62:65]
	v_mfma_f32_16x16x32_bf16 v[58:61], v[148:151], v[172:175], v[58:61]
	v_mfma_f32_16x16x32_bf16 v[54:57], v[140:143], v[180:183], v[54:57]
	v_mfma_f32_16x16x32_bf16 v[50:53], v[148:151], v[180:183], v[50:53]
	v_mfma_f32_16x16x32_bf16 v[38:41], v[140:143], v[188:191], v[38:41]
	v_mfma_f32_16x16x32_bf16 v[34:37], v[148:151], v[188:191], v[34:37]
	v_mfma_f32_16x16x32_bf16 v[22:25], v[140:143], v[196:199], v[22:25]
	v_mfma_f32_16x16x32_bf16 v[18:21], v[148:151], v[196:199], v[18:21]
	v_mfma_f32_16x16x32_bf16 v[62:65], v[144:147], v[176:179], v[62:65]
	v_mfma_f32_16x16x32_bf16 v[58:61], v[152:155], v[176:179], v[58:61]
	v_mfma_f32_16x16x32_bf16 v[54:57], v[144:147], v[184:187], v[54:57]
	v_mfma_f32_16x16x32_bf16 v[50:53], v[152:155], v[184:187], v[50:53]
	v_mfma_f32_16x16x32_bf16 v[38:41], v[144:147], v[192:195], v[38:41]
	v_mfma_f32_16x16x32_bf16 v[34:37], v[152:155], v[192:195], v[34:37]
	v_mfma_f32_16x16x32_bf16 v[22:25], v[144:147], v[200:203], v[22:25]
	v_mfma_f32_16x16x32_bf16 v[18:21], v[152:155], v[200:203], v[18:21]
	s_setprio 0
	s_setprio 1
	v_mfma_f32_16x16x32_bf16 v[46:49], v[156:159], v[172:175], v[46:49]
	v_mfma_f32_16x16x32_bf16 v[42:45], v[164:167], v[172:175], v[42:45]
	v_mfma_f32_16x16x32_bf16 v[30:33], v[156:159], v[180:183], v[30:33]
	v_mfma_f32_16x16x32_bf16 v[26:29], v[164:167], v[180:183], v[26:29]
	v_mfma_f32_16x16x32_bf16 v[14:17], v[156:159], v[188:191], v[14:17]
	v_mfma_f32_16x16x32_bf16 v[10:13], v[164:167], v[188:191], v[10:13]
	v_mfma_f32_16x16x32_bf16 v[6:9], v[156:159], v[196:199], v[6:9]
	v_mfma_f32_16x16x32_bf16 v[2:5], v[164:167], v[196:199], v[2:5]
	v_mfma_f32_16x16x32_bf16 v[46:49], v[160:163], v[176:179], v[46:49]
	v_mfma_f32_16x16x32_bf16 v[42:45], v[168:171], v[176:179], v[42:45]
	v_mfma_f32_16x16x32_bf16 v[30:33], v[160:163], v[184:187], v[30:33]
	v_mfma_f32_16x16x32_bf16 v[26:29], v[168:171], v[184:187], v[26:29]
	v_mfma_f32_16x16x32_bf16 v[14:17], v[160:163], v[192:195], v[14:17]
	v_mfma_f32_16x16x32_bf16 v[10:13], v[168:171], v[192:195], v[10:13]
	v_mfma_f32_16x16x32_bf16 v[6:9], v[160:163], v[200:203], v[6:9]
	v_mfma_f32_16x16x32_bf16 v[2:5], v[168:171], v[200:203], v[2:5]
	s_setprio 0
	s_movk_i32 s7, 0x100
	s_andn2_b64 vcc, exec, s[28:29]
	s_mov_b64 s[30:31], -1
	s_mov_b64 s[28:29], 0
	s_barrier
	s_cbranch_vccz .LBB0_1428
	s_and_b64 vcc, exec, s[18:19]
	s_cbranch_vccz .LBB0_1431
	s_barrier

; #define PG8_STAGE(bufoff, gbase, voff) do { _Pragma("unroll") for (int _i = 0; _i < 2; ++_i) \
;         __builtin_amdgcn_global_load_lds((const unsigned*)((const char*)(gbase) + (voff)[_i]), (PG8_LAS unsigned*)(lds + (bufoff) + ldsw + _i * 8192), 16, 0, 0); } while (0)
; #define PG8_LDA(dst, b, h) do { _Pragma("unroll") for (int m = 0; m < 4; ++m) _Pragma("unroll") for (int k = 0; k < 2; ++k) dst[m][k] = *(const PG8_LAS bf16x8*)(lds + PG8_SA(b, h) + aoff + m * 2048 + k * 1024); } while (0)
; #define PG8_LDB(dst, b, h) do { _Pragma("unroll") for (int n = 0; n < 2; ++n) _Pragma("unroll") for (int k = 0; k < 2; ++k) dst[n][k] = *(const PG8_LAS bf16x8*)(lds + PG8_SB(b, h) + boff + n * 2048 + k * 1024); } while (0)
; #define PG8_MMA(ai, bj, At, Bt) do { __builtin_amdgcn_s_setprio(1); _Pragma("unroll") for (int m = 0; m < 4; ++m) _Pragma("unroll") for (int n = 0; n < 2; ++n) _Pragma("unroll") for (int k = 0; k < 2; ++k) \
;         acc[ai][bj][m][n] = __builtin_amdgcn_mfma_f32_16x16x32_bf16(Bt[n][k], At[m][k], acc[ai][bj][m][n], 0, 0, 0); __builtin_amdgcn_s_setprio(0); } while (0)
; #define PG8_BAR __builtin_amdgcn_s_barrier()
; template <class Epi, class Sched, bool ALIGN_EPI = false, bool SP2 = false>
; __device__ __forceinline__ void gemm_phase(PG8_LAS unsigned char* lds, const Gemm g, const Sched& S, const Epi& E) {
;     ...
;         for (int t = 0; t < nt; t += 2) {
;             if constexpr (Epi::MIDHOOK) { if (t == (nt >> 1)) E.mid(acc, cur, wr, wc, fr, fq); }
;             const bool last = (t == nt - 2);
;             const char* a1 = cA + (size_t)(t + 1) * kstep;
;             const char* a2 = last ? nA : cA + (size_t)(t + 2) * kstep; const char* b2 = last ? nB : cB + (size_t)(t + 2) * kstep;
;             const char* a3 = a2 + kstep; const char* b3 = b2 + kstep;
;             if (last && has_next) S.a_ready(nxt);
;             if constexpr (SP2) {
;             PG8_LDB(B0, 0, 0); PG8_LDB(B1, 0, 1); PG8_SCHED; PG8_LDA(At, 0, 0); PG8_STAGE(PG8_SA(1, 1), a1 + hstep, voffA);
;             PG8_WAIT_V(8); PG8_WAIT_L(0); PG8_BAR; PG8_MMA(0, 0, At, B0); PG8_MMA(0, 1, At, B1); PG8_BAR; PG8_SCHED;
;             PG8_LDA(At, 0, 1); PG8_STAGE(PG8_SB(0, 0), b2, voffB); PG8_STAGE(PG8_SB(0, 1), b2 + hstep, voffB); PG8_STAGE(PG8_SA(0, 0), a2, voffA);
;             PG8_WAIT_V(8); PG8_WAIT_L(0); PG8_BAR; PG8_MMA(1, 0, At, B0); PG8_MMA(1, 1, At, B1); PG8_BAR; PG8_SCHED;
.LBB0_1551:
	ds_read_b128 v[146:149], v153
	ds_read_b128 v[156:159], v153 offset:1024
	ds_read_b128 v[160:163], v153 offset:2048
	ds_read_b128 v[164:167], v153 offset:3072
	ds_read_b128 v[168:171], v154
	ds_read_b128 v[172:175], v154 offset:1024
	ds_read_b128 v[176:179], v154 offset:2048
	ds_read_b128 v[180:183], v154 offset:3072
	s_add_u32 s26, s24, 0xfff80080
	s_addc_u32 s27, s25, -1
	s_cmp_eq_u32 s52, 28
	s_cselect_b32 s29, s17, s27
	s_cselect_b32 s28, s48, s26
	s_cselect_b32 s27, s15, s51
	s_cselect_b32 s26, s49, s50
	v_lshl_add_u64 v[216:217], s[24:25], 0, v[138:139]
	s_add_i32 m0, s23, 0xc000
	ds_read_b128 v[184:187], v155
	ds_read_b128 v[188:191], v155 offset:1024
	ds_read_b128 v[192:195], v155 offset:2048
	ds_read_b128 v[196:199], v155 offset:3072
	ds_read_b128 v[200:203], v155 offset:4096
	ds_read_b128 v[204:207], v155 offset:5120
	ds_read_b128 v[208:211], v155 offset:6144
	ds_read_b128 v[212:215], v155 offset:7168
	global_load_lds_dwordx4 v[216:217], off
	v_lshl_add_u64 v[216:217], s[24:25], 0, v[140:141]
	s_add_i32 m0, s23, 0xe000
	s_nop 0
	global_load_lds_dwordx4 v[216:217], off
	s_waitcnt vmcnt(8)
	s_waitcnt lgkmcnt(0)
	s_setprio 1
	s_barrier
	v_mfma_f32_16x16x32_bf16 v[126:129], v[146:149], v[184:187], v[126:129]
	v_mfma_f32_16x16x32_bf16 v[122:125], v[160:163], v[184:187], v[122:125]
	v_mfma_f32_16x16x32_bf16 v[110:113], v[146:149], v[192:195], v[110:113]
	v_mfma_f32_16x16x32_bf16 v[106:109], v[160:163], v[192:195], v[106:109]
	v_mfma_f32_16x16x32_bf16 v[94:97], v[146:149], v[200:203], v[94:97]
	v_mfma_f32_16x16x32_bf16 v[90:93], v[160:163], v[200:203], v[90:93]
	v_mfma_f32_16x16x32_bf16 v[78:81], v[146:149], v[208:211], v[78:81]
	v_mfma_f32_16x16x32_bf16 v[74:77], v[160:163], v[208:211], v[74:77]
	v_mfma_f32_16x16x32_bf16 v[126:129], v[156:159], v[188:191], v[126:129]
	v_mfma_f32_16x16x32_bf16 v[122:125], v[164:167], v[188:191], v[122:125]
	v_mfma_f32_16x16x32_bf16 v[110:113], v[156:159], v[196:199], v[110:113]
	v_mfma_f32_16x16x32_bf16 v[106:109], v[164:167], v[196:199], v[106:109]
	v_mfma_f32_16x16x32_bf16 v[94:97], v[156:159], v[204:207], v[94:97]
	v_mfma_f32_16x16x32_bf16 v[90:93], v[164:167], v[204:207], v[90:93]
	v_mfma_f32_16x16x32_bf16 v[78:81], v[156:159], v[212:215], v[78:81]
	v_mfma_f32_16x16x32_bf16 v[74:77], v[164:167], v[212:215], v[74:77]
	s_setprio 0
	s_setprio 1
	v_mfma_f32_16x16x32_bf16 v[118:121], v[168:171], v[184:187], v[118:121]
	v_mfma_f32_16x16x32_bf16 v[114:117], v[176:179], v[184:187], v[114:117]
	v_mfma_f32_16x16x32_bf16 v[102:105], v[168:171], v[192:195], v[102:105]
	v_mfma_f32_16x16x32_bf16 v[98:101], v[176:179], v[192:195], v[98:101]
	v_mfma_f32_16x16x32_bf16 v[86:89], v[168:171], v[200:203], v[86:89]
	v_mfma_f32_16x16x32_bf16 v[82:85], v[176:179], v[200:203], v[82:85]
	v_mfma_f32_16x16x32_bf16 v[70:73], v[168:171], v[208:211], v[70:73]
	v_mfma_f32_16x16x32_bf16 v[66:69], v[176:179], v[208:211], v[66:69]
	v_mfma_f32_16x16x32_bf16 v[118:121], v[172:175], v[188:191], v[118:121]
	v_mfma_f32_16x16x32_bf16 v[114:117], v[180:183], v[188:191], v[114:117]
	v_mfma_f32_16x16x32_bf16 v[102:105], v[172:175], v[196:199], v[102:105]
	v_mfma_f32_16x16x32_bf16 v[98:101], v[180:183], v[196:199], v[98:101]
	v_mfma_f32_16x16x32_bf16 v[86:89], v[172:175], v[204:207], v[86:89]
	v_mfma_f32_16x16x32_bf16 v[82:85], v[180:183], v[204:207], v[82:85]
	v_mfma_f32_16x16x32_bf16 v[70:73], v[172:175], v[212:215], v[70:73]
	v_mfma_f32_16x16x32_bf16 v[66:69], v[180:183], v[212:215], v[66:69]
	s_setprio 0
	s_barrier
	s_add_i32 s53, s44, s31
	v_lshl_add_u64 v[216:217], s[26:27], 0, v[134:135]
	s_mov_b32 m0, s53
	ds_read_b128 v[184:187], v155 offset:16384
	ds_read_b128 v[188:191], v155 offset:17408
	ds_read_b128 v[192:195], v155 offset:18432
	ds_read_b128 v[196:199], v155 offset:19456
	ds_read_b128 v[200:203], v155 offset:20480
	ds_read_b128 v[204:207], v155 offset:21504
	ds_read_b128 v[208:211], v155 offset:22528
	ds_read_b128 v[212:215], v155 offset:23552
	global_load_lds_dwordx4 v[216:217], off
	s_add_i32 m0, s53, 0x2000
	s_add_u32 s54, s26, 0x80000
	v_lshl_add_u64 v[218:219], s[26:27], 0, v[130:131]
	s_addc_u32 s55, s27, 0
	s_add_i32 s53, s45, s31
	global_load_lds_dwordx4 v[218:219], off
	v_lshl_add_u64 v[220:221], s[54:55], 0, v[134:135]
	s_mov_b32 m0, s53
	v_lshl_add_u64 v[222:223], s[28:29], 0, v[132:133]
	global_load_lds_dwordx4 v[220:221], off
	v_lshl_add_u64 v[220:221], s[54:55], 0, v[130:131]
	s_add_i32 m0, s53, 0x2000
	s_nop 0
	global_load_lds_dwordx4 v[220:221], off
	v_lshl_add_u64 v[220:221], s[28:29], 0, v[136:137]
	s_mov_b32 m0, s23
	s_nop 0
	global_load_lds_dwordx4 v[220:221], off
	s_mov_b32 m0, s37
	s_nop 0
	global_load_lds_dwordx4 v[222:223], off
	s_waitcnt vmcnt(8)
	s_waitcnt lgkmcnt(0)
	s_setprio 1
	s_barrier
; #define PG8_STAGE(bufoff, gbase, voff) do { _Pragma("unroll") for (int _i = 0; _i < 2; ++_i) \
;         __builtin_amdgcn_global_load_lds((const unsigned*)((const char*)(gbase) + (voff)[_i]), (PG8_LAS unsigned*)(lds + (bufoff) + ldsw + _i * 8192), 16, 0, 0); } while (0)
; #define PG8_LDA(dst, b, h) do { _Pragma("unroll") for (int m = 0; m < 4; ++m) _Pragma("unroll") for (int k = 0; k < 2; ++k) dst[m][k] = *(const PG8_LAS bf16x8*)(lds + PG8_SA(b, h) + aoff + m * 2048 + k * 1024); } while (0)
; #define PG8_LDB(dst, b, h) do { _Pragma("unroll") for (int n = 0; n < 2; ++n) _Pragma("unroll") for (int k = 0; k < 2; ++k) dst[n][k] = *(const PG8_LAS bf16x8*)(lds + PG8_SB(b, h) + boff + n * 2048 + k * 1024); } while (0)
; #define PG8_MMA(ai, bj, At, Bt) do { __builtin_amdgcn_s_setprio(1); _Pragma("unroll") for (int m = 0; m < 4; ++m) _Pragma("unroll") for (int n = 0; n < 2; ++n) _Pragma("unroll") for (int k = 0; k < 2; ++k) \
;         acc[ai][bj][m][n] = __builtin_amdgcn_mfma_f32_16x16x32_bf16(Bt[n][k], At[m][k], acc[ai][bj][m][n], 0, 0, 0); __builtin_amdgcn_s_setprio(0); } while (0)
; #define PG8_WAIT_V(n) asm volatile("s_waitcnt vmcnt(" #n ")" ::: "memory")
; #define PG8_WAIT_L(n) asm volatile("s_waitcnt lgkmcnt(" #n ")" ::: "memory")
; #define PG8_BAR __builtin_amdgcn_s_barrier()
; #define PG8_SCHED __builtin_amdgcn_sched_barrier(0)
; template <class Epi, class Sched, bool ALIGN_EPI = false, bool SP2 = false>
; __device__ __forceinline__ void gemm_phase(PG8_LAS unsigned char* lds, const Gemm g, const Sched& S, const Epi& E) {
;     ...
;             PG8_WAIT_V(8); PG8_WAIT_L(0); PG8_BAR; PG8_MMA(1, 0, At, B0); PG8_MMA(1, 1, At, B1); PG8_BAR; PG8_SCHED;
;             PG8_LDB(B0, 1, 0); PG8_LDB(B1, 1, 1); PG8_SCHED; PG8_LDA(At, 1, 0); PG8_STAGE(PG8_SA(0, 1), a2 + hstep, voffA);
;             PG8_WAIT_V(8); PG8_WAIT_L(0); PG8_BAR; PG8_MMA(0, 0, At, B0); PG8_MMA(0, 1, At, B1); PG8_BAR; PG8_SCHED;
;             PG8_LDA(At, 1, 1); PG8_STAGE(PG8_SB(1, 0), b3, voffB); PG8_STAGE(PG8_SB(1, 1), b3 + hstep, voffB); PG8_STAGE(PG8_SA(1, 0), a3, voffA);
	v_mfma_f32_16x16x32_bf16 v[62:65], v[146:149], v[184:187], v[62:65]
	v_mfma_f32_16x16x32_bf16 v[58:61], v[160:163], v[184:187], v[58:61]
	v_mfma_f32_16x16x32_bf16 v[46:49], v[146:149], v[192:195], v[46:49]
	v_mfma_f32_16x16x32_bf16 v[42:45], v[160:163], v[192:195], v[42:45]
	v_mfma_f32_16x16x32_bf16 v[30:33], v[146:149], v[200:203], v[30:33]
	v_mfma_f32_16x16x32_bf16 v[26:29], v[160:163], v[200:203], v[26:29]
	v_mfma_f32_16x16x32_bf16 v[14:17], v[146:149], v[208:211], v[14:17]
	v_mfma_f32_16x16x32_bf16 v[10:13], v[160:163], v[208:211], v[10:13]
	v_mfma_f32_16x16x32_bf16 v[62:65], v[156:159], v[188:191], v[62:65]
	v_mfma_f32_16x16x32_bf16 v[58:61], v[164:167], v[188:191], v[58:61]
	v_mfma_f32_16x16x32_bf16 v[46:49], v[156:159], v[196:199], v[46:49]
	v_mfma_f32_16x16x32_bf16 v[42:45], v[164:167], v[196:199], v[42:45]
	v_mfma_f32_16x16x32_bf16 v[30:33], v[156:159], v[204:207], v[30:33]
	v_mfma_f32_16x16x32_bf16 v[26:29], v[164:167], v[204:207], v[26:29]
	v_mfma_f32_16x16x32_bf16 v[14:17], v[156:159], v[212:215], v[14:17]
	v_mfma_f32_16x16x32_bf16 v[10:13], v[164:167], v[212:215], v[10:13]
	s_setprio 0
	s_setprio 1
	v_mfma_f32_16x16x32_bf16 v[54:57], v[168:171], v[184:187], v[54:57]
	v_mfma_f32_16x16x32_bf16 v[50:53], v[176:179], v[184:187], v[50:53]
	v_mfma_f32_16x16x32_bf16 v[38:41], v[168:171], v[192:195], v[38:41]
	v_mfma_f32_16x16x32_bf16 v[34:37], v[176:179], v[192:195], v[34:37]
	v_mfma_f32_16x16x32_bf16 v[22:25], v[168:171], v[200:203], v[22:25]
	v_mfma_f32_16x16x32_bf16 v[18:21], v[176:179], v[200:203], v[18:21]
	v_mfma_f32_16x16x32_bf16 v[6:9], v[168:171], v[208:211], v[6:9]
	v_mfma_f32_16x16x32_bf16 v[2:5], v[176:179], v[208:211], v[2:5]
	v_mfma_f32_16x16x32_bf16 v[54:57], v[172:175], v[188:191], v[54:57]
	v_mfma_f32_16x16x32_bf16 v[50:53], v[180:183], v[188:191], v[50:53]
	v_mfma_f32_16x16x32_bf16 v[38:41], v[172:175], v[196:199], v[38:41]
	v_mfma_f32_16x16x32_bf16 v[34:37], v[180:183], v[196:199], v[34:37]
	v_mfma_f32_16x16x32_bf16 v[22:25], v[172:175], v[204:207], v[22:25]
	v_mfma_f32_16x16x32_bf16 v[18:21], v[180:183], v[204:207], v[18:21]
	v_mfma_f32_16x16x32_bf16 v[6:9], v[172:175], v[212:215], v[6:9]
	v_mfma_f32_16x16x32_bf16 v[2:5], v[180:183], v[212:215], v[2:5]
	s_setprio 0
	s_barrier
	s_add_i32 s53, 0, 0x18000
	s_add_i32 s54, 0, 0x1c000
	v_add_u32_e32 v164, s53, v151
	v_add_u32_e32 v180, s54, v151
	ds_read_b128 v[146:149], v164
	ds_read_b128 v[156:159], v164 offset:1024
	ds_read_b128 v[160:163], v164 offset:2048
	ds_read_b128 v[164:167], v164 offset:3072
	ds_read_b128 v[168:171], v180
	ds_read_b128 v[172:175], v180 offset:1024
	ds_read_b128 v[176:179], v180 offset:2048
	ds_read_b128 v[180:183], v180 offset:3072
	s_add_u32 s28, s28, 0x80000
	s_addc_u32 s29, s29, 0
	s_mov_b32 m0, s38
	v_lshl_add_u64 v[224:225], s[28:29], 0, v[136:137]
	ds_read_b128 v[184:187], v155 offset:32768
	ds_read_b128 v[188:191], v155 offset:33792
	ds_read_b128 v[192:195], v155 offset:34816
	ds_read_b128 v[196:199], v155 offset:35840
	ds_read_b128 v[200:203], v155 offset:36864
	ds_read_b128 v[204:207], v155 offset:37888
	ds_read_b128 v[208:211], v155 offset:38912
	ds_read_b128 v[212:215], v155 offset:39936
	global_load_lds_dwordx4 v[224:225], off
	v_lshl_add_u64 v[224:225], s[28:29], 0, v[132:133]
	s_mov_b32 m0, s39
	s_nop 0
	global_load_lds_dwordx4 v[224:225], off
	s_waitcnt vmcnt(8)
	s_waitcnt lgkmcnt(0)
	s_setprio 1
	s_barrier
	v_mfma_f32_16x16x32_bf16 v[126:129], v[146:149], v[184:187], v[126:129]
	v_mfma_f32_16x16x32_bf16 v[122:125], v[160:163], v[184:187], v[122:125]
	v_mfma_f32_16x16x32_bf16 v[110:113], v[146:149], v[192:195], v[110:113]
	v_mfma_f32_16x16x32_bf16 v[106:109], v[160:163], v[192:195], v[106:109]
	v_mfma_f32_16x16x32_bf16 v[94:97], v[146:149], v[200:203], v[94:97]
	v_mfma_f32_16x16x32_bf16 v[90:93], v[160:163], v[200:203], v[90:93]
	v_mfma_f32_16x16x32_bf16 v[78:81], v[146:149], v[208:211], v[78:81]
	v_mfma_f32_16x16x32_bf16 v[74:77], v[160:163], v[208:211], v[74:77]
	v_mfma_f32_16x16x32_bf16 v[126:129], v[156:159], v[188:191], v[126:129]
	v_mfma_f32_16x16x32_bf16 v[122:125], v[164:167], v[188:191], v[122:125]
	v_mfma_f32_16x16x32_bf16 v[110:113], v[156:159], v[196:199], v[110:113]
	v_mfma_f32_16x16x32_bf16 v[106:109], v[164:167], v[196:199], v[106:109]
	v_mfma_f32_16x16x32_bf16 v[94:97], v[156:159], v[204:207], v[94:97]
	v_mfma_f32_16x16x32_bf16 v[90:93], v[164:167], v[204:207], v[90:93]
	v_mfma_f32_16x16x32_bf16 v[78:81], v[156:159], v[212:215], v[78:81]
	v_mfma_f32_16x16x32_bf16 v[74:77], v[164:167], v[212:215], v[74:77]
	s_setprio 0
	s_setprio 1
	v_mfma_f32_16x16x32_bf16 v[118:121], v[168:171], v[184:187], v[118:121]
	v_mfma_f32_16x16x32_bf16 v[114:117], v[176:179], v[184:187], v[114:117]
	v_mfma_f32_16x16x32_bf16 v[102:105], v[168:171], v[192:195], v[102:105]
	v_mfma_f32_16x16x32_bf16 v[98:101], v[176:179], v[192:195], v[98:101]
	v_mfma_f32_16x16x32_bf16 v[86:89], v[168:171], v[200:203], v[86:89]
	v_mfma_f32_16x16x32_bf16 v[82:85], v[176:179], v[200:203], v[82:85]
	v_mfma_f32_16x16x32_bf16 v[70:73], v[168:171], v[208:211], v[70:73]
	v_mfma_f32_16x16x32_bf16 v[66:69], v[176:179], v[208:211], v[66:69]
	v_mfma_f32_16x16x32_bf16 v[118:121], v[172:175], v[188:191], v[118:121]
	v_mfma_f32_16x16x32_bf16 v[114:117], v[180:183], v[188:191], v[114:117]
	v_mfma_f32_16x16x32_bf16 v[102:105], v[172:175], v[196:199], v[102:105]
	v_mfma_f32_16x16x32_bf16 v[98:101], v[180:183], v[196:199], v[98:101]
	v_mfma_f32_16x16x32_bf16 v[86:89], v[172:175], v[204:207], v[86:89]
	v_mfma_f32_16x16x32_bf16 v[82:85], v[180:183], v[204:207], v[82:85]
	v_mfma_f32_16x16x32_bf16 v[70:73], v[172:175], v[212:215], v[70:73]
	v_mfma_f32_16x16x32_bf16 v[66:69], v[180:183], v[212:215], v[66:69]
	s_setprio 0
	s_barrier
; #define PG8_STAGE(bufoff, gbase, voff) do { _Pragma("unroll") for (int _i = 0; _i < 2; ++_i) \
;         __builtin_amdgcn_global_load_lds((const unsigned*)((const char*)(gbase) + (voff)[_i]), (PG8_LAS unsigned*)(lds + (bufoff) + ldsw + _i * 8192), 16, 0, 0); } while (0)
; #define PG8_LDA(dst, b, h) do { _Pragma("unroll") for (int m = 0; m < 4; ++m) _Pragma("unroll") for (int k = 0; k < 2; ++k) dst[m][k] = *(const PG8_LAS bf16x8*)(lds + PG8_SA(b, h) + aoff + m * 2048 + k * 1024); } while (0)
; #define PG8_MMA(ai, bj, At, Bt) do { __builtin_amdgcn_s_setprio(1); _Pragma("unroll") for (int m = 0; m < 4; ++m) _Pragma("unroll") for (int n = 0; n < 2; ++n) _Pragma("unroll") for (int k = 0; k < 2; ++k) \
;         acc[ai][bj][m][n] = __builtin_amdgcn_mfma_f32_16x16x32_bf16(Bt[n][k], At[m][k], acc[ai][bj][m][n], 0, 0, 0); __builtin_amdgcn_s_setprio(0); } while (0)
; #define PG8_WAIT_V(n) asm volatile("s_waitcnt vmcnt(" #n ")" ::: "memory")
; #define PG8_WAIT_L(n) asm volatile("s_waitcnt lgkmcnt(" #n ")" ::: "memory")
; #define PG8_BAR __builtin_amdgcn_s_barrier()
; #define PG8_SCHED __builtin_amdgcn_sched_barrier(0)
; template <class Epi, class Sched, bool ALIGN_EPI = false, bool SP2 = false>
; __device__ __forceinline__ void gemm_phase(PG8_LAS unsigned char* lds, const Gemm g, const Sched& S, const Epi& E) {
;     ...
;         for (int t = 0; t < nt; t += 2) {
;     ...
;             PG8_LDA(At, 1, 1); PG8_STAGE(PG8_SB(1, 0), b3, voffB); PG8_STAGE(PG8_SB(1, 1), b3 + hstep, voffB); PG8_STAGE(PG8_SA(1, 0), a3, voffA);
;             PG8_WAIT_V(8); PG8_WAIT_L(0); PG8_BAR; PG8_MMA(1, 0, At, B0); PG8_MMA(1, 1, At, B1); PG8_BAR; PG8_SCHED;
	s_add_i32 s28, s53, s31
	v_lshl_add_u64 v[216:217], v[216:217], 0, s[10:11]
	s_mov_b32 m0, s28
	ds_read_b128 v[184:187], v155 offset:49152
	ds_read_b128 v[188:191], v155 offset:50176
	ds_read_b128 v[192:195], v155 offset:51200
	ds_read_b128 v[196:199], v155 offset:52224
	ds_read_b128 v[200:203], v155 offset:53248
	ds_read_b128 v[204:207], v155 offset:54272
	ds_read_b128 v[208:211], v155 offset:55296
	ds_read_b128 v[212:215], v155 offset:56320
	global_load_lds_dwordx4 v[216:217], off
	s_add_i32 m0, s28, 0x2000
	s_add_u32 s26, s26, 0x80080
	v_lshl_add_u64 v[216:217], v[218:219], 0, s[10:11]
	s_addc_u32 s27, s27, 0
	s_add_i32 s28, s54, s31
	global_load_lds_dwordx4 v[216:217], off
	v_lshl_add_u64 v[216:217], s[26:27], 0, v[134:135]
	s_mov_b32 m0, s28
	s_nop 0
	global_load_lds_dwordx4 v[216:217], off
	v_lshl_add_u64 v[216:217], s[26:27], 0, v[130:131]
	s_add_i32 m0, s28, 0x2000
	s_nop 0
	global_load_lds_dwordx4 v[216:217], off
	v_lshl_add_u64 v[216:217], v[220:221], 0, s[10:11]
	s_mov_b32 m0, s42
	s_nop 0
	global_load_lds_dwordx4 v[216:217], off
	v_lshl_add_u64 v[216:217], v[222:223], 0, s[10:11]
	s_mov_b32 m0, s43
	s_nop 0
	global_load_lds_dwordx4 v[216:217], off
	s_waitcnt vmcnt(8)
	s_waitcnt lgkmcnt(0)
	s_setprio 1
	s_barrier
	v_mfma_f32_16x16x32_bf16 v[62:65], v[146:149], v[184:187], v[62:65]
	v_mfma_f32_16x16x32_bf16 v[58:61], v[160:163], v[184:187], v[58:61]
	v_mfma_f32_16x16x32_bf16 v[46:49], v[146:149], v[192:195], v[46:49]
	v_mfma_f32_16x16x32_bf16 v[42:45], v[160:163], v[192:195], v[42:45]
	v_mfma_f32_16x16x32_bf16 v[30:33], v[146:149], v[200:203], v[30:33]
	v_mfma_f32_16x16x32_bf16 v[26:29], v[160:163], v[200:203], v[26:29]
	v_mfma_f32_16x16x32_bf16 v[14:17], v[146:149], v[208:211], v[14:17]
	v_mfma_f32_16x16x32_bf16 v[10:13], v[160:163], v[208:211], v[10:13]
	v_mfma_f32_16x16x32_bf16 v[62:65], v[156:159], v[188:191], v[62:65]
	v_mfma_f32_16x16x32_bf16 v[58:61], v[164:167], v[188:191], v[58:61]
	v_mfma_f32_16x16x32_bf16 v[46:49], v[156:159], v[196:199], v[46:49]
	v_mfma_f32_16x16x32_bf16 v[42:45], v[164:167], v[196:199], v[42:45]
	v_mfma_f32_16x16x32_bf16 v[30:33], v[156:159], v[204:207], v[30:33]
	v_mfma_f32_16x16x32_bf16 v[26:29], v[164:167], v[204:207], v[26:29]
	v_mfma_f32_16x16x32_bf16 v[14:17], v[156:159], v[212:215], v[14:17]
	v_mfma_f32_16x16x32_bf16 v[10:13], v[164:167], v[212:215], v[10:13]
	s_setprio 0
	s_setprio 1
	v_mfma_f32_16x16x32_bf16 v[54:57], v[168:171], v[184:187], v[54:57]
	v_mfma_f32_16x16x32_bf16 v[50:53], v[176:179], v[184:187], v[50:53]
	v_mfma_f32_16x16x32_bf16 v[38:41], v[168:171], v[192:195], v[38:41]
	v_mfma_f32_16x16x32_bf16 v[34:37], v[176:179], v[192:195], v[34:37]
	v_mfma_f32_16x16x32_bf16 v[22:25], v[168:171], v[200:203], v[22:25]
	v_mfma_f32_16x16x32_bf16 v[18:21], v[176:179], v[200:203], v[18:21]
	v_mfma_f32_16x16x32_bf16 v[6:9], v[168:171], v[208:211], v[6:9]
	v_mfma_f32_16x16x32_bf16 v[2:5], v[176:179], v[208:211], v[2:5]
	v_mfma_f32_16x16x32_bf16 v[54:57], v[172:175], v[188:191], v[54:57]
	v_mfma_f32_16x16x32_bf16 v[50:53], v[180:183], v[188:191], v[50:53]
	v_mfma_f32_16x16x32_bf16 v[38:41], v[172:175], v[196:199], v[38:41]
	v_mfma_f32_16x16x32_bf16 v[34:37], v[180:183], v[196:199], v[34:37]
	v_mfma_f32_16x16x32_bf16 v[22:25], v[172:175], v[204:207], v[22:25]
	v_mfma_f32_16x16x32_bf16 v[18:21], v[180:183], v[204:207], v[18:21]
	v_mfma_f32_16x16x32_bf16 v[6:9], v[172:175], v[212:215], v[6:9]
	v_mfma_f32_16x16x32_bf16 v[2:5], v[180:183], v[212:215], v[2:5]
	s_setprio 0
	s_add_i32 s52, s52, 2
	s_add_u32 s24, s24, 0x100
	s_addc_u32 s25, s25, 0
	s_add_u32 s50, s50, 0x100
	s_addc_u32 s51, s51, 0
	s_cmp_gt_u32 s52, 29
	s_barrier
	s_cbranch_scc0 .LBB0_1551
	s_and_b64 vcc, exec, s[12:13]
	s_cbranch_vccz .LBB0_1554
	s_barrier

; #define PG8_STAGE(bufoff, gbase, voff) do { _Pragma("unroll") for (int _i = 0; _i < 2; ++_i) \
;         __builtin_amdgcn_global_load_lds((const unsigned*)((const char*)(gbase) + (voff)[_i]), (PG8_LAS unsigned*)(lds + (bufoff) + ldsw + _i * 8192), 16, 0, 0); } while (0)
; #define PG8_LDA(dst, b, h) do { _Pragma("unroll") for (int m = 0; m < 4; ++m) _Pragma("unroll") for (int k = 0; k < 2; ++k) dst[m][k] = *(const PG8_LAS bf16x8*)(lds + PG8_SA(b, h) + aoff + m * 2048 + k * 1024); } while (0)
; #define PG8_LDB(dst, b, h) do { _Pragma("unroll") for (int n = 0; n < 2; ++n) _Pragma("unroll") for (int k = 0; k < 2; ++k) dst[n][k] = *(const PG8_LAS bf16x8*)(lds + PG8_SB(b, h) + boff + n * 2048 + k * 1024); } while (0)
; #define PG8_MMA(ai, bj, At, Bt) do { __builtin_amdgcn_s_setprio(1); _Pragma("unroll") for (int m = 0; m < 4; ++m) _Pragma("unroll") for (int n = 0; n < 2; ++n) _Pragma("unroll") for (int k = 0; k < 2; ++k) \
;         acc[ai][bj][m][n] = __builtin_amdgcn_mfma_f32_16x16x32_bf16(Bt[n][k], At[m][k], acc[ai][bj][m][n], 0, 0, 0); __builtin_amdgcn_s_setprio(0); } while (0)
; #define PG8_BAR __builtin_amdgcn_s_barrier()
; template <class Epi, class Sched, bool ALIGN_EPI = false, bool SP2 = false>
; __device__ __forceinline__ void gemm_phase(PG8_LAS unsigned char* lds, const Gemm g, const Sched& S, const Epi& E) {
;     ...
;         for (int t = 0; t < nt; t += 2) {
;             if constexpr (Epi::MIDHOOK) { if (t == (nt >> 1)) E.mid(acc, cur, wr, wc, fr, fq); }
;             const bool last = (t == nt - 2);
;             const char* a1 = cA + (size_t)(t + 1) * kstep;
;             const char* a2 = last ? nA : cA + (size_t)(t + 2) * kstep; const char* b2 = last ? nB : cB + (size_t)(t + 2) * kstep;
;             const char* a3 = a2 + kstep; const char* b3 = b2 + kstep;
;             if (last && has_next) S.a_ready(nxt);
;             if constexpr (SP2) {
;             PG8_LDB(B0, 0, 0); PG8_LDB(B1, 0, 1); PG8_SCHED; PG8_LDA(At, 0, 0); PG8_STAGE(PG8_SA(1, 1), a1 + hstep, voffA);
;             PG8_WAIT_V(8); PG8_WAIT_L(0); PG8_BAR; PG8_MMA(0, 0, At, B0); PG8_MMA(0, 1, At, B1); PG8_BAR; PG8_SCHED;
;             PG8_LDA(At, 0, 1); PG8_STAGE(PG8_SB(0, 0), b2, voffB); PG8_STAGE(PG8_SB(0, 1), b2 + hstep, voffB); PG8_STAGE(PG8_SA(0, 0), a2, voffA);
;             PG8_WAIT_V(8); PG8_WAIT_L(0); PG8_BAR; PG8_MMA(1, 0, At, B0); PG8_MMA(1, 1, At, B1); PG8_BAR; PG8_SCHED;
.LBB0_1656:
	ds_read_b128 v[154:157], v151
	ds_read_b128 v[158:161], v151 offset:1024
	ds_read_b128 v[162:165], v151 offset:2048
	ds_read_b128 v[166:169], v151 offset:3072
	ds_read_b128 v[170:173], v152
	ds_read_b128 v[174:177], v152 offset:1024
	ds_read_b128 v[178:181], v152 offset:2048
	ds_read_b128 v[182:185], v152 offset:3072
	s_add_u32 s26, s24, 0x100
	s_addc_u32 s27, s25, 0
	s_cmpk_eq_i32 s58, 0x54
	s_cselect_b32 s31, s7, s27
	s_cselect_b32 s30, s6, s26
	s_cselect_b32 s29, s23, s57
	s_cselect_b32 s28, s22, s56
	v_lshl_add_u64 v[146:147], s[24:25], 0, v[138:139]
	s_add_i32 m0, s38, 0xc000
	ds_read_b128 v[186:189], v153
	ds_read_b128 v[190:193], v153 offset:1024
	ds_read_b128 v[194:197], v153 offset:2048
	ds_read_b128 v[198:201], v153 offset:3072
	ds_read_b128 v[202:205], v153 offset:4096
	ds_read_b128 v[206:209], v153 offset:5120
	ds_read_b128 v[210:213], v153 offset:6144
	ds_read_b128 v[214:217], v153 offset:7168
	global_load_lds_dwordx4 v[146:147], off
	v_lshl_add_u64 v[146:147], s[24:25], 0, v[140:141]
	s_add_i32 m0, s38, 0xe000
	s_nop 0
	global_load_lds_dwordx4 v[146:147], off
	s_waitcnt vmcnt(8)
	s_waitcnt lgkmcnt(0)
	s_setprio 1
	s_barrier
	v_mfma_f32_16x16x32_bf16 v[126:129], v[154:157], v[186:189], v[126:129]
	v_mfma_f32_16x16x32_bf16 v[122:125], v[162:165], v[186:189], v[122:125]
	v_mfma_f32_16x16x32_bf16 v[118:121], v[154:157], v[194:197], v[118:121]
	v_mfma_f32_16x16x32_bf16 v[110:113], v[162:165], v[194:197], v[110:113]
	v_mfma_f32_16x16x32_bf16 v[102:105], v[154:157], v[202:205], v[102:105]
	v_mfma_f32_16x16x32_bf16 v[94:97], v[162:165], v[202:205], v[94:97]
	v_mfma_f32_16x16x32_bf16 v[86:89], v[154:157], v[210:213], v[86:89]
	v_mfma_f32_16x16x32_bf16 v[78:81], v[162:165], v[210:213], v[78:81]
	v_mfma_f32_16x16x32_bf16 v[126:129], v[158:161], v[190:193], v[126:129]
	v_mfma_f32_16x16x32_bf16 v[122:125], v[166:169], v[190:193], v[122:125]
	v_mfma_f32_16x16x32_bf16 v[118:121], v[158:161], v[198:201], v[118:121]
	v_mfma_f32_16x16x32_bf16 v[110:113], v[166:169], v[198:201], v[110:113]
	v_mfma_f32_16x16x32_bf16 v[102:105], v[158:161], v[206:209], v[102:105]
	v_mfma_f32_16x16x32_bf16 v[94:97], v[166:169], v[206:209], v[94:97]
	v_mfma_f32_16x16x32_bf16 v[86:89], v[158:161], v[214:217], v[86:89]
	v_mfma_f32_16x16x32_bf16 v[78:81], v[166:169], v[214:217], v[78:81]
	s_setprio 0
	s_setprio 1
	v_mfma_f32_16x16x32_bf16 v[114:117], v[170:173], v[186:189], v[114:117]
	v_mfma_f32_16x16x32_bf16 v[106:109], v[178:181], v[186:189], v[106:109]
	v_mfma_f32_16x16x32_bf16 v[98:101], v[170:173], v[194:197], v[98:101]
	v_mfma_f32_16x16x32_bf16 v[90:93], v[178:181], v[194:197], v[90:93]
	v_mfma_f32_16x16x32_bf16 v[82:85], v[170:173], v[202:205], v[82:85]
	v_mfma_f32_16x16x32_bf16 v[74:77], v[178:181], v[202:205], v[74:77]
	v_mfma_f32_16x16x32_bf16 v[70:73], v[170:173], v[210:213], v[70:73]
	v_mfma_f32_16x16x32_bf16 v[66:69], v[178:181], v[210:213], v[66:69]
	v_mfma_f32_16x16x32_bf16 v[114:117], v[174:177], v[190:193], v[114:117]
	v_mfma_f32_16x16x32_bf16 v[106:109], v[182:185], v[190:193], v[106:109]
	v_mfma_f32_16x16x32_bf16 v[98:101], v[174:177], v[198:201], v[98:101]
	v_mfma_f32_16x16x32_bf16 v[90:93], v[182:185], v[198:201], v[90:93]
	v_mfma_f32_16x16x32_bf16 v[82:85], v[174:177], v[206:209], v[82:85]
	v_mfma_f32_16x16x32_bf16 v[74:77], v[182:185], v[206:209], v[74:77]
	v_mfma_f32_16x16x32_bf16 v[70:73], v[174:177], v[214:217], v[70:73]
	v_mfma_f32_16x16x32_bf16 v[66:69], v[182:185], v[214:217], v[66:69]
	s_setprio 0
	s_barrier
	s_add_i32 s24, s46, s36
	v_lshl_add_u64 v[146:147], s[28:29], 0, v[134:135]
	s_mov_b32 m0, s24
	ds_read_b128 v[186:189], v153 offset:16384
	ds_read_b128 v[190:193], v153 offset:17408
	ds_read_b128 v[194:197], v153 offset:18432
	ds_read_b128 v[198:201], v153 offset:19456
	ds_read_b128 v[202:205], v153 offset:20480
	ds_read_b128 v[206:209], v153 offset:21504
	ds_read_b128 v[210:213], v153 offset:22528
	ds_read_b128 v[214:217], v153 offset:23552
	global_load_lds_dwordx4 v[146:147], off
	s_add_i32 m0, s24, 0x2000
	s_add_u32 s24, s28, 0x160000
	v_lshl_add_u64 v[218:219], s[28:29], 0, v[130:131]
	s_addc_u32 s25, s29, 0
	s_add_i32 s59, s47, s36
	global_load_lds_dwordx4 v[218:219], off
	v_lshl_add_u64 v[220:221], s[24:25], 0, v[134:135]
	s_mov_b32 m0, s59
	v_lshl_add_u64 v[222:223], s[30:31], 0, v[132:133]
	global_load_lds_dwordx4 v[220:221], off
	v_lshl_add_u64 v[220:221], s[24:25], 0, v[130:131]
	s_add_i32 m0, s59, 0x2000
	s_nop 0
	global_load_lds_dwordx4 v[220:221], off
	v_lshl_add_u64 v[220:221], s[30:31], 0, v[136:137]
	s_mov_b32 m0, s38
	s_nop 0
	global_load_lds_dwordx4 v[220:221], off
	s_mov_b32 m0, s39
	s_nop 0
	global_load_lds_dwordx4 v[222:223], off
	s_waitcnt vmcnt(8)
	s_waitcnt lgkmcnt(0)
	s_setprio 1
	s_barrier
; #define PG8_STAGE(bufoff, gbase, voff) do { _Pragma("unroll") for (int _i = 0; _i < 2; ++_i) \
;         __builtin_amdgcn_global_load_lds((const unsigned*)((const char*)(gbase) + (voff)[_i]), (PG8_LAS unsigned*)(lds + (bufoff) + ldsw + _i * 8192), 16, 0, 0); } while (0)
; #define PG8_LDA(dst, b, h) do { _Pragma("unroll") for (int m = 0; m < 4; ++m) _Pragma("unroll") for (int k = 0; k < 2; ++k) dst[m][k] = *(const PG8_LAS bf16x8*)(lds + PG8_SA(b, h) + aoff + m * 2048 + k * 1024); } while (0)
; #define PG8_LDB(dst, b, h) do { _Pragma("unroll") for (int n = 0; n < 2; ++n) _Pragma("unroll") for (int k = 0; k < 2; ++k) dst[n][k] = *(const PG8_LAS bf16x8*)(lds + PG8_SB(b, h) + boff + n * 2048 + k * 1024); } while (0)
; #define PG8_MMA(ai, bj, At, Bt) do { __builtin_amdgcn_s_setprio(1); _Pragma("unroll") for (int m = 0; m < 4; ++m) _Pragma("unroll") for (int n = 0; n < 2; ++n) _Pragma("unroll") for (int k = 0; k < 2; ++k) \
;         acc[ai][bj][m][n] = __builtin_amdgcn_mfma_f32_16x16x32_bf16(Bt[n][k], At[m][k], acc[ai][bj][m][n], 0, 0, 0); __builtin_amdgcn_s_setprio(0); } while (0)
; #define PG8_WAIT_V(n) asm volatile("s_waitcnt vmcnt(" #n ")" ::: "memory")
; #define PG8_WAIT_L(n) asm volatile("s_waitcnt lgkmcnt(" #n ")" ::: "memory")
; #define PG8_BAR __builtin_amdgcn_s_barrier()
; #define PG8_SCHED __builtin_amdgcn_sched_barrier(0)
; template <class Epi, class Sched, bool ALIGN_EPI = false, bool SP2 = false>
; __device__ __forceinline__ void gemm_phase(PG8_LAS unsigned char* lds, const Gemm g, const Sched& S, const Epi& E) {
;     ...
;             PG8_WAIT_V(8); PG8_WAIT_L(0); PG8_BAR; PG8_MMA(1, 0, At, B0); PG8_MMA(1, 1, At, B1); PG8_BAR; PG8_SCHED;
;             PG8_LDB(B0, 1, 0); PG8_LDB(B1, 1, 1); PG8_SCHED; PG8_LDA(At, 1, 0); PG8_STAGE(PG8_SA(0, 1), a2 + hstep, voffA);
;             PG8_WAIT_V(8); PG8_WAIT_L(0); PG8_BAR; PG8_MMA(0, 0, At, B0); PG8_MMA(0, 1, At, B1); PG8_BAR; PG8_SCHED;
;             PG8_LDA(At, 1, 1); PG8_STAGE(PG8_SB(1, 0), b3, voffB); PG8_STAGE(PG8_SB(1, 1), b3 + hstep, voffB); PG8_STAGE(PG8_SA(1, 0), a3, voffA);
	v_mfma_f32_16x16x32_bf16 v[62:65], v[154:157], v[186:189], v[62:65]
	v_mfma_f32_16x16x32_bf16 v[58:61], v[162:165], v[186:189], v[58:61]
	v_mfma_f32_16x16x32_bf16 v[54:57], v[154:157], v[194:197], v[54:57]
	v_mfma_f32_16x16x32_bf16 v[46:49], v[162:165], v[194:197], v[46:49]
	v_mfma_f32_16x16x32_bf16 v[38:41], v[154:157], v[202:205], v[38:41]
	v_mfma_f32_16x16x32_bf16 v[30:33], v[162:165], v[202:205], v[30:33]
	v_mfma_f32_16x16x32_bf16 v[22:25], v[154:157], v[210:213], v[22:25]
	v_mfma_f32_16x16x32_bf16 v[14:17], v[162:165], v[210:213], v[14:17]
	v_mfma_f32_16x16x32_bf16 v[62:65], v[158:161], v[190:193], v[62:65]
	v_mfma_f32_16x16x32_bf16 v[58:61], v[166:169], v[190:193], v[58:61]
	v_mfma_f32_16x16x32_bf16 v[54:57], v[158:161], v[198:201], v[54:57]
	v_mfma_f32_16x16x32_bf16 v[46:49], v[166:169], v[198:201], v[46:49]
	v_mfma_f32_16x16x32_bf16 v[38:41], v[158:161], v[206:209], v[38:41]
	v_mfma_f32_16x16x32_bf16 v[30:33], v[166:169], v[206:209], v[30:33]
	v_mfma_f32_16x16x32_bf16 v[22:25], v[158:161], v[214:217], v[22:25]
	v_mfma_f32_16x16x32_bf16 v[14:17], v[166:169], v[214:217], v[14:17]
	s_setprio 0
	s_setprio 1
	v_mfma_f32_16x16x32_bf16 v[50:53], v[170:173], v[186:189], v[50:53]
	v_mfma_f32_16x16x32_bf16 v[42:45], v[178:181], v[186:189], v[42:45]
	v_mfma_f32_16x16x32_bf16 v[34:37], v[170:173], v[194:197], v[34:37]
	v_mfma_f32_16x16x32_bf16 v[26:29], v[178:181], v[194:197], v[26:29]
	v_mfma_f32_16x16x32_bf16 v[18:21], v[170:173], v[202:205], v[18:21]
	v_mfma_f32_16x16x32_bf16 v[10:13], v[178:181], v[202:205], v[10:13]
	v_mfma_f32_16x16x32_bf16 v[6:9], v[170:173], v[210:213], v[6:9]
	v_mfma_f32_16x16x32_bf16 v[2:5], v[178:181], v[210:213], v[2:5]
	v_mfma_f32_16x16x32_bf16 v[50:53], v[174:177], v[190:193], v[50:53]
	v_mfma_f32_16x16x32_bf16 v[42:45], v[182:185], v[190:193], v[42:45]
	v_mfma_f32_16x16x32_bf16 v[34:37], v[174:177], v[198:201], v[34:37]
	v_mfma_f32_16x16x32_bf16 v[26:29], v[182:185], v[198:201], v[26:29]
	v_mfma_f32_16x16x32_bf16 v[18:21], v[174:177], v[206:209], v[18:21]
	v_mfma_f32_16x16x32_bf16 v[10:13], v[182:185], v[206:209], v[10:13]
	v_mfma_f32_16x16x32_bf16 v[6:9], v[174:177], v[214:217], v[6:9]
	v_mfma_f32_16x16x32_bf16 v[2:5], v[182:185], v[214:217], v[2:5]
	s_setprio 0
	s_barrier
	s_add_i32 s59, 0, 0x18000
	s_add_i32 s60, 0, 0x1c000
	v_add_u32_e32 v166, s59, v149
	v_add_u32_e32 v182, s60, v149
	ds_read_b128 v[154:157], v166
	ds_read_b128 v[158:161], v166 offset:1024
	ds_read_b128 v[162:165], v166 offset:2048
	ds_read_b128 v[166:169], v166 offset:3072
	ds_read_b128 v[170:173], v182
	ds_read_b128 v[174:177], v182 offset:1024
	ds_read_b128 v[178:181], v182 offset:2048
	ds_read_b128 v[182:185], v182 offset:3072
	s_add_u32 s24, s30, 0x160000
	s_addc_u32 s25, s31, 0
	s_mov_b32 m0, s40
	v_lshl_add_u64 v[224:225], s[24:25], 0, v[136:137]
	ds_read_b128 v[186:189], v153 offset:32768
	ds_read_b128 v[190:193], v153 offset:33792
	ds_read_b128 v[194:197], v153 offset:34816
	ds_read_b128 v[198:201], v153 offset:35840
	ds_read_b128 v[202:205], v153 offset:36864
	ds_read_b128 v[206:209], v153 offset:37888
	ds_read_b128 v[210:213], v153 offset:38912
	ds_read_b128 v[214:217], v153 offset:39936
	global_load_lds_dwordx4 v[224:225], off
	v_lshl_add_u64 v[224:225], s[24:25], 0, v[132:133]
	s_mov_b32 m0, s41
	s_nop 0
	global_load_lds_dwordx4 v[224:225], off
	s_waitcnt vmcnt(8)
	s_waitcnt lgkmcnt(0)
	s_setprio 1
	s_barrier
	v_mfma_f32_16x16x32_bf16 v[126:129], v[154:157], v[186:189], v[126:129]
	v_mfma_f32_16x16x32_bf16 v[122:125], v[162:165], v[186:189], v[122:125]
	v_mfma_f32_16x16x32_bf16 v[118:121], v[154:157], v[194:197], v[118:121]
	v_mfma_f32_16x16x32_bf16 v[110:113], v[162:165], v[194:197], v[110:113]
	v_mfma_f32_16x16x32_bf16 v[102:105], v[154:157], v[202:205], v[102:105]
	v_mfma_f32_16x16x32_bf16 v[94:97], v[162:165], v[202:205], v[94:97]
	v_mfma_f32_16x16x32_bf16 v[86:89], v[154:157], v[210:213], v[86:89]
	v_mfma_f32_16x16x32_bf16 v[78:81], v[162:165], v[210:213], v[78:81]
	v_mfma_f32_16x16x32_bf16 v[126:129], v[158:161], v[190:193], v[126:129]
	v_mfma_f32_16x16x32_bf16 v[122:125], v[166:169], v[190:193], v[122:125]
	v_mfma_f32_16x16x32_bf16 v[118:121], v[158:161], v[198:201], v[118:121]
	v_mfma_f32_16x16x32_bf16 v[110:113], v[166:169], v[198:201], v[110:113]
	v_mfma_f32_16x16x32_bf16 v[102:105], v[158:161], v[206:209], v[102:105]
	v_mfma_f32_16x16x32_bf16 v[94:97], v[166:169], v[206:209], v[94:97]
	v_mfma_f32_16x16x32_bf16 v[86:89], v[158:161], v[214:217], v[86:89]
	v_mfma_f32_16x16x32_bf16 v[78:81], v[166:169], v[214:217], v[78:81]
	s_setprio 0
	s_setprio 1
	v_mfma_f32_16x16x32_bf16 v[114:117], v[170:173], v[186:189], v[114:117]
	v_mfma_f32_16x16x32_bf16 v[106:109], v[178:181], v[186:189], v[106:109]
	v_mfma_f32_16x16x32_bf16 v[98:101], v[170:173], v[194:197], v[98:101]
	v_mfma_f32_16x16x32_bf16 v[90:93], v[178:181], v[194:197], v[90:93]
	v_mfma_f32_16x16x32_bf16 v[82:85], v[170:173], v[202:205], v[82:85]
	v_mfma_f32_16x16x32_bf16 v[74:77], v[178:181], v[202:205], v[74:77]
	v_mfma_f32_16x16x32_bf16 v[70:73], v[170:173], v[210:213], v[70:73]
	v_mfma_f32_16x16x32_bf16 v[66:69], v[178:181], v[210:213], v[66:69]
	v_mfma_f32_16x16x32_bf16 v[114:117], v[174:177], v[190:193], v[114:117]
	v_mfma_f32_16x16x32_bf16 v[106:109], v[182:185], v[190:193], v[106:109]
	v_mfma_f32_16x16x32_bf16 v[98:101], v[174:177], v[198:201], v[98:101]
	v_mfma_f32_16x16x32_bf16 v[90:93], v[182:185], v[198:201], v[90:93]
	v_mfma_f32_16x16x32_bf16 v[82:85], v[174:177], v[206:209], v[82:85]
	v_mfma_f32_16x16x32_bf16 v[74:77], v[182:185], v[206:209], v[74:77]
	v_mfma_f32_16x16x32_bf16 v[70:73], v[174:177], v[214:217], v[70:73]
	v_mfma_f32_16x16x32_bf16 v[66:69], v[182:185], v[214:217], v[66:69]
	s_setprio 0
	s_barrier
; #define PG8_STAGE(bufoff, gbase, voff) do { _Pragma("unroll") for (int _i = 0; _i < 2; ++_i) \
;         __builtin_amdgcn_global_load_lds((const unsigned*)((const char*)(gbase) + (voff)[_i]), (PG8_LAS unsigned*)(lds + (bufoff) + ldsw + _i * 8192), 16, 0, 0); } while (0)
; #define PG8_LDA(dst, b, h) do { _Pragma("unroll") for (int m = 0; m < 4; ++m) _Pragma("unroll") for (int k = 0; k < 2; ++k) dst[m][k] = *(const PG8_LAS bf16x8*)(lds + PG8_SA(b, h) + aoff + m * 2048 + k * 1024); } while (0)
; #define PG8_MMA(ai, bj, At, Bt) do { __builtin_amdgcn_s_setprio(1); _Pragma("unroll") for (int m = 0; m < 4; ++m) _Pragma("unroll") for (int n = 0; n < 2; ++n) _Pragma("unroll") for (int k = 0; k < 2; ++k) \
;         acc[ai][bj][m][n] = __builtin_amdgcn_mfma_f32_16x16x32_bf16(Bt[n][k], At[m][k], acc[ai][bj][m][n], 0, 0, 0); __builtin_amdgcn_s_setprio(0); } while (0)
; #define PG8_WAIT_V(n) asm volatile("s_waitcnt vmcnt(" #n ")" ::: "memory")
; #define PG8_WAIT_L(n) asm volatile("s_waitcnt lgkmcnt(" #n ")" ::: "memory")
; #define PG8_BAR __builtin_amdgcn_s_barrier()
; #define PG8_SCHED __builtin_amdgcn_sched_barrier(0)
; template <class Epi, class Sched, bool ALIGN_EPI = false, bool SP2 = false>
; __device__ __forceinline__ void gemm_phase(PG8_LAS unsigned char* lds, const Gemm g, const Sched& S, const Epi& E) {
;     ...
;         for (int t = 0; t < nt; t += 2) {
;     ...
;             PG8_LDA(At, 1, 1); PG8_STAGE(PG8_SB(1, 0), b3, voffB); PG8_STAGE(PG8_SB(1, 1), b3 + hstep, voffB); PG8_STAGE(PG8_SA(1, 0), a3, voffA);
;             PG8_WAIT_V(8); PG8_WAIT_L(0); PG8_BAR; PG8_MMA(1, 0, At, B0); PG8_MMA(1, 1, At, B1); PG8_BAR; PG8_SCHED;
	s_add_i32 s24, s59, s36
	v_lshl_add_u64 v[146:147], v[146:147], 0, s[10:11]
	s_mov_b32 m0, s24
	ds_read_b128 v[186:189], v153 offset:49152
	ds_read_b128 v[190:193], v153 offset:50176
	ds_read_b128 v[194:197], v153 offset:51200
	ds_read_b128 v[198:201], v153 offset:52224
	ds_read_b128 v[202:205], v153 offset:53248
	ds_read_b128 v[206:209], v153 offset:54272
	ds_read_b128 v[210:213], v153 offset:55296
	ds_read_b128 v[214:217], v153 offset:56320
	global_load_lds_dwordx4 v[146:147], off
	s_add_i32 m0, s24, 0x2000
	s_add_u32 s24, s28, 0x160080
	v_lshl_add_u64 v[146:147], v[218:219], 0, s[10:11]
	s_addc_u32 s25, s29, 0
	s_add_i32 s28, s60, s36
	global_load_lds_dwordx4 v[146:147], off
	v_lshl_add_u64 v[146:147], s[24:25], 0, v[134:135]
	s_mov_b32 m0, s28
	s_nop 0
	global_load_lds_dwordx4 v[146:147], off
	v_lshl_add_u64 v[146:147], s[24:25], 0, v[130:131]
	s_add_i32 m0, s28, 0x2000
	s_nop 0
	global_load_lds_dwordx4 v[146:147], off
	v_lshl_add_u64 v[146:147], v[220:221], 0, s[10:11]
	s_mov_b32 m0, s44
	s_nop 0
	global_load_lds_dwordx4 v[146:147], off
	v_lshl_add_u64 v[146:147], v[222:223], 0, s[10:11]
	s_mov_b32 m0, s45
	s_nop 0
	global_load_lds_dwordx4 v[146:147], off
	s_waitcnt vmcnt(8)
	s_waitcnt lgkmcnt(0)
	s_setprio 1
	s_barrier
	v_mfma_f32_16x16x32_bf16 v[62:65], v[154:157], v[186:189], v[62:65]
	v_mfma_f32_16x16x32_bf16 v[58:61], v[162:165], v[186:189], v[58:61]
	v_mfma_f32_16x16x32_bf16 v[54:57], v[154:157], v[194:197], v[54:57]
	v_mfma_f32_16x16x32_bf16 v[46:49], v[162:165], v[194:197], v[46:49]
	v_mfma_f32_16x16x32_bf16 v[38:41], v[154:157], v[202:205], v[38:41]
	v_mfma_f32_16x16x32_bf16 v[30:33], v[162:165], v[202:205], v[30:33]
	v_mfma_f32_16x16x32_bf16 v[22:25], v[154:157], v[210:213], v[22:25]
	v_mfma_f32_16x16x32_bf16 v[14:17], v[162:165], v[210:213], v[14:17]
	v_mfma_f32_16x16x32_bf16 v[62:65], v[158:161], v[190:193], v[62:65]
	v_mfma_f32_16x16x32_bf16 v[58:61], v[166:169], v[190:193], v[58:61]
	v_mfma_f32_16x16x32_bf16 v[54:57], v[158:161], v[198:201], v[54:57]
	v_mfma_f32_16x16x32_bf16 v[46:49], v[166:169], v[198:201], v[46:49]
	v_mfma_f32_16x16x32_bf16 v[38:41], v[158:161], v[206:209], v[38:41]
	v_mfma_f32_16x16x32_bf16 v[30:33], v[166:169], v[206:209], v[30:33]
	v_mfma_f32_16x16x32_bf16 v[22:25], v[158:161], v[214:217], v[22:25]
	v_mfma_f32_16x16x32_bf16 v[14:17], v[166:169], v[214:217], v[14:17]
	s_setprio 0
	s_setprio 1
	v_mfma_f32_16x16x32_bf16 v[50:53], v[170:173], v[186:189], v[50:53]
	v_mfma_f32_16x16x32_bf16 v[42:45], v[178:181], v[186:189], v[42:45]
	v_mfma_f32_16x16x32_bf16 v[34:37], v[170:173], v[194:197], v[34:37]
	v_mfma_f32_16x16x32_bf16 v[26:29], v[178:181], v[194:197], v[26:29]
	v_mfma_f32_16x16x32_bf16 v[18:21], v[170:173], v[202:205], v[18:21]
	v_mfma_f32_16x16x32_bf16 v[10:13], v[178:181], v[202:205], v[10:13]
	v_mfma_f32_16x16x32_bf16 v[6:9], v[170:173], v[210:213], v[6:9]
	v_mfma_f32_16x16x32_bf16 v[2:5], v[178:181], v[210:213], v[2:5]
	v_mfma_f32_16x16x32_bf16 v[50:53], v[174:177], v[190:193], v[50:53]
	v_mfma_f32_16x16x32_bf16 v[42:45], v[182:185], v[190:193], v[42:45]
	v_mfma_f32_16x16x32_bf16 v[34:37], v[174:177], v[198:201], v[34:37]
	v_mfma_f32_16x16x32_bf16 v[26:29], v[182:185], v[198:201], v[26:29]
	v_mfma_f32_16x16x32_bf16 v[18:21], v[174:177], v[206:209], v[18:21]
	v_mfma_f32_16x16x32_bf16 v[10:13], v[182:185], v[206:209], v[10:13]
	v_mfma_f32_16x16x32_bf16 v[6:9], v[174:177], v[214:217], v[6:9]
	v_mfma_f32_16x16x32_bf16 v[2:5], v[182:185], v[214:217], v[2:5]
	s_setprio 0
	s_add_i32 s58, s58, 2
	s_add_u32 s56, s56, 0x100
	s_addc_u32 s57, s57, 0
	s_cmpk_gt_u32 s58, 0x55
	s_mov_b64 s[24:25], s[26:27]
	s_barrier
	s_cbranch_scc0 .LBB0_1656
	s_and_b64 vcc, exec, s[12:13]
	s_cbranch_vccz .LBB0_1659
	s_barrier

; #define PG8_STAGE(bufoff, gbase, voff) do { _Pragma("unroll") for (int _i = 0; _i < 2; ++_i) \
;         __builtin_amdgcn_global_load_lds((const unsigned*)((const char*)(gbase) + (voff)[_i]), (PG8_LAS unsigned*)(lds + (bufoff) + ldsw + _i * 8192), 16, 0, 0); } while (0)
; #define PG8_LDA(dst, b, h) do { _Pragma("unroll") for (int m = 0; m < 4; ++m) _Pragma("unroll") for (int k = 0; k < 2; ++k) dst[m][k] = *(const PG8_LAS bf16x8*)(lds + PG8_SA(b, h) + aoff + m * 2048 + k * 1024); } while (0)
; #define PG8_LDB(dst, b, h) do { _Pragma("unroll") for (int n = 0; n < 2; ++n) _Pragma("unroll") for (int k = 0; k < 2; ++k) dst[n][k] = *(const PG8_LAS bf16x8*)(lds + PG8_SB(b, h) + boff + n * 2048 + k * 1024); } while (0)
; #define PG8_MMA(ai, bj, At, Bt) do { __builtin_amdgcn_s_setprio(1); _Pragma("unroll") for (int m = 0; m < 4; ++m) _Pragma("unroll") for (int n = 0; n < 2; ++n) _Pragma("unroll") for (int k = 0; k < 2; ++k) \
;         acc[ai][bj][m][n] = __builtin_amdgcn_mfma_f32_16x16x32_bf16(Bt[n][k], At[m][k], acc[ai][bj][m][n], 0, 0, 0); __builtin_amdgcn_s_setprio(0); } while (0)
; #define PG8_BAR __builtin_amdgcn_s_barrier()
; template <class Epi, class Sched, bool ALIGN_EPI = false, bool SP2 = false>
; __device__ __forceinline__ void gemm_phase(PG8_LAS unsigned char* lds, const Gemm g, const Sched& S, const Epi& E) {
;     ...
;         for (int t = 0; t < nt; t += 2) {
;             if constexpr (Epi::MIDHOOK) { if (t == (nt >> 1)) E.mid(acc, cur, wr, wc, fr, fq); }
;             const bool last = (t == nt - 2);
;             const char* a1 = cA + (size_t)(t + 1) * kstep;
;             const char* a2 = last ? nA : cA + (size_t)(t + 2) * kstep; const char* b2 = last ? nB : cB + (size_t)(t + 2) * kstep;
;             const char* a3 = a2 + kstep; const char* b3 = b2 + kstep;
;             if (last && has_next) S.a_ready(nxt);
;             if constexpr (SP2) {
;             PG8_LDB(B0, 0, 0); PG8_LDB(B1, 0, 1); PG8_SCHED; PG8_LDA(At, 0, 0); PG8_STAGE(PG8_SA(1, 1), a1 + hstep, voffA);
;             PG8_WAIT_V(8); PG8_WAIT_L(0); PG8_BAR; PG8_MMA(0, 0, At, B0); PG8_MMA(0, 1, At, B1); PG8_BAR; PG8_SCHED;
;             PG8_LDA(At, 0, 1); PG8_STAGE(PG8_SB(0, 0), b2, voffB); PG8_STAGE(PG8_SB(0, 1), b2 + hstep, voffB); PG8_STAGE(PG8_SA(0, 0), a2, voffA);
;             PG8_WAIT_V(8); PG8_WAIT_L(0); PG8_BAR; PG8_MMA(1, 0, At, B0); PG8_MMA(1, 1, At, B1); PG8_BAR; PG8_SCHED;
.LBB0_1676:
	ds_read_b128 v[144:147], v141
	ds_read_b128 v[148:151], v141 offset:1024
	ds_read_b128 v[152:155], v141 offset:2048
	ds_read_b128 v[156:159], v141 offset:3072
	ds_read_b128 v[160:163], v142
	ds_read_b128 v[164:167], v142 offset:1024
	ds_read_b128 v[168:171], v142 offset:2048
	ds_read_b128 v[172:175], v142 offset:3072
	s_add_u32 s28, s26, 0x100
	s_addc_u32 s29, s27, 0
	s_cmp_eq_u32 s60, 18
	s_cselect_b32 s37, s23, s29
	s_cselect_b32 s36, s22, s28
	s_cselect_b32 s31, s25, s59
	s_cselect_b32 s30, s24, s7
	v_lshl_add_u64 v[208:209], s[26:27], 0, v[134:135]
	s_add_i32 m0, s41, 0xc000
	ds_read_b128 v[176:179], v143
	ds_read_b128 v[180:183], v143 offset:1024
	ds_read_b128 v[184:187], v143 offset:2048
	ds_read_b128 v[188:191], v143 offset:3072
	ds_read_b128 v[192:195], v143 offset:4096
	ds_read_b128 v[196:199], v143 offset:5120
	ds_read_b128 v[200:203], v143 offset:6144
	ds_read_b128 v[204:207], v143 offset:7168
	global_load_lds_dwordx4 v[208:209], off
	v_lshl_add_u64 v[208:209], s[26:27], 0, v[136:137]
	s_add_i32 m0, s41, 0xe000
	s_nop 0
	global_load_lds_dwordx4 v[208:209], off
	s_waitcnt vmcnt(8)
	s_waitcnt lgkmcnt(0)
	s_setprio 1
	s_barrier
	v_mfma_f32_16x16x32_bf16 v[126:129], v[144:147], v[176:179], v[126:129]
	v_mfma_f32_16x16x32_bf16 v[122:125], v[152:155], v[176:179], v[122:125]
	v_mfma_f32_16x16x32_bf16 v[118:121], v[144:147], v[184:187], v[118:121]
	v_mfma_f32_16x16x32_bf16 v[114:117], v[152:155], v[184:187], v[114:117]
	v_mfma_f32_16x16x32_bf16 v[106:109], v[144:147], v[192:195], v[106:109]
	v_mfma_f32_16x16x32_bf16 v[98:101], v[152:155], v[192:195], v[98:101]
	v_mfma_f32_16x16x32_bf16 v[90:93], v[144:147], v[200:203], v[90:93]
	v_mfma_f32_16x16x32_bf16 v[82:85], v[152:155], v[200:203], v[82:85]
	v_mfma_f32_16x16x32_bf16 v[126:129], v[148:151], v[180:183], v[126:129]
	v_mfma_f32_16x16x32_bf16 v[122:125], v[156:159], v[180:183], v[122:125]
	v_mfma_f32_16x16x32_bf16 v[118:121], v[148:151], v[188:191], v[118:121]
	v_mfma_f32_16x16x32_bf16 v[114:117], v[156:159], v[188:191], v[114:117]
	v_mfma_f32_16x16x32_bf16 v[106:109], v[148:151], v[196:199], v[106:109]
	v_mfma_f32_16x16x32_bf16 v[98:101], v[156:159], v[196:199], v[98:101]
	v_mfma_f32_16x16x32_bf16 v[90:93], v[148:151], v[204:207], v[90:93]
	v_mfma_f32_16x16x32_bf16 v[82:85], v[156:159], v[204:207], v[82:85]
	s_setprio 0
	s_setprio 1
	v_mfma_f32_16x16x32_bf16 v[110:113], v[160:163], v[176:179], v[110:113]
	v_mfma_f32_16x16x32_bf16 v[102:105], v[168:171], v[176:179], v[102:105]
	v_mfma_f32_16x16x32_bf16 v[94:97], v[160:163], v[184:187], v[94:97]
	v_mfma_f32_16x16x32_bf16 v[86:89], v[168:171], v[184:187], v[86:89]
	v_mfma_f32_16x16x32_bf16 v[78:81], v[160:163], v[192:195], v[78:81]
	v_mfma_f32_16x16x32_bf16 v[74:77], v[168:171], v[192:195], v[74:77]
	v_mfma_f32_16x16x32_bf16 v[70:73], v[160:163], v[200:203], v[70:73]
	v_mfma_f32_16x16x32_bf16 v[66:69], v[168:171], v[200:203], v[66:69]
	v_mfma_f32_16x16x32_bf16 v[110:113], v[164:167], v[180:183], v[110:113]
	v_mfma_f32_16x16x32_bf16 v[102:105], v[172:175], v[180:183], v[102:105]
	v_mfma_f32_16x16x32_bf16 v[94:97], v[164:167], v[188:191], v[94:97]
	v_mfma_f32_16x16x32_bf16 v[86:89], v[172:175], v[188:191], v[86:89]
	v_mfma_f32_16x16x32_bf16 v[78:81], v[164:167], v[196:199], v[78:81]
	v_mfma_f32_16x16x32_bf16 v[74:77], v[172:175], v[196:199], v[74:77]
	v_mfma_f32_16x16x32_bf16 v[70:73], v[164:167], v[204:207], v[70:73]
	v_mfma_f32_16x16x32_bf16 v[66:69], v[172:175], v[204:207], v[66:69]
	s_setprio 0
	s_barrier
	s_add_i32 s26, s50, s39
	v_lshl_add_u64 v[208:209], s[30:31], 0, v[132:133]
	s_mov_b32 m0, s26
	ds_read_b128 v[176:179], v143 offset:16384
	ds_read_b128 v[180:183], v143 offset:17408
	ds_read_b128 v[184:187], v143 offset:18432
	ds_read_b128 v[188:191], v143 offset:19456
	ds_read_b128 v[192:195], v143 offset:20480
	ds_read_b128 v[196:199], v143 offset:21504
	ds_read_b128 v[200:203], v143 offset:22528
	ds_read_b128 v[204:207], v143 offset:23552
	global_load_lds_dwordx4 v[208:209], off
	s_add_i32 m0, s26, 0x2000
	s_add_u32 s26, s30, 0x160000
	v_lshl_add_u64 v[210:211], s[30:31], 0, v[130:131]
	s_addc_u32 s27, s31, 0
	s_add_i32 s61, s51, s39
	global_load_lds_dwordx4 v[210:211], off
	v_lshl_add_u64 v[212:213], s[26:27], 0, v[132:133]
	s_mov_b32 m0, s61
	v_lshl_add_u64 v[214:215], s[36:37], 0, v[130:131]
	global_load_lds_dwordx4 v[212:213], off
	v_lshl_add_u64 v[212:213], s[26:27], 0, v[130:131]
	s_add_i32 m0, s61, 0x2000
	s_nop 0
	global_load_lds_dwordx4 v[212:213], off
	v_lshl_add_u64 v[212:213], s[36:37], 0, v[132:133]
	s_mov_b32 m0, s41
	s_nop 0
	global_load_lds_dwordx4 v[212:213], off
	s_mov_b32 m0, s42
	s_nop 0
	global_load_lds_dwordx4 v[214:215], off
	s_waitcnt vmcnt(8)
	s_waitcnt lgkmcnt(0)
	s_setprio 1
	s_barrier
; #define PG8_STAGE(bufoff, gbase, voff) do { _Pragma("unroll") for (int _i = 0; _i < 2; ++_i) \
;         __builtin_amdgcn_global_load_lds((const unsigned*)((const char*)(gbase) + (voff)[_i]), (PG8_LAS unsigned*)(lds + (bufoff) + ldsw + _i * 8192), 16, 0, 0); } while (0)
; #define PG8_LDA(dst, b, h) do { _Pragma("unroll") for (int m = 0; m < 4; ++m) _Pragma("unroll") for (int k = 0; k < 2; ++k) dst[m][k] = *(const PG8_LAS bf16x8*)(lds + PG8_SA(b, h) + aoff + m * 2048 + k * 1024); } while (0)
; #define PG8_LDB(dst, b, h) do { _Pragma("unroll") for (int n = 0; n < 2; ++n) _Pragma("unroll") for (int k = 0; k < 2; ++k) dst[n][k] = *(const PG8_LAS bf16x8*)(lds + PG8_SB(b, h) + boff + n * 2048 + k * 1024); } while (0)
; #define PG8_MMA(ai, bj, At, Bt) do { __builtin_amdgcn_s_setprio(1); _Pragma("unroll") for (int m = 0; m < 4; ++m) _Pragma("unroll") for (int n = 0; n < 2; ++n) _Pragma("unroll") for (int k = 0; k < 2; ++k) \
;         acc[ai][bj][m][n] = __builtin_amdgcn_mfma_f32_16x16x32_bf16(Bt[n][k], At[m][k], acc[ai][bj][m][n], 0, 0, 0); __builtin_amdgcn_s_setprio(0); } while (0)
; #define PG8_WAIT_V(n) asm volatile("s_waitcnt vmcnt(" #n ")" ::: "memory")
; #define PG8_WAIT_L(n) asm volatile("s_waitcnt lgkmcnt(" #n ")" ::: "memory")
; #define PG8_BAR __builtin_amdgcn_s_barrier()
; #define PG8_SCHED __builtin_amdgcn_sched_barrier(0)
; template <class Epi, class Sched, bool ALIGN_EPI = false, bool SP2 = false>
; __device__ __forceinline__ void gemm_phase(PG8_LAS unsigned char* lds, const Gemm g, const Sched& S, const Epi& E) {
;     ...
;             PG8_WAIT_V(8); PG8_WAIT_L(0); PG8_BAR; PG8_MMA(1, 0, At, B0); PG8_MMA(1, 1, At, B1); PG8_BAR; PG8_SCHED;
;             PG8_LDB(B0, 1, 0); PG8_LDB(B1, 1, 1); PG8_SCHED; PG8_LDA(At, 1, 0); PG8_STAGE(PG8_SA(0, 1), a2 + hstep, voffA);
;             PG8_WAIT_V(8); PG8_WAIT_L(0); PG8_BAR; PG8_MMA(0, 0, At, B0); PG8_MMA(0, 1, At, B1); PG8_BAR; PG8_SCHED;
;             PG8_LDA(At, 1, 1); PG8_STAGE(PG8_SB(1, 0), b3, voffB); PG8_STAGE(PG8_SB(1, 1), b3 + hstep, voffB); PG8_STAGE(PG8_SA(1, 0), a3, voffA);
	v_mfma_f32_16x16x32_bf16 v[62:65], v[144:147], v[176:179], v[62:65]
	v_mfma_f32_16x16x32_bf16 v[58:61], v[152:155], v[176:179], v[58:61]
	v_mfma_f32_16x16x32_bf16 v[54:57], v[144:147], v[184:187], v[54:57]
	v_mfma_f32_16x16x32_bf16 v[50:53], v[152:155], v[184:187], v[50:53]
	v_mfma_f32_16x16x32_bf16 v[42:45], v[144:147], v[192:195], v[42:45]
	v_mfma_f32_16x16x32_bf16 v[34:37], v[152:155], v[192:195], v[34:37]
	v_mfma_f32_16x16x32_bf16 v[26:29], v[144:147], v[200:203], v[26:29]
	v_mfma_f32_16x16x32_bf16 v[18:21], v[152:155], v[200:203], v[18:21]
	v_mfma_f32_16x16x32_bf16 v[62:65], v[148:151], v[180:183], v[62:65]
	v_mfma_f32_16x16x32_bf16 v[58:61], v[156:159], v[180:183], v[58:61]
	v_mfma_f32_16x16x32_bf16 v[54:57], v[148:151], v[188:191], v[54:57]
	v_mfma_f32_16x16x32_bf16 v[50:53], v[156:159], v[188:191], v[50:53]
	v_mfma_f32_16x16x32_bf16 v[42:45], v[148:151], v[196:199], v[42:45]
	v_mfma_f32_16x16x32_bf16 v[34:37], v[156:159], v[196:199], v[34:37]
	v_mfma_f32_16x16x32_bf16 v[26:29], v[148:151], v[204:207], v[26:29]
	v_mfma_f32_16x16x32_bf16 v[18:21], v[156:159], v[204:207], v[18:21]
	s_setprio 0
	s_setprio 1
	v_mfma_f32_16x16x32_bf16 v[46:49], v[160:163], v[176:179], v[46:49]
	v_mfma_f32_16x16x32_bf16 v[38:41], v[168:171], v[176:179], v[38:41]
	v_mfma_f32_16x16x32_bf16 v[30:33], v[160:163], v[184:187], v[30:33]
	v_mfma_f32_16x16x32_bf16 v[22:25], v[168:171], v[184:187], v[22:25]
	v_mfma_f32_16x16x32_bf16 v[14:17], v[160:163], v[192:195], v[14:17]
	v_mfma_f32_16x16x32_bf16 v[10:13], v[168:171], v[192:195], v[10:13]
	v_mfma_f32_16x16x32_bf16 v[6:9], v[160:163], v[200:203], v[6:9]
	v_mfma_f32_16x16x32_bf16 v[2:5], v[168:171], v[200:203], v[2:5]
	v_mfma_f32_16x16x32_bf16 v[46:49], v[164:167], v[180:183], v[46:49]
	v_mfma_f32_16x16x32_bf16 v[38:41], v[172:175], v[180:183], v[38:41]
	v_mfma_f32_16x16x32_bf16 v[30:33], v[164:167], v[188:191], v[30:33]
	v_mfma_f32_16x16x32_bf16 v[22:25], v[172:175], v[188:191], v[22:25]
	v_mfma_f32_16x16x32_bf16 v[14:17], v[164:167], v[196:199], v[14:17]
	v_mfma_f32_16x16x32_bf16 v[10:13], v[172:175], v[196:199], v[10:13]
	v_mfma_f32_16x16x32_bf16 v[6:9], v[164:167], v[204:207], v[6:9]
	v_mfma_f32_16x16x32_bf16 v[2:5], v[172:175], v[204:207], v[2:5]
	s_setprio 0
	s_barrier
	s_add_i32 s61, 0, 0x18000
	s_add_i32 s62, 0, 0x1c000
	v_add_u32_e32 v156, s61, v138
	v_add_u32_e32 v172, s62, v138
	ds_read_b128 v[144:147], v156
	ds_read_b128 v[148:151], v156 offset:1024
	ds_read_b128 v[152:155], v156 offset:2048
	ds_read_b128 v[156:159], v156 offset:3072
	ds_read_b128 v[160:163], v172
	ds_read_b128 v[164:167], v172 offset:1024
	ds_read_b128 v[168:171], v172 offset:2048
	ds_read_b128 v[172:175], v172 offset:3072
	s_add_u32 s26, s36, 0x160000
	s_addc_u32 s27, s37, 0
	s_mov_b32 m0, s43
	v_lshl_add_u64 v[216:217], s[26:27], 0, v[132:133]
	ds_read_b128 v[176:179], v143 offset:32768
	ds_read_b128 v[180:183], v143 offset:33792
	ds_read_b128 v[184:187], v143 offset:34816
	ds_read_b128 v[188:191], v143 offset:35840
	ds_read_b128 v[192:195], v143 offset:36864
	ds_read_b128 v[196:199], v143 offset:37888
	ds_read_b128 v[200:203], v143 offset:38912
	ds_read_b128 v[204:207], v143 offset:39936
	global_load_lds_dwordx4 v[216:217], off
	v_lshl_add_u64 v[216:217], s[26:27], 0, v[130:131]
	s_mov_b32 m0, s44
	s_nop 0
	global_load_lds_dwordx4 v[216:217], off
	s_waitcnt vmcnt(8)
	s_waitcnt lgkmcnt(0)
	s_setprio 1
	s_barrier
	v_mfma_f32_16x16x32_bf16 v[126:129], v[144:147], v[176:179], v[126:129]
	v_mfma_f32_16x16x32_bf16 v[122:125], v[152:155], v[176:179], v[122:125]
	v_mfma_f32_16x16x32_bf16 v[118:121], v[144:147], v[184:187], v[118:121]
	v_mfma_f32_16x16x32_bf16 v[114:117], v[152:155], v[184:187], v[114:117]
	v_mfma_f32_16x16x32_bf16 v[106:109], v[144:147], v[192:195], v[106:109]
	v_mfma_f32_16x16x32_bf16 v[98:101], v[152:155], v[192:195], v[98:101]
	v_mfma_f32_16x16x32_bf16 v[90:93], v[144:147], v[200:203], v[90:93]
	v_mfma_f32_16x16x32_bf16 v[82:85], v[152:155], v[200:203], v[82:85]
	v_mfma_f32_16x16x32_bf16 v[126:129], v[148:151], v[180:183], v[126:129]
	v_mfma_f32_16x16x32_bf16 v[122:125], v[156:159], v[180:183], v[122:125]
	v_mfma_f32_16x16x32_bf16 v[118:121], v[148:151], v[188:191], v[118:121]
	v_mfma_f32_16x16x32_bf16 v[114:117], v[156:159], v[188:191], v[114:117]
	v_mfma_f32_16x16x32_bf16 v[106:109], v[148:151], v[196:199], v[106:109]
	v_mfma_f32_16x16x32_bf16 v[98:101], v[156:159], v[196:199], v[98:101]
	v_mfma_f32_16x16x32_bf16 v[90:93], v[148:151], v[204:207], v[90:93]
	v_mfma_f32_16x16x32_bf16 v[82:85], v[156:159], v[204:207], v[82:85]
	s_setprio 0
	s_setprio 1
	v_mfma_f32_16x16x32_bf16 v[110:113], v[160:163], v[176:179], v[110:113]
	v_mfma_f32_16x16x32_bf16 v[102:105], v[168:171], v[176:179], v[102:105]
	v_mfma_f32_16x16x32_bf16 v[94:97], v[160:163], v[184:187], v[94:97]
	v_mfma_f32_16x16x32_bf16 v[86:89], v[168:171], v[184:187], v[86:89]
	v_mfma_f32_16x16x32_bf16 v[78:81], v[160:163], v[192:195], v[78:81]
	v_mfma_f32_16x16x32_bf16 v[74:77], v[168:171], v[192:195], v[74:77]
	v_mfma_f32_16x16x32_bf16 v[70:73], v[160:163], v[200:203], v[70:73]
	v_mfma_f32_16x16x32_bf16 v[66:69], v[168:171], v[200:203], v[66:69]
	v_mfma_f32_16x16x32_bf16 v[110:113], v[164:167], v[180:183], v[110:113]
	v_mfma_f32_16x16x32_bf16 v[102:105], v[172:175], v[180:183], v[102:105]
	v_mfma_f32_16x16x32_bf16 v[94:97], v[164:167], v[188:191], v[94:97]
	v_mfma_f32_16x16x32_bf16 v[86:89], v[172:175], v[188:191], v[86:89]
	v_mfma_f32_16x16x32_bf16 v[78:81], v[164:167], v[196:199], v[78:81]
	v_mfma_f32_16x16x32_bf16 v[74:77], v[172:175], v[196:199], v[74:77]
	v_mfma_f32_16x16x32_bf16 v[70:73], v[164:167], v[204:207], v[70:73]
	v_mfma_f32_16x16x32_bf16 v[66:69], v[172:175], v[204:207], v[66:69]
	s_setprio 0
	s_barrier
; #define PG8_STAGE(bufoff, gbase, voff) do { _Pragma("unroll") for (int _i = 0; _i < 2; ++_i) \
;         __builtin_amdgcn_global_load_lds((const unsigned*)((const char*)(gbase) + (voff)[_i]), (PG8_LAS unsigned*)(lds + (bufoff) + ldsw + _i * 8192), 16, 0, 0); } while (0)
; #define PG8_LDA(dst, b, h) do { _Pragma("unroll") for (int m = 0; m < 4; ++m) _Pragma("unroll") for (int k = 0; k < 2; ++k) dst[m][k] = *(const PG8_LAS bf16x8*)(lds + PG8_SA(b, h) + aoff + m * 2048 + k * 1024); } while (0)
; #define PG8_MMA(ai, bj, At, Bt) do { __builtin_amdgcn_s_setprio(1); _Pragma("unroll") for (int m = 0; m < 4; ++m) _Pragma("unroll") for (int n = 0; n < 2; ++n) _Pragma("unroll") for (int k = 0; k < 2; ++k) \
;         acc[ai][bj][m][n] = __builtin_amdgcn_mfma_f32_16x16x32_bf16(Bt[n][k], At[m][k], acc[ai][bj][m][n], 0, 0, 0); __builtin_amdgcn_s_setprio(0); } while (0)
; #define PG8_WAIT_V(n) asm volatile("s_waitcnt vmcnt(" #n ")" ::: "memory")
; #define PG8_WAIT_L(n) asm volatile("s_waitcnt lgkmcnt(" #n ")" ::: "memory")
; #define PG8_BAR __builtin_amdgcn_s_barrier()
; #define PG8_SCHED __builtin_amdgcn_sched_barrier(0)
; template <class Epi, class Sched, bool ALIGN_EPI = false, bool SP2 = false>
; __device__ __forceinline__ void gemm_phase(PG8_LAS unsigned char* lds, const Gemm g, const Sched& S, const Epi& E) {
;     ...
;         for (int t = 0; t < nt; t += 2) {
;     ...
;             PG8_LDA(At, 1, 1); PG8_STAGE(PG8_SB(1, 0), b3, voffB); PG8_STAGE(PG8_SB(1, 1), b3 + hstep, voffB); PG8_STAGE(PG8_SA(1, 0), a3, voffA);
;             PG8_WAIT_V(8); PG8_WAIT_L(0); PG8_BAR; PG8_MMA(1, 0, At, B0); PG8_MMA(1, 1, At, B1); PG8_BAR; PG8_SCHED;
	s_add_i32 s26, s61, s39
	v_lshl_add_u64 v[208:209], v[208:209], 0, s[12:13]
	s_mov_b32 m0, s26
	ds_read_b128 v[176:179], v143 offset:49152
	ds_read_b128 v[180:183], v143 offset:50176
	ds_read_b128 v[184:187], v143 offset:51200
	ds_read_b128 v[188:191], v143 offset:52224
	ds_read_b128 v[192:195], v143 offset:53248
	ds_read_b128 v[196:199], v143 offset:54272
	ds_read_b128 v[200:203], v143 offset:55296
	ds_read_b128 v[204:207], v143 offset:56320
	global_load_lds_dwordx4 v[208:209], off
	s_add_i32 m0, s26, 0x2000
	s_add_u32 s26, s30, 0x160080
	v_lshl_add_u64 v[208:209], v[210:211], 0, s[12:13]
	s_addc_u32 s27, s31, 0
	s_add_i32 s30, s62, s39
	global_load_lds_dwordx4 v[208:209], off
	v_lshl_add_u64 v[208:209], s[26:27], 0, v[132:133]
	s_mov_b32 m0, s30
	s_nop 0
	global_load_lds_dwordx4 v[208:209], off
	v_lshl_add_u64 v[208:209], s[26:27], 0, v[130:131]
	s_add_i32 m0, s30, 0x2000
	s_nop 0
	global_load_lds_dwordx4 v[208:209], off
	v_lshl_add_u64 v[208:209], v[212:213], 0, s[12:13]
	s_mov_b32 m0, s47
	s_nop 0
	global_load_lds_dwordx4 v[208:209], off
	v_lshl_add_u64 v[208:209], v[214:215], 0, s[12:13]
	s_mov_b32 m0, s48
	s_nop 0
	global_load_lds_dwordx4 v[208:209], off
	s_waitcnt vmcnt(8)
	s_waitcnt lgkmcnt(0)
	s_setprio 1
	s_barrier
	v_mfma_f32_16x16x32_bf16 v[62:65], v[144:147], v[176:179], v[62:65]
	v_mfma_f32_16x16x32_bf16 v[58:61], v[152:155], v[176:179], v[58:61]
	v_mfma_f32_16x16x32_bf16 v[54:57], v[144:147], v[184:187], v[54:57]
	v_mfma_f32_16x16x32_bf16 v[50:53], v[152:155], v[184:187], v[50:53]
	v_mfma_f32_16x16x32_bf16 v[42:45], v[144:147], v[192:195], v[42:45]
	v_mfma_f32_16x16x32_bf16 v[34:37], v[152:155], v[192:195], v[34:37]
	v_mfma_f32_16x16x32_bf16 v[26:29], v[144:147], v[200:203], v[26:29]
	v_mfma_f32_16x16x32_bf16 v[18:21], v[152:155], v[200:203], v[18:21]
	v_mfma_f32_16x16x32_bf16 v[62:65], v[148:151], v[180:183], v[62:65]
	v_mfma_f32_16x16x32_bf16 v[58:61], v[156:159], v[180:183], v[58:61]
	v_mfma_f32_16x16x32_bf16 v[54:57], v[148:151], v[188:191], v[54:57]
	v_mfma_f32_16x16x32_bf16 v[50:53], v[156:159], v[188:191], v[50:53]
	v_mfma_f32_16x16x32_bf16 v[42:45], v[148:151], v[196:199], v[42:45]
	v_mfma_f32_16x16x32_bf16 v[34:37], v[156:159], v[196:199], v[34:37]
	v_mfma_f32_16x16x32_bf16 v[26:29], v[148:151], v[204:207], v[26:29]
	v_mfma_f32_16x16x32_bf16 v[18:21], v[156:159], v[204:207], v[18:21]
	s_setprio 0
	s_setprio 1
	v_mfma_f32_16x16x32_bf16 v[46:49], v[160:163], v[176:179], v[46:49]
	v_mfma_f32_16x16x32_bf16 v[38:41], v[168:171], v[176:179], v[38:41]
	v_mfma_f32_16x16x32_bf16 v[30:33], v[160:163], v[184:187], v[30:33]
	v_mfma_f32_16x16x32_bf16 v[22:25], v[168:171], v[184:187], v[22:25]
	v_mfma_f32_16x16x32_bf16 v[14:17], v[160:163], v[192:195], v[14:17]
	v_mfma_f32_16x16x32_bf16 v[10:13], v[168:171], v[192:195], v[10:13]
	v_mfma_f32_16x16x32_bf16 v[6:9], v[160:163], v[200:203], v[6:9]
	v_mfma_f32_16x16x32_bf16 v[2:5], v[168:171], v[200:203], v[2:5]
	v_mfma_f32_16x16x32_bf16 v[46:49], v[164:167], v[180:183], v[46:49]
	v_mfma_f32_16x16x32_bf16 v[38:41], v[172:175], v[180:183], v[38:41]
	v_mfma_f32_16x16x32_bf16 v[30:33], v[164:167], v[188:191], v[30:33]
	v_mfma_f32_16x16x32_bf16 v[22:25], v[172:175], v[188:191], v[22:25]
	v_mfma_f32_16x16x32_bf16 v[14:17], v[164:167], v[196:199], v[14:17]
	v_mfma_f32_16x16x32_bf16 v[10:13], v[172:175], v[196:199], v[10:13]
	v_mfma_f32_16x16x32_bf16 v[6:9], v[164:167], v[204:207], v[6:9]
	v_mfma_f32_16x16x32_bf16 v[2:5], v[172:175], v[204:207], v[2:5]
	s_setprio 0
	s_add_i32 s60, s60, 2
	s_add_u32 s7, s7, 0x100
	s_addc_u32 s59, s59, 0
	s_cmp_gt_u32 s60, 19
	s_mov_b64 s[26:27], s[28:29]
	s_barrier
	s_cbranch_scc0 .LBB0_1676
	s_and_b64 vcc, exec, s[14:15]
	s_cbranch_vccz .LBB0_1679
	s_barrier

; #define PG8_STAGE(bufoff, gbase, voff) do { _Pragma("unroll") for (int _i = 0; _i < 2; ++_i) \
;         __builtin_amdgcn_global_load_lds((const unsigned*)((const char*)(gbase) + (voff)[_i]), (PG8_LAS unsigned*)(lds + (bufoff) + ldsw + _i * 8192), 16, 0, 0); } while (0)
; #define PG8_LDA(dst, b, h) do { _Pragma("unroll") for (int m = 0; m < 4; ++m) _Pragma("unroll") for (int k = 0; k < 2; ++k) dst[m][k] = *(const PG8_LAS bf16x8*)(lds + PG8_SA(b, h) + aoff + m * 2048 + k * 1024); } while (0)
; #define PG8_LDB(dst, b, h) do { _Pragma("unroll") for (int n = 0; n < 2; ++n) _Pragma("unroll") for (int k = 0; k < 2; ++k) dst[n][k] = *(const PG8_LAS bf16x8*)(lds + PG8_SB(b, h) + boff + n * 2048 + k * 1024); } while (0)
; #define PG8_WAIT_V(n) asm volatile("s_waitcnt vmcnt(" #n ")" ::: "memory")
; #define PG8_WAIT_L(n) asm volatile("s_waitcnt lgkmcnt(" #n ")" ::: "memory")
; #define PG8_BAR __builtin_amdgcn_s_barrier()
; template <class Epi, class Sched, bool ALIGN_EPI = false, bool SP2 = false>
; __device__ __forceinline__ void gemm_phase(PG8_LAS unsigned char* lds, const Gemm g, const Sched& S, const Epi& E) {
;     ...
;         const char* nA = has_next ? (const char*)g.A + (size_t)nxt.pm * tstep + (size_t)nxt.kt0 * kstep : cA; const char* nB = has_next ? (const char*)g.Bt + (size_t)nxt.pn * tstep + (size_t)nxt.kt0 * kstep : cB;
;         for (int t = 0; t < nt; t += 2) {
;             if constexpr (Epi::MIDHOOK) { if (t == (nt >> 1)) E.mid(acc, cur, wr, wc, fr, fq); }
;             const bool last = (t == nt - 2);
;             const char* a1 = cA + (size_t)(t + 1) * kstep;
;             const char* a2 = last ? nA : cA + (size_t)(t + 2) * kstep; const char* b2 = last ? nB : cB + (size_t)(t + 2) * kstep;
;             const char* a3 = a2 + kstep; const char* b3 = b2 + kstep;
;             if (last && has_next) S.a_ready(nxt);
;             if constexpr (SP2) {
;             PG8_LDB(B0, 0, 0); PG8_LDB(B1, 0, 1); PG8_SCHED; PG8_LDA(At, 0, 0); PG8_STAGE(PG8_SA(1, 1), a1 + hstep, voffA);
;             PG8_WAIT_V(8); PG8_WAIT_L(0); PG8_BAR; PG8_MMA(0, 0, At, B0); PG8_MMA(0, 1, At, B1); PG8_BAR; PG8_SCHED;
;             PG8_LDA(At, 0, 1); PG8_STAGE(PG8_SB(0, 0), b2, voffB); PG8_STAGE(PG8_SB(0, 1), b2 + hstep, voffB); PG8_STAGE(PG8_SA(0, 0), a2, voffA);
;             PG8_WAIT_V(8); PG8_WAIT_L(0); PG8_BAR; PG8_MMA(1, 0, At, B0); PG8_MMA(1, 1, At, B1); PG8_BAR; PG8_SCHED;
.LBB0_1693:
	s_add_u32 s37, s26, s36
	s_addc_u32 s42, s27, 0
	s_add_u32 s40, s37, 0x100
	s_addc_u32 s41, s42, 0
	s_and_b64 s[38:39], s[30:31], exec
	s_cselect_b32 s39, s19, s41
	s_cselect_b32 s38, s63, s40
	s_add_u32 s36, s24, s36
	s_addc_u32 s40, s25, 0
	s_add_u32 s36, s36, 0x100
	s_addc_u32 s40, s40, 0
	s_and_b64 s[30:31], s[30:31], exec
	s_cselect_b32 s41, s17, s40
	s_cselect_b32 s40, s64, s36
	s_add_u32 s44, s37, 0x10080
	ds_read_b128 v[150:153], v147
	ds_read_b128 v[154:157], v147 offset:1024
	ds_read_b128 v[158:161], v147 offset:2048
	ds_read_b128 v[162:165], v147 offset:3072
	ds_read_b128 v[166:169], v148
	ds_read_b128 v[170:173], v148 offset:1024
	ds_read_b128 v[174:177], v148 offset:2048
	ds_read_b128 v[178:181], v148 offset:3072
	s_addc_u32 s45, s42, 0
	s_add_i32 s74, s57, s33
	s_add_i32 m0, s50, 0xc000
	s_add_i32 s75, s50, 0xe000
	s_add_i32 s71, s74, 0x2000
	s_add_u32 s42, s40, 0x10000
	s_addc_u32 s43, s41, 0
	s_add_i32 s73, s58, s33
	s_add_i32 s72, s73, 0x2000
	s_add_i32 s70, 0, 0x18000
	s_add_i32 s69, 0, 0x1c000
	s_add_u32 s36, s38, 0x10000
	s_addc_u32 s37, s39, 0
	s_add_i32 s68, s70, s33
	s_add_i32 s66, s68, 0x2000
	s_add_u32 s30, s40, 0x10080
	s_addc_u32 s31, s41, 0
	s_add_i32 s67, s69, s33
	s_add_i32 s65, s67, 0x2000
	v_lshl_add_u64 v[142:143], s[44:45], 0, v[136:137]
	ds_read_b128 v[182:185], v149
	ds_read_b128 v[186:189], v149 offset:1024
	ds_read_b128 v[190:193], v149 offset:2048
	ds_read_b128 v[194:197], v149 offset:3072
	ds_read_b128 v[198:201], v149 offset:4096
	ds_read_b128 v[202:205], v149 offset:5120
	ds_read_b128 v[206:209], v149 offset:6144
	ds_read_b128 v[210:213], v149 offset:7168
	global_load_lds_dwordx4 v[142:143], off
	v_lshl_add_u64 v[142:143], s[44:45], 0, v[132:133]
	s_mov_b32 m0, s75
	s_nop 0
	global_load_lds_dwordx4 v[142:143], off
	s_waitcnt vmcnt(8)
	s_waitcnt lgkmcnt(0)
	s_setprio 1
	s_barrier
	v_mfma_f32_16x16x32_bf16 v[126:129], v[150:153], v[182:185], v[126:129]
	v_mfma_f32_16x16x32_bf16 v[122:125], v[158:161], v[182:185], v[122:125]
	v_mfma_f32_16x16x32_bf16 v[118:121], v[150:153], v[190:193], v[118:121]
	v_mfma_f32_16x16x32_bf16 v[110:113], v[158:161], v[190:193], v[110:113]
	v_mfma_f32_16x16x32_bf16 v[102:105], v[150:153], v[198:201], v[102:105]
	v_mfma_f32_16x16x32_bf16 v[94:97], v[158:161], v[198:201], v[94:97]
	v_mfma_f32_16x16x32_bf16 v[86:89], v[150:153], v[206:209], v[86:89]
	v_mfma_f32_16x16x32_bf16 v[78:81], v[158:161], v[206:209], v[78:81]
	v_mfma_f32_16x16x32_bf16 v[126:129], v[154:157], v[186:189], v[126:129]
	v_mfma_f32_16x16x32_bf16 v[122:125], v[162:165], v[186:189], v[122:125]
	v_mfma_f32_16x16x32_bf16 v[118:121], v[154:157], v[194:197], v[118:121]
	v_mfma_f32_16x16x32_bf16 v[110:113], v[162:165], v[194:197], v[110:113]
	v_mfma_f32_16x16x32_bf16 v[102:105], v[154:157], v[202:205], v[102:105]
	v_mfma_f32_16x16x32_bf16 v[94:97], v[162:165], v[202:205], v[94:97]
	v_mfma_f32_16x16x32_bf16 v[86:89], v[154:157], v[210:213], v[86:89]
	v_mfma_f32_16x16x32_bf16 v[78:81], v[162:165], v[210:213], v[78:81]
	s_setprio 0
	s_setprio 1
	v_mfma_f32_16x16x32_bf16 v[114:117], v[166:169], v[182:185], v[114:117]
	v_mfma_f32_16x16x32_bf16 v[106:109], v[174:177], v[182:185], v[106:109]
	v_mfma_f32_16x16x32_bf16 v[98:101], v[166:169], v[190:193], v[98:101]
	v_mfma_f32_16x16x32_bf16 v[90:93], v[174:177], v[190:193], v[90:93]
	v_mfma_f32_16x16x32_bf16 v[82:85], v[166:169], v[198:201], v[82:85]
	v_mfma_f32_16x16x32_bf16 v[74:77], v[174:177], v[198:201], v[74:77]
	v_mfma_f32_16x16x32_bf16 v[70:73], v[166:169], v[206:209], v[70:73]
	v_mfma_f32_16x16x32_bf16 v[66:69], v[174:177], v[206:209], v[66:69]
	v_mfma_f32_16x16x32_bf16 v[114:117], v[170:173], v[186:189], v[114:117]
	v_mfma_f32_16x16x32_bf16 v[106:109], v[178:181], v[186:189], v[106:109]
	v_mfma_f32_16x16x32_bf16 v[98:101], v[170:173], v[194:197], v[98:101]
	v_mfma_f32_16x16x32_bf16 v[90:93], v[178:181], v[194:197], v[90:93]
	v_mfma_f32_16x16x32_bf16 v[82:85], v[170:173], v[202:205], v[82:85]
	v_mfma_f32_16x16x32_bf16 v[74:77], v[178:181], v[202:205], v[74:77]
	v_mfma_f32_16x16x32_bf16 v[70:73], v[170:173], v[210:213], v[70:73]
	v_mfma_f32_16x16x32_bf16 v[66:69], v[178:181], v[210:213], v[66:69]
	s_setprio 0
	s_barrier
	s_mov_b32 m0, s74
	v_lshl_add_u64 v[142:143], s[40:41], 0, v[134:135]
	ds_read_b128 v[182:185], v149 offset:16384
	ds_read_b128 v[186:189], v149 offset:17408
	ds_read_b128 v[190:193], v149 offset:18432
	ds_read_b128 v[194:197], v149 offset:19456
	ds_read_b128 v[198:201], v149 offset:20480
	ds_read_b128 v[202:205], v149 offset:21504
	ds_read_b128 v[206:209], v149 offset:22528
	ds_read_b128 v[210:213], v149 offset:23552
	global_load_lds_dwordx4 v[142:143], off
	v_lshl_add_u64 v[214:215], s[40:41], 0, v[130:131]
	s_mov_b32 m0, s71
	v_lshl_add_u64 v[216:217], s[42:43], 0, v[134:135]
	global_load_lds_dwordx4 v[214:215], off
	s_mov_b32 m0, s73
	v_lshl_add_u64 v[218:219], s[38:39], 0, v[132:133]
	global_load_lds_dwordx4 v[216:217], off
	v_lshl_add_u64 v[216:217], s[42:43], 0, v[130:131]
	s_mov_b32 m0, s72
	s_nop 0
	global_load_lds_dwordx4 v[216:217], off
	v_lshl_add_u64 v[216:217], s[38:39], 0, v[136:137]
	s_mov_b32 m0, s50
	s_nop 0
	global_load_lds_dwordx4 v[216:217], off
	s_mov_b32 m0, s51
	s_nop 0
	global_load_lds_dwordx4 v[218:219], off
	s_waitcnt vmcnt(8)
	s_waitcnt lgkmcnt(0)
	s_setprio 1
	s_barrier
; #define PG8_STAGE(bufoff, gbase, voff) do { _Pragma("unroll") for (int _i = 0; _i < 2; ++_i) \
;         __builtin_amdgcn_global_load_lds((const unsigned*)((const char*)(gbase) + (voff)[_i]), (PG8_LAS unsigned*)(lds + (bufoff) + ldsw + _i * 8192), 16, 0, 0); } while (0)
; #define PG8_LDA(dst, b, h) do { _Pragma("unroll") for (int m = 0; m < 4; ++m) _Pragma("unroll") for (int k = 0; k < 2; ++k) dst[m][k] = *(const PG8_LAS bf16x8*)(lds + PG8_SA(b, h) + aoff + m * 2048 + k * 1024); } while (0)
; #define PG8_LDB(dst, b, h) do { _Pragma("unroll") for (int n = 0; n < 2; ++n) _Pragma("unroll") for (int k = 0; k < 2; ++k) dst[n][k] = *(const PG8_LAS bf16x8*)(lds + PG8_SB(b, h) + boff + n * 2048 + k * 1024); } while (0)
; #define PG8_MMA(ai, bj, At, Bt) do { __builtin_amdgcn_s_setprio(1); _Pragma("unroll") for (int m = 0; m < 4; ++m) _Pragma("unroll") for (int n = 0; n < 2; ++n) _Pragma("unroll") for (int k = 0; k < 2; ++k) \
;         acc[ai][bj][m][n] = __builtin_amdgcn_mfma_f32_16x16x32_bf16(Bt[n][k], At[m][k], acc[ai][bj][m][n], 0, 0, 0); __builtin_amdgcn_s_setprio(0); } while (0)
; #define PG8_WAIT_V(n) asm volatile("s_waitcnt vmcnt(" #n ")" ::: "memory")
; #define PG8_WAIT_L(n) asm volatile("s_waitcnt lgkmcnt(" #n ")" ::: "memory")
; #define PG8_BAR __builtin_amdgcn_s_barrier()
; #define PG8_SCHED __builtin_amdgcn_sched_barrier(0)
; template <class Epi, class Sched, bool ALIGN_EPI = false, bool SP2 = false>
; __device__ __forceinline__ void gemm_phase(PG8_LAS unsigned char* lds, const Gemm g, const Sched& S, const Epi& E) {
;     ...
;             PG8_WAIT_V(8); PG8_WAIT_L(0); PG8_BAR; PG8_MMA(1, 0, At, B0); PG8_MMA(1, 1, At, B1); PG8_BAR; PG8_SCHED;
;             PG8_LDB(B0, 1, 0); PG8_LDB(B1, 1, 1); PG8_SCHED; PG8_LDA(At, 1, 0); PG8_STAGE(PG8_SA(0, 1), a2 + hstep, voffA);
;             PG8_WAIT_V(8); PG8_WAIT_L(0); PG8_BAR; PG8_MMA(0, 0, At, B0); PG8_MMA(0, 1, At, B1); PG8_BAR; PG8_SCHED;
;             PG8_LDA(At, 1, 1); PG8_STAGE(PG8_SB(1, 0), b3, voffB); PG8_STAGE(PG8_SB(1, 1), b3 + hstep, voffB); PG8_STAGE(PG8_SA(1, 0), a3, voffA);
	v_mfma_f32_16x16x32_bf16 v[62:65], v[150:153], v[182:185], v[62:65]
	v_mfma_f32_16x16x32_bf16 v[58:61], v[158:161], v[182:185], v[58:61]
	v_mfma_f32_16x16x32_bf16 v[54:57], v[150:153], v[190:193], v[54:57]
	v_mfma_f32_16x16x32_bf16 v[46:49], v[158:161], v[190:193], v[46:49]
	v_mfma_f32_16x16x32_bf16 v[38:41], v[150:153], v[198:201], v[38:41]
	v_mfma_f32_16x16x32_bf16 v[30:33], v[158:161], v[198:201], v[30:33]
	v_mfma_f32_16x16x32_bf16 v[22:25], v[150:153], v[206:209], v[22:25]
	v_mfma_f32_16x16x32_bf16 v[14:17], v[158:161], v[206:209], v[14:17]
	v_mfma_f32_16x16x32_bf16 v[62:65], v[154:157], v[186:189], v[62:65]
	v_mfma_f32_16x16x32_bf16 v[58:61], v[162:165], v[186:189], v[58:61]
	v_mfma_f32_16x16x32_bf16 v[54:57], v[154:157], v[194:197], v[54:57]
	v_mfma_f32_16x16x32_bf16 v[46:49], v[162:165], v[194:197], v[46:49]
	v_mfma_f32_16x16x32_bf16 v[38:41], v[154:157], v[202:205], v[38:41]
	v_mfma_f32_16x16x32_bf16 v[30:33], v[162:165], v[202:205], v[30:33]
	v_mfma_f32_16x16x32_bf16 v[22:25], v[154:157], v[210:213], v[22:25]
	v_mfma_f32_16x16x32_bf16 v[14:17], v[162:165], v[210:213], v[14:17]
	s_setprio 0
	s_setprio 1
	v_mfma_f32_16x16x32_bf16 v[50:53], v[166:169], v[182:185], v[50:53]
	v_mfma_f32_16x16x32_bf16 v[42:45], v[174:177], v[182:185], v[42:45]
	v_mfma_f32_16x16x32_bf16 v[34:37], v[166:169], v[190:193], v[34:37]
	v_mfma_f32_16x16x32_bf16 v[26:29], v[174:177], v[190:193], v[26:29]
	v_mfma_f32_16x16x32_bf16 v[18:21], v[166:169], v[198:201], v[18:21]
	v_mfma_f32_16x16x32_bf16 v[10:13], v[174:177], v[198:201], v[10:13]
	v_mfma_f32_16x16x32_bf16 v[6:9], v[166:169], v[206:209], v[6:9]
	v_mfma_f32_16x16x32_bf16 v[2:5], v[174:177], v[206:209], v[2:5]
	v_mfma_f32_16x16x32_bf16 v[50:53], v[170:173], v[186:189], v[50:53]
	v_mfma_f32_16x16x32_bf16 v[42:45], v[178:181], v[186:189], v[42:45]
	v_mfma_f32_16x16x32_bf16 v[34:37], v[170:173], v[194:197], v[34:37]
	v_mfma_f32_16x16x32_bf16 v[26:29], v[178:181], v[194:197], v[26:29]
	v_mfma_f32_16x16x32_bf16 v[18:21], v[170:173], v[202:205], v[18:21]
	v_mfma_f32_16x16x32_bf16 v[10:13], v[178:181], v[202:205], v[10:13]
	v_mfma_f32_16x16x32_bf16 v[6:9], v[170:173], v[210:213], v[6:9]
	v_mfma_f32_16x16x32_bf16 v[2:5], v[178:181], v[210:213], v[2:5]
	s_setprio 0
	s_barrier
	v_add_u32_e32 v162, s70, v145
	v_add_u32_e32 v178, s69, v145
	ds_read_b128 v[150:153], v162
	ds_read_b128 v[154:157], v162 offset:1024
	ds_read_b128 v[158:161], v162 offset:2048
	ds_read_b128 v[162:165], v162 offset:3072
	ds_read_b128 v[166:169], v178
	ds_read_b128 v[170:173], v178 offset:1024
	ds_read_b128 v[174:177], v178 offset:2048
	ds_read_b128 v[178:181], v178 offset:3072
	s_mov_b32 m0, s52
	v_lshl_add_u64 v[220:221], s[36:37], 0, v[136:137]
	ds_read_b128 v[182:185], v149 offset:32768
	ds_read_b128 v[186:189], v149 offset:33792
	ds_read_b128 v[190:193], v149 offset:34816
	ds_read_b128 v[194:197], v149 offset:35840
	ds_read_b128 v[198:201], v149 offset:36864
	ds_read_b128 v[202:205], v149 offset:37888
	ds_read_b128 v[206:209], v149 offset:38912
	ds_read_b128 v[210:213], v149 offset:39936
	global_load_lds_dwordx4 v[220:221], off
	v_lshl_add_u64 v[220:221], s[36:37], 0, v[132:133]
	s_mov_b32 m0, s53
	s_nop 0
	global_load_lds_dwordx4 v[220:221], off
	s_waitcnt vmcnt(8)
	s_waitcnt lgkmcnt(0)
	s_setprio 1
	s_barrier
	v_mfma_f32_16x16x32_bf16 v[126:129], v[150:153], v[182:185], v[126:129]
	v_mfma_f32_16x16x32_bf16 v[122:125], v[158:161], v[182:185], v[122:125]
	v_mfma_f32_16x16x32_bf16 v[118:121], v[150:153], v[190:193], v[118:121]
	v_mfma_f32_16x16x32_bf16 v[110:113], v[158:161], v[190:193], v[110:113]
	v_mfma_f32_16x16x32_bf16 v[102:105], v[150:153], v[198:201], v[102:105]
	v_mfma_f32_16x16x32_bf16 v[94:97], v[158:161], v[198:201], v[94:97]
	v_mfma_f32_16x16x32_bf16 v[86:89], v[150:153], v[206:209], v[86:89]
	v_mfma_f32_16x16x32_bf16 v[78:81], v[158:161], v[206:209], v[78:81]
	v_mfma_f32_16x16x32_bf16 v[126:129], v[154:157], v[186:189], v[126:129]
	v_mfma_f32_16x16x32_bf16 v[122:125], v[162:165], v[186:189], v[122:125]
	v_mfma_f32_16x16x32_bf16 v[118:121], v[154:157], v[194:197], v[118:121]
	v_mfma_f32_16x16x32_bf16 v[110:113], v[162:165], v[194:197], v[110:113]
	v_mfma_f32_16x16x32_bf16 v[102:105], v[154:157], v[202:205], v[102:105]
	v_mfma_f32_16x16x32_bf16 v[94:97], v[162:165], v[202:205], v[94:97]
	v_mfma_f32_16x16x32_bf16 v[86:89], v[154:157], v[210:213], v[86:89]
	v_mfma_f32_16x16x32_bf16 v[78:81], v[162:165], v[210:213], v[78:81]
	s_setprio 0
	s_setprio 1
	v_mfma_f32_16x16x32_bf16 v[114:117], v[166:169], v[182:185], v[114:117]
	v_mfma_f32_16x16x32_bf16 v[106:109], v[174:177], v[182:185], v[106:109]
	v_mfma_f32_16x16x32_bf16 v[98:101], v[166:169], v[190:193], v[98:101]
	v_mfma_f32_16x16x32_bf16 v[90:93], v[174:177], v[190:193], v[90:93]
	v_mfma_f32_16x16x32_bf16 v[82:85], v[166:169], v[198:201], v[82:85]
	v_mfma_f32_16x16x32_bf16 v[74:77], v[174:177], v[198:201], v[74:77]
	v_mfma_f32_16x16x32_bf16 v[70:73], v[166:169], v[206:209], v[70:73]
	v_mfma_f32_16x16x32_bf16 v[66:69], v[174:177], v[206:209], v[66:69]
	v_mfma_f32_16x16x32_bf16 v[114:117], v[170:173], v[186:189], v[114:117]
	v_mfma_f32_16x16x32_bf16 v[106:109], v[178:181], v[186:189], v[106:109]
	v_mfma_f32_16x16x32_bf16 v[98:101], v[170:173], v[194:197], v[98:101]
	v_mfma_f32_16x16x32_bf16 v[90:93], v[178:181], v[194:197], v[90:93]
	v_mfma_f32_16x16x32_bf16 v[82:85], v[170:173], v[202:205], v[82:85]
	v_mfma_f32_16x16x32_bf16 v[74:77], v[178:181], v[202:205], v[74:77]
	v_mfma_f32_16x16x32_bf16 v[70:73], v[170:173], v[210:213], v[70:73]
	v_mfma_f32_16x16x32_bf16 v[66:69], v[178:181], v[210:213], v[66:69]
	s_setprio 0
	s_barrier
; #define PG8_STAGE(bufoff, gbase, voff) do { _Pragma("unroll") for (int _i = 0; _i < 2; ++_i) \
;         __builtin_amdgcn_global_load_lds((const unsigned*)((const char*)(gbase) + (voff)[_i]), (PG8_LAS unsigned*)(lds + (bufoff) + ldsw + _i * 8192), 16, 0, 0); } while (0)
; #define PG8_LDA(dst, b, h) do { _Pragma("unroll") for (int m = 0; m < 4; ++m) _Pragma("unroll") for (int k = 0; k < 2; ++k) dst[m][k] = *(const PG8_LAS bf16x8*)(lds + PG8_SA(b, h) + aoff + m * 2048 + k * 1024); } while (0)
; #define PG8_MMA(ai, bj, At, Bt) do { __builtin_amdgcn_s_setprio(1); _Pragma("unroll") for (int m = 0; m < 4; ++m) _Pragma("unroll") for (int n = 0; n < 2; ++n) _Pragma("unroll") for (int k = 0; k < 2; ++k) \
;         acc[ai][bj][m][n] = __builtin_amdgcn_mfma_f32_16x16x32_bf16(Bt[n][k], At[m][k], acc[ai][bj][m][n], 0, 0, 0); __builtin_amdgcn_s_setprio(0); } while (0)
; #define PG8_WAIT_V(n) asm volatile("s_waitcnt vmcnt(" #n ")" ::: "memory")
; #define PG8_WAIT_L(n) asm volatile("s_waitcnt lgkmcnt(" #n ")" ::: "memory")
; #define PG8_BAR __builtin_amdgcn_s_barrier()
; #define PG8_SCHED __builtin_amdgcn_sched_barrier(0)
; template <class Epi, class Sched, bool ALIGN_EPI = false, bool SP2 = false>
; __device__ __forceinline__ void gemm_phase(PG8_LAS unsigned char* lds, const Gemm g, const Sched& S, const Epi& E) {
;     ...
;         for (int t = 0; t < nt; t += 2) {
;     ...
;             PG8_LDA(At, 1, 1); PG8_STAGE(PG8_SB(1, 0), b3, voffB); PG8_STAGE(PG8_SB(1, 1), b3 + hstep, voffB); PG8_STAGE(PG8_SA(1, 0), a3, voffA);
;             PG8_WAIT_V(8); PG8_WAIT_L(0); PG8_BAR; PG8_MMA(1, 0, At, B0); PG8_MMA(1, 1, At, B1); PG8_BAR; PG8_SCHED;
	s_mov_b32 m0, s68
	v_lshl_add_u64 v[142:143], v[142:143], 0, s[10:11]
	ds_read_b128 v[182:185], v149 offset:49152
	ds_read_b128 v[186:189], v149 offset:50176
	ds_read_b128 v[190:193], v149 offset:51200
	ds_read_b128 v[194:197], v149 offset:52224
	ds_read_b128 v[198:201], v149 offset:53248
	ds_read_b128 v[202:205], v149 offset:54272
	ds_read_b128 v[206:209], v149 offset:55296
	ds_read_b128 v[210:213], v149 offset:56320
	global_load_lds_dwordx4 v[142:143], off
	v_lshl_add_u64 v[142:143], v[214:215], 0, s[10:11]
	s_mov_b32 m0, s66
	s_nop 0
	global_load_lds_dwordx4 v[142:143], off
	v_lshl_add_u64 v[142:143], s[30:31], 0, v[134:135]
	s_mov_b32 m0, s67
	s_nop 0
	global_load_lds_dwordx4 v[142:143], off
	v_lshl_add_u64 v[142:143], s[30:31], 0, v[130:131]
	s_mov_b32 m0, s65
	s_nop 0
	global_load_lds_dwordx4 v[142:143], off
	v_lshl_add_u64 v[142:143], v[216:217], 0, s[10:11]
	s_mov_b32 m0, s55
	s_nop 0
	global_load_lds_dwordx4 v[142:143], off
	v_lshl_add_u64 v[142:143], v[218:219], 0, s[10:11]
	s_mov_b32 m0, s56
	s_nop 0
	global_load_lds_dwordx4 v[142:143], off
	s_waitcnt vmcnt(8)
	s_waitcnt lgkmcnt(0)
	s_setprio 1
	s_barrier
	v_mfma_f32_16x16x32_bf16 v[62:65], v[150:153], v[182:185], v[62:65]
	v_mfma_f32_16x16x32_bf16 v[58:61], v[158:161], v[182:185], v[58:61]
	v_mfma_f32_16x16x32_bf16 v[54:57], v[150:153], v[190:193], v[54:57]
	v_mfma_f32_16x16x32_bf16 v[46:49], v[158:161], v[190:193], v[46:49]
	v_mfma_f32_16x16x32_bf16 v[38:41], v[150:153], v[198:201], v[38:41]
	v_mfma_f32_16x16x32_bf16 v[30:33], v[158:161], v[198:201], v[30:33]
	v_mfma_f32_16x16x32_bf16 v[22:25], v[150:153], v[206:209], v[22:25]
	v_mfma_f32_16x16x32_bf16 v[14:17], v[158:161], v[206:209], v[14:17]
	v_mfma_f32_16x16x32_bf16 v[62:65], v[154:157], v[186:189], v[62:65]
	v_mfma_f32_16x16x32_bf16 v[58:61], v[162:165], v[186:189], v[58:61]
	v_mfma_f32_16x16x32_bf16 v[54:57], v[154:157], v[194:197], v[54:57]
	v_mfma_f32_16x16x32_bf16 v[46:49], v[162:165], v[194:197], v[46:49]
	v_mfma_f32_16x16x32_bf16 v[38:41], v[154:157], v[202:205], v[38:41]
	v_mfma_f32_16x16x32_bf16 v[30:33], v[162:165], v[202:205], v[30:33]
	v_mfma_f32_16x16x32_bf16 v[22:25], v[154:157], v[210:213], v[22:25]
	v_mfma_f32_16x16x32_bf16 v[14:17], v[162:165], v[210:213], v[14:17]
	s_setprio 0
	s_setprio 1
	v_mfma_f32_16x16x32_bf16 v[50:53], v[166:169], v[182:185], v[50:53]
	v_mfma_f32_16x16x32_bf16 v[42:45], v[174:177], v[182:185], v[42:45]
	v_mfma_f32_16x16x32_bf16 v[34:37], v[166:169], v[190:193], v[34:37]
	v_mfma_f32_16x16x32_bf16 v[26:29], v[174:177], v[190:193], v[26:29]
	v_mfma_f32_16x16x32_bf16 v[18:21], v[166:169], v[198:201], v[18:21]
	v_mfma_f32_16x16x32_bf16 v[10:13], v[174:177], v[198:201], v[10:13]
	v_mfma_f32_16x16x32_bf16 v[6:9], v[166:169], v[206:209], v[6:9]
	v_mfma_f32_16x16x32_bf16 v[2:5], v[174:177], v[206:209], v[2:5]
	v_mfma_f32_16x16x32_bf16 v[50:53], v[170:173], v[186:189], v[50:53]
	v_mfma_f32_16x16x32_bf16 v[42:45], v[178:181], v[186:189], v[42:45]
	v_mfma_f32_16x16x32_bf16 v[34:37], v[170:173], v[194:197], v[34:37]
	v_mfma_f32_16x16x32_bf16 v[26:29], v[178:181], v[194:197], v[26:29]
	v_mfma_f32_16x16x32_bf16 v[18:21], v[170:173], v[202:205], v[18:21]
	v_mfma_f32_16x16x32_bf16 v[10:13], v[178:181], v[202:205], v[10:13]
	v_mfma_f32_16x16x32_bf16 v[6:9], v[170:173], v[210:213], v[6:9]
	v_mfma_f32_16x16x32_bf16 v[2:5], v[178:181], v[210:213], v[2:5]
	s_setprio 0
	s_movk_i32 s36, 0x100
	s_andn2_b64 vcc, exec, s[28:29]
	s_mov_b64 s[30:31], -1
	s_mov_b64 s[28:29], 0
	s_barrier
	s_cbranch_vccz .LBB0_1693
	s_and_b64 vcc, exec, s[12:13]
	s_cbranch_vccz .LBB0_1696
	s_barrier

; #define PG8_STAGE(bufoff, gbase, voff) do { _Pragma("unroll") for (int _i = 0; _i < 2; ++_i) \
;         __builtin_amdgcn_global_load_lds((const unsigned*)((const char*)(gbase) + (voff)[_i]), (PG8_LAS unsigned*)(lds + (bufoff) + ldsw + _i * 8192), 16, 0, 0); } while (0)
; #define PG8_LDA(dst, b, h) do { _Pragma("unroll") for (int m = 0; m < 4; ++m) _Pragma("unroll") for (int k = 0; k < 2; ++k) dst[m][k] = *(const PG8_LAS bf16x8*)(lds + PG8_SA(b, h) + aoff + m * 2048 + k * 1024); } while (0)
; #define PG8_LDB(dst, b, h) do { _Pragma("unroll") for (int n = 0; n < 2; ++n) _Pragma("unroll") for (int k = 0; k < 2; ++k) dst[n][k] = *(const PG8_LAS bf16x8*)(lds + PG8_SB(b, h) + boff + n * 2048 + k * 1024); } while (0)
; #define PG8_MMA(ai, bj, At, Bt) do { __builtin_amdgcn_s_setprio(1); _Pragma("unroll") for (int m = 0; m < 4; ++m) _Pragma("unroll") for (int n = 0; n < 2; ++n) _Pragma("unroll") for (int k = 0; k < 2; ++k) \
;         acc[ai][bj][m][n] = __builtin_amdgcn_mfma_f32_16x16x32_bf16(Bt[n][k], At[m][k], acc[ai][bj][m][n], 0, 0, 0); __builtin_amdgcn_s_setprio(0); } while (0)
; #define PG8_BAR __builtin_amdgcn_s_barrier()
; template <class Epi, class Sched, bool ALIGN_EPI = false, bool SP2 = false>
; __device__ __forceinline__ void gemm_phase(PG8_LAS unsigned char* lds, const Gemm g, const Sched& S, const Epi& E) {
;     ...
;         for (int t = 0; t < nt; t += 2) {
;             if constexpr (Epi::MIDHOOK) { if (t == (nt >> 1)) E.mid(acc, cur, wr, wc, fr, fq); }
;             const bool last = (t == nt - 2);
;             const char* a1 = cA + (size_t)(t + 1) * kstep;
;             const char* a2 = last ? nA : cA + (size_t)(t + 2) * kstep; const char* b2 = last ? nB : cB + (size_t)(t + 2) * kstep;
;             const char* a3 = a2 + kstep; const char* b3 = b2 + kstep;
;             if (last && has_next) S.a_ready(nxt);
;             if constexpr (SP2) {
;             PG8_LDB(B0, 0, 0); PG8_LDB(B1, 0, 1); PG8_SCHED; PG8_LDA(At, 0, 0); PG8_STAGE(PG8_SA(1, 1), a1 + hstep, voffA);
;             PG8_WAIT_V(8); PG8_WAIT_L(0); PG8_BAR; PG8_MMA(0, 0, At, B0); PG8_MMA(0, 1, At, B1); PG8_BAR; PG8_SCHED;
;             PG8_LDA(At, 0, 1); PG8_STAGE(PG8_SB(0, 0), b2, voffB); PG8_STAGE(PG8_SB(0, 1), b2 + hstep, voffB); PG8_STAGE(PG8_SA(0, 0), a2, voffA);
;             PG8_WAIT_V(8); PG8_WAIT_L(0); PG8_BAR; PG8_MMA(1, 0, At, B0); PG8_MMA(1, 1, At, B1); PG8_BAR; PG8_SCHED;
.LBB0_1820:
	ds_read_b128 v[146:149], v155
	ds_read_b128 v[158:161], v155 offset:1024
	ds_read_b128 v[162:165], v155 offset:2048
	ds_read_b128 v[166:169], v155 offset:3072
	ds_read_b128 v[170:173], v156
	ds_read_b128 v[174:177], v156 offset:1024
	ds_read_b128 v[178:181], v156 offset:2048
	ds_read_b128 v[182:185], v156 offset:3072
	s_add_u32 s38, s36, 0xfff80080
	s_addc_u32 s39, s37, -1
	s_cmp_eq_u32 s58, 28
	s_cselect_b32 s41, s25, s39
	s_cselect_b32 s40, s54, s38
	s_cselect_b32 s39, s23, s57
	s_cselect_b32 s38, s55, s56
	v_lshl_add_u64 v[150:151], s[36:37], 0, v[138:139]
	s_add_i32 m0, s31, 0xc000
	ds_read_b128 v[186:189], v157
	ds_read_b128 v[190:193], v157 offset:1024
	ds_read_b128 v[194:197], v157 offset:2048
	ds_read_b128 v[198:201], v157 offset:3072
	ds_read_b128 v[202:205], v157 offset:4096
	ds_read_b128 v[206:209], v157 offset:5120
	ds_read_b128 v[210:213], v157 offset:6144
	ds_read_b128 v[214:217], v157 offset:7168
	global_load_lds_dwordx4 v[150:151], off
	v_lshl_add_u64 v[150:151], s[36:37], 0, v[140:141]
	s_add_i32 m0, s31, 0xe000
	s_nop 0
	global_load_lds_dwordx4 v[150:151], off
	s_waitcnt vmcnt(8)
	s_waitcnt lgkmcnt(0)
	s_setprio 1
	s_barrier
	v_mfma_f32_16x16x32_bf16 v[126:129], v[146:149], v[186:189], v[126:129]
	v_mfma_f32_16x16x32_bf16 v[122:125], v[162:165], v[186:189], v[122:125]
	v_mfma_f32_16x16x32_bf16 v[110:113], v[146:149], v[194:197], v[110:113]
	v_mfma_f32_16x16x32_bf16 v[106:109], v[162:165], v[194:197], v[106:109]
	v_mfma_f32_16x16x32_bf16 v[94:97], v[146:149], v[202:205], v[94:97]
	v_mfma_f32_16x16x32_bf16 v[90:93], v[162:165], v[202:205], v[90:93]
	v_mfma_f32_16x16x32_bf16 v[78:81], v[146:149], v[210:213], v[78:81]
	v_mfma_f32_16x16x32_bf16 v[74:77], v[162:165], v[210:213], v[74:77]
	v_mfma_f32_16x16x32_bf16 v[126:129], v[158:161], v[190:193], v[126:129]
	v_mfma_f32_16x16x32_bf16 v[122:125], v[166:169], v[190:193], v[122:125]
	v_mfma_f32_16x16x32_bf16 v[110:113], v[158:161], v[198:201], v[110:113]
	v_mfma_f32_16x16x32_bf16 v[106:109], v[166:169], v[198:201], v[106:109]
	v_mfma_f32_16x16x32_bf16 v[94:97], v[158:161], v[206:209], v[94:97]
	v_mfma_f32_16x16x32_bf16 v[90:93], v[166:169], v[206:209], v[90:93]
	v_mfma_f32_16x16x32_bf16 v[78:81], v[158:161], v[214:217], v[78:81]
	v_mfma_f32_16x16x32_bf16 v[74:77], v[166:169], v[214:217], v[74:77]
	s_setprio 0
	s_setprio 1
	v_mfma_f32_16x16x32_bf16 v[118:121], v[170:173], v[186:189], v[118:121]
	v_mfma_f32_16x16x32_bf16 v[114:117], v[178:181], v[186:189], v[114:117]
	v_mfma_f32_16x16x32_bf16 v[102:105], v[170:173], v[194:197], v[102:105]
	v_mfma_f32_16x16x32_bf16 v[98:101], v[178:181], v[194:197], v[98:101]
	v_mfma_f32_16x16x32_bf16 v[86:89], v[170:173], v[202:205], v[86:89]
	v_mfma_f32_16x16x32_bf16 v[82:85], v[178:181], v[202:205], v[82:85]
	v_mfma_f32_16x16x32_bf16 v[70:73], v[170:173], v[210:213], v[70:73]
	v_mfma_f32_16x16x32_bf16 v[66:69], v[178:181], v[210:213], v[66:69]
	v_mfma_f32_16x16x32_bf16 v[118:121], v[174:177], v[190:193], v[118:121]
	v_mfma_f32_16x16x32_bf16 v[114:117], v[182:185], v[190:193], v[114:117]
	v_mfma_f32_16x16x32_bf16 v[102:105], v[174:177], v[198:201], v[102:105]
	v_mfma_f32_16x16x32_bf16 v[98:101], v[182:185], v[198:201], v[98:101]
	v_mfma_f32_16x16x32_bf16 v[86:89], v[174:177], v[206:209], v[86:89]
	v_mfma_f32_16x16x32_bf16 v[82:85], v[182:185], v[206:209], v[82:85]
	v_mfma_f32_16x16x32_bf16 v[70:73], v[174:177], v[214:217], v[70:73]
	v_mfma_f32_16x16x32_bf16 v[66:69], v[182:185], v[214:217], v[66:69]
	s_setprio 0
	s_barrier
	s_add_i32 s59, s51, s3
	v_lshl_add_u64 v[150:151], s[38:39], 0, v[134:135]
	s_mov_b32 m0, s59
	ds_read_b128 v[186:189], v157 offset:16384
	ds_read_b128 v[190:193], v157 offset:17408
	ds_read_b128 v[194:197], v157 offset:18432
	ds_read_b128 v[198:201], v157 offset:19456
	ds_read_b128 v[202:205], v157 offset:20480
	ds_read_b128 v[206:209], v157 offset:21504
	ds_read_b128 v[210:213], v157 offset:22528
	ds_read_b128 v[214:217], v157 offset:23552
	global_load_lds_dwordx4 v[150:151], off
	s_add_i32 m0, s59, 0x2000
	s_add_u32 s60, s38, 0x80000
	v_lshl_add_u64 v[218:219], s[38:39], 0, v[130:131]
	s_addc_u32 s61, s39, 0
	s_add_i32 s59, s52, s3
	global_load_lds_dwordx4 v[218:219], off
	v_lshl_add_u64 v[220:221], s[60:61], 0, v[134:135]
	s_mov_b32 m0, s59
	v_lshl_add_u64 v[222:223], s[40:41], 0, v[132:133]
	global_load_lds_dwordx4 v[220:221], off
	v_lshl_add_u64 v[220:221], s[60:61], 0, v[130:131]
	s_add_i32 m0, s59, 0x2000
	s_nop 0
	global_load_lds_dwordx4 v[220:221], off
	v_lshl_add_u64 v[220:221], s[40:41], 0, v[136:137]
	s_mov_b32 m0, s31
	s_nop 0
	global_load_lds_dwordx4 v[220:221], off
	s_mov_b32 m0, s43
	s_nop 0
	global_load_lds_dwordx4 v[222:223], off
	s_waitcnt vmcnt(8)
	s_waitcnt lgkmcnt(0)
	s_setprio 1
	s_barrier
; #define PG8_STAGE(bufoff, gbase, voff) do { _Pragma("unroll") for (int _i = 0; _i < 2; ++_i) \
;         __builtin_amdgcn_global_load_lds((const unsigned*)((const char*)(gbase) + (voff)[_i]), (PG8_LAS unsigned*)(lds + (bufoff) + ldsw + _i * 8192), 16, 0, 0); } while (0)
; #define PG8_LDA(dst, b, h) do { _Pragma("unroll") for (int m = 0; m < 4; ++m) _Pragma("unroll") for (int k = 0; k < 2; ++k) dst[m][k] = *(const PG8_LAS bf16x8*)(lds + PG8_SA(b, h) + aoff + m * 2048 + k * 1024); } while (0)
; #define PG8_LDB(dst, b, h) do { _Pragma("unroll") for (int n = 0; n < 2; ++n) _Pragma("unroll") for (int k = 0; k < 2; ++k) dst[n][k] = *(const PG8_LAS bf16x8*)(lds + PG8_SB(b, h) + boff + n * 2048 + k * 1024); } while (0)
; #define PG8_MMA(ai, bj, At, Bt) do { __builtin_amdgcn_s_setprio(1); _Pragma("unroll") for (int m = 0; m < 4; ++m) _Pragma("unroll") for (int n = 0; n < 2; ++n) _Pragma("unroll") for (int k = 0; k < 2; ++k) \
;         acc[ai][bj][m][n] = __builtin_amdgcn_mfma_f32_16x16x32_bf16(Bt[n][k], At[m][k], acc[ai][bj][m][n], 0, 0, 0); __builtin_amdgcn_s_setprio(0); } while (0)
; #define PG8_WAIT_V(n) asm volatile("s_waitcnt vmcnt(" #n ")" ::: "memory")
; #define PG8_WAIT_L(n) asm volatile("s_waitcnt lgkmcnt(" #n ")" ::: "memory")
; #define PG8_BAR __builtin_amdgcn_s_barrier()
; #define PG8_SCHED __builtin_amdgcn_sched_barrier(0)
; template <class Epi, class Sched, bool ALIGN_EPI = false, bool SP2 = false>
; __device__ __forceinline__ void gemm_phase(PG8_LAS unsigned char* lds, const Gemm g, const Sched& S, const Epi& E) {
;     ...
;             PG8_WAIT_V(8); PG8_WAIT_L(0); PG8_BAR; PG8_MMA(1, 0, At, B0); PG8_MMA(1, 1, At, B1); PG8_BAR; PG8_SCHED;
;             PG8_LDB(B0, 1, 0); PG8_LDB(B1, 1, 1); PG8_SCHED; PG8_LDA(At, 1, 0); PG8_STAGE(PG8_SA(0, 1), a2 + hstep, voffA);
;             PG8_WAIT_V(8); PG8_WAIT_L(0); PG8_BAR; PG8_MMA(0, 0, At, B0); PG8_MMA(0, 1, At, B1); PG8_BAR; PG8_SCHED;
;             PG8_LDA(At, 1, 1); PG8_STAGE(PG8_SB(1, 0), b3, voffB); PG8_STAGE(PG8_SB(1, 1), b3 + hstep, voffB); PG8_STAGE(PG8_SA(1, 0), a3, voffA);
	v_mfma_f32_16x16x32_bf16 v[62:65], v[146:149], v[186:189], v[62:65]
	v_mfma_f32_16x16x32_bf16 v[58:61], v[162:165], v[186:189], v[58:61]
	v_mfma_f32_16x16x32_bf16 v[46:49], v[146:149], v[194:197], v[46:49]
	v_mfma_f32_16x16x32_bf16 v[42:45], v[162:165], v[194:197], v[42:45]
	v_mfma_f32_16x16x32_bf16 v[30:33], v[146:149], v[202:205], v[30:33]
	v_mfma_f32_16x16x32_bf16 v[26:29], v[162:165], v[202:205], v[26:29]
	v_mfma_f32_16x16x32_bf16 v[14:17], v[146:149], v[210:213], v[14:17]
	v_mfma_f32_16x16x32_bf16 v[10:13], v[162:165], v[210:213], v[10:13]
	v_mfma_f32_16x16x32_bf16 v[62:65], v[158:161], v[190:193], v[62:65]
	v_mfma_f32_16x16x32_bf16 v[58:61], v[166:169], v[190:193], v[58:61]
	v_mfma_f32_16x16x32_bf16 v[46:49], v[158:161], v[198:201], v[46:49]
	v_mfma_f32_16x16x32_bf16 v[42:45], v[166:169], v[198:201], v[42:45]
	v_mfma_f32_16x16x32_bf16 v[30:33], v[158:161], v[206:209], v[30:33]
	v_mfma_f32_16x16x32_bf16 v[26:29], v[166:169], v[206:209], v[26:29]
	v_mfma_f32_16x16x32_bf16 v[14:17], v[158:161], v[214:217], v[14:17]
	v_mfma_f32_16x16x32_bf16 v[10:13], v[166:169], v[214:217], v[10:13]
	s_setprio 0
	s_setprio 1
	v_mfma_f32_16x16x32_bf16 v[54:57], v[170:173], v[186:189], v[54:57]
	v_mfma_f32_16x16x32_bf16 v[50:53], v[178:181], v[186:189], v[50:53]
	v_mfma_f32_16x16x32_bf16 v[38:41], v[170:173], v[194:197], v[38:41]
	v_mfma_f32_16x16x32_bf16 v[34:37], v[178:181], v[194:197], v[34:37]
	v_mfma_f32_16x16x32_bf16 v[22:25], v[170:173], v[202:205], v[22:25]
	v_mfma_f32_16x16x32_bf16 v[18:21], v[178:181], v[202:205], v[18:21]
	v_mfma_f32_16x16x32_bf16 v[6:9], v[170:173], v[210:213], v[6:9]
	v_mfma_f32_16x16x32_bf16 v[2:5], v[178:181], v[210:213], v[2:5]
	v_mfma_f32_16x16x32_bf16 v[54:57], v[174:177], v[190:193], v[54:57]
	v_mfma_f32_16x16x32_bf16 v[50:53], v[182:185], v[190:193], v[50:53]
	v_mfma_f32_16x16x32_bf16 v[38:41], v[174:177], v[198:201], v[38:41]
	v_mfma_f32_16x16x32_bf16 v[34:37], v[182:185], v[198:201], v[34:37]
	v_mfma_f32_16x16x32_bf16 v[22:25], v[174:177], v[206:209], v[22:25]
	v_mfma_f32_16x16x32_bf16 v[18:21], v[182:185], v[206:209], v[18:21]
	v_mfma_f32_16x16x32_bf16 v[6:9], v[174:177], v[214:217], v[6:9]
	v_mfma_f32_16x16x32_bf16 v[2:5], v[182:185], v[214:217], v[2:5]
	s_setprio 0
	s_barrier
	s_add_i32 s59, 0, 0x18000
	s_add_i32 s60, 0, 0x1c000
	v_add_u32_e32 v166, s59, v153
	v_add_u32_e32 v182, s60, v153
	ds_read_b128 v[146:149], v166
	ds_read_b128 v[158:161], v166 offset:1024
	ds_read_b128 v[162:165], v166 offset:2048
	ds_read_b128 v[166:169], v166 offset:3072
	ds_read_b128 v[170:173], v182
	ds_read_b128 v[174:177], v182 offset:1024
	ds_read_b128 v[178:181], v182 offset:2048
	ds_read_b128 v[182:185], v182 offset:3072
	s_add_u32 s40, s40, 0x80000
	s_addc_u32 s41, s41, 0
	s_mov_b32 m0, s44
	v_lshl_add_u64 v[224:225], s[40:41], 0, v[136:137]
	ds_read_b128 v[186:189], v157 offset:32768
	ds_read_b128 v[190:193], v157 offset:33792
	ds_read_b128 v[194:197], v157 offset:34816
	ds_read_b128 v[198:201], v157 offset:35840
	ds_read_b128 v[202:205], v157 offset:36864
	ds_read_b128 v[206:209], v157 offset:37888
	ds_read_b128 v[210:213], v157 offset:38912
	ds_read_b128 v[214:217], v157 offset:39936
	global_load_lds_dwordx4 v[224:225], off
	v_lshl_add_u64 v[224:225], s[40:41], 0, v[132:133]
	s_mov_b32 m0, s45
	s_nop 0
	global_load_lds_dwordx4 v[224:225], off
	s_waitcnt vmcnt(8)
	s_waitcnt lgkmcnt(0)
	s_setprio 1
	s_barrier
	v_mfma_f32_16x16x32_bf16 v[126:129], v[146:149], v[186:189], v[126:129]
	v_mfma_f32_16x16x32_bf16 v[122:125], v[162:165], v[186:189], v[122:125]
	v_mfma_f32_16x16x32_bf16 v[110:113], v[146:149], v[194:197], v[110:113]
	v_mfma_f32_16x16x32_bf16 v[106:109], v[162:165], v[194:197], v[106:109]
	v_mfma_f32_16x16x32_bf16 v[94:97], v[146:149], v[202:205], v[94:97]
	v_mfma_f32_16x16x32_bf16 v[90:93], v[162:165], v[202:205], v[90:93]
	v_mfma_f32_16x16x32_bf16 v[78:81], v[146:149], v[210:213], v[78:81]
	v_mfma_f32_16x16x32_bf16 v[74:77], v[162:165], v[210:213], v[74:77]
	v_mfma_f32_16x16x32_bf16 v[126:129], v[158:161], v[190:193], v[126:129]
	v_mfma_f32_16x16x32_bf16 v[122:125], v[166:169], v[190:193], v[122:125]
	v_mfma_f32_16x16x32_bf16 v[110:113], v[158:161], v[198:201], v[110:113]
	v_mfma_f32_16x16x32_bf16 v[106:109], v[166:169], v[198:201], v[106:109]
	v_mfma_f32_16x16x32_bf16 v[94:97], v[158:161], v[206:209], v[94:97]
	v_mfma_f32_16x16x32_bf16 v[90:93], v[166:169], v[206:209], v[90:93]
	v_mfma_f32_16x16x32_bf16 v[78:81], v[158:161], v[214:217], v[78:81]
	v_mfma_f32_16x16x32_bf16 v[74:77], v[166:169], v[214:217], v[74:77]
	s_setprio 0
	s_setprio 1
	v_mfma_f32_16x16x32_bf16 v[118:121], v[170:173], v[186:189], v[118:121]
	v_mfma_f32_16x16x32_bf16 v[114:117], v[178:181], v[186:189], v[114:117]
	v_mfma_f32_16x16x32_bf16 v[102:105], v[170:173], v[194:197], v[102:105]
	v_mfma_f32_16x16x32_bf16 v[98:101], v[178:181], v[194:197], v[98:101]
	v_mfma_f32_16x16x32_bf16 v[86:89], v[170:173], v[202:205], v[86:89]
	v_mfma_f32_16x16x32_bf16 v[82:85], v[178:181], v[202:205], v[82:85]
	v_mfma_f32_16x16x32_bf16 v[70:73], v[170:173], v[210:213], v[70:73]
	v_mfma_f32_16x16x32_bf16 v[66:69], v[178:181], v[210:213], v[66:69]
	v_mfma_f32_16x16x32_bf16 v[118:121], v[174:177], v[190:193], v[118:121]
	v_mfma_f32_16x16x32_bf16 v[114:117], v[182:185], v[190:193], v[114:117]
	v_mfma_f32_16x16x32_bf16 v[102:105], v[174:177], v[198:201], v[102:105]
	v_mfma_f32_16x16x32_bf16 v[98:101], v[182:185], v[198:201], v[98:101]
	v_mfma_f32_16x16x32_bf16 v[86:89], v[174:177], v[206:209], v[86:89]
	v_mfma_f32_16x16x32_bf16 v[82:85], v[182:185], v[206:209], v[82:85]
	v_mfma_f32_16x16x32_bf16 v[70:73], v[174:177], v[214:217], v[70:73]
	v_mfma_f32_16x16x32_bf16 v[66:69], v[182:185], v[214:217], v[66:69]
	s_setprio 0
	s_barrier
; #define PG8_STAGE(bufoff, gbase, voff) do { _Pragma("unroll") for (int _i = 0; _i < 2; ++_i) \
;         __builtin_amdgcn_global_load_lds((const unsigned*)((const char*)(gbase) + (voff)[_i]), (PG8_LAS unsigned*)(lds + (bufoff) + ldsw + _i * 8192), 16, 0, 0); } while (0)
; #define PG8_LDA(dst, b, h) do { _Pragma("unroll") for (int m = 0; m < 4; ++m) _Pragma("unroll") for (int k = 0; k < 2; ++k) dst[m][k] = *(const PG8_LAS bf16x8*)(lds + PG8_SA(b, h) + aoff + m * 2048 + k * 1024); } while (0)
; #define PG8_MMA(ai, bj, At, Bt) do { __builtin_amdgcn_s_setprio(1); _Pragma("unroll") for (int m = 0; m < 4; ++m) _Pragma("unroll") for (int n = 0; n < 2; ++n) _Pragma("unroll") for (int k = 0; k < 2; ++k) \
;         acc[ai][bj][m][n] = __builtin_amdgcn_mfma_f32_16x16x32_bf16(Bt[n][k], At[m][k], acc[ai][bj][m][n], 0, 0, 0); __builtin_amdgcn_s_setprio(0); } while (0)
; #define PG8_WAIT_V(n) asm volatile("s_waitcnt vmcnt(" #n ")" ::: "memory")
; #define PG8_WAIT_L(n) asm volatile("s_waitcnt lgkmcnt(" #n ")" ::: "memory")
; #define PG8_BAR __builtin_amdgcn_s_barrier()
; #define PG8_SCHED __builtin_amdgcn_sched_barrier(0)
; template <class Epi, class Sched, bool ALIGN_EPI = false, bool SP2 = false>
; __device__ __forceinline__ void gemm_phase(PG8_LAS unsigned char* lds, const Gemm g, const Sched& S, const Epi& E) {
;     ...
;         for (int t = 0; t < nt; t += 2) {
;     ...
;             PG8_LDA(At, 1, 1); PG8_STAGE(PG8_SB(1, 0), b3, voffB); PG8_STAGE(PG8_SB(1, 1), b3 + hstep, voffB); PG8_STAGE(PG8_SA(1, 0), a3, voffA);
;             PG8_WAIT_V(8); PG8_WAIT_L(0); PG8_BAR; PG8_MMA(1, 0, At, B0); PG8_MMA(1, 1, At, B1); PG8_BAR; PG8_SCHED;
	s_add_i32 s40, s59, s3
	v_lshl_add_u64 v[150:151], v[150:151], 0, s[12:13]
	s_mov_b32 m0, s40
	ds_read_b128 v[186:189], v157 offset:49152
	ds_read_b128 v[190:193], v157 offset:50176
	ds_read_b128 v[194:197], v157 offset:51200
	ds_read_b128 v[198:201], v157 offset:52224
	ds_read_b128 v[202:205], v157 offset:53248
	ds_read_b128 v[206:209], v157 offset:54272
	ds_read_b128 v[210:213], v157 offset:55296
	ds_read_b128 v[214:217], v157 offset:56320
	global_load_lds_dwordx4 v[150:151], off
	s_add_i32 m0, s40, 0x2000
	s_add_u32 s38, s38, 0x80080
	v_lshl_add_u64 v[150:151], v[218:219], 0, s[12:13]
	s_addc_u32 s39, s39, 0
	s_add_i32 s40, s60, s3
	global_load_lds_dwordx4 v[150:151], off
	v_lshl_add_u64 v[150:151], s[38:39], 0, v[134:135]
	s_mov_b32 m0, s40
	s_nop 0
	global_load_lds_dwordx4 v[150:151], off
	v_lshl_add_u64 v[150:151], s[38:39], 0, v[130:131]
	s_add_i32 m0, s40, 0x2000
	s_nop 0
	global_load_lds_dwordx4 v[150:151], off
	v_lshl_add_u64 v[150:151], v[220:221], 0, s[12:13]
	s_mov_b32 m0, s48
	s_nop 0
	global_load_lds_dwordx4 v[150:151], off
	v_lshl_add_u64 v[150:151], v[222:223], 0, s[12:13]
	s_mov_b32 m0, s49
	s_nop 0
	global_load_lds_dwordx4 v[150:151], off
	s_waitcnt vmcnt(8)
	s_waitcnt lgkmcnt(0)
	s_setprio 1
	s_barrier
	v_mfma_f32_16x16x32_bf16 v[62:65], v[146:149], v[186:189], v[62:65]
	v_mfma_f32_16x16x32_bf16 v[58:61], v[162:165], v[186:189], v[58:61]
	v_mfma_f32_16x16x32_bf16 v[46:49], v[146:149], v[194:197], v[46:49]
	v_mfma_f32_16x16x32_bf16 v[42:45], v[162:165], v[194:197], v[42:45]
	v_mfma_f32_16x16x32_bf16 v[30:33], v[146:149], v[202:205], v[30:33]
	v_mfma_f32_16x16x32_bf16 v[26:29], v[162:165], v[202:205], v[26:29]
	v_mfma_f32_16x16x32_bf16 v[14:17], v[146:149], v[210:213], v[14:17]
	v_mfma_f32_16x16x32_bf16 v[10:13], v[162:165], v[210:213], v[10:13]
	v_mfma_f32_16x16x32_bf16 v[62:65], v[158:161], v[190:193], v[62:65]
	v_mfma_f32_16x16x32_bf16 v[58:61], v[166:169], v[190:193], v[58:61]
	v_mfma_f32_16x16x32_bf16 v[46:49], v[158:161], v[198:201], v[46:49]
	v_mfma_f32_16x16x32_bf16 v[42:45], v[166:169], v[198:201], v[42:45]
	v_mfma_f32_16x16x32_bf16 v[30:33], v[158:161], v[206:209], v[30:33]
	v_mfma_f32_16x16x32_bf16 v[26:29], v[166:169], v[206:209], v[26:29]
	v_mfma_f32_16x16x32_bf16 v[14:17], v[158:161], v[214:217], v[14:17]
	v_mfma_f32_16x16x32_bf16 v[10:13], v[166:169], v[214:217], v[10:13]
	s_setprio 0
	s_setprio 1
	v_mfma_f32_16x16x32_bf16 v[54:57], v[170:173], v[186:189], v[54:57]
	v_mfma_f32_16x16x32_bf16 v[50:53], v[178:181], v[186:189], v[50:53]
	v_mfma_f32_16x16x32_bf16 v[38:41], v[170:173], v[194:197], v[38:41]
	v_mfma_f32_16x16x32_bf16 v[34:37], v[178:181], v[194:197], v[34:37]
	v_mfma_f32_16x16x32_bf16 v[22:25], v[170:173], v[202:205], v[22:25]
	v_mfma_f32_16x16x32_bf16 v[18:21], v[178:181], v[202:205], v[18:21]
	v_mfma_f32_16x16x32_bf16 v[6:9], v[170:173], v[210:213], v[6:9]
	v_mfma_f32_16x16x32_bf16 v[2:5], v[178:181], v[210:213], v[2:5]
	v_mfma_f32_16x16x32_bf16 v[54:57], v[174:177], v[190:193], v[54:57]
	v_mfma_f32_16x16x32_bf16 v[50:53], v[182:185], v[190:193], v[50:53]
	v_mfma_f32_16x16x32_bf16 v[38:41], v[174:177], v[198:201], v[38:41]
	v_mfma_f32_16x16x32_bf16 v[34:37], v[182:185], v[198:201], v[34:37]
	v_mfma_f32_16x16x32_bf16 v[22:25], v[174:177], v[206:209], v[22:25]
	v_mfma_f32_16x16x32_bf16 v[18:21], v[182:185], v[206:209], v[18:21]
	v_mfma_f32_16x16x32_bf16 v[6:9], v[174:177], v[214:217], v[6:9]
	v_mfma_f32_16x16x32_bf16 v[2:5], v[182:185], v[214:217], v[2:5]
	s_setprio 0
	s_add_i32 s58, s58, 2
	s_add_u32 s36, s36, 0x100
	s_addc_u32 s37, s37, 0
	s_add_u32 s56, s56, 0x100
	s_addc_u32 s57, s57, 0
	s_cmp_gt_u32 s58, 29
	s_barrier
	s_cbranch_scc0 .LBB0_1820
	s_and_b64 vcc, exec, s[14:15]
	s_cbranch_vccz .LBB0_1823
	s_barrier

; #define PG8_STAGE(bufoff, gbase, voff) do { _Pragma("unroll") for (int _i = 0; _i < 2; ++_i) \
;         __builtin_amdgcn_global_load_lds((const unsigned*)((const char*)(gbase) + (voff)[_i]), (PG8_LAS unsigned*)(lds + (bufoff) + ldsw + _i * 8192), 16, 0, 0); } while (0)
; #define PG8_LDA(dst, b, h) do { _Pragma("unroll") for (int m = 0; m < 4; ++m) _Pragma("unroll") for (int k = 0; k < 2; ++k) dst[m][k] = *(const PG8_LAS bf16x8*)(lds + PG8_SA(b, h) + aoff + m * 2048 + k * 1024); } while (0)
; #define PG8_LDB(dst, b, h) do { _Pragma("unroll") for (int n = 0; n < 2; ++n) _Pragma("unroll") for (int k = 0; k < 2; ++k) dst[n][k] = *(const PG8_LAS bf16x8*)(lds + PG8_SB(b, h) + boff + n * 2048 + k * 1024); } while (0)
; #define PG8_WAIT_V(n) asm volatile("s_waitcnt vmcnt(" #n ")" ::: "memory")
; #define PG8_WAIT_L(n) asm volatile("s_waitcnt lgkmcnt(" #n ")" ::: "memory")
; #define PG8_BAR __builtin_amdgcn_s_barrier()
; template <class Epi, class Sched, bool ALIGN_EPI = false, bool SP2 = false>
; __device__ __forceinline__ void gemm_phase(PG8_LAS unsigned char* lds, const Gemm g, const Sched& S, const Epi& E) {
;     ...
;         const char* nA = has_next ? (const char*)g.A + (size_t)nxt.pm * tstep + (size_t)nxt.kt0 * kstep : cA; const char* nB = has_next ? (const char*)g.Bt + (size_t)nxt.pn * tstep + (size_t)nxt.kt0 * kstep : cB;
;         for (int t = 0; t < nt; t += 2) {
;             if constexpr (Epi::MIDHOOK) { if (t == (nt >> 1)) E.mid(acc, cur, wr, wc, fr, fq); }
;             const bool last = (t == nt - 2);
;             const char* a1 = cA + (size_t)(t + 1) * kstep;
;             const char* a2 = last ? nA : cA + (size_t)(t + 2) * kstep; const char* b2 = last ? nB : cB + (size_t)(t + 2) * kstep;
;             const char* a3 = a2 + kstep; const char* b3 = b2 + kstep;
;             if (last && has_next) S.a_ready(nxt);
;             if constexpr (SP2) {
;             PG8_LDB(B0, 0, 0); PG8_LDB(B1, 0, 1); PG8_SCHED; PG8_LDA(At, 0, 0); PG8_STAGE(PG8_SA(1, 1), a1 + hstep, voffA);
;             PG8_WAIT_V(8); PG8_WAIT_L(0); PG8_BAR; PG8_MMA(0, 0, At, B0); PG8_MMA(0, 1, At, B1); PG8_BAR; PG8_SCHED;
;             PG8_LDA(At, 0, 1); PG8_STAGE(PG8_SB(0, 0), b2, voffB); PG8_STAGE(PG8_SB(0, 1), b2 + hstep, voffB); PG8_STAGE(PG8_SA(0, 0), a2, voffA);
;             PG8_WAIT_V(8); PG8_WAIT_L(0); PG8_BAR; PG8_MMA(1, 0, At, B0); PG8_MMA(1, 1, At, B1); PG8_BAR; PG8_SCHED;
.LBB0_1840:
	s_add_u32 s25, s12, s3
	s_addc_u32 s27, s13, 0
	s_add_u32 s42, s25, 0x100
	s_addc_u32 s43, s27, 0
	s_and_b64 s[40:41], s[38:39], exec
	s_cselect_b32 s43, s29, s43
	s_cselect_b32 s42, s28, s42
	s_add_u32 s3, s8, s3
	s_addc_u32 s40, s9, 0
	s_add_u32 s3, s3, 0x100
	s_addc_u32 s40, s40, 0
	s_and_b64 s[38:39], s[38:39], exec
	s_cselect_b32 s45, s31, s40
	s_cselect_b32 s44, s30, s3
	s_add_u32 s48, s25, 0x80080
	ds_read_b128 v[140:143], v137
	ds_read_b128 v[144:147], v137 offset:1024
	ds_read_b128 v[148:151], v137 offset:2048
	ds_read_b128 v[152:155], v137 offset:3072
	ds_read_b128 v[156:159], v138
	ds_read_b128 v[160:163], v138 offset:1024
	ds_read_b128 v[164:167], v138 offset:2048
	ds_read_b128 v[168:171], v138 offset:3072
	s_addc_u32 s49, s27, 0
	s_add_i32 s74, s63, s51
	s_add_i32 m0, s54, 0xc000
	s_add_i32 s77, s54, 0xe000
	s_add_i32 s71, s74, 0x2000
	s_add_u32 s46, s44, 0x80000
	s_addc_u32 s47, s45, 0
	s_add_i32 s73, s64, s51
	s_add_i32 s72, s73, 0x2000
	s_add_i32 s70, 0, 0x18000
	s_add_i32 s27, 0, 0x1c000
	s_add_u32 s40, s42, 0x80000
	s_addc_u32 s41, s43, 0
	s_add_i32 s25, s70, s51
	s_add_i32 s3, s25, 0x2000
	s_add_u32 s38, s44, 0x80080
	s_addc_u32 s39, s45, 0
	s_add_i32 s76, s27, s51
	s_add_i32 s75, s76, 0x2000
	v_lshl_add_u64 v[204:205], s[48:49], 0, v[132:133]
	ds_read_b128 v[172:175], v139
	ds_read_b128 v[176:179], v139 offset:1024
	ds_read_b128 v[180:183], v139 offset:2048
	ds_read_b128 v[184:187], v139 offset:3072
	ds_read_b128 v[188:191], v139 offset:4096
	ds_read_b128 v[192:195], v139 offset:5120
	ds_read_b128 v[196:199], v139 offset:6144
	ds_read_b128 v[200:203], v139 offset:7168
	global_load_lds_dwordx4 v[204:205], off
	v_lshl_add_u64 v[204:205], s[48:49], 0, v[130:131]
	s_mov_b32 m0, s77
	s_nop 0
	global_load_lds_dwordx4 v[204:205], off
	s_waitcnt vmcnt(8)
	s_waitcnt lgkmcnt(0)
	s_setprio 1
	s_barrier
	v_mfma_f32_16x16x32_bf16 v[126:129], v[140:143], v[172:175], v[126:129]
	v_mfma_f32_16x16x32_bf16 v[122:125], v[148:151], v[172:175], v[122:125]
	v_mfma_f32_16x16x32_bf16 v[118:121], v[140:143], v[180:183], v[118:121]
	v_mfma_f32_16x16x32_bf16 v[114:117], v[148:151], v[180:183], v[114:117]
	v_mfma_f32_16x16x32_bf16 v[106:109], v[140:143], v[188:191], v[106:109]
	v_mfma_f32_16x16x32_bf16 v[98:101], v[148:151], v[188:191], v[98:101]
	v_mfma_f32_16x16x32_bf16 v[90:93], v[140:143], v[196:199], v[90:93]
	v_mfma_f32_16x16x32_bf16 v[82:85], v[148:151], v[196:199], v[82:85]
	v_mfma_f32_16x16x32_bf16 v[126:129], v[144:147], v[176:179], v[126:129]
	v_mfma_f32_16x16x32_bf16 v[122:125], v[152:155], v[176:179], v[122:125]
	v_mfma_f32_16x16x32_bf16 v[118:121], v[144:147], v[184:187], v[118:121]
	v_mfma_f32_16x16x32_bf16 v[114:117], v[152:155], v[184:187], v[114:117]
	v_mfma_f32_16x16x32_bf16 v[106:109], v[144:147], v[192:195], v[106:109]
	v_mfma_f32_16x16x32_bf16 v[98:101], v[152:155], v[192:195], v[98:101]
	v_mfma_f32_16x16x32_bf16 v[90:93], v[144:147], v[200:203], v[90:93]
	v_mfma_f32_16x16x32_bf16 v[82:85], v[152:155], v[200:203], v[82:85]
	s_setprio 0
	s_setprio 1
	v_mfma_f32_16x16x32_bf16 v[110:113], v[156:159], v[172:175], v[110:113]
	v_mfma_f32_16x16x32_bf16 v[102:105], v[164:167], v[172:175], v[102:105]
	v_mfma_f32_16x16x32_bf16 v[94:97], v[156:159], v[180:183], v[94:97]
	v_mfma_f32_16x16x32_bf16 v[86:89], v[164:167], v[180:183], v[86:89]
	v_mfma_f32_16x16x32_bf16 v[78:81], v[156:159], v[188:191], v[78:81]
	v_mfma_f32_16x16x32_bf16 v[74:77], v[164:167], v[188:191], v[74:77]
	v_mfma_f32_16x16x32_bf16 v[70:73], v[156:159], v[196:199], v[70:73]
	v_mfma_f32_16x16x32_bf16 v[66:69], v[164:167], v[196:199], v[66:69]
	v_mfma_f32_16x16x32_bf16 v[110:113], v[160:163], v[176:179], v[110:113]
	v_mfma_f32_16x16x32_bf16 v[102:105], v[168:171], v[176:179], v[102:105]
	v_mfma_f32_16x16x32_bf16 v[94:97], v[160:163], v[184:187], v[94:97]
	v_mfma_f32_16x16x32_bf16 v[86:89], v[168:171], v[184:187], v[86:89]
	v_mfma_f32_16x16x32_bf16 v[78:81], v[160:163], v[192:195], v[78:81]
	v_mfma_f32_16x16x32_bf16 v[74:77], v[168:171], v[192:195], v[74:77]
	v_mfma_f32_16x16x32_bf16 v[70:73], v[160:163], v[200:203], v[70:73]
	v_mfma_f32_16x16x32_bf16 v[66:69], v[168:171], v[200:203], v[66:69]
	s_setprio 0
	s_barrier
	s_mov_b32 m0, s74
	v_lshl_add_u64 v[204:205], s[44:45], 0, v[132:133]
	ds_read_b128 v[172:175], v139 offset:16384
	ds_read_b128 v[176:179], v139 offset:17408
	ds_read_b128 v[180:183], v139 offset:18432
	ds_read_b128 v[184:187], v139 offset:19456
	ds_read_b128 v[188:191], v139 offset:20480
	ds_read_b128 v[192:195], v139 offset:21504
	ds_read_b128 v[196:199], v139 offset:22528
	ds_read_b128 v[200:203], v139 offset:23552
	global_load_lds_dwordx4 v[204:205], off
	v_lshl_add_u64 v[206:207], s[44:45], 0, v[130:131]
	s_mov_b32 m0, s71
	v_lshl_add_u64 v[208:209], s[46:47], 0, v[132:133]
	global_load_lds_dwordx4 v[206:207], off
	s_mov_b32 m0, s73
	v_lshl_add_u64 v[210:211], s[42:43], 0, v[130:131]
	global_load_lds_dwordx4 v[208:209], off
	v_lshl_add_u64 v[208:209], s[46:47], 0, v[130:131]
	s_mov_b32 m0, s72
	s_nop 0
	global_load_lds_dwordx4 v[208:209], off
	v_lshl_add_u64 v[208:209], s[42:43], 0, v[132:133]
	s_mov_b32 m0, s54
	s_nop 0
	global_load_lds_dwordx4 v[208:209], off
	s_mov_b32 m0, s55
	s_nop 0
	global_load_lds_dwordx4 v[210:211], off
	s_waitcnt vmcnt(8)
	s_waitcnt lgkmcnt(0)
	s_setprio 1
	s_barrier
; #define PG8_STAGE(bufoff, gbase, voff) do { _Pragma("unroll") for (int _i = 0; _i < 2; ++_i) \
;         __builtin_amdgcn_global_load_lds((const unsigned*)((const char*)(gbase) + (voff)[_i]), (PG8_LAS unsigned*)(lds + (bufoff) + ldsw + _i * 8192), 16, 0, 0); } while (0)
; #define PG8_LDA(dst, b, h) do { _Pragma("unroll") for (int m = 0; m < 4; ++m) _Pragma("unroll") for (int k = 0; k < 2; ++k) dst[m][k] = *(const PG8_LAS bf16x8*)(lds + PG8_SA(b, h) + aoff + m * 2048 + k * 1024); } while (0)
; #define PG8_LDB(dst, b, h) do { _Pragma("unroll") for (int n = 0; n < 2; ++n) _Pragma("unroll") for (int k = 0; k < 2; ++k) dst[n][k] = *(const PG8_LAS bf16x8*)(lds + PG8_SB(b, h) + boff + n * 2048 + k * 1024); } while (0)
; #define PG8_MMA(ai, bj, At, Bt) do { __builtin_amdgcn_s_setprio(1); _Pragma("unroll") for (int m = 0; m < 4; ++m) _Pragma("unroll") for (int n = 0; n < 2; ++n) _Pragma("unroll") for (int k = 0; k < 2; ++k) \
;         acc[ai][bj][m][n] = __builtin_amdgcn_mfma_f32_16x16x32_bf16(Bt[n][k], At[m][k], acc[ai][bj][m][n], 0, 0, 0); __builtin_amdgcn_s_setprio(0); } while (0)
; #define PG8_WAIT_V(n) asm volatile("s_waitcnt vmcnt(" #n ")" ::: "memory")
; #define PG8_WAIT_L(n) asm volatile("s_waitcnt lgkmcnt(" #n ")" ::: "memory")
; #define PG8_BAR __builtin_amdgcn_s_barrier()
; #define PG8_SCHED __builtin_amdgcn_sched_barrier(0)
; template <class Epi, class Sched, bool ALIGN_EPI = false, bool SP2 = false>
; __device__ __forceinline__ void gemm_phase(PG8_LAS unsigned char* lds, const Gemm g, const Sched& S, const Epi& E) {
;     ...
;             PG8_WAIT_V(8); PG8_WAIT_L(0); PG8_BAR; PG8_MMA(1, 0, At, B0); PG8_MMA(1, 1, At, B1); PG8_BAR; PG8_SCHED;
;             PG8_LDB(B0, 1, 0); PG8_LDB(B1, 1, 1); PG8_SCHED; PG8_LDA(At, 1, 0); PG8_STAGE(PG8_SA(0, 1), a2 + hstep, voffA);
;             PG8_WAIT_V(8); PG8_WAIT_L(0); PG8_BAR; PG8_MMA(0, 0, At, B0); PG8_MMA(0, 1, At, B1); PG8_BAR; PG8_SCHED;
;             PG8_LDA(At, 1, 1); PG8_STAGE(PG8_SB(1, 0), b3, voffB); PG8_STAGE(PG8_SB(1, 1), b3 + hstep, voffB); PG8_STAGE(PG8_SA(1, 0), a3, voffA);
	v_mfma_f32_16x16x32_bf16 v[62:65], v[140:143], v[172:175], v[62:65]
	v_mfma_f32_16x16x32_bf16 v[58:61], v[148:151], v[172:175], v[58:61]
	v_mfma_f32_16x16x32_bf16 v[54:57], v[140:143], v[180:183], v[54:57]
	v_mfma_f32_16x16x32_bf16 v[50:53], v[148:151], v[180:183], v[50:53]
	v_mfma_f32_16x16x32_bf16 v[42:45], v[140:143], v[188:191], v[42:45]
	v_mfma_f32_16x16x32_bf16 v[34:37], v[148:151], v[188:191], v[34:37]
	v_mfma_f32_16x16x32_bf16 v[26:29], v[140:143], v[196:199], v[26:29]
	v_mfma_f32_16x16x32_bf16 v[18:21], v[148:151], v[196:199], v[18:21]
	v_mfma_f32_16x16x32_bf16 v[62:65], v[144:147], v[176:179], v[62:65]
	v_mfma_f32_16x16x32_bf16 v[58:61], v[152:155], v[176:179], v[58:61]
	v_mfma_f32_16x16x32_bf16 v[54:57], v[144:147], v[184:187], v[54:57]
	v_mfma_f32_16x16x32_bf16 v[50:53], v[152:155], v[184:187], v[50:53]
	v_mfma_f32_16x16x32_bf16 v[42:45], v[144:147], v[192:195], v[42:45]
	v_mfma_f32_16x16x32_bf16 v[34:37], v[152:155], v[192:195], v[34:37]
	v_mfma_f32_16x16x32_bf16 v[26:29], v[144:147], v[200:203], v[26:29]
	v_mfma_f32_16x16x32_bf16 v[18:21], v[152:155], v[200:203], v[18:21]
	s_setprio 0
	s_setprio 1
	v_mfma_f32_16x16x32_bf16 v[46:49], v[156:159], v[172:175], v[46:49]
	v_mfma_f32_16x16x32_bf16 v[38:41], v[164:167], v[172:175], v[38:41]
	v_mfma_f32_16x16x32_bf16 v[30:33], v[156:159], v[180:183], v[30:33]
	v_mfma_f32_16x16x32_bf16 v[22:25], v[164:167], v[180:183], v[22:25]
	v_mfma_f32_16x16x32_bf16 v[14:17], v[156:159], v[188:191], v[14:17]
	v_mfma_f32_16x16x32_bf16 v[10:13], v[164:167], v[188:191], v[10:13]
	v_mfma_f32_16x16x32_bf16 v[6:9], v[156:159], v[196:199], v[6:9]
	v_mfma_f32_16x16x32_bf16 v[2:5], v[164:167], v[196:199], v[2:5]
	v_mfma_f32_16x16x32_bf16 v[46:49], v[160:163], v[176:179], v[46:49]
	v_mfma_f32_16x16x32_bf16 v[38:41], v[168:171], v[176:179], v[38:41]
	v_mfma_f32_16x16x32_bf16 v[30:33], v[160:163], v[184:187], v[30:33]
	v_mfma_f32_16x16x32_bf16 v[22:25], v[168:171], v[184:187], v[22:25]
	v_mfma_f32_16x16x32_bf16 v[14:17], v[160:163], v[192:195], v[14:17]
	v_mfma_f32_16x16x32_bf16 v[10:13], v[168:171], v[192:195], v[10:13]
	v_mfma_f32_16x16x32_bf16 v[6:9], v[160:163], v[200:203], v[6:9]
	v_mfma_f32_16x16x32_bf16 v[2:5], v[168:171], v[200:203], v[2:5]
	s_setprio 0
	s_barrier
	v_add_u32_e32 v152, s70, v134
	v_add_u32_e32 v168, s27, v134
	ds_read_b128 v[140:143], v152
	ds_read_b128 v[144:147], v152 offset:1024
	ds_read_b128 v[148:151], v152 offset:2048
	ds_read_b128 v[152:155], v152 offset:3072
	ds_read_b128 v[156:159], v168
	ds_read_b128 v[160:163], v168 offset:1024
	ds_read_b128 v[164:167], v168 offset:2048
	ds_read_b128 v[168:171], v168 offset:3072
	s_mov_b32 m0, s56
	v_lshl_add_u64 v[212:213], s[40:41], 0, v[132:133]
	ds_read_b128 v[172:175], v139 offset:32768
	ds_read_b128 v[176:179], v139 offset:33792
	ds_read_b128 v[180:183], v139 offset:34816
	ds_read_b128 v[184:187], v139 offset:35840
	ds_read_b128 v[188:191], v139 offset:36864
	ds_read_b128 v[192:195], v139 offset:37888
	ds_read_b128 v[196:199], v139 offset:38912
	ds_read_b128 v[200:203], v139 offset:39936
	global_load_lds_dwordx4 v[212:213], off
	v_lshl_add_u64 v[212:213], s[40:41], 0, v[130:131]
	s_mov_b32 m0, s57
	s_nop 0
	global_load_lds_dwordx4 v[212:213], off
	s_waitcnt vmcnt(8)
	s_waitcnt lgkmcnt(0)
	s_setprio 1
	s_barrier
	v_mfma_f32_16x16x32_bf16 v[126:129], v[140:143], v[172:175], v[126:129]
	v_mfma_f32_16x16x32_bf16 v[122:125], v[148:151], v[172:175], v[122:125]
	v_mfma_f32_16x16x32_bf16 v[118:121], v[140:143], v[180:183], v[118:121]
	v_mfma_f32_16x16x32_bf16 v[114:117], v[148:151], v[180:183], v[114:117]
	v_mfma_f32_16x16x32_bf16 v[106:109], v[140:143], v[188:191], v[106:109]
	v_mfma_f32_16x16x32_bf16 v[98:101], v[148:151], v[188:191], v[98:101]
	v_mfma_f32_16x16x32_bf16 v[90:93], v[140:143], v[196:199], v[90:93]
	v_mfma_f32_16x16x32_bf16 v[82:85], v[148:151], v[196:199], v[82:85]
	v_mfma_f32_16x16x32_bf16 v[126:129], v[144:147], v[176:179], v[126:129]
	v_mfma_f32_16x16x32_bf16 v[122:125], v[152:155], v[176:179], v[122:125]
	v_mfma_f32_16x16x32_bf16 v[118:121], v[144:147], v[184:187], v[118:121]
	v_mfma_f32_16x16x32_bf16 v[114:117], v[152:155], v[184:187], v[114:117]
	v_mfma_f32_16x16x32_bf16 v[106:109], v[144:147], v[192:195], v[106:109]
	v_mfma_f32_16x16x32_bf16 v[98:101], v[152:155], v[192:195], v[98:101]
	v_mfma_f32_16x16x32_bf16 v[90:93], v[144:147], v[200:203], v[90:93]
	v_mfma_f32_16x16x32_bf16 v[82:85], v[152:155], v[200:203], v[82:85]
	s_setprio 0
	s_setprio 1
	v_mfma_f32_16x16x32_bf16 v[110:113], v[156:159], v[172:175], v[110:113]
	v_mfma_f32_16x16x32_bf16 v[102:105], v[164:167], v[172:175], v[102:105]
	v_mfma_f32_16x16x32_bf16 v[94:97], v[156:159], v[180:183], v[94:97]
	v_mfma_f32_16x16x32_bf16 v[86:89], v[164:167], v[180:183], v[86:89]
	v_mfma_f32_16x16x32_bf16 v[78:81], v[156:159], v[188:191], v[78:81]
	v_mfma_f32_16x16x32_bf16 v[74:77], v[164:167], v[188:191], v[74:77]
	v_mfma_f32_16x16x32_bf16 v[70:73], v[156:159], v[196:199], v[70:73]
	v_mfma_f32_16x16x32_bf16 v[66:69], v[164:167], v[196:199], v[66:69]
	v_mfma_f32_16x16x32_bf16 v[110:113], v[160:163], v[176:179], v[110:113]
	v_mfma_f32_16x16x32_bf16 v[102:105], v[168:171], v[176:179], v[102:105]
	v_mfma_f32_16x16x32_bf16 v[94:97], v[160:163], v[184:187], v[94:97]
	v_mfma_f32_16x16x32_bf16 v[86:89], v[168:171], v[184:187], v[86:89]
	v_mfma_f32_16x16x32_bf16 v[78:81], v[160:163], v[192:195], v[78:81]
	v_mfma_f32_16x16x32_bf16 v[74:77], v[168:171], v[192:195], v[74:77]
	v_mfma_f32_16x16x32_bf16 v[70:73], v[160:163], v[200:203], v[70:73]
	v_mfma_f32_16x16x32_bf16 v[66:69], v[168:171], v[200:203], v[66:69]
	s_setprio 0
	s_barrier
; #define PG8_STAGE(bufoff, gbase, voff) do { _Pragma("unroll") for (int _i = 0; _i < 2; ++_i) \
;         __builtin_amdgcn_global_load_lds((const unsigned*)((const char*)(gbase) + (voff)[_i]), (PG8_LAS unsigned*)(lds + (bufoff) + ldsw + _i * 8192), 16, 0, 0); } while (0)
; #define PG8_LDA(dst, b, h) do { _Pragma("unroll") for (int m = 0; m < 4; ++m) _Pragma("unroll") for (int k = 0; k < 2; ++k) dst[m][k] = *(const PG8_LAS bf16x8*)(lds + PG8_SA(b, h) + aoff + m * 2048 + k * 1024); } while (0)
; #define PG8_MMA(ai, bj, At, Bt) do { __builtin_amdgcn_s_setprio(1); _Pragma("unroll") for (int m = 0; m < 4; ++m) _Pragma("unroll") for (int n = 0; n < 2; ++n) _Pragma("unroll") for (int k = 0; k < 2; ++k) \
;         acc[ai][bj][m][n] = __builtin_amdgcn_mfma_f32_16x16x32_bf16(Bt[n][k], At[m][k], acc[ai][bj][m][n], 0, 0, 0); __builtin_amdgcn_s_setprio(0); } while (0)
; #define PG8_WAIT_V(n) asm volatile("s_waitcnt vmcnt(" #n ")" ::: "memory")
; #define PG8_WAIT_L(n) asm volatile("s_waitcnt lgkmcnt(" #n ")" ::: "memory")
; #define PG8_BAR __builtin_amdgcn_s_barrier()
; #define PG8_SCHED __builtin_amdgcn_sched_barrier(0)
; template <class Epi, class Sched, bool ALIGN_EPI = false, bool SP2 = false>
; __device__ __forceinline__ void gemm_phase(PG8_LAS unsigned char* lds, const Gemm g, const Sched& S, const Epi& E) {
;     ...
;         for (int t = 0; t < nt; t += 2) {
;     ...
;             PG8_LDA(At, 1, 1); PG8_STAGE(PG8_SB(1, 0), b3, voffB); PG8_STAGE(PG8_SB(1, 1), b3 + hstep, voffB); PG8_STAGE(PG8_SA(1, 0), a3, voffA);
;             PG8_WAIT_V(8); PG8_WAIT_L(0); PG8_BAR; PG8_MMA(1, 0, At, B0); PG8_MMA(1, 1, At, B1); PG8_BAR; PG8_SCHED;
	s_mov_b32 m0, s25
	v_lshl_add_u64 v[204:205], v[204:205], 0, s[10:11]
	ds_read_b128 v[172:175], v139 offset:49152
	ds_read_b128 v[176:179], v139 offset:50176
	ds_read_b128 v[180:183], v139 offset:51200
	ds_read_b128 v[184:187], v139 offset:52224
	ds_read_b128 v[188:191], v139 offset:53248
	ds_read_b128 v[192:195], v139 offset:54272
	ds_read_b128 v[196:199], v139 offset:55296
	ds_read_b128 v[200:203], v139 offset:56320
	global_load_lds_dwordx4 v[204:205], off
	v_lshl_add_u64 v[204:205], v[206:207], 0, s[10:11]
	s_mov_b32 m0, s3
	s_nop 0
	global_load_lds_dwordx4 v[204:205], off
	v_lshl_add_u64 v[204:205], s[38:39], 0, v[132:133]
	s_mov_b32 m0, s76
	s_nop 0
	global_load_lds_dwordx4 v[204:205], off
	v_lshl_add_u64 v[204:205], s[38:39], 0, v[130:131]
	s_mov_b32 m0, s75
	s_nop 0
	global_load_lds_dwordx4 v[204:205], off
	v_lshl_add_u64 v[204:205], v[208:209], 0, s[10:11]
	s_mov_b32 m0, s60
	s_nop 0
	global_load_lds_dwordx4 v[204:205], off
	v_lshl_add_u64 v[204:205], v[210:211], 0, s[10:11]
	s_mov_b32 m0, s61
	s_nop 0
	global_load_lds_dwordx4 v[204:205], off
	s_waitcnt vmcnt(8)
	s_waitcnt lgkmcnt(0)
	s_setprio 1
	s_barrier
	v_mfma_f32_16x16x32_bf16 v[62:65], v[140:143], v[172:175], v[62:65]
	v_mfma_f32_16x16x32_bf16 v[58:61], v[148:151], v[172:175], v[58:61]
	v_mfma_f32_16x16x32_bf16 v[54:57], v[140:143], v[180:183], v[54:57]
	v_mfma_f32_16x16x32_bf16 v[50:53], v[148:151], v[180:183], v[50:53]
	v_mfma_f32_16x16x32_bf16 v[42:45], v[140:143], v[188:191], v[42:45]
	v_mfma_f32_16x16x32_bf16 v[34:37], v[148:151], v[188:191], v[34:37]
	v_mfma_f32_16x16x32_bf16 v[26:29], v[140:143], v[196:199], v[26:29]
	v_mfma_f32_16x16x32_bf16 v[18:21], v[148:151], v[196:199], v[18:21]
	v_mfma_f32_16x16x32_bf16 v[62:65], v[144:147], v[176:179], v[62:65]
	v_mfma_f32_16x16x32_bf16 v[58:61], v[152:155], v[176:179], v[58:61]
	v_mfma_f32_16x16x32_bf16 v[54:57], v[144:147], v[184:187], v[54:57]
	v_mfma_f32_16x16x32_bf16 v[50:53], v[152:155], v[184:187], v[50:53]
	v_mfma_f32_16x16x32_bf16 v[42:45], v[144:147], v[192:195], v[42:45]
	v_mfma_f32_16x16x32_bf16 v[34:37], v[152:155], v[192:195], v[34:37]
	v_mfma_f32_16x16x32_bf16 v[26:29], v[144:147], v[200:203], v[26:29]
	v_mfma_f32_16x16x32_bf16 v[18:21], v[152:155], v[200:203], v[18:21]
	s_setprio 0
	s_setprio 1
	v_mfma_f32_16x16x32_bf16 v[46:49], v[156:159], v[172:175], v[46:49]
	v_mfma_f32_16x16x32_bf16 v[38:41], v[164:167], v[172:175], v[38:41]
	v_mfma_f32_16x16x32_bf16 v[30:33], v[156:159], v[180:183], v[30:33]
	v_mfma_f32_16x16x32_bf16 v[22:25], v[164:167], v[180:183], v[22:25]
	v_mfma_f32_16x16x32_bf16 v[14:17], v[156:159], v[188:191], v[14:17]
	v_mfma_f32_16x16x32_bf16 v[10:13], v[164:167], v[188:191], v[10:13]
	v_mfma_f32_16x16x32_bf16 v[6:9], v[156:159], v[196:199], v[6:9]
	v_mfma_f32_16x16x32_bf16 v[2:5], v[164:167], v[196:199], v[2:5]
	v_mfma_f32_16x16x32_bf16 v[46:49], v[160:163], v[176:179], v[46:49]
	v_mfma_f32_16x16x32_bf16 v[38:41], v[168:171], v[176:179], v[38:41]
	v_mfma_f32_16x16x32_bf16 v[30:33], v[160:163], v[184:187], v[30:33]
	v_mfma_f32_16x16x32_bf16 v[22:25], v[168:171], v[184:187], v[22:25]
	v_mfma_f32_16x16x32_bf16 v[14:17], v[160:163], v[192:195], v[14:17]
	v_mfma_f32_16x16x32_bf16 v[10:13], v[168:171], v[192:195], v[10:13]
	v_mfma_f32_16x16x32_bf16 v[6:9], v[160:163], v[200:203], v[6:9]
	v_mfma_f32_16x16x32_bf16 v[2:5], v[168:171], v[200:203], v[2:5]
	s_setprio 0
	s_movk_i32 s3, 0x100
	s_andn2_b64 vcc, exec, s[36:37]
	s_mov_b64 s[38:39], -1
	s_mov_b64 s[36:37], 0
	s_barrier
	s_cbranch_vccz .LBB0_1840
	s_and_b64 vcc, exec, s[14:15]
	s_cbranch_vccz .LBB0_1843
	s_barrier
